# scan fast paths: RWKV counted waits, GDN earlier q reload, LDS swizzle and per-chunk state swaps removed (bank conflicts not limiting)
# speedup vs baseline: 1.1206x; 1.0005x over previous
; __device__ __forceinline__ void scan_gdn(const Params& p, int l, int seq, int h, int qt, char* smem, const unsigned* wflags, unsigned wexpect) {
;     ...
;     const int nsteps = min(16, T - c * 16);
;     const float* vb = vec + cur * 16 * 288;
;     const float* sb = scb + cur * 64;
;     GdRegs RA, RB;
;     float* ydummy = yb + 16 * 32 + tid;
;     gd_load(RA, vb, sb, 0, k0, cl);
.LBB0_188:
	s_or_b64 exec, exec, s[50:51]
	s_lshl_b32 s52, s14, 4
	s_sub_i32 s51, s18, s52
	s_min_i32 s50, s51, 16
	s_cmp_lt_i32 s51, 1
	s_cbranch_scc1 .LBB0_193
	s_cmp_lg_u32 s50, 16
	s_cbranch_scc1 .Lgdf_slow0
	v_add_u32_e32 v166, 0x9200, v2
	v_mov_b32_e32 v167, 0
	v_add_u32_e32 v161, v151, v167
	v_sub_u32_e32 v162, v151, v167
	v_mov_b32_e32 v163, v150
	v_mov_b32_e32 v164, 0
	v_cndmask_b32_e64 v166, v149, v166, s[44:45]
	s_mov_b32 s51, 0
	s_branch .Lgdf_body

; __device__ __forceinline__ void scan_gdn(const Params& p, int l, int seq, int h, int qt, char* smem, const unsigned* wflags, unsigned wexpect) {
;     ...
;     const int nsteps = min(16, T - c * 16);
;     const float* vb = vec + cur * 16 * 288;
;     const float* sb = scb + cur * 64;
;     GdRegs RA, RB;
;     float* ydummy = yb + 16 * 32 + tid;
;     gd_load(RA, vb, sb, 0, k0, cl);
.LBB0_224:
	s_or_b64 exec, exec, s[50:51]
	s_lshl_b32 s14, s58, 4
	s_sub_i32 s51, s18, s14
	s_min_i32 s50, s51, 16
	s_cmp_lt_i32 s51, 1
	s_cbranch_scc1 .LBB0_229
	s_cmp_lg_u32 s50, 16
	s_cbranch_scc1 .Lgdf_slow1
	v_add_u32_e32 v166, 0x9200, v2
	v_mov_b32_e32 v167, 0
	s_movk_i32 s51, 0x4800
	v_add3_u32 v161, v151, v167, s51
	v_sub_u32_e32 v162, v151, v167
	v_add_u32_e32 v162, 0x4800, v162
	v_add_u32_e32 v163, 0x4800, v150
	v_mov_b32_e32 v164, 0x100
	v_cndmask_b32_e64 v166, v149, v166, s[44:45]
	s_mov_b32 s51, 1
	s_branch .Lgdf_body

; __device__ __forceinline__ void scan_ssm(const Params& p, int l, int seq, int h, char* smem, const unsigned* wflags, unsigned wexpect) {
;     ...
;     const int nsteps = min(16, T - c * 16);
;     const float* vb = vec + cur * 16 * 320;
;     const float* sb = scb + cur * 32;
;     SsRegs RA, RB;
;     float* ydummy = yb + 16 * 64 + tid * 2;
;     ss_load(RA, vb, sb, 0, n0, prow0);
.LBB0_643:
	s_or_b64 exec, exec, s[50:51]
	s_lshl_b32 s26, s14, 4
	s_sub_i32 s50, s18, s26
	s_min_i32 s27, s50, 16
	s_cmp_lt_i32 s50, 1
	s_cbranch_scc1 .LBB0_648
	s_cmp_lg_u32 s27, 16
	s_cbranch_scc1 .Lssf_slow0
	v_add_u32_e32 v154, 0xa100, v2
	v_mov_b32_e32 v155, 0
	v_add_u32_e32 v150, v126, v155
	v_sub_u32_e32 v151, v126, v155
	v_mov_b32_e32 v152, v165
	v_mov_b32_e32 v153, 0
	v_cndmask_b32_e64 v154, v164, v154, s[44:45]
	s_mov_b32 s50, 0
	s_branch .Lssf_body

; __device__ __forceinline__ void scan_ssm(const Params& p, int l, int seq, int h, char* smem, const unsigned* wflags, unsigned wexpect) {
;     ...
;     const int nsteps = min(16, T - c * 16);
;     const float* vb = vec + cur * 16 * 320;
;     const float* sb = scb + cur * 32;
;     SsRegs RA, RB;
;     float* ydummy = yb + 16 * 64 + tid * 2;
;     ss_load(RA, vb, sb, 0, n0, prow0);
.LBB0_679:
	s_or_b64 exec, exec, s[50:51]
	s_lshl_b32 s14, s26, 4
	s_sub_i32 s27, s18, s14
	s_min_i32 s26, s27, 16
	s_cmp_lt_i32 s27, 1
	s_cbranch_scc1 .LBB0_684
	s_cmp_lg_u32 s26, 16
	s_cbranch_scc1 .Lssf_slow1
	v_add_u32_e32 v154, 0xa100, v2
	v_mov_b32_e32 v155, 0
	s_movk_i32 s50, 0x5000
	v_add3_u32 v150, v126, v155, s50
	v_sub_u32_e32 v151, v126, v155
	v_add_u32_e32 v151, 0x5000, v151
	v_add_u32_e32 v152, 0x5000, v165
	v_mov_b32_e32 v153, 0x80
	v_cndmask_b32_e64 v154, v164, v154, s[44:45]
	s_mov_b32 s50, 1
	s_branch .Lssf_body

; __device__ __forceinline__ float red8(float v) { v = red4(v); v += dppf<0x141>(v); return v; }
; __device__ __forceinline__ f32x2 lo2(const f32x4& v) { return __builtin_shufflevector(v, v, 0, 1); }
; __device__ __forceinline__ f32x2 hi2(const f32x4& v) { return __builtin_shufflevector(v, v, 2, 3); }
; __device__ __forceinline__ f32x2 splat2(float x) { return (f32x2){x, x}; }
; #define SCAN_INTERLEAVE(nds, nvalu)                                   \
;   _Pragma("unroll") for (int i_ = 0; i_ < (nds); ++i_) {               \
;     __builtin_amdgcn_sched_group_barrier(0x100, 1, 0);                 \
;     __builtin_amdgcn_sched_group_barrier(0x002, (nvalu), 0);           \
;   }
; __device__ __forceinline__ float gd_step(f32x2 (&S)[8], const GdRegs& R) {
;   f32x2 k0a = splat2(0.f), k1a = splat2(0.f), q0a = splat2(0.f), q1a = splat2(0.f);
; #pragma unroll
;   for (int q = 0; q < 4; ++q) {
;     k0a += S[2 * q] * lo2(R.k[q]);
;     k1a += S[2 * q + 1] * hi2(R.k[q]);
;     q0a += S[2 * q] * lo2(R.q[q]);
;     q1a += S[2 * q + 1] * hi2(R.q[q]);
;   }
;   k0a += k1a; q0a += q1a;
;   const float dK = red8(k0a.x + k0a.y), dQ = red8(q0a.x + q0a.y);
;   const float vn = R.sc.y * (R.v - R.sc.x * dK);
;   const float o = R.sc.x * dQ + R.sc.z * vn;
;   const f32x2 al2 = splat2(R.sc.x), vn2 = splat2(vn);
; #pragma unroll
;   for (int q = 0; q < 4; ++q) {
;     S[2 * q] = S[2 * q] * al2 + lo2(R.k[q]) * vn2;
;     S[2 * q + 1] = S[2 * q + 1] * al2 + hi2(R.k[q]) * vn2;
;   }
;   return o;
; }
; __device__ __forceinline__ void scan_gdn(const Params& p, int l, int seq, int h, int qt, char* smem, const unsigned* wflags, unsigned wexpect) {
;     ...
;     for (int t = 0; t < nsteps; t += 2) {
;       gd_load(RB, vb, sb, min(t + 1, 15), k0, cl);
;       const float o0v = gd_step(S, RA);
;       *((part == 0) ? (yb + t * 32 + cl) : ydummy) = o0v;
;       SCAN_INTERLEAVE(10, 4);
;       if (t + 1 < nsteps) {
;         gd_load(RA, vb, sb, min(t + 2, 15), k0, cl);
;         const float o1v = gd_step(S, RB);
;         *((part == 0) ? (yb + (t + 1) * 32 + cl) : ydummy) = o1v;
;         SCAN_INTERLEAVE(10, 4);
;       }
.Lgdf_body:
	ds_read_b32 v100, v163 offset:1024
	ds_read_b128 v[92:95], v164 offset:36864
	ds_read_b128 v[60:63], v161 offset:512
	ds_read_b128 v[36:39], v161 offset:0
	ds_read_b128 v[64:67], v162 offset:528
	ds_read_b128 v[40:43], v162 offset:16
	ds_read_b128 v[68:71], v161 offset:544
	ds_read_b128 v[44:47], v161 offset:32
	ds_read_b128 v[72:75], v162 offset:560
	ds_read_b128 v[48:51], v162 offset:48
	s_waitcnt lgkmcnt(0)
	s_nop 0
	ds_read_b128 v[76:79], v161 offset:1664
	ds_read_b128 v[80:83], v162 offset:1680
	ds_read_b128 v[84:87], v161 offset:1696
	ds_read_b128 v[88:91], v162 offset:1712
	ds_read_b32 v101, v163 offset:2176
	ds_read_b128 v[96:99], v164 offset:36880
	ds_read_b128 v[52:55], v161 offset:1184
	ds_read_b128 v[56:59], v162 offset:1200
	v_pk_mul_f32 v[102:103], v[120:121], v[60:61]
	v_pk_mul_f32 v[104:105], v[120:121], v[36:37]
	v_pk_fma_f32 v[102:103], v[122:123], v[62:63], v[102:103]
	v_pk_fma_f32 v[104:105], v[122:123], v[38:39], v[104:105]
	v_pk_mul_f32 v[120:121], v[120:121], v[92:93] op_sel_hi:[1,0]
	v_pk_fma_f32 v[102:103], v[124:125], v[64:65], v[102:103]
	v_pk_fma_f32 v[104:105], v[124:125], v[40:41], v[104:105]
	v_pk_mul_f32 v[122:123], v[122:123], v[92:93] op_sel_hi:[1,0]
	v_pk_fma_f32 v[102:103], v[126:127], v[66:67], v[102:103]
	v_pk_fma_f32 v[104:105], v[126:127], v[42:43], v[104:105]
	v_pk_mul_f32 v[124:125], v[124:125], v[92:93] op_sel_hi:[1,0]
	ds_read_b128 v[36:39], v161 offset:1152
	ds_read_b128 v[40:43], v162 offset:1168
	v_pk_fma_f32 v[102:103], v[128:129], v[68:69], v[102:103]
	v_pk_fma_f32 v[104:105], v[128:129], v[44:45], v[104:105]
	v_pk_mul_f32 v[126:127], v[126:127], v[92:93] op_sel_hi:[1,0]
	v_pk_fma_f32 v[102:103], v[130:131], v[70:71], v[102:103]
	v_pk_fma_f32 v[104:105], v[130:131], v[46:47], v[104:105]
	v_pk_fma_f32 v[102:103], v[132:133], v[72:73], v[102:103]
	v_pk_fma_f32 v[104:105], v[132:133], v[48:49], v[104:105]
	v_pk_fma_f32 v[102:103], v[134:135], v[74:75], v[102:103]
	v_pk_fma_f32 v[104:105], v[134:135], v[50:51], v[104:105]
	v_add_f32_e64 v102, v102, v103
	v_add_f32_e64 v104, v104, v105
	v_pk_mul_f32 v[128:129], v[128:129], v[92:93] op_sel_hi:[1,0]
	v_add_f32_dpp v102, v102, v102 quad_perm:[1,0,3,2] row_mask:0xf bank_mask:0xf bound_ctrl:1
	v_add_f32_dpp v104, v104, v104 quad_perm:[1,0,3,2] row_mask:0xf bank_mask:0xf bound_ctrl:1
	v_pk_mul_f32 v[130:131], v[130:131], v[92:93] op_sel_hi:[1,0]
	v_add_f32_dpp v102, v102, v102 quad_perm:[2,3,0,1] row_mask:0xf bank_mask:0xf bound_ctrl:1
	v_add_f32_dpp v104, v104, v104 quad_perm:[2,3,0,1] row_mask:0xf bank_mask:0xf bound_ctrl:1
	v_pk_mul_f32 v[132:133], v[132:133], v[92:93] op_sel_hi:[1,0]
	v_add_f32_dpp v102, v102, v102 row_half_mirror row_mask:0xf bank_mask:0xf bound_ctrl:1
	v_add_f32_dpp v104, v104, v104 row_half_mirror row_mask:0xf bank_mask:0xf bound_ctrl:1
	v_fma_f32 v105, -v92, v102, v100
	v_pk_mul_f32 v[106:107], v[92:93], v[104:105]
	v_pk_mul_f32 v[134:135], v[134:135], v[92:93] op_sel_hi:[1,0]
	v_pk_fma_f32 v[120:121], v[60:61], v[106:107], v[120:121] op_sel:[0,1,0]
	v_pk_fma_f32 v[122:123], v[62:63], v[106:107], v[122:123] op_sel:[0,1,0]
	v_fma_f32 v106, v94, v107, v106
	v_pk_fma_f32 v[124:125], v[64:65], v[106:107], v[124:125] op_sel:[0,1,0]
	v_pk_fma_f32 v[126:127], v[66:67], v[106:107], v[126:127] op_sel:[0,1,0]
	v_pk_fma_f32 v[128:129], v[68:69], v[106:107], v[128:129] op_sel:[0,1,0]
	v_pk_fma_f32 v[130:131], v[70:71], v[106:107], v[130:131] op_sel:[0,1,0]
	v_pk_fma_f32 v[132:133], v[72:73], v[106:107], v[132:133] op_sel:[0,1,0]
	v_pk_fma_f32 v[134:135], v[74:75], v[106:107], v[134:135] op_sel:[0,1,0]
	ds_write_b32 v166, v106 offset:0
	s_waitcnt lgkmcnt(1)
	s_nop 0
	ds_read_b128 v[60:63], v161 offset:2816
	ds_read_b128 v[64:67], v162 offset:2832
	ds_read_b128 v[68:71], v161 offset:2848
	ds_read_b128 v[72:75], v162 offset:2864
	ds_read_b32 v100, v163 offset:3328
	ds_read_b128 v[92:95], v164 offset:36896
	ds_read_b128 v[44:47], v161 offset:2336
	ds_read_b128 v[48:51], v162 offset:2352
	v_pk_mul_f32 v[102:103], v[120:121], v[76:77]
	v_pk_mul_f32 v[104:105], v[120:121], v[36:37]
	v_pk_fma_f32 v[102:103], v[122:123], v[78:79], v[102:103]
	v_pk_fma_f32 v[104:105], v[122:123], v[38:39], v[104:105]
	v_pk_mul_f32 v[120:121], v[120:121], v[96:97] op_sel_hi:[1,0]
	v_pk_fma_f32 v[102:103], v[124:125], v[80:81], v[102:103]
	v_pk_fma_f32 v[104:105], v[124:125], v[40:41], v[104:105]
	v_pk_mul_f32 v[122:123], v[122:123], v[96:97] op_sel_hi:[1,0]
	v_pk_fma_f32 v[102:103], v[126:127], v[82:83], v[102:103]
	v_pk_fma_f32 v[104:105], v[126:127], v[42:43], v[104:105]
	v_pk_mul_f32 v[124:125], v[124:125], v[96:97] op_sel_hi:[1,0]
	ds_read_b128 v[36:39], v161 offset:2304
	ds_read_b128 v[40:43], v162 offset:2320
	v_pk_fma_f32 v[102:103], v[128:129], v[84:85], v[102:103]
	v_pk_fma_f32 v[104:105], v[128:129], v[52:53], v[104:105]
	v_pk_mul_f32 v[126:127], v[126:127], v[96:97] op_sel_hi:[1,0]
	v_pk_fma_f32 v[102:103], v[130:131], v[86:87], v[102:103]
	v_pk_fma_f32 v[104:105], v[130:131], v[54:55], v[104:105]
	v_pk_fma_f32 v[102:103], v[132:133], v[88:89], v[102:103]
	v_pk_fma_f32 v[104:105], v[132:133], v[56:57], v[104:105]
	v_pk_fma_f32 v[102:103], v[134:135], v[90:91], v[102:103]
	v_pk_fma_f32 v[104:105], v[134:135], v[58:59], v[104:105]
	v_add_f32_e64 v102, v102, v103
	v_add_f32_e64 v104, v104, v105
	v_pk_mul_f32 v[128:129], v[128:129], v[96:97] op_sel_hi:[1,0]
	v_add_f32_dpp v102, v102, v102 quad_perm:[1,0,3,2] row_mask:0xf bank_mask:0xf bound_ctrl:1
	v_add_f32_dpp v104, v104, v104 quad_perm:[1,0,3,2] row_mask:0xf bank_mask:0xf bound_ctrl:1
	v_pk_mul_f32 v[130:131], v[130:131], v[96:97] op_sel_hi:[1,0]
	v_add_f32_dpp v102, v102, v102 quad_perm:[2,3,0,1] row_mask:0xf bank_mask:0xf bound_ctrl:1
	v_add_f32_dpp v104, v104, v104 quad_perm:[2,3,0,1] row_mask:0xf bank_mask:0xf bound_ctrl:1
	v_pk_mul_f32 v[132:133], v[132:133], v[96:97] op_sel_hi:[1,0]
	v_add_f32_dpp v102, v102, v102 row_half_mirror row_mask:0xf bank_mask:0xf bound_ctrl:1
	v_add_f32_dpp v104, v104, v104 row_half_mirror row_mask:0xf bank_mask:0xf bound_ctrl:1
	v_fma_f32 v105, -v96, v102, v101
	v_pk_mul_f32 v[106:107], v[96:97], v[104:105]
	v_pk_mul_f32 v[134:135], v[134:135], v[96:97] op_sel_hi:[1,0]
	v_pk_fma_f32 v[120:121], v[76:77], v[106:107], v[120:121] op_sel:[0,1,0]
	v_pk_fma_f32 v[122:123], v[78:79], v[106:107], v[122:123] op_sel:[0,1,0]
	v_fma_f32 v106, v98, v107, v106
	v_pk_fma_f32 v[124:125], v[80:81], v[106:107], v[124:125] op_sel:[0,1,0]
	v_pk_fma_f32 v[126:127], v[82:83], v[106:107], v[126:127] op_sel:[0,1,0]
	v_pk_fma_f32 v[128:129], v[84:85], v[106:107], v[128:129] op_sel:[0,1,0]
	v_pk_fma_f32 v[130:131], v[86:87], v[106:107], v[130:131] op_sel:[0,1,0]
	v_pk_fma_f32 v[132:133], v[88:89], v[106:107], v[132:133] op_sel:[0,1,0]
	v_pk_fma_f32 v[134:135], v[90:91], v[106:107], v[134:135] op_sel:[0,1,0]
	ds_write_b32 v166, v106 offset:128
	s_waitcnt lgkmcnt(1)
; __device__ __forceinline__ float red8(float v) { v = red4(v); v += dppf<0x141>(v); return v; }
; __device__ __forceinline__ f32x2 lo2(const f32x4& v) { return __builtin_shufflevector(v, v, 0, 1); }
; __device__ __forceinline__ f32x2 hi2(const f32x4& v) { return __builtin_shufflevector(v, v, 2, 3); }
; __device__ __forceinline__ f32x2 splat2(float x) { return (f32x2){x, x}; }
; #define SCAN_INTERLEAVE(nds, nvalu)                                   \
;   _Pragma("unroll") for (int i_ = 0; i_ < (nds); ++i_) {               \
;     __builtin_amdgcn_sched_group_barrier(0x100, 1, 0);                 \
;     __builtin_amdgcn_sched_group_barrier(0x002, (nvalu), 0);           \
;   }
; __device__ __forceinline__ float gd_step(f32x2 (&S)[8], const GdRegs& R) {
;   f32x2 k0a = splat2(0.f), k1a = splat2(0.f), q0a = splat2(0.f), q1a = splat2(0.f);
; #pragma unroll
;   for (int q = 0; q < 4; ++q) {
;     k0a += S[2 * q] * lo2(R.k[q]);
;     k1a += S[2 * q + 1] * hi2(R.k[q]);
;     q0a += S[2 * q] * lo2(R.q[q]);
;     q1a += S[2 * q + 1] * hi2(R.q[q]);
;   }
;   k0a += k1a; q0a += q1a;
;   const float dK = red8(k0a.x + k0a.y), dQ = red8(q0a.x + q0a.y);
;   const float vn = R.sc.y * (R.v - R.sc.x * dK);
;   const float o = R.sc.x * dQ + R.sc.z * vn;
;   const f32x2 al2 = splat2(R.sc.x), vn2 = splat2(vn);
; #pragma unroll
;   for (int q = 0; q < 4; ++q) {
;     S[2 * q] = S[2 * q] * al2 + lo2(R.k[q]) * vn2;
;     S[2 * q + 1] = S[2 * q + 1] * al2 + hi2(R.k[q]) * vn2;
;   }
;   return o;
; }
; __device__ __forceinline__ void scan_gdn(const Params& p, int l, int seq, int h, int qt, char* smem, const unsigned* wflags, unsigned wexpect) {
;     ...
;     for (int t = 0; t < nsteps; t += 2) {
;       gd_load(RB, vb, sb, min(t + 1, 15), k0, cl);
;       const float o0v = gd_step(S, RA);
;       *((part == 0) ? (yb + t * 32 + cl) : ydummy) = o0v;
;       SCAN_INTERLEAVE(10, 4);
;       if (t + 1 < nsteps) {
;         gd_load(RA, vb, sb, min(t + 2, 15), k0, cl);
;         const float o1v = gd_step(S, RB);
;         *((part == 0) ? (yb + (t + 1) * 32 + cl) : ydummy) = o1v;
;         SCAN_INTERLEAVE(10, 4);
;       }
	s_nop 0
	ds_read_b128 v[76:79], v161 offset:3968
	ds_read_b128 v[80:83], v162 offset:3984
	ds_read_b128 v[84:87], v161 offset:4000
	ds_read_b128 v[88:91], v162 offset:4016
	ds_read_b32 v101, v163 offset:4480
	ds_read_b128 v[96:99], v164 offset:36912
	ds_read_b128 v[52:55], v161 offset:3488
	ds_read_b128 v[56:59], v162 offset:3504
	v_pk_mul_f32 v[102:103], v[120:121], v[60:61]
	v_pk_mul_f32 v[104:105], v[120:121], v[36:37]
	v_pk_fma_f32 v[102:103], v[122:123], v[62:63], v[102:103]
	v_pk_fma_f32 v[104:105], v[122:123], v[38:39], v[104:105]
	v_pk_mul_f32 v[120:121], v[120:121], v[92:93] op_sel_hi:[1,0]
	v_pk_fma_f32 v[102:103], v[124:125], v[64:65], v[102:103]
	v_pk_fma_f32 v[104:105], v[124:125], v[40:41], v[104:105]
	v_pk_mul_f32 v[122:123], v[122:123], v[92:93] op_sel_hi:[1,0]
	v_pk_fma_f32 v[102:103], v[126:127], v[66:67], v[102:103]
	v_pk_fma_f32 v[104:105], v[126:127], v[42:43], v[104:105]
	v_pk_mul_f32 v[124:125], v[124:125], v[92:93] op_sel_hi:[1,0]
	ds_read_b128 v[36:39], v161 offset:3456
	ds_read_b128 v[40:43], v162 offset:3472
	v_pk_fma_f32 v[102:103], v[128:129], v[68:69], v[102:103]
	v_pk_fma_f32 v[104:105], v[128:129], v[44:45], v[104:105]
	v_pk_mul_f32 v[126:127], v[126:127], v[92:93] op_sel_hi:[1,0]
	v_pk_fma_f32 v[102:103], v[130:131], v[70:71], v[102:103]
	v_pk_fma_f32 v[104:105], v[130:131], v[46:47], v[104:105]
	v_pk_fma_f32 v[102:103], v[132:133], v[72:73], v[102:103]
	v_pk_fma_f32 v[104:105], v[132:133], v[48:49], v[104:105]
	v_pk_fma_f32 v[102:103], v[134:135], v[74:75], v[102:103]
	v_pk_fma_f32 v[104:105], v[134:135], v[50:51], v[104:105]
	v_add_f32_e64 v102, v102, v103
	v_add_f32_e64 v104, v104, v105
	v_pk_mul_f32 v[128:129], v[128:129], v[92:93] op_sel_hi:[1,0]
	v_add_f32_dpp v102, v102, v102 quad_perm:[1,0,3,2] row_mask:0xf bank_mask:0xf bound_ctrl:1
	v_add_f32_dpp v104, v104, v104 quad_perm:[1,0,3,2] row_mask:0xf bank_mask:0xf bound_ctrl:1
	v_pk_mul_f32 v[130:131], v[130:131], v[92:93] op_sel_hi:[1,0]
	v_add_f32_dpp v102, v102, v102 quad_perm:[2,3,0,1] row_mask:0xf bank_mask:0xf bound_ctrl:1
	v_add_f32_dpp v104, v104, v104 quad_perm:[2,3,0,1] row_mask:0xf bank_mask:0xf bound_ctrl:1
	v_pk_mul_f32 v[132:133], v[132:133], v[92:93] op_sel_hi:[1,0]
	v_add_f32_dpp v102, v102, v102 row_half_mirror row_mask:0xf bank_mask:0xf bound_ctrl:1
	v_add_f32_dpp v104, v104, v104 row_half_mirror row_mask:0xf bank_mask:0xf bound_ctrl:1
	v_fma_f32 v105, -v92, v102, v100
	v_pk_mul_f32 v[106:107], v[92:93], v[104:105]
	v_pk_mul_f32 v[134:135], v[134:135], v[92:93] op_sel_hi:[1,0]
	v_pk_fma_f32 v[120:121], v[60:61], v[106:107], v[120:121] op_sel:[0,1,0]
	v_pk_fma_f32 v[122:123], v[62:63], v[106:107], v[122:123] op_sel:[0,1,0]
	v_fma_f32 v106, v94, v107, v106
	v_pk_fma_f32 v[124:125], v[64:65], v[106:107], v[124:125] op_sel:[0,1,0]
	v_pk_fma_f32 v[126:127], v[66:67], v[106:107], v[126:127] op_sel:[0,1,0]
	v_pk_fma_f32 v[128:129], v[68:69], v[106:107], v[128:129] op_sel:[0,1,0]
	v_pk_fma_f32 v[130:131], v[70:71], v[106:107], v[130:131] op_sel:[0,1,0]
	v_pk_fma_f32 v[132:133], v[72:73], v[106:107], v[132:133] op_sel:[0,1,0]
	v_pk_fma_f32 v[134:135], v[74:75], v[106:107], v[134:135] op_sel:[0,1,0]
	ds_write_b32 v166, v106 offset:256
	s_waitcnt lgkmcnt(1)
	s_nop 0
	ds_read_b128 v[60:63], v161 offset:5120
	ds_read_b128 v[64:67], v162 offset:5136
	ds_read_b128 v[68:71], v161 offset:5152
	ds_read_b128 v[72:75], v162 offset:5168
	ds_read_b32 v100, v163 offset:5632
	ds_read_b128 v[92:95], v164 offset:36928
	ds_read_b128 v[44:47], v161 offset:4640
	ds_read_b128 v[48:51], v162 offset:4656
	v_pk_mul_f32 v[102:103], v[120:121], v[76:77]
	v_pk_mul_f32 v[104:105], v[120:121], v[36:37]
	v_pk_fma_f32 v[102:103], v[122:123], v[78:79], v[102:103]
	v_pk_fma_f32 v[104:105], v[122:123], v[38:39], v[104:105]
	v_pk_mul_f32 v[120:121], v[120:121], v[96:97] op_sel_hi:[1,0]
	v_pk_fma_f32 v[102:103], v[124:125], v[80:81], v[102:103]
	v_pk_fma_f32 v[104:105], v[124:125], v[40:41], v[104:105]
	v_pk_mul_f32 v[122:123], v[122:123], v[96:97] op_sel_hi:[1,0]
	v_pk_fma_f32 v[102:103], v[126:127], v[82:83], v[102:103]
	v_pk_fma_f32 v[104:105], v[126:127], v[42:43], v[104:105]
	v_pk_mul_f32 v[124:125], v[124:125], v[96:97] op_sel_hi:[1,0]
	ds_read_b128 v[36:39], v161 offset:4608
	ds_read_b128 v[40:43], v162 offset:4624
	v_pk_fma_f32 v[102:103], v[128:129], v[84:85], v[102:103]
	v_pk_fma_f32 v[104:105], v[128:129], v[52:53], v[104:105]
	v_pk_mul_f32 v[126:127], v[126:127], v[96:97] op_sel_hi:[1,0]
	v_pk_fma_f32 v[102:103], v[130:131], v[86:87], v[102:103]
	v_pk_fma_f32 v[104:105], v[130:131], v[54:55], v[104:105]
	v_pk_fma_f32 v[102:103], v[132:133], v[88:89], v[102:103]
	v_pk_fma_f32 v[104:105], v[132:133], v[56:57], v[104:105]
	v_pk_fma_f32 v[102:103], v[134:135], v[90:91], v[102:103]
	v_pk_fma_f32 v[104:105], v[134:135], v[58:59], v[104:105]
	v_add_f32_e64 v102, v102, v103
	v_add_f32_e64 v104, v104, v105
	v_pk_mul_f32 v[128:129], v[128:129], v[96:97] op_sel_hi:[1,0]
	v_add_f32_dpp v102, v102, v102 quad_perm:[1,0,3,2] row_mask:0xf bank_mask:0xf bound_ctrl:1
	v_add_f32_dpp v104, v104, v104 quad_perm:[1,0,3,2] row_mask:0xf bank_mask:0xf bound_ctrl:1
	v_pk_mul_f32 v[130:131], v[130:131], v[96:97] op_sel_hi:[1,0]
	v_add_f32_dpp v102, v102, v102 quad_perm:[2,3,0,1] row_mask:0xf bank_mask:0xf bound_ctrl:1
	v_add_f32_dpp v104, v104, v104 quad_perm:[2,3,0,1] row_mask:0xf bank_mask:0xf bound_ctrl:1
	v_pk_mul_f32 v[132:133], v[132:133], v[96:97] op_sel_hi:[1,0]
	v_add_f32_dpp v102, v102, v102 row_half_mirror row_mask:0xf bank_mask:0xf bound_ctrl:1
	v_add_f32_dpp v104, v104, v104 row_half_mirror row_mask:0xf bank_mask:0xf bound_ctrl:1
	v_fma_f32 v105, -v96, v102, v101
	v_pk_mul_f32 v[106:107], v[96:97], v[104:105]
	v_pk_mul_f32 v[134:135], v[134:135], v[96:97] op_sel_hi:[1,0]
	v_pk_fma_f32 v[120:121], v[76:77], v[106:107], v[120:121] op_sel:[0,1,0]
	v_pk_fma_f32 v[122:123], v[78:79], v[106:107], v[122:123] op_sel:[0,1,0]
	v_fma_f32 v106, v98, v107, v106
	v_pk_fma_f32 v[124:125], v[80:81], v[106:107], v[124:125] op_sel:[0,1,0]
	v_pk_fma_f32 v[126:127], v[82:83], v[106:107], v[126:127] op_sel:[0,1,0]
	v_pk_fma_f32 v[128:129], v[84:85], v[106:107], v[128:129] op_sel:[0,1,0]
	v_pk_fma_f32 v[130:131], v[86:87], v[106:107], v[130:131] op_sel:[0,1,0]
	v_pk_fma_f32 v[132:133], v[88:89], v[106:107], v[132:133] op_sel:[0,1,0]
	v_pk_fma_f32 v[134:135], v[90:91], v[106:107], v[134:135] op_sel:[0,1,0]
	ds_write_b32 v166, v106 offset:384
	s_waitcnt lgkmcnt(1)
; __device__ __forceinline__ float red8(float v) { v = red4(v); v += dppf<0x141>(v); return v; }
; __device__ __forceinline__ f32x2 lo2(const f32x4& v) { return __builtin_shufflevector(v, v, 0, 1); }
; __device__ __forceinline__ f32x2 hi2(const f32x4& v) { return __builtin_shufflevector(v, v, 2, 3); }
; __device__ __forceinline__ f32x2 splat2(float x) { return (f32x2){x, x}; }
; #define SCAN_INTERLEAVE(nds, nvalu)                                   \
;   _Pragma("unroll") for (int i_ = 0; i_ < (nds); ++i_) {               \
;     __builtin_amdgcn_sched_group_barrier(0x100, 1, 0);                 \
;     __builtin_amdgcn_sched_group_barrier(0x002, (nvalu), 0);           \
;   }
; __device__ __forceinline__ float gd_step(f32x2 (&S)[8], const GdRegs& R) {
;   f32x2 k0a = splat2(0.f), k1a = splat2(0.f), q0a = splat2(0.f), q1a = splat2(0.f);
; #pragma unroll
;   for (int q = 0; q < 4; ++q) {
;     k0a += S[2 * q] * lo2(R.k[q]);
;     k1a += S[2 * q + 1] * hi2(R.k[q]);
;     q0a += S[2 * q] * lo2(R.q[q]);
;     q1a += S[2 * q + 1] * hi2(R.q[q]);
;   }
;   k0a += k1a; q0a += q1a;
;   const float dK = red8(k0a.x + k0a.y), dQ = red8(q0a.x + q0a.y);
;   const float vn = R.sc.y * (R.v - R.sc.x * dK);
;   const float o = R.sc.x * dQ + R.sc.z * vn;
;   const f32x2 al2 = splat2(R.sc.x), vn2 = splat2(vn);
; #pragma unroll
;   for (int q = 0; q < 4; ++q) {
;     S[2 * q] = S[2 * q] * al2 + lo2(R.k[q]) * vn2;
;     S[2 * q + 1] = S[2 * q + 1] * al2 + hi2(R.k[q]) * vn2;
;   }
;   return o;
; }
; __device__ __forceinline__ void scan_gdn(const Params& p, int l, int seq, int h, int qt, char* smem, const unsigned* wflags, unsigned wexpect) {
;     ...
;     for (int t = 0; t < nsteps; t += 2) {
;       gd_load(RB, vb, sb, min(t + 1, 15), k0, cl);
;       const float o0v = gd_step(S, RA);
;       *((part == 0) ? (yb + t * 32 + cl) : ydummy) = o0v;
;       SCAN_INTERLEAVE(10, 4);
;       if (t + 1 < nsteps) {
;         gd_load(RA, vb, sb, min(t + 2, 15), k0, cl);
;         const float o1v = gd_step(S, RB);
;         *((part == 0) ? (yb + (t + 1) * 32 + cl) : ydummy) = o1v;
;         SCAN_INTERLEAVE(10, 4);
;       }
	s_nop 0
	ds_read_b128 v[76:79], v161 offset:6272
	ds_read_b128 v[80:83], v162 offset:6288
	ds_read_b128 v[84:87], v161 offset:6304
	ds_read_b128 v[88:91], v162 offset:6320
	ds_read_b32 v101, v163 offset:6784
	ds_read_b128 v[96:99], v164 offset:36944
	ds_read_b128 v[52:55], v161 offset:5792
	ds_read_b128 v[56:59], v162 offset:5808
	v_pk_mul_f32 v[102:103], v[120:121], v[60:61]
	v_pk_mul_f32 v[104:105], v[120:121], v[36:37]
	v_pk_fma_f32 v[102:103], v[122:123], v[62:63], v[102:103]
	v_pk_fma_f32 v[104:105], v[122:123], v[38:39], v[104:105]
	v_pk_mul_f32 v[120:121], v[120:121], v[92:93] op_sel_hi:[1,0]
	v_pk_fma_f32 v[102:103], v[124:125], v[64:65], v[102:103]
	v_pk_fma_f32 v[104:105], v[124:125], v[40:41], v[104:105]
	v_pk_mul_f32 v[122:123], v[122:123], v[92:93] op_sel_hi:[1,0]
	v_pk_fma_f32 v[102:103], v[126:127], v[66:67], v[102:103]
	v_pk_fma_f32 v[104:105], v[126:127], v[42:43], v[104:105]
	v_pk_mul_f32 v[124:125], v[124:125], v[92:93] op_sel_hi:[1,0]
	ds_read_b128 v[36:39], v161 offset:5760
	ds_read_b128 v[40:43], v162 offset:5776
	v_pk_fma_f32 v[102:103], v[128:129], v[68:69], v[102:103]
	v_pk_fma_f32 v[104:105], v[128:129], v[44:45], v[104:105]
	v_pk_mul_f32 v[126:127], v[126:127], v[92:93] op_sel_hi:[1,0]
	v_pk_fma_f32 v[102:103], v[130:131], v[70:71], v[102:103]
	v_pk_fma_f32 v[104:105], v[130:131], v[46:47], v[104:105]
	v_pk_fma_f32 v[102:103], v[132:133], v[72:73], v[102:103]
	v_pk_fma_f32 v[104:105], v[132:133], v[48:49], v[104:105]
	v_pk_fma_f32 v[102:103], v[134:135], v[74:75], v[102:103]
	v_pk_fma_f32 v[104:105], v[134:135], v[50:51], v[104:105]
	v_add_f32_e64 v102, v102, v103
	v_add_f32_e64 v104, v104, v105
	v_pk_mul_f32 v[128:129], v[128:129], v[92:93] op_sel_hi:[1,0]
	v_add_f32_dpp v102, v102, v102 quad_perm:[1,0,3,2] row_mask:0xf bank_mask:0xf bound_ctrl:1
	v_add_f32_dpp v104, v104, v104 quad_perm:[1,0,3,2] row_mask:0xf bank_mask:0xf bound_ctrl:1
	v_pk_mul_f32 v[130:131], v[130:131], v[92:93] op_sel_hi:[1,0]
	v_add_f32_dpp v102, v102, v102 quad_perm:[2,3,0,1] row_mask:0xf bank_mask:0xf bound_ctrl:1
	v_add_f32_dpp v104, v104, v104 quad_perm:[2,3,0,1] row_mask:0xf bank_mask:0xf bound_ctrl:1
	v_pk_mul_f32 v[132:133], v[132:133], v[92:93] op_sel_hi:[1,0]
	v_add_f32_dpp v102, v102, v102 row_half_mirror row_mask:0xf bank_mask:0xf bound_ctrl:1
	v_add_f32_dpp v104, v104, v104 row_half_mirror row_mask:0xf bank_mask:0xf bound_ctrl:1
	v_fma_f32 v105, -v92, v102, v100
	v_pk_mul_f32 v[106:107], v[92:93], v[104:105]
	v_pk_mul_f32 v[134:135], v[134:135], v[92:93] op_sel_hi:[1,0]
	v_pk_fma_f32 v[120:121], v[60:61], v[106:107], v[120:121] op_sel:[0,1,0]
	v_pk_fma_f32 v[122:123], v[62:63], v[106:107], v[122:123] op_sel:[0,1,0]
	v_fma_f32 v106, v94, v107, v106
	v_pk_fma_f32 v[124:125], v[64:65], v[106:107], v[124:125] op_sel:[0,1,0]
	v_pk_fma_f32 v[126:127], v[66:67], v[106:107], v[126:127] op_sel:[0,1,0]
	v_pk_fma_f32 v[128:129], v[68:69], v[106:107], v[128:129] op_sel:[0,1,0]
	v_pk_fma_f32 v[130:131], v[70:71], v[106:107], v[130:131] op_sel:[0,1,0]
	v_pk_fma_f32 v[132:133], v[72:73], v[106:107], v[132:133] op_sel:[0,1,0]
	v_pk_fma_f32 v[134:135], v[74:75], v[106:107], v[134:135] op_sel:[0,1,0]
	ds_write_b32 v166, v106 offset:512
	s_waitcnt lgkmcnt(1)
	s_nop 0
	ds_read_b128 v[60:63], v161 offset:7424
	ds_read_b128 v[64:67], v162 offset:7440
	ds_read_b128 v[68:71], v161 offset:7456
	ds_read_b128 v[72:75], v162 offset:7472
	ds_read_b32 v100, v163 offset:7936
	ds_read_b128 v[92:95], v164 offset:36960
	ds_read_b128 v[44:47], v161 offset:6944
	ds_read_b128 v[48:51], v162 offset:6960
	v_pk_mul_f32 v[102:103], v[120:121], v[76:77]
	v_pk_mul_f32 v[104:105], v[120:121], v[36:37]
	v_pk_fma_f32 v[102:103], v[122:123], v[78:79], v[102:103]
	v_pk_fma_f32 v[104:105], v[122:123], v[38:39], v[104:105]
	v_pk_mul_f32 v[120:121], v[120:121], v[96:97] op_sel_hi:[1,0]
	v_pk_fma_f32 v[102:103], v[124:125], v[80:81], v[102:103]
	v_pk_fma_f32 v[104:105], v[124:125], v[40:41], v[104:105]
	v_pk_mul_f32 v[122:123], v[122:123], v[96:97] op_sel_hi:[1,0]
	v_pk_fma_f32 v[102:103], v[126:127], v[82:83], v[102:103]
	v_pk_fma_f32 v[104:105], v[126:127], v[42:43], v[104:105]
	v_pk_mul_f32 v[124:125], v[124:125], v[96:97] op_sel_hi:[1,0]
	ds_read_b128 v[36:39], v161 offset:6912
	ds_read_b128 v[40:43], v162 offset:6928
	v_pk_fma_f32 v[102:103], v[128:129], v[84:85], v[102:103]
	v_pk_fma_f32 v[104:105], v[128:129], v[52:53], v[104:105]
	v_pk_mul_f32 v[126:127], v[126:127], v[96:97] op_sel_hi:[1,0]
	v_pk_fma_f32 v[102:103], v[130:131], v[86:87], v[102:103]
	v_pk_fma_f32 v[104:105], v[130:131], v[54:55], v[104:105]
	v_pk_fma_f32 v[102:103], v[132:133], v[88:89], v[102:103]
	v_pk_fma_f32 v[104:105], v[132:133], v[56:57], v[104:105]
	v_pk_fma_f32 v[102:103], v[134:135], v[90:91], v[102:103]
	v_pk_fma_f32 v[104:105], v[134:135], v[58:59], v[104:105]
	v_add_f32_e64 v102, v102, v103
	v_add_f32_e64 v104, v104, v105
	v_pk_mul_f32 v[128:129], v[128:129], v[96:97] op_sel_hi:[1,0]
	v_add_f32_dpp v102, v102, v102 quad_perm:[1,0,3,2] row_mask:0xf bank_mask:0xf bound_ctrl:1
	v_add_f32_dpp v104, v104, v104 quad_perm:[1,0,3,2] row_mask:0xf bank_mask:0xf bound_ctrl:1
	v_pk_mul_f32 v[130:131], v[130:131], v[96:97] op_sel_hi:[1,0]
	v_add_f32_dpp v102, v102, v102 quad_perm:[2,3,0,1] row_mask:0xf bank_mask:0xf bound_ctrl:1
	v_add_f32_dpp v104, v104, v104 quad_perm:[2,3,0,1] row_mask:0xf bank_mask:0xf bound_ctrl:1
	v_pk_mul_f32 v[132:133], v[132:133], v[96:97] op_sel_hi:[1,0]
	v_add_f32_dpp v102, v102, v102 row_half_mirror row_mask:0xf bank_mask:0xf bound_ctrl:1
	v_add_f32_dpp v104, v104, v104 row_half_mirror row_mask:0xf bank_mask:0xf bound_ctrl:1
	v_fma_f32 v105, -v96, v102, v101
	v_pk_mul_f32 v[106:107], v[96:97], v[104:105]
	v_pk_mul_f32 v[134:135], v[134:135], v[96:97] op_sel_hi:[1,0]
	v_pk_fma_f32 v[120:121], v[76:77], v[106:107], v[120:121] op_sel:[0,1,0]
	v_pk_fma_f32 v[122:123], v[78:79], v[106:107], v[122:123] op_sel:[0,1,0]
	v_fma_f32 v106, v98, v107, v106
	v_pk_fma_f32 v[124:125], v[80:81], v[106:107], v[124:125] op_sel:[0,1,0]
	v_pk_fma_f32 v[126:127], v[82:83], v[106:107], v[126:127] op_sel:[0,1,0]
	v_pk_fma_f32 v[128:129], v[84:85], v[106:107], v[128:129] op_sel:[0,1,0]
	v_pk_fma_f32 v[130:131], v[86:87], v[106:107], v[130:131] op_sel:[0,1,0]
	v_pk_fma_f32 v[132:133], v[88:89], v[106:107], v[132:133] op_sel:[0,1,0]
	v_pk_fma_f32 v[134:135], v[90:91], v[106:107], v[134:135] op_sel:[0,1,0]
	ds_write_b32 v166, v106 offset:640
	s_waitcnt lgkmcnt(1)
; __device__ __forceinline__ float red8(float v) { v = red4(v); v += dppf<0x141>(v); return v; }
; __device__ __forceinline__ f32x2 lo2(const f32x4& v) { return __builtin_shufflevector(v, v, 0, 1); }
; __device__ __forceinline__ f32x2 hi2(const f32x4& v) { return __builtin_shufflevector(v, v, 2, 3); }
; __device__ __forceinline__ f32x2 splat2(float x) { return (f32x2){x, x}; }
; #define SCAN_INTERLEAVE(nds, nvalu)                                   \
;   _Pragma("unroll") for (int i_ = 0; i_ < (nds); ++i_) {               \
;     __builtin_amdgcn_sched_group_barrier(0x100, 1, 0);                 \
;     __builtin_amdgcn_sched_group_barrier(0x002, (nvalu), 0);           \
;   }
; __device__ __forceinline__ float gd_step(f32x2 (&S)[8], const GdRegs& R) {
;   f32x2 k0a = splat2(0.f), k1a = splat2(0.f), q0a = splat2(0.f), q1a = splat2(0.f);
; #pragma unroll
;   for (int q = 0; q < 4; ++q) {
;     k0a += S[2 * q] * lo2(R.k[q]);
;     k1a += S[2 * q + 1] * hi2(R.k[q]);
;     q0a += S[2 * q] * lo2(R.q[q]);
;     q1a += S[2 * q + 1] * hi2(R.q[q]);
;   }
;   k0a += k1a; q0a += q1a;
;   const float dK = red8(k0a.x + k0a.y), dQ = red8(q0a.x + q0a.y);
;   const float vn = R.sc.y * (R.v - R.sc.x * dK);
;   const float o = R.sc.x * dQ + R.sc.z * vn;
;   const f32x2 al2 = splat2(R.sc.x), vn2 = splat2(vn);
; #pragma unroll
;   for (int q = 0; q < 4; ++q) {
;     S[2 * q] = S[2 * q] * al2 + lo2(R.k[q]) * vn2;
;     S[2 * q + 1] = S[2 * q + 1] * al2 + hi2(R.k[q]) * vn2;
;   }
;   return o;
; }
; __device__ __forceinline__ void scan_gdn(const Params& p, int l, int seq, int h, int qt, char* smem, const unsigned* wflags, unsigned wexpect) {
;     ...
;     for (int t = 0; t < nsteps; t += 2) {
;       gd_load(RB, vb, sb, min(t + 1, 15), k0, cl);
;       const float o0v = gd_step(S, RA);
;       *((part == 0) ? (yb + t * 32 + cl) : ydummy) = o0v;
;       SCAN_INTERLEAVE(10, 4);
;       if (t + 1 < nsteps) {
;         gd_load(RA, vb, sb, min(t + 2, 15), k0, cl);
;         const float o1v = gd_step(S, RB);
;         *((part == 0) ? (yb + (t + 1) * 32 + cl) : ydummy) = o1v;
;         SCAN_INTERLEAVE(10, 4);
;       }
	s_nop 0
	ds_read_b128 v[76:79], v161 offset:8576
	ds_read_b128 v[80:83], v162 offset:8592
	ds_read_b128 v[84:87], v161 offset:8608
	ds_read_b128 v[88:91], v162 offset:8624
	ds_read_b32 v101, v163 offset:9088
	ds_read_b128 v[96:99], v164 offset:36976
	ds_read_b128 v[52:55], v161 offset:8096
	ds_read_b128 v[56:59], v162 offset:8112
	v_pk_mul_f32 v[102:103], v[120:121], v[60:61]
	v_pk_mul_f32 v[104:105], v[120:121], v[36:37]
	v_pk_fma_f32 v[102:103], v[122:123], v[62:63], v[102:103]
	v_pk_fma_f32 v[104:105], v[122:123], v[38:39], v[104:105]
	v_pk_mul_f32 v[120:121], v[120:121], v[92:93] op_sel_hi:[1,0]
	v_pk_fma_f32 v[102:103], v[124:125], v[64:65], v[102:103]
	v_pk_fma_f32 v[104:105], v[124:125], v[40:41], v[104:105]
	v_pk_mul_f32 v[122:123], v[122:123], v[92:93] op_sel_hi:[1,0]
	v_pk_fma_f32 v[102:103], v[126:127], v[66:67], v[102:103]
	v_pk_fma_f32 v[104:105], v[126:127], v[42:43], v[104:105]
	v_pk_mul_f32 v[124:125], v[124:125], v[92:93] op_sel_hi:[1,0]
	ds_read_b128 v[36:39], v161 offset:8064
	ds_read_b128 v[40:43], v162 offset:8080
	v_pk_fma_f32 v[102:103], v[128:129], v[68:69], v[102:103]
	v_pk_fma_f32 v[104:105], v[128:129], v[44:45], v[104:105]
	v_pk_mul_f32 v[126:127], v[126:127], v[92:93] op_sel_hi:[1,0]
	v_pk_fma_f32 v[102:103], v[130:131], v[70:71], v[102:103]
	v_pk_fma_f32 v[104:105], v[130:131], v[46:47], v[104:105]
	v_pk_fma_f32 v[102:103], v[132:133], v[72:73], v[102:103]
	v_pk_fma_f32 v[104:105], v[132:133], v[48:49], v[104:105]
	v_pk_fma_f32 v[102:103], v[134:135], v[74:75], v[102:103]
	v_pk_fma_f32 v[104:105], v[134:135], v[50:51], v[104:105]
	v_add_f32_e64 v102, v102, v103
	v_add_f32_e64 v104, v104, v105
	v_pk_mul_f32 v[128:129], v[128:129], v[92:93] op_sel_hi:[1,0]
	v_add_f32_dpp v102, v102, v102 quad_perm:[1,0,3,2] row_mask:0xf bank_mask:0xf bound_ctrl:1
	v_add_f32_dpp v104, v104, v104 quad_perm:[1,0,3,2] row_mask:0xf bank_mask:0xf bound_ctrl:1
	v_pk_mul_f32 v[130:131], v[130:131], v[92:93] op_sel_hi:[1,0]
	v_add_f32_dpp v102, v102, v102 quad_perm:[2,3,0,1] row_mask:0xf bank_mask:0xf bound_ctrl:1
	v_add_f32_dpp v104, v104, v104 quad_perm:[2,3,0,1] row_mask:0xf bank_mask:0xf bound_ctrl:1
	v_pk_mul_f32 v[132:133], v[132:133], v[92:93] op_sel_hi:[1,0]
	v_add_f32_dpp v102, v102, v102 row_half_mirror row_mask:0xf bank_mask:0xf bound_ctrl:1
	v_add_f32_dpp v104, v104, v104 row_half_mirror row_mask:0xf bank_mask:0xf bound_ctrl:1
	v_fma_f32 v105, -v92, v102, v100
	v_pk_mul_f32 v[106:107], v[92:93], v[104:105]
	v_pk_mul_f32 v[134:135], v[134:135], v[92:93] op_sel_hi:[1,0]
	v_pk_fma_f32 v[120:121], v[60:61], v[106:107], v[120:121] op_sel:[0,1,0]
	v_pk_fma_f32 v[122:123], v[62:63], v[106:107], v[122:123] op_sel:[0,1,0]
	v_fma_f32 v106, v94, v107, v106
	v_pk_fma_f32 v[124:125], v[64:65], v[106:107], v[124:125] op_sel:[0,1,0]
	v_pk_fma_f32 v[126:127], v[66:67], v[106:107], v[126:127] op_sel:[0,1,0]
	v_pk_fma_f32 v[128:129], v[68:69], v[106:107], v[128:129] op_sel:[0,1,0]
	v_pk_fma_f32 v[130:131], v[70:71], v[106:107], v[130:131] op_sel:[0,1,0]
	v_pk_fma_f32 v[132:133], v[72:73], v[106:107], v[132:133] op_sel:[0,1,0]
	v_pk_fma_f32 v[134:135], v[74:75], v[106:107], v[134:135] op_sel:[0,1,0]
	ds_write_b32 v166, v106 offset:768
	s_waitcnt lgkmcnt(1)
	s_nop 0
	ds_read_b128 v[60:63], v161 offset:9728
	ds_read_b128 v[64:67], v162 offset:9744
	ds_read_b128 v[68:71], v161 offset:9760
	ds_read_b128 v[72:75], v162 offset:9776
	ds_read_b32 v100, v163 offset:10240
	ds_read_b128 v[92:95], v164 offset:36992
	ds_read_b128 v[44:47], v161 offset:9248
	ds_read_b128 v[48:51], v162 offset:9264
	v_pk_mul_f32 v[102:103], v[120:121], v[76:77]
	v_pk_mul_f32 v[104:105], v[120:121], v[36:37]
	v_pk_fma_f32 v[102:103], v[122:123], v[78:79], v[102:103]
	v_pk_fma_f32 v[104:105], v[122:123], v[38:39], v[104:105]
	v_pk_mul_f32 v[120:121], v[120:121], v[96:97] op_sel_hi:[1,0]
	v_pk_fma_f32 v[102:103], v[124:125], v[80:81], v[102:103]
	v_pk_fma_f32 v[104:105], v[124:125], v[40:41], v[104:105]
	v_pk_mul_f32 v[122:123], v[122:123], v[96:97] op_sel_hi:[1,0]
	v_pk_fma_f32 v[102:103], v[126:127], v[82:83], v[102:103]
	v_pk_fma_f32 v[104:105], v[126:127], v[42:43], v[104:105]
	v_pk_mul_f32 v[124:125], v[124:125], v[96:97] op_sel_hi:[1,0]
	ds_read_b128 v[36:39], v161 offset:9216
	ds_read_b128 v[40:43], v162 offset:9232
	v_pk_fma_f32 v[102:103], v[128:129], v[84:85], v[102:103]
	v_pk_fma_f32 v[104:105], v[128:129], v[52:53], v[104:105]
	v_pk_mul_f32 v[126:127], v[126:127], v[96:97] op_sel_hi:[1,0]
	v_pk_fma_f32 v[102:103], v[130:131], v[86:87], v[102:103]
	v_pk_fma_f32 v[104:105], v[130:131], v[54:55], v[104:105]
	v_pk_fma_f32 v[102:103], v[132:133], v[88:89], v[102:103]
	v_pk_fma_f32 v[104:105], v[132:133], v[56:57], v[104:105]
	v_pk_fma_f32 v[102:103], v[134:135], v[90:91], v[102:103]
	v_pk_fma_f32 v[104:105], v[134:135], v[58:59], v[104:105]
	v_add_f32_e64 v102, v102, v103
	v_add_f32_e64 v104, v104, v105
	v_pk_mul_f32 v[128:129], v[128:129], v[96:97] op_sel_hi:[1,0]
	v_add_f32_dpp v102, v102, v102 quad_perm:[1,0,3,2] row_mask:0xf bank_mask:0xf bound_ctrl:1
	v_add_f32_dpp v104, v104, v104 quad_perm:[1,0,3,2] row_mask:0xf bank_mask:0xf bound_ctrl:1
	v_pk_mul_f32 v[130:131], v[130:131], v[96:97] op_sel_hi:[1,0]
	v_add_f32_dpp v102, v102, v102 quad_perm:[2,3,0,1] row_mask:0xf bank_mask:0xf bound_ctrl:1
	v_add_f32_dpp v104, v104, v104 quad_perm:[2,3,0,1] row_mask:0xf bank_mask:0xf bound_ctrl:1
	v_pk_mul_f32 v[132:133], v[132:133], v[96:97] op_sel_hi:[1,0]
	v_add_f32_dpp v102, v102, v102 row_half_mirror row_mask:0xf bank_mask:0xf bound_ctrl:1
	v_add_f32_dpp v104, v104, v104 row_half_mirror row_mask:0xf bank_mask:0xf bound_ctrl:1
	v_fma_f32 v105, -v96, v102, v101
	v_pk_mul_f32 v[106:107], v[96:97], v[104:105]
	v_pk_mul_f32 v[134:135], v[134:135], v[96:97] op_sel_hi:[1,0]
	v_pk_fma_f32 v[120:121], v[76:77], v[106:107], v[120:121] op_sel:[0,1,0]
	v_pk_fma_f32 v[122:123], v[78:79], v[106:107], v[122:123] op_sel:[0,1,0]
	v_fma_f32 v106, v98, v107, v106
	v_pk_fma_f32 v[124:125], v[80:81], v[106:107], v[124:125] op_sel:[0,1,0]
	v_pk_fma_f32 v[126:127], v[82:83], v[106:107], v[126:127] op_sel:[0,1,0]
	v_pk_fma_f32 v[128:129], v[84:85], v[106:107], v[128:129] op_sel:[0,1,0]
	v_pk_fma_f32 v[130:131], v[86:87], v[106:107], v[130:131] op_sel:[0,1,0]
	v_pk_fma_f32 v[132:133], v[88:89], v[106:107], v[132:133] op_sel:[0,1,0]
	v_pk_fma_f32 v[134:135], v[90:91], v[106:107], v[134:135] op_sel:[0,1,0]
	ds_write_b32 v166, v106 offset:896
	s_waitcnt lgkmcnt(1)
; __device__ __forceinline__ float red8(float v) { v = red4(v); v += dppf<0x141>(v); return v; }
; __device__ __forceinline__ f32x2 lo2(const f32x4& v) { return __builtin_shufflevector(v, v, 0, 1); }
; __device__ __forceinline__ f32x2 hi2(const f32x4& v) { return __builtin_shufflevector(v, v, 2, 3); }
; __device__ __forceinline__ f32x2 splat2(float x) { return (f32x2){x, x}; }
; #define SCAN_INTERLEAVE(nds, nvalu)                                   \
;   _Pragma("unroll") for (int i_ = 0; i_ < (nds); ++i_) {               \
;     __builtin_amdgcn_sched_group_barrier(0x100, 1, 0);                 \
;     __builtin_amdgcn_sched_group_barrier(0x002, (nvalu), 0);           \
;   }
; __device__ __forceinline__ float gd_step(f32x2 (&S)[8], const GdRegs& R) {
;   f32x2 k0a = splat2(0.f), k1a = splat2(0.f), q0a = splat2(0.f), q1a = splat2(0.f);
; #pragma unroll
;   for (int q = 0; q < 4; ++q) {
;     k0a += S[2 * q] * lo2(R.k[q]);
;     k1a += S[2 * q + 1] * hi2(R.k[q]);
;     q0a += S[2 * q] * lo2(R.q[q]);
;     q1a += S[2 * q + 1] * hi2(R.q[q]);
;   }
;   k0a += k1a; q0a += q1a;
;   const float dK = red8(k0a.x + k0a.y), dQ = red8(q0a.x + q0a.y);
;   const float vn = R.sc.y * (R.v - R.sc.x * dK);
;   const float o = R.sc.x * dQ + R.sc.z * vn;
;   const f32x2 al2 = splat2(R.sc.x), vn2 = splat2(vn);
; #pragma unroll
;   for (int q = 0; q < 4; ++q) {
;     S[2 * q] = S[2 * q] * al2 + lo2(R.k[q]) * vn2;
;     S[2 * q + 1] = S[2 * q + 1] * al2 + hi2(R.k[q]) * vn2;
;   }
;   return o;
; }
; __device__ __forceinline__ void scan_gdn(const Params& p, int l, int seq, int h, int qt, char* smem, const unsigned* wflags, unsigned wexpect) {
;     ...
;     for (int t = 0; t < nsteps; t += 2) {
;       gd_load(RB, vb, sb, min(t + 1, 15), k0, cl);
;       const float o0v = gd_step(S, RA);
;       *((part == 0) ? (yb + t * 32 + cl) : ydummy) = o0v;
;       SCAN_INTERLEAVE(10, 4);
;       if (t + 1 < nsteps) {
;         gd_load(RA, vb, sb, min(t + 2, 15), k0, cl);
;         const float o1v = gd_step(S, RB);
;         *((part == 0) ? (yb + (t + 1) * 32 + cl) : ydummy) = o1v;
;         SCAN_INTERLEAVE(10, 4);
;       }
	s_nop 0
	ds_read_b128 v[76:79], v161 offset:10880
	ds_read_b128 v[80:83], v162 offset:10896
	ds_read_b128 v[84:87], v161 offset:10912
	ds_read_b128 v[88:91], v162 offset:10928
	ds_read_b32 v101, v163 offset:11392
	ds_read_b128 v[96:99], v164 offset:37008
	ds_read_b128 v[52:55], v161 offset:10400
	ds_read_b128 v[56:59], v162 offset:10416
	v_pk_mul_f32 v[102:103], v[120:121], v[60:61]
	v_pk_mul_f32 v[104:105], v[120:121], v[36:37]
	v_pk_fma_f32 v[102:103], v[122:123], v[62:63], v[102:103]
	v_pk_fma_f32 v[104:105], v[122:123], v[38:39], v[104:105]
	v_pk_mul_f32 v[120:121], v[120:121], v[92:93] op_sel_hi:[1,0]
	v_pk_fma_f32 v[102:103], v[124:125], v[64:65], v[102:103]
	v_pk_fma_f32 v[104:105], v[124:125], v[40:41], v[104:105]
	v_pk_mul_f32 v[122:123], v[122:123], v[92:93] op_sel_hi:[1,0]
	v_pk_fma_f32 v[102:103], v[126:127], v[66:67], v[102:103]
	v_pk_fma_f32 v[104:105], v[126:127], v[42:43], v[104:105]
	v_pk_mul_f32 v[124:125], v[124:125], v[92:93] op_sel_hi:[1,0]
	ds_read_b128 v[36:39], v161 offset:10368
	ds_read_b128 v[40:43], v162 offset:10384
	v_pk_fma_f32 v[102:103], v[128:129], v[68:69], v[102:103]
	v_pk_fma_f32 v[104:105], v[128:129], v[44:45], v[104:105]
	v_pk_mul_f32 v[126:127], v[126:127], v[92:93] op_sel_hi:[1,0]
	v_pk_fma_f32 v[102:103], v[130:131], v[70:71], v[102:103]
	v_pk_fma_f32 v[104:105], v[130:131], v[46:47], v[104:105]
	v_pk_fma_f32 v[102:103], v[132:133], v[72:73], v[102:103]
	v_pk_fma_f32 v[104:105], v[132:133], v[48:49], v[104:105]
	v_pk_fma_f32 v[102:103], v[134:135], v[74:75], v[102:103]
	v_pk_fma_f32 v[104:105], v[134:135], v[50:51], v[104:105]
	v_add_f32_e64 v102, v102, v103
	v_add_f32_e64 v104, v104, v105
	v_pk_mul_f32 v[128:129], v[128:129], v[92:93] op_sel_hi:[1,0]
	v_add_f32_dpp v102, v102, v102 quad_perm:[1,0,3,2] row_mask:0xf bank_mask:0xf bound_ctrl:1
	v_add_f32_dpp v104, v104, v104 quad_perm:[1,0,3,2] row_mask:0xf bank_mask:0xf bound_ctrl:1
	v_pk_mul_f32 v[130:131], v[130:131], v[92:93] op_sel_hi:[1,0]
	v_add_f32_dpp v102, v102, v102 quad_perm:[2,3,0,1] row_mask:0xf bank_mask:0xf bound_ctrl:1
	v_add_f32_dpp v104, v104, v104 quad_perm:[2,3,0,1] row_mask:0xf bank_mask:0xf bound_ctrl:1
	v_pk_mul_f32 v[132:133], v[132:133], v[92:93] op_sel_hi:[1,0]
	v_add_f32_dpp v102, v102, v102 row_half_mirror row_mask:0xf bank_mask:0xf bound_ctrl:1
	v_add_f32_dpp v104, v104, v104 row_half_mirror row_mask:0xf bank_mask:0xf bound_ctrl:1
	v_fma_f32 v105, -v92, v102, v100
	v_pk_mul_f32 v[106:107], v[92:93], v[104:105]
	v_pk_mul_f32 v[134:135], v[134:135], v[92:93] op_sel_hi:[1,0]
	v_pk_fma_f32 v[120:121], v[60:61], v[106:107], v[120:121] op_sel:[0,1,0]
	v_pk_fma_f32 v[122:123], v[62:63], v[106:107], v[122:123] op_sel:[0,1,0]
	v_fma_f32 v106, v94, v107, v106
	v_pk_fma_f32 v[124:125], v[64:65], v[106:107], v[124:125] op_sel:[0,1,0]
	v_pk_fma_f32 v[126:127], v[66:67], v[106:107], v[126:127] op_sel:[0,1,0]
	v_pk_fma_f32 v[128:129], v[68:69], v[106:107], v[128:129] op_sel:[0,1,0]
	v_pk_fma_f32 v[130:131], v[70:71], v[106:107], v[130:131] op_sel:[0,1,0]
	v_pk_fma_f32 v[132:133], v[72:73], v[106:107], v[132:133] op_sel:[0,1,0]
	v_pk_fma_f32 v[134:135], v[74:75], v[106:107], v[134:135] op_sel:[0,1,0]
	ds_write_b32 v166, v106 offset:1024
	s_waitcnt lgkmcnt(1)
	s_nop 0
	ds_read_b128 v[60:63], v161 offset:12032
	ds_read_b128 v[64:67], v162 offset:12048
	ds_read_b128 v[68:71], v161 offset:12064
	ds_read_b128 v[72:75], v162 offset:12080
	ds_read_b32 v100, v163 offset:12544
	ds_read_b128 v[92:95], v164 offset:37024
	ds_read_b128 v[44:47], v161 offset:11552
	ds_read_b128 v[48:51], v162 offset:11568
	v_pk_mul_f32 v[102:103], v[120:121], v[76:77]
	v_pk_mul_f32 v[104:105], v[120:121], v[36:37]
	v_pk_fma_f32 v[102:103], v[122:123], v[78:79], v[102:103]
	v_pk_fma_f32 v[104:105], v[122:123], v[38:39], v[104:105]
	v_pk_mul_f32 v[120:121], v[120:121], v[96:97] op_sel_hi:[1,0]
	v_pk_fma_f32 v[102:103], v[124:125], v[80:81], v[102:103]
	v_pk_fma_f32 v[104:105], v[124:125], v[40:41], v[104:105]
	v_pk_mul_f32 v[122:123], v[122:123], v[96:97] op_sel_hi:[1,0]
	v_pk_fma_f32 v[102:103], v[126:127], v[82:83], v[102:103]
	v_pk_fma_f32 v[104:105], v[126:127], v[42:43], v[104:105]
	v_pk_mul_f32 v[124:125], v[124:125], v[96:97] op_sel_hi:[1,0]
	ds_read_b128 v[36:39], v161 offset:11520
	ds_read_b128 v[40:43], v162 offset:11536
	v_pk_fma_f32 v[102:103], v[128:129], v[84:85], v[102:103]
	v_pk_fma_f32 v[104:105], v[128:129], v[52:53], v[104:105]
	v_pk_mul_f32 v[126:127], v[126:127], v[96:97] op_sel_hi:[1,0]
	v_pk_fma_f32 v[102:103], v[130:131], v[86:87], v[102:103]
	v_pk_fma_f32 v[104:105], v[130:131], v[54:55], v[104:105]
	v_pk_fma_f32 v[102:103], v[132:133], v[88:89], v[102:103]
	v_pk_fma_f32 v[104:105], v[132:133], v[56:57], v[104:105]
	v_pk_fma_f32 v[102:103], v[134:135], v[90:91], v[102:103]
	v_pk_fma_f32 v[104:105], v[134:135], v[58:59], v[104:105]
	v_add_f32_e64 v102, v102, v103
	v_add_f32_e64 v104, v104, v105
	v_pk_mul_f32 v[128:129], v[128:129], v[96:97] op_sel_hi:[1,0]
	v_add_f32_dpp v102, v102, v102 quad_perm:[1,0,3,2] row_mask:0xf bank_mask:0xf bound_ctrl:1
	v_add_f32_dpp v104, v104, v104 quad_perm:[1,0,3,2] row_mask:0xf bank_mask:0xf bound_ctrl:1
	v_pk_mul_f32 v[130:131], v[130:131], v[96:97] op_sel_hi:[1,0]
	v_add_f32_dpp v102, v102, v102 quad_perm:[2,3,0,1] row_mask:0xf bank_mask:0xf bound_ctrl:1
	v_add_f32_dpp v104, v104, v104 quad_perm:[2,3,0,1] row_mask:0xf bank_mask:0xf bound_ctrl:1
	v_pk_mul_f32 v[132:133], v[132:133], v[96:97] op_sel_hi:[1,0]
	v_add_f32_dpp v102, v102, v102 row_half_mirror row_mask:0xf bank_mask:0xf bound_ctrl:1
	v_add_f32_dpp v104, v104, v104 row_half_mirror row_mask:0xf bank_mask:0xf bound_ctrl:1
	v_fma_f32 v105, -v96, v102, v101
	v_pk_mul_f32 v[106:107], v[96:97], v[104:105]
	v_pk_mul_f32 v[134:135], v[134:135], v[96:97] op_sel_hi:[1,0]
	v_pk_fma_f32 v[120:121], v[76:77], v[106:107], v[120:121] op_sel:[0,1,0]
	v_pk_fma_f32 v[122:123], v[78:79], v[106:107], v[122:123] op_sel:[0,1,0]
	v_fma_f32 v106, v98, v107, v106
	v_pk_fma_f32 v[124:125], v[80:81], v[106:107], v[124:125] op_sel:[0,1,0]
	v_pk_fma_f32 v[126:127], v[82:83], v[106:107], v[126:127] op_sel:[0,1,0]
	v_pk_fma_f32 v[128:129], v[84:85], v[106:107], v[128:129] op_sel:[0,1,0]
	v_pk_fma_f32 v[130:131], v[86:87], v[106:107], v[130:131] op_sel:[0,1,0]
	v_pk_fma_f32 v[132:133], v[88:89], v[106:107], v[132:133] op_sel:[0,1,0]
	v_pk_fma_f32 v[134:135], v[90:91], v[106:107], v[134:135] op_sel:[0,1,0]
	ds_write_b32 v166, v106 offset:1152
	s_waitcnt lgkmcnt(1)
; __device__ __forceinline__ float red8(float v) { v = red4(v); v += dppf<0x141>(v); return v; }
; __device__ __forceinline__ f32x2 lo2(const f32x4& v) { return __builtin_shufflevector(v, v, 0, 1); }
; __device__ __forceinline__ f32x2 hi2(const f32x4& v) { return __builtin_shufflevector(v, v, 2, 3); }
; __device__ __forceinline__ f32x2 splat2(float x) { return (f32x2){x, x}; }
; #define SCAN_INTERLEAVE(nds, nvalu)                                   \
;   _Pragma("unroll") for (int i_ = 0; i_ < (nds); ++i_) {               \
;     __builtin_amdgcn_sched_group_barrier(0x100, 1, 0);                 \
;     __builtin_amdgcn_sched_group_barrier(0x002, (nvalu), 0);           \
;   }
; __device__ __forceinline__ float gd_step(f32x2 (&S)[8], const GdRegs& R) {
;   f32x2 k0a = splat2(0.f), k1a = splat2(0.f), q0a = splat2(0.f), q1a = splat2(0.f);
; #pragma unroll
;   for (int q = 0; q < 4; ++q) {
;     k0a += S[2 * q] * lo2(R.k[q]);
;     k1a += S[2 * q + 1] * hi2(R.k[q]);
;     q0a += S[2 * q] * lo2(R.q[q]);
;     q1a += S[2 * q + 1] * hi2(R.q[q]);
;   }
;   k0a += k1a; q0a += q1a;
;   const float dK = red8(k0a.x + k0a.y), dQ = red8(q0a.x + q0a.y);
;   const float vn = R.sc.y * (R.v - R.sc.x * dK);
;   const float o = R.sc.x * dQ + R.sc.z * vn;
;   const f32x2 al2 = splat2(R.sc.x), vn2 = splat2(vn);
; #pragma unroll
;   for (int q = 0; q < 4; ++q) {
;     S[2 * q] = S[2 * q] * al2 + lo2(R.k[q]) * vn2;
;     S[2 * q + 1] = S[2 * q + 1] * al2 + hi2(R.k[q]) * vn2;
;   }
;   return o;
; }
; __device__ __forceinline__ void scan_gdn(const Params& p, int l, int seq, int h, int qt, char* smem, const unsigned* wflags, unsigned wexpect) {
;     ...
;     for (int t = 0; t < nsteps; t += 2) {
;       gd_load(RB, vb, sb, min(t + 1, 15), k0, cl);
;       const float o0v = gd_step(S, RA);
;       *((part == 0) ? (yb + t * 32 + cl) : ydummy) = o0v;
;       SCAN_INTERLEAVE(10, 4);
;       if (t + 1 < nsteps) {
;         gd_load(RA, vb, sb, min(t + 2, 15), k0, cl);
;         const float o1v = gd_step(S, RB);
;         *((part == 0) ? (yb + (t + 1) * 32 + cl) : ydummy) = o1v;
;         SCAN_INTERLEAVE(10, 4);
;       }
	s_nop 0
	ds_read_b128 v[76:79], v161 offset:13184
	ds_read_b128 v[80:83], v162 offset:13200
	ds_read_b128 v[84:87], v161 offset:13216
	ds_read_b128 v[88:91], v162 offset:13232
	ds_read_b32 v101, v163 offset:13696
	ds_read_b128 v[96:99], v164 offset:37040
	ds_read_b128 v[52:55], v161 offset:12704
	ds_read_b128 v[56:59], v162 offset:12720
	v_pk_mul_f32 v[102:103], v[120:121], v[60:61]
	v_pk_mul_f32 v[104:105], v[120:121], v[36:37]
	v_pk_fma_f32 v[102:103], v[122:123], v[62:63], v[102:103]
	v_pk_fma_f32 v[104:105], v[122:123], v[38:39], v[104:105]
	v_pk_mul_f32 v[120:121], v[120:121], v[92:93] op_sel_hi:[1,0]
	v_pk_fma_f32 v[102:103], v[124:125], v[64:65], v[102:103]
	v_pk_fma_f32 v[104:105], v[124:125], v[40:41], v[104:105]
	v_pk_mul_f32 v[122:123], v[122:123], v[92:93] op_sel_hi:[1,0]
	v_pk_fma_f32 v[102:103], v[126:127], v[66:67], v[102:103]
	v_pk_fma_f32 v[104:105], v[126:127], v[42:43], v[104:105]
	v_pk_mul_f32 v[124:125], v[124:125], v[92:93] op_sel_hi:[1,0]
	ds_read_b128 v[36:39], v161 offset:12672
	ds_read_b128 v[40:43], v162 offset:12688
	v_pk_fma_f32 v[102:103], v[128:129], v[68:69], v[102:103]
	v_pk_fma_f32 v[104:105], v[128:129], v[44:45], v[104:105]
	v_pk_mul_f32 v[126:127], v[126:127], v[92:93] op_sel_hi:[1,0]
	v_pk_fma_f32 v[102:103], v[130:131], v[70:71], v[102:103]
	v_pk_fma_f32 v[104:105], v[130:131], v[46:47], v[104:105]
	v_pk_fma_f32 v[102:103], v[132:133], v[72:73], v[102:103]
	v_pk_fma_f32 v[104:105], v[132:133], v[48:49], v[104:105]
	v_pk_fma_f32 v[102:103], v[134:135], v[74:75], v[102:103]
	v_pk_fma_f32 v[104:105], v[134:135], v[50:51], v[104:105]
	v_add_f32_e64 v102, v102, v103
	v_add_f32_e64 v104, v104, v105
	v_pk_mul_f32 v[128:129], v[128:129], v[92:93] op_sel_hi:[1,0]
	v_add_f32_dpp v102, v102, v102 quad_perm:[1,0,3,2] row_mask:0xf bank_mask:0xf bound_ctrl:1
	v_add_f32_dpp v104, v104, v104 quad_perm:[1,0,3,2] row_mask:0xf bank_mask:0xf bound_ctrl:1
	v_pk_mul_f32 v[130:131], v[130:131], v[92:93] op_sel_hi:[1,0]
	v_add_f32_dpp v102, v102, v102 quad_perm:[2,3,0,1] row_mask:0xf bank_mask:0xf bound_ctrl:1
	v_add_f32_dpp v104, v104, v104 quad_perm:[2,3,0,1] row_mask:0xf bank_mask:0xf bound_ctrl:1
	v_pk_mul_f32 v[132:133], v[132:133], v[92:93] op_sel_hi:[1,0]
	v_add_f32_dpp v102, v102, v102 row_half_mirror row_mask:0xf bank_mask:0xf bound_ctrl:1
	v_add_f32_dpp v104, v104, v104 row_half_mirror row_mask:0xf bank_mask:0xf bound_ctrl:1
	v_fma_f32 v105, -v92, v102, v100
	v_pk_mul_f32 v[106:107], v[92:93], v[104:105]
	v_pk_mul_f32 v[134:135], v[134:135], v[92:93] op_sel_hi:[1,0]
	v_pk_fma_f32 v[120:121], v[60:61], v[106:107], v[120:121] op_sel:[0,1,0]
	v_pk_fma_f32 v[122:123], v[62:63], v[106:107], v[122:123] op_sel:[0,1,0]
	v_fma_f32 v106, v94, v107, v106
	v_pk_fma_f32 v[124:125], v[64:65], v[106:107], v[124:125] op_sel:[0,1,0]
	v_pk_fma_f32 v[126:127], v[66:67], v[106:107], v[126:127] op_sel:[0,1,0]
	v_pk_fma_f32 v[128:129], v[68:69], v[106:107], v[128:129] op_sel:[0,1,0]
	v_pk_fma_f32 v[130:131], v[70:71], v[106:107], v[130:131] op_sel:[0,1,0]
	v_pk_fma_f32 v[132:133], v[72:73], v[106:107], v[132:133] op_sel:[0,1,0]
	v_pk_fma_f32 v[134:135], v[74:75], v[106:107], v[134:135] op_sel:[0,1,0]
	ds_write_b32 v166, v106 offset:1280
	s_waitcnt lgkmcnt(1)
	s_nop 0
	ds_read_b128 v[60:63], v161 offset:14336
	ds_read_b128 v[64:67], v162 offset:14352
	ds_read_b128 v[68:71], v161 offset:14368
	ds_read_b128 v[72:75], v162 offset:14384
	ds_read_b32 v100, v163 offset:14848
	ds_read_b128 v[92:95], v164 offset:37056
	ds_read_b128 v[44:47], v161 offset:13856
	ds_read_b128 v[48:51], v162 offset:13872
	v_pk_mul_f32 v[102:103], v[120:121], v[76:77]
	v_pk_mul_f32 v[104:105], v[120:121], v[36:37]
	v_pk_fma_f32 v[102:103], v[122:123], v[78:79], v[102:103]
	v_pk_fma_f32 v[104:105], v[122:123], v[38:39], v[104:105]
	v_pk_mul_f32 v[120:121], v[120:121], v[96:97] op_sel_hi:[1,0]
	v_pk_fma_f32 v[102:103], v[124:125], v[80:81], v[102:103]
	v_pk_fma_f32 v[104:105], v[124:125], v[40:41], v[104:105]
	v_pk_mul_f32 v[122:123], v[122:123], v[96:97] op_sel_hi:[1,0]
	v_pk_fma_f32 v[102:103], v[126:127], v[82:83], v[102:103]
	v_pk_fma_f32 v[104:105], v[126:127], v[42:43], v[104:105]
	v_pk_mul_f32 v[124:125], v[124:125], v[96:97] op_sel_hi:[1,0]
	ds_read_b128 v[36:39], v161 offset:13824
	ds_read_b128 v[40:43], v162 offset:13840
	v_pk_fma_f32 v[102:103], v[128:129], v[84:85], v[102:103]
	v_pk_fma_f32 v[104:105], v[128:129], v[52:53], v[104:105]
	v_pk_mul_f32 v[126:127], v[126:127], v[96:97] op_sel_hi:[1,0]
	v_pk_fma_f32 v[102:103], v[130:131], v[86:87], v[102:103]
	v_pk_fma_f32 v[104:105], v[130:131], v[54:55], v[104:105]
	v_pk_fma_f32 v[102:103], v[132:133], v[88:89], v[102:103]
	v_pk_fma_f32 v[104:105], v[132:133], v[56:57], v[104:105]
	v_pk_fma_f32 v[102:103], v[134:135], v[90:91], v[102:103]
	v_pk_fma_f32 v[104:105], v[134:135], v[58:59], v[104:105]
	v_add_f32_e64 v102, v102, v103
	v_add_f32_e64 v104, v104, v105
	v_pk_mul_f32 v[128:129], v[128:129], v[96:97] op_sel_hi:[1,0]
	v_add_f32_dpp v102, v102, v102 quad_perm:[1,0,3,2] row_mask:0xf bank_mask:0xf bound_ctrl:1
	v_add_f32_dpp v104, v104, v104 quad_perm:[1,0,3,2] row_mask:0xf bank_mask:0xf bound_ctrl:1
	v_pk_mul_f32 v[130:131], v[130:131], v[96:97] op_sel_hi:[1,0]
	v_add_f32_dpp v102, v102, v102 quad_perm:[2,3,0,1] row_mask:0xf bank_mask:0xf bound_ctrl:1
	v_add_f32_dpp v104, v104, v104 quad_perm:[2,3,0,1] row_mask:0xf bank_mask:0xf bound_ctrl:1
	v_pk_mul_f32 v[132:133], v[132:133], v[96:97] op_sel_hi:[1,0]
	v_add_f32_dpp v102, v102, v102 row_half_mirror row_mask:0xf bank_mask:0xf bound_ctrl:1
	v_add_f32_dpp v104, v104, v104 row_half_mirror row_mask:0xf bank_mask:0xf bound_ctrl:1
	v_fma_f32 v105, -v96, v102, v101
	v_pk_mul_f32 v[106:107], v[96:97], v[104:105]
	v_pk_mul_f32 v[134:135], v[134:135], v[96:97] op_sel_hi:[1,0]
	v_pk_fma_f32 v[120:121], v[76:77], v[106:107], v[120:121] op_sel:[0,1,0]
	v_pk_fma_f32 v[122:123], v[78:79], v[106:107], v[122:123] op_sel:[0,1,0]
	v_fma_f32 v106, v98, v107, v106
	v_pk_fma_f32 v[124:125], v[80:81], v[106:107], v[124:125] op_sel:[0,1,0]
	v_pk_fma_f32 v[126:127], v[82:83], v[106:107], v[126:127] op_sel:[0,1,0]
	v_pk_fma_f32 v[128:129], v[84:85], v[106:107], v[128:129] op_sel:[0,1,0]
	v_pk_fma_f32 v[130:131], v[86:87], v[106:107], v[130:131] op_sel:[0,1,0]
	v_pk_fma_f32 v[132:133], v[88:89], v[106:107], v[132:133] op_sel:[0,1,0]
	v_pk_fma_f32 v[134:135], v[90:91], v[106:107], v[134:135] op_sel:[0,1,0]
	ds_write_b32 v166, v106 offset:1408
	s_waitcnt lgkmcnt(1)
; __device__ __forceinline__ float red8(float v) { v = red4(v); v += dppf<0x141>(v); return v; }
; __device__ __forceinline__ f32x2 lo2(const f32x4& v) { return __builtin_shufflevector(v, v, 0, 1); }
; __device__ __forceinline__ f32x2 hi2(const f32x4& v) { return __builtin_shufflevector(v, v, 2, 3); }
; __device__ __forceinline__ f32x2 splat2(float x) { return (f32x2){x, x}; }
; #define SCAN_INTERLEAVE(nds, nvalu)                                   \
;   _Pragma("unroll") for (int i_ = 0; i_ < (nds); ++i_) {               \
;     __builtin_amdgcn_sched_group_barrier(0x100, 1, 0);                 \
;     __builtin_amdgcn_sched_group_barrier(0x002, (nvalu), 0);           \
;   }
; __device__ __forceinline__ float gd_step(f32x2 (&S)[8], const GdRegs& R) {
;   f32x2 k0a = splat2(0.f), k1a = splat2(0.f), q0a = splat2(0.f), q1a = splat2(0.f);
; #pragma unroll
;   for (int q = 0; q < 4; ++q) {
;     k0a += S[2 * q] * lo2(R.k[q]);
;     k1a += S[2 * q + 1] * hi2(R.k[q]);
;     q0a += S[2 * q] * lo2(R.q[q]);
;     q1a += S[2 * q + 1] * hi2(R.q[q]);
;   }
;   k0a += k1a; q0a += q1a;
;   const float dK = red8(k0a.x + k0a.y), dQ = red8(q0a.x + q0a.y);
;   const float vn = R.sc.y * (R.v - R.sc.x * dK);
;   const float o = R.sc.x * dQ + R.sc.z * vn;
;   const f32x2 al2 = splat2(R.sc.x), vn2 = splat2(vn);
; #pragma unroll
;   for (int q = 0; q < 4; ++q) {
;     S[2 * q] = S[2 * q] * al2 + lo2(R.k[q]) * vn2;
;     S[2 * q + 1] = S[2 * q + 1] * al2 + hi2(R.k[q]) * vn2;
;   }
;   return o;
; }
; __device__ __forceinline__ void scan_gdn(const Params& p, int l, int seq, int h, int qt, char* smem, const unsigned* wflags, unsigned wexpect) {
;     ...
;     for (int t = 0; t < nsteps; t += 2) {
;       gd_load(RB, vb, sb, min(t + 1, 15), k0, cl);
;       const float o0v = gd_step(S, RA);
;       *((part == 0) ? (yb + t * 32 + cl) : ydummy) = o0v;
;       SCAN_INTERLEAVE(10, 4);
;       if (t + 1 < nsteps) {
;         gd_load(RA, vb, sb, min(t + 2, 15), k0, cl);
;         const float o1v = gd_step(S, RB);
;         *((part == 0) ? (yb + (t + 1) * 32 + cl) : ydummy) = o1v;
;         SCAN_INTERLEAVE(10, 4);
;       }
	s_nop 0
	ds_read_b128 v[76:79], v161 offset:15488
	ds_read_b128 v[80:83], v162 offset:15504
	ds_read_b128 v[84:87], v161 offset:15520
	ds_read_b128 v[88:91], v162 offset:15536
	ds_read_b32 v101, v163 offset:16000
	ds_read_b128 v[96:99], v164 offset:37072
	ds_read_b128 v[52:55], v161 offset:15008
	ds_read_b128 v[56:59], v162 offset:15024
	v_pk_mul_f32 v[102:103], v[120:121], v[60:61]
	v_pk_mul_f32 v[104:105], v[120:121], v[36:37]
	v_pk_fma_f32 v[102:103], v[122:123], v[62:63], v[102:103]
	v_pk_fma_f32 v[104:105], v[122:123], v[38:39], v[104:105]
	v_pk_mul_f32 v[120:121], v[120:121], v[92:93] op_sel_hi:[1,0]
	v_pk_fma_f32 v[102:103], v[124:125], v[64:65], v[102:103]
	v_pk_fma_f32 v[104:105], v[124:125], v[40:41], v[104:105]
	v_pk_mul_f32 v[122:123], v[122:123], v[92:93] op_sel_hi:[1,0]
	v_pk_fma_f32 v[102:103], v[126:127], v[66:67], v[102:103]
	v_pk_fma_f32 v[104:105], v[126:127], v[42:43], v[104:105]
	v_pk_mul_f32 v[124:125], v[124:125], v[92:93] op_sel_hi:[1,0]
	ds_read_b128 v[36:39], v161 offset:14976
	ds_read_b128 v[40:43], v162 offset:14992
	v_pk_fma_f32 v[102:103], v[128:129], v[68:69], v[102:103]
	v_pk_fma_f32 v[104:105], v[128:129], v[44:45], v[104:105]
	v_pk_mul_f32 v[126:127], v[126:127], v[92:93] op_sel_hi:[1,0]
	v_pk_fma_f32 v[102:103], v[130:131], v[70:71], v[102:103]
	v_pk_fma_f32 v[104:105], v[130:131], v[46:47], v[104:105]
	v_pk_fma_f32 v[102:103], v[132:133], v[72:73], v[102:103]
	v_pk_fma_f32 v[104:105], v[132:133], v[48:49], v[104:105]
	v_pk_fma_f32 v[102:103], v[134:135], v[74:75], v[102:103]
	v_pk_fma_f32 v[104:105], v[134:135], v[50:51], v[104:105]
	v_add_f32_e64 v102, v102, v103
	v_add_f32_e64 v104, v104, v105
	v_pk_mul_f32 v[128:129], v[128:129], v[92:93] op_sel_hi:[1,0]
	v_add_f32_dpp v102, v102, v102 quad_perm:[1,0,3,2] row_mask:0xf bank_mask:0xf bound_ctrl:1
	v_add_f32_dpp v104, v104, v104 quad_perm:[1,0,3,2] row_mask:0xf bank_mask:0xf bound_ctrl:1
	v_pk_mul_f32 v[130:131], v[130:131], v[92:93] op_sel_hi:[1,0]
	v_add_f32_dpp v102, v102, v102 quad_perm:[2,3,0,1] row_mask:0xf bank_mask:0xf bound_ctrl:1
	v_add_f32_dpp v104, v104, v104 quad_perm:[2,3,0,1] row_mask:0xf bank_mask:0xf bound_ctrl:1
	v_pk_mul_f32 v[132:133], v[132:133], v[92:93] op_sel_hi:[1,0]
	v_add_f32_dpp v102, v102, v102 row_half_mirror row_mask:0xf bank_mask:0xf bound_ctrl:1
	v_add_f32_dpp v104, v104, v104 row_half_mirror row_mask:0xf bank_mask:0xf bound_ctrl:1
	v_fma_f32 v105, -v92, v102, v100
	v_pk_mul_f32 v[106:107], v[92:93], v[104:105]
	v_pk_mul_f32 v[134:135], v[134:135], v[92:93] op_sel_hi:[1,0]
	v_pk_fma_f32 v[120:121], v[60:61], v[106:107], v[120:121] op_sel:[0,1,0]
	v_pk_fma_f32 v[122:123], v[62:63], v[106:107], v[122:123] op_sel:[0,1,0]
	v_fma_f32 v106, v94, v107, v106
	v_pk_fma_f32 v[124:125], v[64:65], v[106:107], v[124:125] op_sel:[0,1,0]
	v_pk_fma_f32 v[126:127], v[66:67], v[106:107], v[126:127] op_sel:[0,1,0]
	v_pk_fma_f32 v[128:129], v[68:69], v[106:107], v[128:129] op_sel:[0,1,0]
	v_pk_fma_f32 v[130:131], v[70:71], v[106:107], v[130:131] op_sel:[0,1,0]
	v_pk_fma_f32 v[132:133], v[72:73], v[106:107], v[132:133] op_sel:[0,1,0]
	v_pk_fma_f32 v[134:135], v[74:75], v[106:107], v[134:135] op_sel:[0,1,0]
	ds_write_b32 v166, v106 offset:1536
	s_waitcnt lgkmcnt(1)
	s_nop 0
	ds_read_b128 v[60:63], v161 offset:16640
	ds_read_b128 v[64:67], v162 offset:16656
	ds_read_b128 v[68:71], v161 offset:16672
	ds_read_b128 v[72:75], v162 offset:16688
	ds_read_b32 v100, v163 offset:17152
	ds_read_b128 v[92:95], v164 offset:37088
	ds_read_b128 v[44:47], v161 offset:16160
	ds_read_b128 v[48:51], v162 offset:16176
	v_pk_mul_f32 v[102:103], v[120:121], v[76:77]
	v_pk_mul_f32 v[104:105], v[120:121], v[36:37]
	v_pk_fma_f32 v[102:103], v[122:123], v[78:79], v[102:103]
	v_pk_fma_f32 v[104:105], v[122:123], v[38:39], v[104:105]
	v_pk_mul_f32 v[120:121], v[120:121], v[96:97] op_sel_hi:[1,0]
	v_pk_fma_f32 v[102:103], v[124:125], v[80:81], v[102:103]
	v_pk_fma_f32 v[104:105], v[124:125], v[40:41], v[104:105]
	v_pk_mul_f32 v[122:123], v[122:123], v[96:97] op_sel_hi:[1,0]
	v_pk_fma_f32 v[102:103], v[126:127], v[82:83], v[102:103]
	v_pk_fma_f32 v[104:105], v[126:127], v[42:43], v[104:105]
	v_pk_mul_f32 v[124:125], v[124:125], v[96:97] op_sel_hi:[1,0]
	ds_read_b128 v[36:39], v161 offset:16128
	ds_read_b128 v[40:43], v162 offset:16144
	v_pk_fma_f32 v[102:103], v[128:129], v[84:85], v[102:103]
	v_pk_fma_f32 v[104:105], v[128:129], v[52:53], v[104:105]
	v_pk_mul_f32 v[126:127], v[126:127], v[96:97] op_sel_hi:[1,0]
	v_pk_fma_f32 v[102:103], v[130:131], v[86:87], v[102:103]
	v_pk_fma_f32 v[104:105], v[130:131], v[54:55], v[104:105]
	v_pk_fma_f32 v[102:103], v[132:133], v[88:89], v[102:103]
	v_pk_fma_f32 v[104:105], v[132:133], v[56:57], v[104:105]
	v_pk_fma_f32 v[102:103], v[134:135], v[90:91], v[102:103]
	v_pk_fma_f32 v[104:105], v[134:135], v[58:59], v[104:105]
	v_add_f32_e64 v102, v102, v103
	v_add_f32_e64 v104, v104, v105
	v_pk_mul_f32 v[128:129], v[128:129], v[96:97] op_sel_hi:[1,0]
	v_add_f32_dpp v102, v102, v102 quad_perm:[1,0,3,2] row_mask:0xf bank_mask:0xf bound_ctrl:1
	v_add_f32_dpp v104, v104, v104 quad_perm:[1,0,3,2] row_mask:0xf bank_mask:0xf bound_ctrl:1
	v_pk_mul_f32 v[130:131], v[130:131], v[96:97] op_sel_hi:[1,0]
	v_add_f32_dpp v102, v102, v102 quad_perm:[2,3,0,1] row_mask:0xf bank_mask:0xf bound_ctrl:1
	v_add_f32_dpp v104, v104, v104 quad_perm:[2,3,0,1] row_mask:0xf bank_mask:0xf bound_ctrl:1
	v_pk_mul_f32 v[132:133], v[132:133], v[96:97] op_sel_hi:[1,0]
	v_add_f32_dpp v102, v102, v102 row_half_mirror row_mask:0xf bank_mask:0xf bound_ctrl:1
	v_add_f32_dpp v104, v104, v104 row_half_mirror row_mask:0xf bank_mask:0xf bound_ctrl:1
	v_fma_f32 v105, -v96, v102, v101
	v_pk_mul_f32 v[106:107], v[96:97], v[104:105]
	v_pk_mul_f32 v[134:135], v[134:135], v[96:97] op_sel_hi:[1,0]
	v_pk_fma_f32 v[120:121], v[76:77], v[106:107], v[120:121] op_sel:[0,1,0]
	v_pk_fma_f32 v[122:123], v[78:79], v[106:107], v[122:123] op_sel:[0,1,0]
	v_fma_f32 v106, v98, v107, v106
	v_pk_fma_f32 v[124:125], v[80:81], v[106:107], v[124:125] op_sel:[0,1,0]
	v_pk_fma_f32 v[126:127], v[82:83], v[106:107], v[126:127] op_sel:[0,1,0]
	v_pk_fma_f32 v[128:129], v[84:85], v[106:107], v[128:129] op_sel:[0,1,0]
	v_pk_fma_f32 v[130:131], v[86:87], v[106:107], v[130:131] op_sel:[0,1,0]
	v_pk_fma_f32 v[132:133], v[88:89], v[106:107], v[132:133] op_sel:[0,1,0]
	v_pk_fma_f32 v[134:135], v[90:91], v[106:107], v[134:135] op_sel:[0,1,0]
	ds_write_b32 v166, v106 offset:1664
	s_waitcnt lgkmcnt(1)
; __device__ __forceinline__ float red8(float v) { v = red4(v); v += dppf<0x141>(v); return v; }
; __device__ __forceinline__ f32x2 lo2(const f32x4& v) { return __builtin_shufflevector(v, v, 0, 1); }
; __device__ __forceinline__ f32x2 hi2(const f32x4& v) { return __builtin_shufflevector(v, v, 2, 3); }
; __device__ __forceinline__ f32x2 splat2(float x) { return (f32x2){x, x}; }
; #define SCAN_INTERLEAVE(nds, nvalu)                                   \
;   _Pragma("unroll") for (int i_ = 0; i_ < (nds); ++i_) {               \
;     __builtin_amdgcn_sched_group_barrier(0x100, 1, 0);                 \
;     __builtin_amdgcn_sched_group_barrier(0x002, (nvalu), 0);           \
;   }
; __device__ __forceinline__ float gd_step(f32x2 (&S)[8], const GdRegs& R) {
;   f32x2 k0a = splat2(0.f), k1a = splat2(0.f), q0a = splat2(0.f), q1a = splat2(0.f);
; #pragma unroll
;   for (int q = 0; q < 4; ++q) {
;     k0a += S[2 * q] * lo2(R.k[q]);
;     k1a += S[2 * q + 1] * hi2(R.k[q]);
;     q0a += S[2 * q] * lo2(R.q[q]);
;     q1a += S[2 * q + 1] * hi2(R.q[q]);
;   }
;   k0a += k1a; q0a += q1a;
;   const float dK = red8(k0a.x + k0a.y), dQ = red8(q0a.x + q0a.y);
;   const float vn = R.sc.y * (R.v - R.sc.x * dK);
;   const float o = R.sc.x * dQ + R.sc.z * vn;
;   const f32x2 al2 = splat2(R.sc.x), vn2 = splat2(vn);
; #pragma unroll
;   for (int q = 0; q < 4; ++q) {
;     S[2 * q] = S[2 * q] * al2 + lo2(R.k[q]) * vn2;
;     S[2 * q + 1] = S[2 * q + 1] * al2 + hi2(R.k[q]) * vn2;
;   }
;   return o;
; }
; __device__ __forceinline__ void scan_gdn(const Params& p, int l, int seq, int h, int qt, char* smem, const unsigned* wflags, unsigned wexpect) {
;     ...
;     for (int t = 0; t < nsteps; t += 2) {
;       gd_load(RB, vb, sb, min(t + 1, 15), k0, cl);
;       const float o0v = gd_step(S, RA);
;       *((part == 0) ? (yb + t * 32 + cl) : ydummy) = o0v;
;       SCAN_INTERLEAVE(10, 4);
;       if (t + 1 < nsteps) {
;         gd_load(RA, vb, sb, min(t + 2, 15), k0, cl);
;         const float o1v = gd_step(S, RB);
;         *((part == 0) ? (yb + (t + 1) * 32 + cl) : ydummy) = o1v;
;         SCAN_INTERLEAVE(10, 4);
;       }
;     }
	s_nop 0
	ds_read_b128 v[76:79], v161 offset:17792
	ds_read_b128 v[80:83], v162 offset:17808
	ds_read_b128 v[84:87], v161 offset:17824
	ds_read_b128 v[88:91], v162 offset:17840
	ds_read_b32 v101, v163 offset:18304
	ds_read_b128 v[96:99], v164 offset:37104
	ds_read_b128 v[52:55], v161 offset:17312
	ds_read_b128 v[56:59], v162 offset:17328
	v_pk_mul_f32 v[102:103], v[120:121], v[60:61]
	v_pk_mul_f32 v[104:105], v[120:121], v[36:37]
	v_pk_fma_f32 v[102:103], v[122:123], v[62:63], v[102:103]
	v_pk_fma_f32 v[104:105], v[122:123], v[38:39], v[104:105]
	v_pk_mul_f32 v[120:121], v[120:121], v[92:93] op_sel_hi:[1,0]
	v_pk_fma_f32 v[102:103], v[124:125], v[64:65], v[102:103]
	v_pk_fma_f32 v[104:105], v[124:125], v[40:41], v[104:105]
	v_pk_mul_f32 v[122:123], v[122:123], v[92:93] op_sel_hi:[1,0]
	v_pk_fma_f32 v[102:103], v[126:127], v[66:67], v[102:103]
	v_pk_fma_f32 v[104:105], v[126:127], v[42:43], v[104:105]
	v_pk_mul_f32 v[124:125], v[124:125], v[92:93] op_sel_hi:[1,0]
	ds_read_b128 v[36:39], v161 offset:17280
	ds_read_b128 v[40:43], v162 offset:17296
	v_pk_fma_f32 v[102:103], v[128:129], v[68:69], v[102:103]
	v_pk_fma_f32 v[104:105], v[128:129], v[44:45], v[104:105]
	v_pk_mul_f32 v[126:127], v[126:127], v[92:93] op_sel_hi:[1,0]
	v_pk_fma_f32 v[102:103], v[130:131], v[70:71], v[102:103]
	v_pk_fma_f32 v[104:105], v[130:131], v[46:47], v[104:105]
	v_pk_fma_f32 v[102:103], v[132:133], v[72:73], v[102:103]
	v_pk_fma_f32 v[104:105], v[132:133], v[48:49], v[104:105]
	v_pk_fma_f32 v[102:103], v[134:135], v[74:75], v[102:103]
	v_pk_fma_f32 v[104:105], v[134:135], v[50:51], v[104:105]
	v_add_f32_e64 v102, v102, v103
	v_add_f32_e64 v104, v104, v105
	v_pk_mul_f32 v[128:129], v[128:129], v[92:93] op_sel_hi:[1,0]
	v_add_f32_dpp v102, v102, v102 quad_perm:[1,0,3,2] row_mask:0xf bank_mask:0xf bound_ctrl:1
	v_add_f32_dpp v104, v104, v104 quad_perm:[1,0,3,2] row_mask:0xf bank_mask:0xf bound_ctrl:1
	v_pk_mul_f32 v[130:131], v[130:131], v[92:93] op_sel_hi:[1,0]
	v_add_f32_dpp v102, v102, v102 quad_perm:[2,3,0,1] row_mask:0xf bank_mask:0xf bound_ctrl:1
	v_add_f32_dpp v104, v104, v104 quad_perm:[2,3,0,1] row_mask:0xf bank_mask:0xf bound_ctrl:1
	v_pk_mul_f32 v[132:133], v[132:133], v[92:93] op_sel_hi:[1,0]
	v_add_f32_dpp v102, v102, v102 row_half_mirror row_mask:0xf bank_mask:0xf bound_ctrl:1
	v_add_f32_dpp v104, v104, v104 row_half_mirror row_mask:0xf bank_mask:0xf bound_ctrl:1
	v_fma_f32 v105, -v92, v102, v100
	v_pk_mul_f32 v[106:107], v[92:93], v[104:105]
	v_pk_mul_f32 v[134:135], v[134:135], v[92:93] op_sel_hi:[1,0]
	v_pk_fma_f32 v[120:121], v[60:61], v[106:107], v[120:121] op_sel:[0,1,0]
	v_pk_fma_f32 v[122:123], v[62:63], v[106:107], v[122:123] op_sel:[0,1,0]
	v_fma_f32 v106, v94, v107, v106
	v_pk_fma_f32 v[124:125], v[64:65], v[106:107], v[124:125] op_sel:[0,1,0]
	v_pk_fma_f32 v[126:127], v[66:67], v[106:107], v[126:127] op_sel:[0,1,0]
	v_pk_fma_f32 v[128:129], v[68:69], v[106:107], v[128:129] op_sel:[0,1,0]
	v_pk_fma_f32 v[130:131], v[70:71], v[106:107], v[130:131] op_sel:[0,1,0]
	v_pk_fma_f32 v[132:133], v[72:73], v[106:107], v[132:133] op_sel:[0,1,0]
	v_pk_fma_f32 v[134:135], v[74:75], v[106:107], v[134:135] op_sel:[0,1,0]
	ds_write_b32 v166, v106 offset:1792
	s_waitcnt lgkmcnt(1)
	s_nop 0
	ds_read_b128 v[60:63], v161 offset:18944
	ds_read_b128 v[64:67], v162 offset:18960
	ds_read_b128 v[68:71], v161 offset:18976
	ds_read_b128 v[72:75], v162 offset:18992
	ds_read_b32 v100, v163 offset:19456
	ds_read_b128 v[92:95], v164 offset:37120
	ds_read_b128 v[44:47], v161 offset:18464
	ds_read_b128 v[48:51], v162 offset:18480
	v_pk_mul_f32 v[102:103], v[120:121], v[76:77]
	v_pk_mul_f32 v[104:105], v[120:121], v[36:37]
	v_pk_fma_f32 v[102:103], v[122:123], v[78:79], v[102:103]
	v_pk_fma_f32 v[104:105], v[122:123], v[38:39], v[104:105]
	v_pk_mul_f32 v[120:121], v[120:121], v[96:97] op_sel_hi:[1,0]
	v_pk_fma_f32 v[102:103], v[124:125], v[80:81], v[102:103]
	v_pk_fma_f32 v[104:105], v[124:125], v[40:41], v[104:105]
	v_pk_mul_f32 v[122:123], v[122:123], v[96:97] op_sel_hi:[1,0]
	v_pk_fma_f32 v[102:103], v[126:127], v[82:83], v[102:103]
	v_pk_fma_f32 v[104:105], v[126:127], v[42:43], v[104:105]
	v_pk_mul_f32 v[124:125], v[124:125], v[96:97] op_sel_hi:[1,0]
	ds_read_b128 v[36:39], v161 offset:18432
	ds_read_b128 v[40:43], v162 offset:18448
	v_pk_fma_f32 v[102:103], v[128:129], v[84:85], v[102:103]
	v_pk_fma_f32 v[104:105], v[128:129], v[52:53], v[104:105]
	v_pk_mul_f32 v[126:127], v[126:127], v[96:97] op_sel_hi:[1,0]
	v_pk_fma_f32 v[102:103], v[130:131], v[86:87], v[102:103]
	v_pk_fma_f32 v[104:105], v[130:131], v[54:55], v[104:105]
	v_pk_fma_f32 v[102:103], v[132:133], v[88:89], v[102:103]
	v_pk_fma_f32 v[104:105], v[132:133], v[56:57], v[104:105]
	v_pk_fma_f32 v[102:103], v[134:135], v[90:91], v[102:103]
	v_pk_fma_f32 v[104:105], v[134:135], v[58:59], v[104:105]
	v_add_f32_e64 v102, v102, v103
	v_add_f32_e64 v104, v104, v105
	v_pk_mul_f32 v[128:129], v[128:129], v[96:97] op_sel_hi:[1,0]
	v_add_f32_dpp v102, v102, v102 quad_perm:[1,0,3,2] row_mask:0xf bank_mask:0xf bound_ctrl:1
	v_add_f32_dpp v104, v104, v104 quad_perm:[1,0,3,2] row_mask:0xf bank_mask:0xf bound_ctrl:1
	v_pk_mul_f32 v[130:131], v[130:131], v[96:97] op_sel_hi:[1,0]
	v_add_f32_dpp v102, v102, v102 quad_perm:[2,3,0,1] row_mask:0xf bank_mask:0xf bound_ctrl:1
	v_add_f32_dpp v104, v104, v104 quad_perm:[2,3,0,1] row_mask:0xf bank_mask:0xf bound_ctrl:1
	v_pk_mul_f32 v[132:133], v[132:133], v[96:97] op_sel_hi:[1,0]
	v_add_f32_dpp v102, v102, v102 row_half_mirror row_mask:0xf bank_mask:0xf bound_ctrl:1
	v_add_f32_dpp v104, v104, v104 row_half_mirror row_mask:0xf bank_mask:0xf bound_ctrl:1
	v_fma_f32 v105, -v96, v102, v101
	v_pk_mul_f32 v[106:107], v[96:97], v[104:105]
	v_pk_mul_f32 v[134:135], v[134:135], v[96:97] op_sel_hi:[1,0]
	v_pk_fma_f32 v[120:121], v[76:77], v[106:107], v[120:121] op_sel:[0,1,0]
	v_pk_fma_f32 v[122:123], v[78:79], v[106:107], v[122:123] op_sel:[0,1,0]
	v_fma_f32 v106, v98, v107, v106
	v_pk_fma_f32 v[124:125], v[80:81], v[106:107], v[124:125] op_sel:[0,1,0]
	v_pk_fma_f32 v[126:127], v[82:83], v[106:107], v[126:127] op_sel:[0,1,0]
	v_pk_fma_f32 v[128:129], v[84:85], v[106:107], v[128:129] op_sel:[0,1,0]
	v_pk_fma_f32 v[130:131], v[86:87], v[106:107], v[130:131] op_sel:[0,1,0]
	v_pk_fma_f32 v[132:133], v[88:89], v[106:107], v[132:133] op_sel:[0,1,0]
	v_pk_fma_f32 v[134:135], v[90:91], v[106:107], v[134:135] op_sel:[0,1,0]
	ds_write_b32 v166, v106 offset:1920
	s_cmp_eq_u32 s51, 0
	s_cbranch_scc1 .LBB0_193
	s_branch .LBB0_229
	.p2align 3
; __device__ __forceinline__ float red8(float v) { v = red4(v); v += dppf<0x141>(v); return v; }
; __device__ __forceinline__ f32x2 lo2(const f32x4& v) { return __builtin_shufflevector(v, v, 0, 1); }
; __device__ __forceinline__ f32x2 hi2(const f32x4& v) { return __builtin_shufflevector(v, v, 2, 3); }
; __device__ __forceinline__ f32x2 splat2(float x) { return (f32x2){x, x}; }
; __device__ __forceinline__ f32x2 rw_step(f32x2 (&S)[2][4], const RwRegs& R) {
;   float sa[2], sy[2];
; #pragma unroll
;   for (int r = 0; r < 2; ++r) {
;     f32x2 a0 = S[r][0] * lo2(R.a[0]);
;     f32x2 a1 = S[r][1] * hi2(R.a[0]);
;     f32x2 y0 = S[r][0] * lo2(R.wr[0]);
;     f32x2 y1 = S[r][1] * hi2(R.wr[0]);
;     a0 += S[r][2] * lo2(R.a[1]);
;     a1 += S[r][3] * hi2(R.a[1]);
;     y0 += S[r][2] * lo2(R.wr[1]);
;     y1 += S[r][3] * hi2(R.wr[1]);
;     a0 += a1; y0 += y1;
;     sa[r] = a0.x + a0.y; sy[r] = y0.x + y0.y;
;   }
;   sa[0] = red8(sa[0]); sa[1] = red8(sa[1]); sy[0] = red8(sy[0]); sy[1] = red8(sy[1]);
;   f32x2 yv;
; #pragma unroll
;   for (int r = 0; r < 2; ++r) {
;     const float vr = r ? R.v.y : R.v.x;
;     const f32x2 sa2 = splat2(sa[r]), vv2 = splat2(vr);
;     S[r][0] = S[r][0] * lo2(R.w[0]) + (sa2 * lo2(R.b[0]) + vv2 * lo2(R.k[0]));
;     S[r][1] = S[r][1] * hi2(R.w[0]) + (sa2 * hi2(R.b[0]) + vv2 * hi2(R.k[0]));
;     S[r][2] = S[r][2] * lo2(R.w[1]) + (sa2 * lo2(R.b[1]) + vv2 * lo2(R.k[1]));
;     S[r][3] = S[r][3] * hi2(R.w[1]) + (sa2 * hi2(R.b[1]) + vv2 * hi2(R.k[1]));
;     const float y = sy[r] + sa[r] * R.sc.x + vr * R.sc.y;
;     if (r) yv.y = y; else yv.x = y;
;   }
;   return yv;
; }
; __device__ __forceinline__ void scan_rwkv(const Params& p, int l, int seq, int h, char* smem, const unsigned* wflags, unsigned wexpect) {
;     ...
;     for (int t = 0; t < nsteps; t += 2) {
;       rw_load(RB, vb, sb, min(t + 1, 15), k0, vrow0);
;       const f32x2 y0v = rw_step(S, RA);
;       *(f32x2*)((part == 0) ? (yb + t * 64 + vrow0) : ydummy) = y0v;
;       SCAN_INTERLEAVE(13, 4);
;       if (t + 1 < nsteps) {
;         rw_load(RA, vb, sb, min(t + 2, 15), k0, vrow0);
;         const f32x2 y1v = rw_step(S, RB);
;         *(f32x2*)((part == 0) ? (yb + (t + 1) * 64 + vrow0) : ydummy) = y1v;
;         SCAN_INTERLEAVE(13, 4);
;       }
.Lrwf_body:
	ds_read_b128 v[68:71], v205 offset:0
	ds_read_b128 v[72:75], v205 offset:16
	ds_read_b128 v[76:79], v205 offset:512
	ds_read_b128 v[80:83], v205 offset:528
	ds_read_b128 v[84:87], v205 offset:1024
	ds_read_b128 v[88:91], v205 offset:1040
	ds_read_b64 v[92:93], v206 offset:1280
	ds_read_b64 v[94:95], v207 offset:49152
	ds_read_b128 v[96:99], v205 offset:768
	ds_read_b128 v[100:103], v205 offset:784
	ds_read_b128 v[112:115], v205 offset:256
	ds_read_b128 v[116:119], v205 offset:272
	s_waitcnt lgkmcnt(0)
	s_nop 0
	v_pk_mul_f32 v[144:145], v[8:9], v[68:69]
	v_pk_mul_f32 v[148:149], v[8:9], v[76:77]
	v_pk_mul_f32 v[146:147], v[16:17], v[68:69]
	v_pk_mul_f32 v[174:175], v[16:17], v[76:77]
	v_pk_fma_f32 v[144:145], v[10:11], v[70:71], v[144:145]
	v_pk_fma_f32 v[148:149], v[10:11], v[78:79], v[148:149]
	v_pk_fma_f32 v[146:147], v[18:19], v[70:71], v[146:147]
	v_pk_fma_f32 v[174:175], v[18:19], v[78:79], v[174:175]
	v_pk_fma_f32 v[144:145], v[4:5], v[72:73], v[144:145]
	v_pk_fma_f32 v[148:149], v[4:5], v[80:81], v[148:149]
	v_pk_fma_f32 v[146:147], v[12:13], v[72:73], v[146:147]
	v_pk_fma_f32 v[174:175], v[12:13], v[80:81], v[174:175]
	v_pk_fma_f32 v[144:145], v[6:7], v[74:75], v[144:145]
	v_pk_fma_f32 v[148:149], v[6:7], v[82:83], v[148:149]
	v_pk_fma_f32 v[146:147], v[14:15], v[74:75], v[146:147]
	v_pk_fma_f32 v[174:175], v[14:15], v[82:83], v[174:175]
	ds_read_b128 v[68:71], v205 offset:1536
	ds_read_b128 v[72:75], v205 offset:1552
	ds_read_b128 v[76:79], v205 offset:2048
	ds_read_b128 v[80:83], v205 offset:2064
	ds_read_b128 v[104:107], v205 offset:2304
	ds_read_b128 v[108:111], v205 offset:2320
	ds_read_b128 v[120:123], v205 offset:1792
	ds_read_b128 v[124:127], v205 offset:1808
	v_add_f32_e64 v144, v144, v145
	v_pk_mul_f32 v[128:129], v[92:93], v[84:85] op_sel_hi:[0,1]
	v_pk_mul_f32 v[136:137], v[92:93], v[84:85] op_sel:[1,0]
	v_add_f32_e64 v148, v148, v149
	v_add_f32_e64 v145, v146, v147
	v_add_f32_e64 v149, v174, v175
	v_pk_mul_f32 v[130:131], v[92:93], v[86:87] op_sel_hi:[0,1]
	v_pk_mul_f32 v[138:139], v[92:93], v[86:87] op_sel:[1,0]
	v_add_f32_dpp v144, v144, v144 quad_perm:[1,0,3,2] row_mask:0xf bank_mask:0xf bound_ctrl:1
	v_add_f32_dpp v148, v148, v148 quad_perm:[1,0,3,2] row_mask:0xf bank_mask:0xf bound_ctrl:1
	v_add_f32_dpp v145, v145, v145 quad_perm:[1,0,3,2] row_mask:0xf bank_mask:0xf bound_ctrl:1
	v_add_f32_dpp v149, v149, v149 quad_perm:[1,0,3,2] row_mask:0xf bank_mask:0xf bound_ctrl:1
	v_pk_mul_f32 v[132:133], v[92:93], v[88:89] op_sel_hi:[0,1]
	v_pk_mul_f32 v[140:141], v[92:93], v[88:89] op_sel:[1,0]
	v_add_f32_dpp v144, v144, v144 quad_perm:[2,3,0,1] row_mask:0xf bank_mask:0xf bound_ctrl:1
	v_add_f32_dpp v148, v148, v148 quad_perm:[2,3,0,1] row_mask:0xf bank_mask:0xf bound_ctrl:1
	v_add_f32_dpp v145, v145, v145 quad_perm:[2,3,0,1] row_mask:0xf bank_mask:0xf bound_ctrl:1
	v_add_f32_dpp v149, v149, v149 quad_perm:[2,3,0,1] row_mask:0xf bank_mask:0xf bound_ctrl:1
	v_pk_mul_f32 v[134:135], v[92:93], v[90:91] op_sel_hi:[0,1]
	v_pk_mul_f32 v[142:143], v[92:93], v[90:91] op_sel:[1,0]
	v_add_f32_dpp v144, v144, v144 row_half_mirror row_mask:0xf bank_mask:0xf bound_ctrl:1
	v_add_f32_dpp v148, v148, v148 row_half_mirror row_mask:0xf bank_mask:0xf bound_ctrl:1
	v_add_f32_dpp v145, v145, v145 row_half_mirror row_mask:0xf bank_mask:0xf bound_ctrl:1
	v_add_f32_dpp v149, v149, v149 row_half_mirror row_mask:0xf bank_mask:0xf bound_ctrl:1
	v_pk_fma_f32 v[176:177], v[144:145], v[94:95], v[148:149] op_sel_hi:[1,0,1]
	v_pk_fma_f32 v[128:129], v[96:97], v[144:145], v[128:129] op_sel_hi:[1,0,1]
	v_pk_fma_f32 v[176:177], v[92:93], v[94:95], v[176:177] op_sel:[0,1,0]
	v_pk_fma_f32 v[136:137], v[96:97], v[144:145], v[136:137] op_sel:[0,1,0]
	ds_read_b64 v[94:95], v207 offset:49168
	ds_read_b128 v[84:87], v205 offset:2560
	ds_read_b128 v[88:91], v205 offset:2576
	ds_read_b64 v[92:93], v206 offset:2816
	ds_write_b64 v208, v[176:177] offset:0
	v_pk_fma_f32 v[8:9], v[8:9], v[112:113], v[128:129]
	v_pk_fma_f32 v[16:17], v[16:17], v[112:113], v[136:137]
	v_pk_fma_f32 v[130:131], v[98:99], v[144:145], v[130:131] op_sel_hi:[1,0,1]
	v_pk_fma_f32 v[138:139], v[98:99], v[144:145], v[138:139] op_sel:[0,1,0]
	v_pk_fma_f32 v[10:11], v[10:11], v[114:115], v[130:131]
	v_pk_fma_f32 v[18:19], v[18:19], v[114:115], v[138:139]
	v_pk_fma_f32 v[132:133], v[100:101], v[144:145], v[132:133] op_sel_hi:[1,0,1]
	v_pk_fma_f32 v[140:141], v[100:101], v[144:145], v[140:141] op_sel:[0,1,0]
	v_pk_fma_f32 v[4:5], v[4:5], v[116:117], v[132:133]
	v_pk_fma_f32 v[12:13], v[12:13], v[116:117], v[140:141]
	v_pk_fma_f32 v[134:135], v[102:103], v[144:145], v[134:135] op_sel_hi:[1,0,1]
	v_pk_fma_f32 v[142:143], v[102:103], v[144:145], v[142:143] op_sel:[0,1,0]
	v_pk_fma_f32 v[6:7], v[6:7], v[118:119], v[134:135]
	v_pk_fma_f32 v[14:15], v[14:15], v[118:119], v[142:143]
	s_waitcnt lgkmcnt(5)
	s_nop 0
	v_pk_mul_f32 v[144:145], v[8:9], v[68:69]
	v_pk_mul_f32 v[148:149], v[8:9], v[76:77]
	v_pk_mul_f32 v[146:147], v[16:17], v[68:69]
	v_pk_mul_f32 v[174:175], v[16:17], v[76:77]
	v_pk_fma_f32 v[144:145], v[10:11], v[70:71], v[144:145]
	v_pk_fma_f32 v[148:149], v[10:11], v[78:79], v[148:149]
	v_pk_fma_f32 v[146:147], v[18:19], v[70:71], v[146:147]
	v_pk_fma_f32 v[174:175], v[18:19], v[78:79], v[174:175]
	v_pk_fma_f32 v[144:145], v[4:5], v[72:73], v[144:145]
	v_pk_fma_f32 v[148:149], v[4:5], v[80:81], v[148:149]
	v_pk_fma_f32 v[146:147], v[12:13], v[72:73], v[146:147]
	v_pk_fma_f32 v[174:175], v[12:13], v[80:81], v[174:175]
	v_pk_fma_f32 v[144:145], v[6:7], v[74:75], v[144:145]
	v_pk_fma_f32 v[148:149], v[6:7], v[82:83], v[148:149]
	v_pk_fma_f32 v[146:147], v[14:15], v[74:75], v[146:147]
	v_pk_fma_f32 v[174:175], v[14:15], v[82:83], v[174:175]
	ds_read_b128 v[68:71], v205 offset:3072
	ds_read_b128 v[72:75], v205 offset:3088
	ds_read_b128 v[76:79], v205 offset:3584
	ds_read_b128 v[80:83], v205 offset:3600
	ds_read_b128 v[96:99], v205 offset:3840
	ds_read_b128 v[100:103], v205 offset:3856
	ds_read_b128 v[112:115], v205 offset:3328
	ds_read_b128 v[116:119], v205 offset:3344
	s_waitcnt lgkmcnt(9)
; __device__ __forceinline__ float red8(float v) { v = red4(v); v += dppf<0x141>(v); return v; }
; __device__ __forceinline__ f32x2 lo2(const f32x4& v) { return __builtin_shufflevector(v, v, 0, 1); }
; __device__ __forceinline__ f32x2 hi2(const f32x4& v) { return __builtin_shufflevector(v, v, 2, 3); }
; __device__ __forceinline__ f32x2 splat2(float x) { return (f32x2){x, x}; }
; __device__ __forceinline__ f32x2 rw_step(f32x2 (&S)[2][4], const RwRegs& R) {
;   float sa[2], sy[2];
; #pragma unroll
;   for (int r = 0; r < 2; ++r) {
;     f32x2 a0 = S[r][0] * lo2(R.a[0]);
;     f32x2 a1 = S[r][1] * hi2(R.a[0]);
;     f32x2 y0 = S[r][0] * lo2(R.wr[0]);
;     f32x2 y1 = S[r][1] * hi2(R.wr[0]);
;     a0 += S[r][2] * lo2(R.a[1]);
;     a1 += S[r][3] * hi2(R.a[1]);
;     y0 += S[r][2] * lo2(R.wr[1]);
;     y1 += S[r][3] * hi2(R.wr[1]);
;     a0 += a1; y0 += y1;
;     sa[r] = a0.x + a0.y; sy[r] = y0.x + y0.y;
;   }
;   sa[0] = red8(sa[0]); sa[1] = red8(sa[1]); sy[0] = red8(sy[0]); sy[1] = red8(sy[1]);
;   f32x2 yv;
; #pragma unroll
;   for (int r = 0; r < 2; ++r) {
;     const float vr = r ? R.v.y : R.v.x;
;     const f32x2 sa2 = splat2(sa[r]), vv2 = splat2(vr);
;     S[r][0] = S[r][0] * lo2(R.w[0]) + (sa2 * lo2(R.b[0]) + vv2 * lo2(R.k[0]));
;     S[r][1] = S[r][1] * hi2(R.w[0]) + (sa2 * hi2(R.b[0]) + vv2 * hi2(R.k[0]));
;     S[r][2] = S[r][2] * lo2(R.w[1]) + (sa2 * lo2(R.b[1]) + vv2 * lo2(R.k[1]));
;     S[r][3] = S[r][3] * hi2(R.w[1]) + (sa2 * hi2(R.b[1]) + vv2 * hi2(R.k[1]));
;     const float y = sy[r] + sa[r] * R.sc.x + vr * R.sc.y;
;     if (r) yv.y = y; else yv.x = y;
;   }
;   return yv;
; }
; __device__ __forceinline__ void scan_rwkv(const Params& p, int l, int seq, int h, char* smem, const unsigned* wflags, unsigned wexpect) {
;     ...
;     for (int t = 0; t < nsteps; t += 2) {
;       rw_load(RB, vb, sb, min(t + 1, 15), k0, vrow0);
;       const f32x2 y0v = rw_step(S, RA);
;       *(f32x2*)((part == 0) ? (yb + t * 64 + vrow0) : ydummy) = y0v;
;       SCAN_INTERLEAVE(13, 4);
;       if (t + 1 < nsteps) {
;         rw_load(RA, vb, sb, min(t + 2, 15), k0, vrow0);
;         const f32x2 y1v = rw_step(S, RB);
;         *(f32x2*)((part == 0) ? (yb + (t + 1) * 64 + vrow0) : ydummy) = y1v;
;         SCAN_INTERLEAVE(13, 4);
;       }
	v_add_f32_e32 v144, v144, v145
	v_pk_mul_f32 v[128:129], v[92:93], v[84:85] op_sel_hi:[0,1]
	v_pk_mul_f32 v[136:137], v[92:93], v[84:85] op_sel:[1,0]
	v_add_f32_e64 v148, v148, v149
	v_add_f32_e64 v145, v146, v147
	v_add_f32_e64 v149, v174, v175
	v_pk_mul_f32 v[130:131], v[92:93], v[86:87] op_sel_hi:[0,1]
	v_pk_mul_f32 v[138:139], v[92:93], v[86:87] op_sel:[1,0]
	v_add_f32_dpp v144, v144, v144 quad_perm:[1,0,3,2] row_mask:0xf bank_mask:0xf bound_ctrl:1
	v_add_f32_dpp v148, v148, v148 quad_perm:[1,0,3,2] row_mask:0xf bank_mask:0xf bound_ctrl:1
	v_add_f32_dpp v145, v145, v145 quad_perm:[1,0,3,2] row_mask:0xf bank_mask:0xf bound_ctrl:1
	v_add_f32_dpp v149, v149, v149 quad_perm:[1,0,3,2] row_mask:0xf bank_mask:0xf bound_ctrl:1
	v_pk_mul_f32 v[132:133], v[92:93], v[88:89] op_sel_hi:[0,1]
	v_pk_mul_f32 v[140:141], v[92:93], v[88:89] op_sel:[1,0]
	v_add_f32_dpp v144, v144, v144 quad_perm:[2,3,0,1] row_mask:0xf bank_mask:0xf bound_ctrl:1
	v_add_f32_dpp v148, v148, v148 quad_perm:[2,3,0,1] row_mask:0xf bank_mask:0xf bound_ctrl:1
	v_add_f32_dpp v145, v145, v145 quad_perm:[2,3,0,1] row_mask:0xf bank_mask:0xf bound_ctrl:1
	v_add_f32_dpp v149, v149, v149 quad_perm:[2,3,0,1] row_mask:0xf bank_mask:0xf bound_ctrl:1
	v_pk_mul_f32 v[134:135], v[92:93], v[90:91] op_sel_hi:[0,1]
	v_pk_mul_f32 v[142:143], v[92:93], v[90:91] op_sel:[1,0]
	v_add_f32_dpp v144, v144, v144 row_half_mirror row_mask:0xf bank_mask:0xf bound_ctrl:1
	v_add_f32_dpp v148, v148, v148 row_half_mirror row_mask:0xf bank_mask:0xf bound_ctrl:1
	v_add_f32_dpp v145, v145, v145 row_half_mirror row_mask:0xf bank_mask:0xf bound_ctrl:1
	v_add_f32_dpp v149, v149, v149 row_half_mirror row_mask:0xf bank_mask:0xf bound_ctrl:1
	v_pk_fma_f32 v[176:177], v[144:145], v[94:95], v[148:149] op_sel_hi:[1,0,1]
	v_pk_fma_f32 v[128:129], v[104:105], v[144:145], v[128:129] op_sel_hi:[1,0,1]
	v_pk_fma_f32 v[176:177], v[92:93], v[94:95], v[176:177] op_sel:[0,1,0]
	v_pk_fma_f32 v[136:137], v[104:105], v[144:145], v[136:137] op_sel:[0,1,0]
	ds_read_b64 v[94:95], v207 offset:49184
	ds_read_b128 v[84:87], v205 offset:4096
	ds_read_b128 v[88:91], v205 offset:4112
	ds_read_b64 v[92:93], v206 offset:4352
	ds_write_b64 v208, v[176:177] offset:256
	v_pk_fma_f32 v[8:9], v[8:9], v[120:121], v[128:129]
	v_pk_fma_f32 v[16:17], v[16:17], v[120:121], v[136:137]
	v_pk_fma_f32 v[130:131], v[106:107], v[144:145], v[130:131] op_sel_hi:[1,0,1]
	v_pk_fma_f32 v[138:139], v[106:107], v[144:145], v[138:139] op_sel:[0,1,0]
	v_pk_fma_f32 v[10:11], v[10:11], v[122:123], v[130:131]
	v_pk_fma_f32 v[18:19], v[18:19], v[122:123], v[138:139]
	v_pk_fma_f32 v[132:133], v[108:109], v[144:145], v[132:133] op_sel_hi:[1,0,1]
	v_pk_fma_f32 v[140:141], v[108:109], v[144:145], v[140:141] op_sel:[0,1,0]
	v_pk_fma_f32 v[4:5], v[4:5], v[124:125], v[132:133]
	v_pk_fma_f32 v[12:13], v[12:13], v[124:125], v[140:141]
	v_pk_fma_f32 v[134:135], v[110:111], v[144:145], v[134:135] op_sel_hi:[1,0,1]
	v_pk_fma_f32 v[142:143], v[110:111], v[144:145], v[142:143] op_sel:[0,1,0]
	v_pk_fma_f32 v[6:7], v[6:7], v[126:127], v[134:135]
	v_pk_fma_f32 v[14:15], v[14:15], v[126:127], v[142:143]
	s_waitcnt lgkmcnt(5)
	s_nop 0
	v_pk_mul_f32 v[144:145], v[8:9], v[68:69]
	v_pk_mul_f32 v[148:149], v[8:9], v[76:77]
	v_pk_mul_f32 v[146:147], v[16:17], v[68:69]
	v_pk_mul_f32 v[174:175], v[16:17], v[76:77]
	v_pk_fma_f32 v[144:145], v[10:11], v[70:71], v[144:145]
	v_pk_fma_f32 v[148:149], v[10:11], v[78:79], v[148:149]
	v_pk_fma_f32 v[146:147], v[18:19], v[70:71], v[146:147]
	v_pk_fma_f32 v[174:175], v[18:19], v[78:79], v[174:175]
	v_pk_fma_f32 v[144:145], v[4:5], v[72:73], v[144:145]
	v_pk_fma_f32 v[148:149], v[4:5], v[80:81], v[148:149]
	v_pk_fma_f32 v[146:147], v[12:13], v[72:73], v[146:147]
	v_pk_fma_f32 v[174:175], v[12:13], v[80:81], v[174:175]
	v_pk_fma_f32 v[144:145], v[6:7], v[74:75], v[144:145]
	v_pk_fma_f32 v[148:149], v[6:7], v[82:83], v[148:149]
	v_pk_fma_f32 v[146:147], v[14:15], v[74:75], v[146:147]
	v_pk_fma_f32 v[174:175], v[14:15], v[82:83], v[174:175]
	ds_read_b128 v[68:71], v205 offset:4608
	ds_read_b128 v[72:75], v205 offset:4624
	ds_read_b128 v[76:79], v205 offset:5120
	ds_read_b128 v[80:83], v205 offset:5136
	ds_read_b128 v[104:107], v205 offset:5376
	ds_read_b128 v[108:111], v205 offset:5392
	ds_read_b128 v[120:123], v205 offset:4864
	ds_read_b128 v[124:127], v205 offset:4880
	s_waitcnt lgkmcnt(9)
; __device__ __forceinline__ float red8(float v) { v = red4(v); v += dppf<0x141>(v); return v; }
; __device__ __forceinline__ f32x2 lo2(const f32x4& v) { return __builtin_shufflevector(v, v, 0, 1); }
; __device__ __forceinline__ f32x2 hi2(const f32x4& v) { return __builtin_shufflevector(v, v, 2, 3); }
; __device__ __forceinline__ f32x2 splat2(float x) { return (f32x2){x, x}; }
; __device__ __forceinline__ f32x2 rw_step(f32x2 (&S)[2][4], const RwRegs& R) {
;   float sa[2], sy[2];
; #pragma unroll
;   for (int r = 0; r < 2; ++r) {
;     f32x2 a0 = S[r][0] * lo2(R.a[0]);
;     f32x2 a1 = S[r][1] * hi2(R.a[0]);
;     f32x2 y0 = S[r][0] * lo2(R.wr[0]);
;     f32x2 y1 = S[r][1] * hi2(R.wr[0]);
;     a0 += S[r][2] * lo2(R.a[1]);
;     a1 += S[r][3] * hi2(R.a[1]);
;     y0 += S[r][2] * lo2(R.wr[1]);
;     y1 += S[r][3] * hi2(R.wr[1]);
;     a0 += a1; y0 += y1;
;     sa[r] = a0.x + a0.y; sy[r] = y0.x + y0.y;
;   }
;   sa[0] = red8(sa[0]); sa[1] = red8(sa[1]); sy[0] = red8(sy[0]); sy[1] = red8(sy[1]);
;   f32x2 yv;
; #pragma unroll
;   for (int r = 0; r < 2; ++r) {
;     const float vr = r ? R.v.y : R.v.x;
;     const f32x2 sa2 = splat2(sa[r]), vv2 = splat2(vr);
;     S[r][0] = S[r][0] * lo2(R.w[0]) + (sa2 * lo2(R.b[0]) + vv2 * lo2(R.k[0]));
;     S[r][1] = S[r][1] * hi2(R.w[0]) + (sa2 * hi2(R.b[0]) + vv2 * hi2(R.k[0]));
;     S[r][2] = S[r][2] * lo2(R.w[1]) + (sa2 * lo2(R.b[1]) + vv2 * lo2(R.k[1]));
;     S[r][3] = S[r][3] * hi2(R.w[1]) + (sa2 * hi2(R.b[1]) + vv2 * hi2(R.k[1]));
;     const float y = sy[r] + sa[r] * R.sc.x + vr * R.sc.y;
;     if (r) yv.y = y; else yv.x = y;
;   }
;   return yv;
; }
; __device__ __forceinline__ void scan_rwkv(const Params& p, int l, int seq, int h, char* smem, const unsigned* wflags, unsigned wexpect) {
;     ...
;     for (int t = 0; t < nsteps; t += 2) {
;       rw_load(RB, vb, sb, min(t + 1, 15), k0, vrow0);
;       const f32x2 y0v = rw_step(S, RA);
;       *(f32x2*)((part == 0) ? (yb + t * 64 + vrow0) : ydummy) = y0v;
;       SCAN_INTERLEAVE(13, 4);
;       if (t + 1 < nsteps) {
;         rw_load(RA, vb, sb, min(t + 2, 15), k0, vrow0);
;         const f32x2 y1v = rw_step(S, RB);
;         *(f32x2*)((part == 0) ? (yb + (t + 1) * 64 + vrow0) : ydummy) = y1v;
;         SCAN_INTERLEAVE(13, 4);
;       }
	v_add_f32_e32 v144, v144, v145
	v_pk_mul_f32 v[128:129], v[92:93], v[84:85] op_sel_hi:[0,1]
	v_pk_mul_f32 v[136:137], v[92:93], v[84:85] op_sel:[1,0]
	v_add_f32_e64 v148, v148, v149
	v_add_f32_e64 v145, v146, v147
	v_add_f32_e64 v149, v174, v175
	v_pk_mul_f32 v[130:131], v[92:93], v[86:87] op_sel_hi:[0,1]
	v_pk_mul_f32 v[138:139], v[92:93], v[86:87] op_sel:[1,0]
	v_add_f32_dpp v144, v144, v144 quad_perm:[1,0,3,2] row_mask:0xf bank_mask:0xf bound_ctrl:1
	v_add_f32_dpp v148, v148, v148 quad_perm:[1,0,3,2] row_mask:0xf bank_mask:0xf bound_ctrl:1
	v_add_f32_dpp v145, v145, v145 quad_perm:[1,0,3,2] row_mask:0xf bank_mask:0xf bound_ctrl:1
	v_add_f32_dpp v149, v149, v149 quad_perm:[1,0,3,2] row_mask:0xf bank_mask:0xf bound_ctrl:1
	v_pk_mul_f32 v[132:133], v[92:93], v[88:89] op_sel_hi:[0,1]
	v_pk_mul_f32 v[140:141], v[92:93], v[88:89] op_sel:[1,0]
	v_add_f32_dpp v144, v144, v144 quad_perm:[2,3,0,1] row_mask:0xf bank_mask:0xf bound_ctrl:1
	v_add_f32_dpp v148, v148, v148 quad_perm:[2,3,0,1] row_mask:0xf bank_mask:0xf bound_ctrl:1
	v_add_f32_dpp v145, v145, v145 quad_perm:[2,3,0,1] row_mask:0xf bank_mask:0xf bound_ctrl:1
	v_add_f32_dpp v149, v149, v149 quad_perm:[2,3,0,1] row_mask:0xf bank_mask:0xf bound_ctrl:1
	v_pk_mul_f32 v[134:135], v[92:93], v[90:91] op_sel_hi:[0,1]
	v_pk_mul_f32 v[142:143], v[92:93], v[90:91] op_sel:[1,0]
	v_add_f32_dpp v144, v144, v144 row_half_mirror row_mask:0xf bank_mask:0xf bound_ctrl:1
	v_add_f32_dpp v148, v148, v148 row_half_mirror row_mask:0xf bank_mask:0xf bound_ctrl:1
	v_add_f32_dpp v145, v145, v145 row_half_mirror row_mask:0xf bank_mask:0xf bound_ctrl:1
	v_add_f32_dpp v149, v149, v149 row_half_mirror row_mask:0xf bank_mask:0xf bound_ctrl:1
	v_pk_fma_f32 v[176:177], v[144:145], v[94:95], v[148:149] op_sel_hi:[1,0,1]
	v_pk_fma_f32 v[128:129], v[96:97], v[144:145], v[128:129] op_sel_hi:[1,0,1]
	v_pk_fma_f32 v[176:177], v[92:93], v[94:95], v[176:177] op_sel:[0,1,0]
	v_pk_fma_f32 v[136:137], v[96:97], v[144:145], v[136:137] op_sel:[0,1,0]
	ds_read_b64 v[94:95], v207 offset:49200
	ds_read_b128 v[84:87], v205 offset:5632
	ds_read_b128 v[88:91], v205 offset:5648
	ds_read_b64 v[92:93], v206 offset:5888
	ds_write_b64 v208, v[176:177] offset:512
	v_pk_fma_f32 v[8:9], v[8:9], v[112:113], v[128:129]
	v_pk_fma_f32 v[16:17], v[16:17], v[112:113], v[136:137]
	v_pk_fma_f32 v[130:131], v[98:99], v[144:145], v[130:131] op_sel_hi:[1,0,1]
	v_pk_fma_f32 v[138:139], v[98:99], v[144:145], v[138:139] op_sel:[0,1,0]
	v_pk_fma_f32 v[10:11], v[10:11], v[114:115], v[130:131]
	v_pk_fma_f32 v[18:19], v[18:19], v[114:115], v[138:139]
	v_pk_fma_f32 v[132:133], v[100:101], v[144:145], v[132:133] op_sel_hi:[1,0,1]
	v_pk_fma_f32 v[140:141], v[100:101], v[144:145], v[140:141] op_sel:[0,1,0]
	v_pk_fma_f32 v[4:5], v[4:5], v[116:117], v[132:133]
	v_pk_fma_f32 v[12:13], v[12:13], v[116:117], v[140:141]
	v_pk_fma_f32 v[134:135], v[102:103], v[144:145], v[134:135] op_sel_hi:[1,0,1]
	v_pk_fma_f32 v[142:143], v[102:103], v[144:145], v[142:143] op_sel:[0,1,0]
	v_pk_fma_f32 v[6:7], v[6:7], v[118:119], v[134:135]
	v_pk_fma_f32 v[14:15], v[14:15], v[118:119], v[142:143]
	s_waitcnt lgkmcnt(5)
	s_nop 0
	v_pk_mul_f32 v[144:145], v[8:9], v[68:69]
	v_pk_mul_f32 v[148:149], v[8:9], v[76:77]
	v_pk_mul_f32 v[146:147], v[16:17], v[68:69]
	v_pk_mul_f32 v[174:175], v[16:17], v[76:77]
	v_pk_fma_f32 v[144:145], v[10:11], v[70:71], v[144:145]
	v_pk_fma_f32 v[148:149], v[10:11], v[78:79], v[148:149]
	v_pk_fma_f32 v[146:147], v[18:19], v[70:71], v[146:147]
	v_pk_fma_f32 v[174:175], v[18:19], v[78:79], v[174:175]
	v_pk_fma_f32 v[144:145], v[4:5], v[72:73], v[144:145]
	v_pk_fma_f32 v[148:149], v[4:5], v[80:81], v[148:149]
	v_pk_fma_f32 v[146:147], v[12:13], v[72:73], v[146:147]
	v_pk_fma_f32 v[174:175], v[12:13], v[80:81], v[174:175]
	v_pk_fma_f32 v[144:145], v[6:7], v[74:75], v[144:145]
	v_pk_fma_f32 v[148:149], v[6:7], v[82:83], v[148:149]
	v_pk_fma_f32 v[146:147], v[14:15], v[74:75], v[146:147]
	v_pk_fma_f32 v[174:175], v[14:15], v[82:83], v[174:175]
	ds_read_b128 v[68:71], v205 offset:6144
	ds_read_b128 v[72:75], v205 offset:6160
	ds_read_b128 v[76:79], v205 offset:6656
	ds_read_b128 v[80:83], v205 offset:6672
	ds_read_b128 v[96:99], v205 offset:6912
	ds_read_b128 v[100:103], v205 offset:6928
	ds_read_b128 v[112:115], v205 offset:6400
	ds_read_b128 v[116:119], v205 offset:6416
	s_waitcnt lgkmcnt(9)
; __device__ __forceinline__ float red8(float v) { v = red4(v); v += dppf<0x141>(v); return v; }
; __device__ __forceinline__ f32x2 lo2(const f32x4& v) { return __builtin_shufflevector(v, v, 0, 1); }
; __device__ __forceinline__ f32x2 hi2(const f32x4& v) { return __builtin_shufflevector(v, v, 2, 3); }
; __device__ __forceinline__ f32x2 splat2(float x) { return (f32x2){x, x}; }
; __device__ __forceinline__ f32x2 rw_step(f32x2 (&S)[2][4], const RwRegs& R) {
;   float sa[2], sy[2];
; #pragma unroll
;   for (int r = 0; r < 2; ++r) {
;     f32x2 a0 = S[r][0] * lo2(R.a[0]);
;     f32x2 a1 = S[r][1] * hi2(R.a[0]);
;     f32x2 y0 = S[r][0] * lo2(R.wr[0]);
;     f32x2 y1 = S[r][1] * hi2(R.wr[0]);
;     a0 += S[r][2] * lo2(R.a[1]);
;     a1 += S[r][3] * hi2(R.a[1]);
;     y0 += S[r][2] * lo2(R.wr[1]);
;     y1 += S[r][3] * hi2(R.wr[1]);
;     a0 += a1; y0 += y1;
;     sa[r] = a0.x + a0.y; sy[r] = y0.x + y0.y;
;   }
;   sa[0] = red8(sa[0]); sa[1] = red8(sa[1]); sy[0] = red8(sy[0]); sy[1] = red8(sy[1]);
;   f32x2 yv;
; #pragma unroll
;   for (int r = 0; r < 2; ++r) {
;     const float vr = r ? R.v.y : R.v.x;
;     const f32x2 sa2 = splat2(sa[r]), vv2 = splat2(vr);
;     S[r][0] = S[r][0] * lo2(R.w[0]) + (sa2 * lo2(R.b[0]) + vv2 * lo2(R.k[0]));
;     S[r][1] = S[r][1] * hi2(R.w[0]) + (sa2 * hi2(R.b[0]) + vv2 * hi2(R.k[0]));
;     S[r][2] = S[r][2] * lo2(R.w[1]) + (sa2 * lo2(R.b[1]) + vv2 * lo2(R.k[1]));
;     S[r][3] = S[r][3] * hi2(R.w[1]) + (sa2 * hi2(R.b[1]) + vv2 * hi2(R.k[1]));
;     const float y = sy[r] + sa[r] * R.sc.x + vr * R.sc.y;
;     if (r) yv.y = y; else yv.x = y;
;   }
;   return yv;
; }
; __device__ __forceinline__ void scan_rwkv(const Params& p, int l, int seq, int h, char* smem, const unsigned* wflags, unsigned wexpect) {
;     ...
;     for (int t = 0; t < nsteps; t += 2) {
;       rw_load(RB, vb, sb, min(t + 1, 15), k0, vrow0);
;       const f32x2 y0v = rw_step(S, RA);
;       *(f32x2*)((part == 0) ? (yb + t * 64 + vrow0) : ydummy) = y0v;
;       SCAN_INTERLEAVE(13, 4);
;       if (t + 1 < nsteps) {
;         rw_load(RA, vb, sb, min(t + 2, 15), k0, vrow0);
;         const f32x2 y1v = rw_step(S, RB);
;         *(f32x2*)((part == 0) ? (yb + (t + 1) * 64 + vrow0) : ydummy) = y1v;
;         SCAN_INTERLEAVE(13, 4);
;       }
	v_add_f32_e32 v144, v144, v145
	v_pk_mul_f32 v[128:129], v[92:93], v[84:85] op_sel_hi:[0,1]
	v_pk_mul_f32 v[136:137], v[92:93], v[84:85] op_sel:[1,0]
	v_add_f32_e64 v148, v148, v149
	v_add_f32_e64 v145, v146, v147
	v_add_f32_e64 v149, v174, v175
	v_pk_mul_f32 v[130:131], v[92:93], v[86:87] op_sel_hi:[0,1]
	v_pk_mul_f32 v[138:139], v[92:93], v[86:87] op_sel:[1,0]
	v_add_f32_dpp v144, v144, v144 quad_perm:[1,0,3,2] row_mask:0xf bank_mask:0xf bound_ctrl:1
	v_add_f32_dpp v148, v148, v148 quad_perm:[1,0,3,2] row_mask:0xf bank_mask:0xf bound_ctrl:1
	v_add_f32_dpp v145, v145, v145 quad_perm:[1,0,3,2] row_mask:0xf bank_mask:0xf bound_ctrl:1
	v_add_f32_dpp v149, v149, v149 quad_perm:[1,0,3,2] row_mask:0xf bank_mask:0xf bound_ctrl:1
	v_pk_mul_f32 v[132:133], v[92:93], v[88:89] op_sel_hi:[0,1]
	v_pk_mul_f32 v[140:141], v[92:93], v[88:89] op_sel:[1,0]
	v_add_f32_dpp v144, v144, v144 quad_perm:[2,3,0,1] row_mask:0xf bank_mask:0xf bound_ctrl:1
	v_add_f32_dpp v148, v148, v148 quad_perm:[2,3,0,1] row_mask:0xf bank_mask:0xf bound_ctrl:1
	v_add_f32_dpp v145, v145, v145 quad_perm:[2,3,0,1] row_mask:0xf bank_mask:0xf bound_ctrl:1
	v_add_f32_dpp v149, v149, v149 quad_perm:[2,3,0,1] row_mask:0xf bank_mask:0xf bound_ctrl:1
	v_pk_mul_f32 v[134:135], v[92:93], v[90:91] op_sel_hi:[0,1]
	v_pk_mul_f32 v[142:143], v[92:93], v[90:91] op_sel:[1,0]
	v_add_f32_dpp v144, v144, v144 row_half_mirror row_mask:0xf bank_mask:0xf bound_ctrl:1
	v_add_f32_dpp v148, v148, v148 row_half_mirror row_mask:0xf bank_mask:0xf bound_ctrl:1
	v_add_f32_dpp v145, v145, v145 row_half_mirror row_mask:0xf bank_mask:0xf bound_ctrl:1
	v_add_f32_dpp v149, v149, v149 row_half_mirror row_mask:0xf bank_mask:0xf bound_ctrl:1
	v_pk_fma_f32 v[176:177], v[144:145], v[94:95], v[148:149] op_sel_hi:[1,0,1]
	v_pk_fma_f32 v[128:129], v[104:105], v[144:145], v[128:129] op_sel_hi:[1,0,1]
	v_pk_fma_f32 v[176:177], v[92:93], v[94:95], v[176:177] op_sel:[0,1,0]
	v_pk_fma_f32 v[136:137], v[104:105], v[144:145], v[136:137] op_sel:[0,1,0]
	ds_read_b64 v[94:95], v207 offset:49216
	ds_read_b128 v[84:87], v205 offset:7168
	ds_read_b128 v[88:91], v205 offset:7184
	ds_read_b64 v[92:93], v206 offset:7424
	ds_write_b64 v208, v[176:177] offset:768
	v_pk_fma_f32 v[8:9], v[8:9], v[120:121], v[128:129]
	v_pk_fma_f32 v[16:17], v[16:17], v[120:121], v[136:137]
	v_pk_fma_f32 v[130:131], v[106:107], v[144:145], v[130:131] op_sel_hi:[1,0,1]
	v_pk_fma_f32 v[138:139], v[106:107], v[144:145], v[138:139] op_sel:[0,1,0]
	v_pk_fma_f32 v[10:11], v[10:11], v[122:123], v[130:131]
	v_pk_fma_f32 v[18:19], v[18:19], v[122:123], v[138:139]
	v_pk_fma_f32 v[132:133], v[108:109], v[144:145], v[132:133] op_sel_hi:[1,0,1]
	v_pk_fma_f32 v[140:141], v[108:109], v[144:145], v[140:141] op_sel:[0,1,0]
	v_pk_fma_f32 v[4:5], v[4:5], v[124:125], v[132:133]
	v_pk_fma_f32 v[12:13], v[12:13], v[124:125], v[140:141]
	v_pk_fma_f32 v[134:135], v[110:111], v[144:145], v[134:135] op_sel_hi:[1,0,1]
	v_pk_fma_f32 v[142:143], v[110:111], v[144:145], v[142:143] op_sel:[0,1,0]
	v_pk_fma_f32 v[6:7], v[6:7], v[126:127], v[134:135]
	v_pk_fma_f32 v[14:15], v[14:15], v[126:127], v[142:143]
	s_waitcnt lgkmcnt(5)
	s_nop 0
	v_pk_mul_f32 v[144:145], v[8:9], v[68:69]
	v_pk_mul_f32 v[148:149], v[8:9], v[76:77]
	v_pk_mul_f32 v[146:147], v[16:17], v[68:69]
	v_pk_mul_f32 v[174:175], v[16:17], v[76:77]
	v_pk_fma_f32 v[144:145], v[10:11], v[70:71], v[144:145]
	v_pk_fma_f32 v[148:149], v[10:11], v[78:79], v[148:149]
	v_pk_fma_f32 v[146:147], v[18:19], v[70:71], v[146:147]
	v_pk_fma_f32 v[174:175], v[18:19], v[78:79], v[174:175]
	v_pk_fma_f32 v[144:145], v[4:5], v[72:73], v[144:145]
	v_pk_fma_f32 v[148:149], v[4:5], v[80:81], v[148:149]
	v_pk_fma_f32 v[146:147], v[12:13], v[72:73], v[146:147]
	v_pk_fma_f32 v[174:175], v[12:13], v[80:81], v[174:175]
	v_pk_fma_f32 v[144:145], v[6:7], v[74:75], v[144:145]
	v_pk_fma_f32 v[148:149], v[6:7], v[82:83], v[148:149]
	v_pk_fma_f32 v[146:147], v[14:15], v[74:75], v[146:147]
	v_pk_fma_f32 v[174:175], v[14:15], v[82:83], v[174:175]
	ds_read_b128 v[68:71], v205 offset:7680
	ds_read_b128 v[72:75], v205 offset:7696
	ds_read_b128 v[76:79], v205 offset:8192
	ds_read_b128 v[80:83], v205 offset:8208
	ds_read_b128 v[104:107], v205 offset:8448
	ds_read_b128 v[108:111], v205 offset:8464
	ds_read_b128 v[120:123], v205 offset:7936
	ds_read_b128 v[124:127], v205 offset:7952
	s_waitcnt lgkmcnt(9)
; __device__ __forceinline__ float red8(float v) { v = red4(v); v += dppf<0x141>(v); return v; }
; __device__ __forceinline__ f32x2 lo2(const f32x4& v) { return __builtin_shufflevector(v, v, 0, 1); }
; __device__ __forceinline__ f32x2 hi2(const f32x4& v) { return __builtin_shufflevector(v, v, 2, 3); }
; __device__ __forceinline__ f32x2 splat2(float x) { return (f32x2){x, x}; }
; __device__ __forceinline__ f32x2 rw_step(f32x2 (&S)[2][4], const RwRegs& R) {
;   float sa[2], sy[2];
; #pragma unroll
;   for (int r = 0; r < 2; ++r) {
;     f32x2 a0 = S[r][0] * lo2(R.a[0]);
;     f32x2 a1 = S[r][1] * hi2(R.a[0]);
;     f32x2 y0 = S[r][0] * lo2(R.wr[0]);
;     f32x2 y1 = S[r][1] * hi2(R.wr[0]);
;     a0 += S[r][2] * lo2(R.a[1]);
;     a1 += S[r][3] * hi2(R.a[1]);
;     y0 += S[r][2] * lo2(R.wr[1]);
;     y1 += S[r][3] * hi2(R.wr[1]);
;     a0 += a1; y0 += y1;
;     sa[r] = a0.x + a0.y; sy[r] = y0.x + y0.y;
;   }
;   sa[0] = red8(sa[0]); sa[1] = red8(sa[1]); sy[0] = red8(sy[0]); sy[1] = red8(sy[1]);
;   f32x2 yv;
; #pragma unroll
;   for (int r = 0; r < 2; ++r) {
;     const float vr = r ? R.v.y : R.v.x;
;     const f32x2 sa2 = splat2(sa[r]), vv2 = splat2(vr);
;     S[r][0] = S[r][0] * lo2(R.w[0]) + (sa2 * lo2(R.b[0]) + vv2 * lo2(R.k[0]));
;     S[r][1] = S[r][1] * hi2(R.w[0]) + (sa2 * hi2(R.b[0]) + vv2 * hi2(R.k[0]));
;     S[r][2] = S[r][2] * lo2(R.w[1]) + (sa2 * lo2(R.b[1]) + vv2 * lo2(R.k[1]));
;     S[r][3] = S[r][3] * hi2(R.w[1]) + (sa2 * hi2(R.b[1]) + vv2 * hi2(R.k[1]));
;     const float y = sy[r] + sa[r] * R.sc.x + vr * R.sc.y;
;     if (r) yv.y = y; else yv.x = y;
;   }
;   return yv;
; }
; __device__ __forceinline__ void scan_rwkv(const Params& p, int l, int seq, int h, char* smem, const unsigned* wflags, unsigned wexpect) {
;     ...
;     for (int t = 0; t < nsteps; t += 2) {
;       rw_load(RB, vb, sb, min(t + 1, 15), k0, vrow0);
;       const f32x2 y0v = rw_step(S, RA);
;       *(f32x2*)((part == 0) ? (yb + t * 64 + vrow0) : ydummy) = y0v;
;       SCAN_INTERLEAVE(13, 4);
;       if (t + 1 < nsteps) {
;         rw_load(RA, vb, sb, min(t + 2, 15), k0, vrow0);
;         const f32x2 y1v = rw_step(S, RB);
;         *(f32x2*)((part == 0) ? (yb + (t + 1) * 64 + vrow0) : ydummy) = y1v;
;         SCAN_INTERLEAVE(13, 4);
;       }
	v_add_f32_e32 v144, v144, v145
	v_pk_mul_f32 v[128:129], v[92:93], v[84:85] op_sel_hi:[0,1]
	v_pk_mul_f32 v[136:137], v[92:93], v[84:85] op_sel:[1,0]
	v_add_f32_e64 v148, v148, v149
	v_add_f32_e64 v145, v146, v147
	v_add_f32_e64 v149, v174, v175
	v_pk_mul_f32 v[130:131], v[92:93], v[86:87] op_sel_hi:[0,1]
	v_pk_mul_f32 v[138:139], v[92:93], v[86:87] op_sel:[1,0]
	v_add_f32_dpp v144, v144, v144 quad_perm:[1,0,3,2] row_mask:0xf bank_mask:0xf bound_ctrl:1
	v_add_f32_dpp v148, v148, v148 quad_perm:[1,0,3,2] row_mask:0xf bank_mask:0xf bound_ctrl:1
	v_add_f32_dpp v145, v145, v145 quad_perm:[1,0,3,2] row_mask:0xf bank_mask:0xf bound_ctrl:1
	v_add_f32_dpp v149, v149, v149 quad_perm:[1,0,3,2] row_mask:0xf bank_mask:0xf bound_ctrl:1
	v_pk_mul_f32 v[132:133], v[92:93], v[88:89] op_sel_hi:[0,1]
	v_pk_mul_f32 v[140:141], v[92:93], v[88:89] op_sel:[1,0]
	v_add_f32_dpp v144, v144, v144 quad_perm:[2,3,0,1] row_mask:0xf bank_mask:0xf bound_ctrl:1
	v_add_f32_dpp v148, v148, v148 quad_perm:[2,3,0,1] row_mask:0xf bank_mask:0xf bound_ctrl:1
	v_add_f32_dpp v145, v145, v145 quad_perm:[2,3,0,1] row_mask:0xf bank_mask:0xf bound_ctrl:1
	v_add_f32_dpp v149, v149, v149 quad_perm:[2,3,0,1] row_mask:0xf bank_mask:0xf bound_ctrl:1
	v_pk_mul_f32 v[134:135], v[92:93], v[90:91] op_sel_hi:[0,1]
	v_pk_mul_f32 v[142:143], v[92:93], v[90:91] op_sel:[1,0]
	v_add_f32_dpp v144, v144, v144 row_half_mirror row_mask:0xf bank_mask:0xf bound_ctrl:1
	v_add_f32_dpp v148, v148, v148 row_half_mirror row_mask:0xf bank_mask:0xf bound_ctrl:1
	v_add_f32_dpp v145, v145, v145 row_half_mirror row_mask:0xf bank_mask:0xf bound_ctrl:1
	v_add_f32_dpp v149, v149, v149 row_half_mirror row_mask:0xf bank_mask:0xf bound_ctrl:1
	v_pk_fma_f32 v[176:177], v[144:145], v[94:95], v[148:149] op_sel_hi:[1,0,1]
	v_pk_fma_f32 v[128:129], v[96:97], v[144:145], v[128:129] op_sel_hi:[1,0,1]
	v_pk_fma_f32 v[176:177], v[92:93], v[94:95], v[176:177] op_sel:[0,1,0]
	v_pk_fma_f32 v[136:137], v[96:97], v[144:145], v[136:137] op_sel:[0,1,0]
	ds_read_b64 v[94:95], v207 offset:49232
	ds_read_b128 v[84:87], v205 offset:8704
	ds_read_b128 v[88:91], v205 offset:8720
	ds_read_b64 v[92:93], v206 offset:8960
	ds_write_b64 v208, v[176:177] offset:1024
	v_pk_fma_f32 v[8:9], v[8:9], v[112:113], v[128:129]
	v_pk_fma_f32 v[16:17], v[16:17], v[112:113], v[136:137]
	v_pk_fma_f32 v[130:131], v[98:99], v[144:145], v[130:131] op_sel_hi:[1,0,1]
	v_pk_fma_f32 v[138:139], v[98:99], v[144:145], v[138:139] op_sel:[0,1,0]
	v_pk_fma_f32 v[10:11], v[10:11], v[114:115], v[130:131]
	v_pk_fma_f32 v[18:19], v[18:19], v[114:115], v[138:139]
	v_pk_fma_f32 v[132:133], v[100:101], v[144:145], v[132:133] op_sel_hi:[1,0,1]
	v_pk_fma_f32 v[140:141], v[100:101], v[144:145], v[140:141] op_sel:[0,1,0]
	v_pk_fma_f32 v[4:5], v[4:5], v[116:117], v[132:133]
	v_pk_fma_f32 v[12:13], v[12:13], v[116:117], v[140:141]
	v_pk_fma_f32 v[134:135], v[102:103], v[144:145], v[134:135] op_sel_hi:[1,0,1]
	v_pk_fma_f32 v[142:143], v[102:103], v[144:145], v[142:143] op_sel:[0,1,0]
	v_pk_fma_f32 v[6:7], v[6:7], v[118:119], v[134:135]
	v_pk_fma_f32 v[14:15], v[14:15], v[118:119], v[142:143]
	s_waitcnt lgkmcnt(5)
	s_nop 0
	v_pk_mul_f32 v[144:145], v[8:9], v[68:69]
	v_pk_mul_f32 v[148:149], v[8:9], v[76:77]
	v_pk_mul_f32 v[146:147], v[16:17], v[68:69]
	v_pk_mul_f32 v[174:175], v[16:17], v[76:77]
	v_pk_fma_f32 v[144:145], v[10:11], v[70:71], v[144:145]
	v_pk_fma_f32 v[148:149], v[10:11], v[78:79], v[148:149]
	v_pk_fma_f32 v[146:147], v[18:19], v[70:71], v[146:147]
	v_pk_fma_f32 v[174:175], v[18:19], v[78:79], v[174:175]
	v_pk_fma_f32 v[144:145], v[4:5], v[72:73], v[144:145]
	v_pk_fma_f32 v[148:149], v[4:5], v[80:81], v[148:149]
	v_pk_fma_f32 v[146:147], v[12:13], v[72:73], v[146:147]
	v_pk_fma_f32 v[174:175], v[12:13], v[80:81], v[174:175]
	v_pk_fma_f32 v[144:145], v[6:7], v[74:75], v[144:145]
	v_pk_fma_f32 v[148:149], v[6:7], v[82:83], v[148:149]
	v_pk_fma_f32 v[146:147], v[14:15], v[74:75], v[146:147]
	v_pk_fma_f32 v[174:175], v[14:15], v[82:83], v[174:175]
	ds_read_b128 v[68:71], v205 offset:9216
	ds_read_b128 v[72:75], v205 offset:9232
	ds_read_b128 v[76:79], v205 offset:9728
	ds_read_b128 v[80:83], v205 offset:9744
	ds_read_b128 v[96:99], v205 offset:9984
	ds_read_b128 v[100:103], v205 offset:10000
	ds_read_b128 v[112:115], v205 offset:9472
	ds_read_b128 v[116:119], v205 offset:9488
	s_waitcnt lgkmcnt(9)
; __device__ __forceinline__ float red8(float v) { v = red4(v); v += dppf<0x141>(v); return v; }
; __device__ __forceinline__ f32x2 lo2(const f32x4& v) { return __builtin_shufflevector(v, v, 0, 1); }
; __device__ __forceinline__ f32x2 hi2(const f32x4& v) { return __builtin_shufflevector(v, v, 2, 3); }
; __device__ __forceinline__ f32x2 splat2(float x) { return (f32x2){x, x}; }
; __device__ __forceinline__ f32x2 rw_step(f32x2 (&S)[2][4], const RwRegs& R) {
;   float sa[2], sy[2];
; #pragma unroll
;   for (int r = 0; r < 2; ++r) {
;     f32x2 a0 = S[r][0] * lo2(R.a[0]);
;     f32x2 a1 = S[r][1] * hi2(R.a[0]);
;     f32x2 y0 = S[r][0] * lo2(R.wr[0]);
;     f32x2 y1 = S[r][1] * hi2(R.wr[0]);
;     a0 += S[r][2] * lo2(R.a[1]);
;     a1 += S[r][3] * hi2(R.a[1]);
;     y0 += S[r][2] * lo2(R.wr[1]);
;     y1 += S[r][3] * hi2(R.wr[1]);
;     a0 += a1; y0 += y1;
;     sa[r] = a0.x + a0.y; sy[r] = y0.x + y0.y;
;   }
;   sa[0] = red8(sa[0]); sa[1] = red8(sa[1]); sy[0] = red8(sy[0]); sy[1] = red8(sy[1]);
;   f32x2 yv;
; #pragma unroll
;   for (int r = 0; r < 2; ++r) {
;     const float vr = r ? R.v.y : R.v.x;
;     const f32x2 sa2 = splat2(sa[r]), vv2 = splat2(vr);
;     S[r][0] = S[r][0] * lo2(R.w[0]) + (sa2 * lo2(R.b[0]) + vv2 * lo2(R.k[0]));
;     S[r][1] = S[r][1] * hi2(R.w[0]) + (sa2 * hi2(R.b[0]) + vv2 * hi2(R.k[0]));
;     S[r][2] = S[r][2] * lo2(R.w[1]) + (sa2 * lo2(R.b[1]) + vv2 * lo2(R.k[1]));
;     S[r][3] = S[r][3] * hi2(R.w[1]) + (sa2 * hi2(R.b[1]) + vv2 * hi2(R.k[1]));
;     const float y = sy[r] + sa[r] * R.sc.x + vr * R.sc.y;
;     if (r) yv.y = y; else yv.x = y;
;   }
;   return yv;
; }
; __device__ __forceinline__ void scan_rwkv(const Params& p, int l, int seq, int h, char* smem, const unsigned* wflags, unsigned wexpect) {
;     ...
;     for (int t = 0; t < nsteps; t += 2) {
;       rw_load(RB, vb, sb, min(t + 1, 15), k0, vrow0);
;       const f32x2 y0v = rw_step(S, RA);
;       *(f32x2*)((part == 0) ? (yb + t * 64 + vrow0) : ydummy) = y0v;
;       SCAN_INTERLEAVE(13, 4);
;       if (t + 1 < nsteps) {
;         rw_load(RA, vb, sb, min(t + 2, 15), k0, vrow0);
;         const f32x2 y1v = rw_step(S, RB);
;         *(f32x2*)((part == 0) ? (yb + (t + 1) * 64 + vrow0) : ydummy) = y1v;
;         SCAN_INTERLEAVE(13, 4);
;       }
	v_add_f32_e32 v144, v144, v145
	v_pk_mul_f32 v[128:129], v[92:93], v[84:85] op_sel_hi:[0,1]
	v_pk_mul_f32 v[136:137], v[92:93], v[84:85] op_sel:[1,0]
	v_add_f32_e64 v148, v148, v149
	v_add_f32_e64 v145, v146, v147
	v_add_f32_e64 v149, v174, v175
	v_pk_mul_f32 v[130:131], v[92:93], v[86:87] op_sel_hi:[0,1]
	v_pk_mul_f32 v[138:139], v[92:93], v[86:87] op_sel:[1,0]
	v_add_f32_dpp v144, v144, v144 quad_perm:[1,0,3,2] row_mask:0xf bank_mask:0xf bound_ctrl:1
	v_add_f32_dpp v148, v148, v148 quad_perm:[1,0,3,2] row_mask:0xf bank_mask:0xf bound_ctrl:1
	v_add_f32_dpp v145, v145, v145 quad_perm:[1,0,3,2] row_mask:0xf bank_mask:0xf bound_ctrl:1
	v_add_f32_dpp v149, v149, v149 quad_perm:[1,0,3,2] row_mask:0xf bank_mask:0xf bound_ctrl:1
	v_pk_mul_f32 v[132:133], v[92:93], v[88:89] op_sel_hi:[0,1]
	v_pk_mul_f32 v[140:141], v[92:93], v[88:89] op_sel:[1,0]
	v_add_f32_dpp v144, v144, v144 quad_perm:[2,3,0,1] row_mask:0xf bank_mask:0xf bound_ctrl:1
	v_add_f32_dpp v148, v148, v148 quad_perm:[2,3,0,1] row_mask:0xf bank_mask:0xf bound_ctrl:1
	v_add_f32_dpp v145, v145, v145 quad_perm:[2,3,0,1] row_mask:0xf bank_mask:0xf bound_ctrl:1
	v_add_f32_dpp v149, v149, v149 quad_perm:[2,3,0,1] row_mask:0xf bank_mask:0xf bound_ctrl:1
	v_pk_mul_f32 v[134:135], v[92:93], v[90:91] op_sel_hi:[0,1]
	v_pk_mul_f32 v[142:143], v[92:93], v[90:91] op_sel:[1,0]
	v_add_f32_dpp v144, v144, v144 row_half_mirror row_mask:0xf bank_mask:0xf bound_ctrl:1
	v_add_f32_dpp v148, v148, v148 row_half_mirror row_mask:0xf bank_mask:0xf bound_ctrl:1
	v_add_f32_dpp v145, v145, v145 row_half_mirror row_mask:0xf bank_mask:0xf bound_ctrl:1
	v_add_f32_dpp v149, v149, v149 row_half_mirror row_mask:0xf bank_mask:0xf bound_ctrl:1
	v_pk_fma_f32 v[176:177], v[144:145], v[94:95], v[148:149] op_sel_hi:[1,0,1]
	v_pk_fma_f32 v[128:129], v[104:105], v[144:145], v[128:129] op_sel_hi:[1,0,1]
	v_pk_fma_f32 v[176:177], v[92:93], v[94:95], v[176:177] op_sel:[0,1,0]
	v_pk_fma_f32 v[136:137], v[104:105], v[144:145], v[136:137] op_sel:[0,1,0]
	ds_read_b64 v[94:95], v207 offset:49248
	ds_read_b128 v[84:87], v205 offset:10240
	ds_read_b128 v[88:91], v205 offset:10256
	ds_read_b64 v[92:93], v206 offset:10496
	ds_write_b64 v208, v[176:177] offset:1280
	v_pk_fma_f32 v[8:9], v[8:9], v[120:121], v[128:129]
	v_pk_fma_f32 v[16:17], v[16:17], v[120:121], v[136:137]
	v_pk_fma_f32 v[130:131], v[106:107], v[144:145], v[130:131] op_sel_hi:[1,0,1]
	v_pk_fma_f32 v[138:139], v[106:107], v[144:145], v[138:139] op_sel:[0,1,0]
	v_pk_fma_f32 v[10:11], v[10:11], v[122:123], v[130:131]
	v_pk_fma_f32 v[18:19], v[18:19], v[122:123], v[138:139]
	v_pk_fma_f32 v[132:133], v[108:109], v[144:145], v[132:133] op_sel_hi:[1,0,1]
	v_pk_fma_f32 v[140:141], v[108:109], v[144:145], v[140:141] op_sel:[0,1,0]
	v_pk_fma_f32 v[4:5], v[4:5], v[124:125], v[132:133]
	v_pk_fma_f32 v[12:13], v[12:13], v[124:125], v[140:141]
	v_pk_fma_f32 v[134:135], v[110:111], v[144:145], v[134:135] op_sel_hi:[1,0,1]
	v_pk_fma_f32 v[142:143], v[110:111], v[144:145], v[142:143] op_sel:[0,1,0]
	v_pk_fma_f32 v[6:7], v[6:7], v[126:127], v[134:135]
	v_pk_fma_f32 v[14:15], v[14:15], v[126:127], v[142:143]
	s_waitcnt lgkmcnt(5)
	s_nop 0
	v_pk_mul_f32 v[144:145], v[8:9], v[68:69]
	v_pk_mul_f32 v[148:149], v[8:9], v[76:77]
	v_pk_mul_f32 v[146:147], v[16:17], v[68:69]
	v_pk_mul_f32 v[174:175], v[16:17], v[76:77]
	v_pk_fma_f32 v[144:145], v[10:11], v[70:71], v[144:145]
	v_pk_fma_f32 v[148:149], v[10:11], v[78:79], v[148:149]
	v_pk_fma_f32 v[146:147], v[18:19], v[70:71], v[146:147]
	v_pk_fma_f32 v[174:175], v[18:19], v[78:79], v[174:175]
	v_pk_fma_f32 v[144:145], v[4:5], v[72:73], v[144:145]
	v_pk_fma_f32 v[148:149], v[4:5], v[80:81], v[148:149]
	v_pk_fma_f32 v[146:147], v[12:13], v[72:73], v[146:147]
	v_pk_fma_f32 v[174:175], v[12:13], v[80:81], v[174:175]
	v_pk_fma_f32 v[144:145], v[6:7], v[74:75], v[144:145]
	v_pk_fma_f32 v[148:149], v[6:7], v[82:83], v[148:149]
	v_pk_fma_f32 v[146:147], v[14:15], v[74:75], v[146:147]
	v_pk_fma_f32 v[174:175], v[14:15], v[82:83], v[174:175]
	ds_read_b128 v[68:71], v205 offset:10752
	ds_read_b128 v[72:75], v205 offset:10768
	ds_read_b128 v[76:79], v205 offset:11264
	ds_read_b128 v[80:83], v205 offset:11280
	ds_read_b128 v[104:107], v205 offset:11520
	ds_read_b128 v[108:111], v205 offset:11536
	ds_read_b128 v[120:123], v205 offset:11008
	ds_read_b128 v[124:127], v205 offset:11024
	s_waitcnt lgkmcnt(9)
; __device__ __forceinline__ float red8(float v) { v = red4(v); v += dppf<0x141>(v); return v; }
; __device__ __forceinline__ f32x2 lo2(const f32x4& v) { return __builtin_shufflevector(v, v, 0, 1); }
; __device__ __forceinline__ f32x2 hi2(const f32x4& v) { return __builtin_shufflevector(v, v, 2, 3); }
; __device__ __forceinline__ f32x2 splat2(float x) { return (f32x2){x, x}; }
; __device__ __forceinline__ f32x2 rw_step(f32x2 (&S)[2][4], const RwRegs& R) {
;   float sa[2], sy[2];
; #pragma unroll
;   for (int r = 0; r < 2; ++r) {
;     f32x2 a0 = S[r][0] * lo2(R.a[0]);
;     f32x2 a1 = S[r][1] * hi2(R.a[0]);
;     f32x2 y0 = S[r][0] * lo2(R.wr[0]);
;     f32x2 y1 = S[r][1] * hi2(R.wr[0]);
;     a0 += S[r][2] * lo2(R.a[1]);
;     a1 += S[r][3] * hi2(R.a[1]);
;     y0 += S[r][2] * lo2(R.wr[1]);
;     y1 += S[r][3] * hi2(R.wr[1]);
;     a0 += a1; y0 += y1;
;     sa[r] = a0.x + a0.y; sy[r] = y0.x + y0.y;
;   }
;   sa[0] = red8(sa[0]); sa[1] = red8(sa[1]); sy[0] = red8(sy[0]); sy[1] = red8(sy[1]);
;   f32x2 yv;
; #pragma unroll
;   for (int r = 0; r < 2; ++r) {
;     const float vr = r ? R.v.y : R.v.x;
;     const f32x2 sa2 = splat2(sa[r]), vv2 = splat2(vr);
;     S[r][0] = S[r][0] * lo2(R.w[0]) + (sa2 * lo2(R.b[0]) + vv2 * lo2(R.k[0]));
;     S[r][1] = S[r][1] * hi2(R.w[0]) + (sa2 * hi2(R.b[0]) + vv2 * hi2(R.k[0]));
;     S[r][2] = S[r][2] * lo2(R.w[1]) + (sa2 * lo2(R.b[1]) + vv2 * lo2(R.k[1]));
;     S[r][3] = S[r][3] * hi2(R.w[1]) + (sa2 * hi2(R.b[1]) + vv2 * hi2(R.k[1]));
;     const float y = sy[r] + sa[r] * R.sc.x + vr * R.sc.y;
;     if (r) yv.y = y; else yv.x = y;
;   }
;   return yv;
; }
; __device__ __forceinline__ void scan_rwkv(const Params& p, int l, int seq, int h, char* smem, const unsigned* wflags, unsigned wexpect) {
;     ...
;     for (int t = 0; t < nsteps; t += 2) {
;       rw_load(RB, vb, sb, min(t + 1, 15), k0, vrow0);
;       const f32x2 y0v = rw_step(S, RA);
;       *(f32x2*)((part == 0) ? (yb + t * 64 + vrow0) : ydummy) = y0v;
;       SCAN_INTERLEAVE(13, 4);
;       if (t + 1 < nsteps) {
;         rw_load(RA, vb, sb, min(t + 2, 15), k0, vrow0);
;         const f32x2 y1v = rw_step(S, RB);
;         *(f32x2*)((part == 0) ? (yb + (t + 1) * 64 + vrow0) : ydummy) = y1v;
;         SCAN_INTERLEAVE(13, 4);
;       }
	v_add_f32_e32 v144, v144, v145
	v_pk_mul_f32 v[128:129], v[92:93], v[84:85] op_sel_hi:[0,1]
	v_pk_mul_f32 v[136:137], v[92:93], v[84:85] op_sel:[1,0]
	v_add_f32_e64 v148, v148, v149
	v_add_f32_e64 v145, v146, v147
	v_add_f32_e64 v149, v174, v175
	v_pk_mul_f32 v[130:131], v[92:93], v[86:87] op_sel_hi:[0,1]
	v_pk_mul_f32 v[138:139], v[92:93], v[86:87] op_sel:[1,0]
	v_add_f32_dpp v144, v144, v144 quad_perm:[1,0,3,2] row_mask:0xf bank_mask:0xf bound_ctrl:1
	v_add_f32_dpp v148, v148, v148 quad_perm:[1,0,3,2] row_mask:0xf bank_mask:0xf bound_ctrl:1
	v_add_f32_dpp v145, v145, v145 quad_perm:[1,0,3,2] row_mask:0xf bank_mask:0xf bound_ctrl:1
	v_add_f32_dpp v149, v149, v149 quad_perm:[1,0,3,2] row_mask:0xf bank_mask:0xf bound_ctrl:1
	v_pk_mul_f32 v[132:133], v[92:93], v[88:89] op_sel_hi:[0,1]
	v_pk_mul_f32 v[140:141], v[92:93], v[88:89] op_sel:[1,0]
	v_add_f32_dpp v144, v144, v144 quad_perm:[2,3,0,1] row_mask:0xf bank_mask:0xf bound_ctrl:1
	v_add_f32_dpp v148, v148, v148 quad_perm:[2,3,0,1] row_mask:0xf bank_mask:0xf bound_ctrl:1
	v_add_f32_dpp v145, v145, v145 quad_perm:[2,3,0,1] row_mask:0xf bank_mask:0xf bound_ctrl:1
	v_add_f32_dpp v149, v149, v149 quad_perm:[2,3,0,1] row_mask:0xf bank_mask:0xf bound_ctrl:1
	v_pk_mul_f32 v[134:135], v[92:93], v[90:91] op_sel_hi:[0,1]
	v_pk_mul_f32 v[142:143], v[92:93], v[90:91] op_sel:[1,0]
	v_add_f32_dpp v144, v144, v144 row_half_mirror row_mask:0xf bank_mask:0xf bound_ctrl:1
	v_add_f32_dpp v148, v148, v148 row_half_mirror row_mask:0xf bank_mask:0xf bound_ctrl:1
	v_add_f32_dpp v145, v145, v145 row_half_mirror row_mask:0xf bank_mask:0xf bound_ctrl:1
	v_add_f32_dpp v149, v149, v149 row_half_mirror row_mask:0xf bank_mask:0xf bound_ctrl:1
	v_pk_fma_f32 v[176:177], v[144:145], v[94:95], v[148:149] op_sel_hi:[1,0,1]
	v_pk_fma_f32 v[128:129], v[96:97], v[144:145], v[128:129] op_sel_hi:[1,0,1]
	v_pk_fma_f32 v[176:177], v[92:93], v[94:95], v[176:177] op_sel:[0,1,0]
	v_pk_fma_f32 v[136:137], v[96:97], v[144:145], v[136:137] op_sel:[0,1,0]
	ds_read_b64 v[94:95], v207 offset:49264
	ds_read_b128 v[84:87], v205 offset:11776
	ds_read_b128 v[88:91], v205 offset:11792
	ds_read_b64 v[92:93], v206 offset:12032
	ds_write_b64 v208, v[176:177] offset:1536
	v_pk_fma_f32 v[8:9], v[8:9], v[112:113], v[128:129]
	v_pk_fma_f32 v[16:17], v[16:17], v[112:113], v[136:137]
	v_pk_fma_f32 v[130:131], v[98:99], v[144:145], v[130:131] op_sel_hi:[1,0,1]
	v_pk_fma_f32 v[138:139], v[98:99], v[144:145], v[138:139] op_sel:[0,1,0]
	v_pk_fma_f32 v[10:11], v[10:11], v[114:115], v[130:131]
	v_pk_fma_f32 v[18:19], v[18:19], v[114:115], v[138:139]
	v_pk_fma_f32 v[132:133], v[100:101], v[144:145], v[132:133] op_sel_hi:[1,0,1]
	v_pk_fma_f32 v[140:141], v[100:101], v[144:145], v[140:141] op_sel:[0,1,0]
	v_pk_fma_f32 v[4:5], v[4:5], v[116:117], v[132:133]
	v_pk_fma_f32 v[12:13], v[12:13], v[116:117], v[140:141]
	v_pk_fma_f32 v[134:135], v[102:103], v[144:145], v[134:135] op_sel_hi:[1,0,1]
	v_pk_fma_f32 v[142:143], v[102:103], v[144:145], v[142:143] op_sel:[0,1,0]
	v_pk_fma_f32 v[6:7], v[6:7], v[118:119], v[134:135]
	v_pk_fma_f32 v[14:15], v[14:15], v[118:119], v[142:143]
	s_waitcnt lgkmcnt(5)
	s_nop 0
	v_pk_mul_f32 v[144:145], v[8:9], v[68:69]
	v_pk_mul_f32 v[148:149], v[8:9], v[76:77]
	v_pk_mul_f32 v[146:147], v[16:17], v[68:69]
	v_pk_mul_f32 v[174:175], v[16:17], v[76:77]
	v_pk_fma_f32 v[144:145], v[10:11], v[70:71], v[144:145]
	v_pk_fma_f32 v[148:149], v[10:11], v[78:79], v[148:149]
	v_pk_fma_f32 v[146:147], v[18:19], v[70:71], v[146:147]
	v_pk_fma_f32 v[174:175], v[18:19], v[78:79], v[174:175]
	v_pk_fma_f32 v[144:145], v[4:5], v[72:73], v[144:145]
	v_pk_fma_f32 v[148:149], v[4:5], v[80:81], v[148:149]
	v_pk_fma_f32 v[146:147], v[12:13], v[72:73], v[146:147]
	v_pk_fma_f32 v[174:175], v[12:13], v[80:81], v[174:175]
	v_pk_fma_f32 v[144:145], v[6:7], v[74:75], v[144:145]
	v_pk_fma_f32 v[148:149], v[6:7], v[82:83], v[148:149]
	v_pk_fma_f32 v[146:147], v[14:15], v[74:75], v[146:147]
	v_pk_fma_f32 v[174:175], v[14:15], v[82:83], v[174:175]
	ds_read_b128 v[68:71], v205 offset:12288
	ds_read_b128 v[72:75], v205 offset:12304
	ds_read_b128 v[76:79], v205 offset:12800
	ds_read_b128 v[80:83], v205 offset:12816
	ds_read_b128 v[96:99], v205 offset:13056
	ds_read_b128 v[100:103], v205 offset:13072
	ds_read_b128 v[112:115], v205 offset:12544
	ds_read_b128 v[116:119], v205 offset:12560
	s_waitcnt lgkmcnt(9)
; __device__ __forceinline__ float red8(float v) { v = red4(v); v += dppf<0x141>(v); return v; }
; __device__ __forceinline__ f32x2 lo2(const f32x4& v) { return __builtin_shufflevector(v, v, 0, 1); }
; __device__ __forceinline__ f32x2 hi2(const f32x4& v) { return __builtin_shufflevector(v, v, 2, 3); }
; __device__ __forceinline__ f32x2 splat2(float x) { return (f32x2){x, x}; }
; __device__ __forceinline__ f32x2 rw_step(f32x2 (&S)[2][4], const RwRegs& R) {
;   float sa[2], sy[2];
; #pragma unroll
;   for (int r = 0; r < 2; ++r) {
;     f32x2 a0 = S[r][0] * lo2(R.a[0]);
;     f32x2 a1 = S[r][1] * hi2(R.a[0]);
;     f32x2 y0 = S[r][0] * lo2(R.wr[0]);
;     f32x2 y1 = S[r][1] * hi2(R.wr[0]);
;     a0 += S[r][2] * lo2(R.a[1]);
;     a1 += S[r][3] * hi2(R.a[1]);
;     y0 += S[r][2] * lo2(R.wr[1]);
;     y1 += S[r][3] * hi2(R.wr[1]);
;     a0 += a1; y0 += y1;
;     sa[r] = a0.x + a0.y; sy[r] = y0.x + y0.y;
;   }
;   sa[0] = red8(sa[0]); sa[1] = red8(sa[1]); sy[0] = red8(sy[0]); sy[1] = red8(sy[1]);
;   f32x2 yv;
; #pragma unroll
;   for (int r = 0; r < 2; ++r) {
;     const float vr = r ? R.v.y : R.v.x;
;     const f32x2 sa2 = splat2(sa[r]), vv2 = splat2(vr);
;     S[r][0] = S[r][0] * lo2(R.w[0]) + (sa2 * lo2(R.b[0]) + vv2 * lo2(R.k[0]));
;     S[r][1] = S[r][1] * hi2(R.w[0]) + (sa2 * hi2(R.b[0]) + vv2 * hi2(R.k[0]));
;     S[r][2] = S[r][2] * lo2(R.w[1]) + (sa2 * lo2(R.b[1]) + vv2 * lo2(R.k[1]));
;     S[r][3] = S[r][3] * hi2(R.w[1]) + (sa2 * hi2(R.b[1]) + vv2 * hi2(R.k[1]));
;     const float y = sy[r] + sa[r] * R.sc.x + vr * R.sc.y;
;     if (r) yv.y = y; else yv.x = y;
;   }
;   return yv;
; }
; __device__ __forceinline__ void scan_rwkv(const Params& p, int l, int seq, int h, char* smem, const unsigned* wflags, unsigned wexpect) {
;     ...
;     rw_load(RA, vb, sb, 0, k0, vrow0);
;     for (int t = 0; t < nsteps; t += 2) {
;       rw_load(RB, vb, sb, min(t + 1, 15), k0, vrow0);
;       const f32x2 y0v = rw_step(S, RA);
;       *(f32x2*)((part == 0) ? (yb + t * 64 + vrow0) : ydummy) = y0v;
;       SCAN_INTERLEAVE(13, 4);
;       if (t + 1 < nsteps) {
;         rw_load(RA, vb, sb, min(t + 2, 15), k0, vrow0);
;         const f32x2 y1v = rw_step(S, RB);
;         *(f32x2*)((part == 0) ? (yb + (t + 1) * 64 + vrow0) : ydummy) = y1v;
;         SCAN_INTERLEAVE(13, 4);
;       }
	v_add_f32_e32 v144, v144, v145
	v_pk_mul_f32 v[128:129], v[92:93], v[84:85] op_sel_hi:[0,1]
	v_pk_mul_f32 v[136:137], v[92:93], v[84:85] op_sel:[1,0]
	v_add_f32_e64 v148, v148, v149
	v_add_f32_e64 v145, v146, v147
	v_add_f32_e64 v149, v174, v175
	v_pk_mul_f32 v[130:131], v[92:93], v[86:87] op_sel_hi:[0,1]
	v_pk_mul_f32 v[138:139], v[92:93], v[86:87] op_sel:[1,0]
	v_add_f32_dpp v144, v144, v144 quad_perm:[1,0,3,2] row_mask:0xf bank_mask:0xf bound_ctrl:1
	v_add_f32_dpp v148, v148, v148 quad_perm:[1,0,3,2] row_mask:0xf bank_mask:0xf bound_ctrl:1
	v_add_f32_dpp v145, v145, v145 quad_perm:[1,0,3,2] row_mask:0xf bank_mask:0xf bound_ctrl:1
	v_add_f32_dpp v149, v149, v149 quad_perm:[1,0,3,2] row_mask:0xf bank_mask:0xf bound_ctrl:1
	v_pk_mul_f32 v[132:133], v[92:93], v[88:89] op_sel_hi:[0,1]
	v_pk_mul_f32 v[140:141], v[92:93], v[88:89] op_sel:[1,0]
	v_add_f32_dpp v144, v144, v144 quad_perm:[2,3,0,1] row_mask:0xf bank_mask:0xf bound_ctrl:1
	v_add_f32_dpp v148, v148, v148 quad_perm:[2,3,0,1] row_mask:0xf bank_mask:0xf bound_ctrl:1
	v_add_f32_dpp v145, v145, v145 quad_perm:[2,3,0,1] row_mask:0xf bank_mask:0xf bound_ctrl:1
	v_add_f32_dpp v149, v149, v149 quad_perm:[2,3,0,1] row_mask:0xf bank_mask:0xf bound_ctrl:1
	v_pk_mul_f32 v[134:135], v[92:93], v[90:91] op_sel_hi:[0,1]
	v_pk_mul_f32 v[142:143], v[92:93], v[90:91] op_sel:[1,0]
	v_add_f32_dpp v144, v144, v144 row_half_mirror row_mask:0xf bank_mask:0xf bound_ctrl:1
	v_add_f32_dpp v148, v148, v148 row_half_mirror row_mask:0xf bank_mask:0xf bound_ctrl:1
	v_add_f32_dpp v145, v145, v145 row_half_mirror row_mask:0xf bank_mask:0xf bound_ctrl:1
	v_add_f32_dpp v149, v149, v149 row_half_mirror row_mask:0xf bank_mask:0xf bound_ctrl:1
	v_pk_fma_f32 v[176:177], v[144:145], v[94:95], v[148:149] op_sel_hi:[1,0,1]
	v_pk_fma_f32 v[128:129], v[104:105], v[144:145], v[128:129] op_sel_hi:[1,0,1]
	v_pk_fma_f32 v[176:177], v[92:93], v[94:95], v[176:177] op_sel:[0,1,0]
	v_pk_fma_f32 v[136:137], v[104:105], v[144:145], v[136:137] op_sel:[0,1,0]
	ds_read_b64 v[94:95], v207 offset:49280
	ds_read_b128 v[84:87], v205 offset:13312
	ds_read_b128 v[88:91], v205 offset:13328
	ds_read_b64 v[92:93], v206 offset:13568
	ds_write_b64 v208, v[176:177] offset:1792
	v_pk_fma_f32 v[8:9], v[8:9], v[120:121], v[128:129]
	v_pk_fma_f32 v[16:17], v[16:17], v[120:121], v[136:137]
	v_pk_fma_f32 v[130:131], v[106:107], v[144:145], v[130:131] op_sel_hi:[1,0,1]
	v_pk_fma_f32 v[138:139], v[106:107], v[144:145], v[138:139] op_sel:[0,1,0]
	v_pk_fma_f32 v[10:11], v[10:11], v[122:123], v[130:131]
	v_pk_fma_f32 v[18:19], v[18:19], v[122:123], v[138:139]
	v_pk_fma_f32 v[132:133], v[108:109], v[144:145], v[132:133] op_sel_hi:[1,0,1]
	v_pk_fma_f32 v[140:141], v[108:109], v[144:145], v[140:141] op_sel:[0,1,0]
	v_pk_fma_f32 v[4:5], v[4:5], v[124:125], v[132:133]
	v_pk_fma_f32 v[12:13], v[12:13], v[124:125], v[140:141]
	v_pk_fma_f32 v[134:135], v[110:111], v[144:145], v[134:135] op_sel_hi:[1,0,1]
	v_pk_fma_f32 v[142:143], v[110:111], v[144:145], v[142:143] op_sel:[0,1,0]
	v_pk_fma_f32 v[6:7], v[6:7], v[126:127], v[134:135]
	v_pk_fma_f32 v[14:15], v[14:15], v[126:127], v[142:143]
	s_waitcnt lgkmcnt(5)
	s_nop 0
	v_pk_mul_f32 v[144:145], v[8:9], v[68:69]
	v_pk_mul_f32 v[148:149], v[8:9], v[76:77]
	v_pk_mul_f32 v[146:147], v[16:17], v[68:69]
	v_pk_mul_f32 v[174:175], v[16:17], v[76:77]
	v_pk_fma_f32 v[144:145], v[10:11], v[70:71], v[144:145]
	v_pk_fma_f32 v[148:149], v[10:11], v[78:79], v[148:149]
	v_pk_fma_f32 v[146:147], v[18:19], v[70:71], v[146:147]
	v_pk_fma_f32 v[174:175], v[18:19], v[78:79], v[174:175]
	v_pk_fma_f32 v[144:145], v[4:5], v[72:73], v[144:145]
	v_pk_fma_f32 v[148:149], v[4:5], v[80:81], v[148:149]
	v_pk_fma_f32 v[146:147], v[12:13], v[72:73], v[146:147]
	v_pk_fma_f32 v[174:175], v[12:13], v[80:81], v[174:175]
	v_pk_fma_f32 v[144:145], v[6:7], v[74:75], v[144:145]
	v_pk_fma_f32 v[148:149], v[6:7], v[82:83], v[148:149]
	v_pk_fma_f32 v[146:147], v[14:15], v[74:75], v[146:147]
	v_pk_fma_f32 v[174:175], v[14:15], v[82:83], v[174:175]
	ds_read_b128 v[68:71], v205 offset:13824
	ds_read_b128 v[72:75], v205 offset:13840
	ds_read_b128 v[76:79], v205 offset:14336
	ds_read_b128 v[80:83], v205 offset:14352
	ds_read_b128 v[104:107], v205 offset:14592
	ds_read_b128 v[108:111], v205 offset:14608
	ds_read_b128 v[120:123], v205 offset:14080
	ds_read_b128 v[124:127], v205 offset:14096
	s_waitcnt lgkmcnt(9)
; __device__ __forceinline__ float red8(float v) { v = red4(v); v += dppf<0x141>(v); return v; }
; __device__ __forceinline__ f32x2 lo2(const f32x4& v) { return __builtin_shufflevector(v, v, 0, 1); }
; __device__ __forceinline__ f32x2 hi2(const f32x4& v) { return __builtin_shufflevector(v, v, 2, 3); }
; __device__ __forceinline__ f32x2 splat2(float x) { return (f32x2){x, x}; }
; __device__ __forceinline__ f32x2 rw_step(f32x2 (&S)[2][4], const RwRegs& R) {
;   float sa[2], sy[2];
; #pragma unroll
;   for (int r = 0; r < 2; ++r) {
;     f32x2 a0 = S[r][0] * lo2(R.a[0]);
;     f32x2 a1 = S[r][1] * hi2(R.a[0]);
;     f32x2 y0 = S[r][0] * lo2(R.wr[0]);
;     f32x2 y1 = S[r][1] * hi2(R.wr[0]);
;     a0 += S[r][2] * lo2(R.a[1]);
;     a1 += S[r][3] * hi2(R.a[1]);
;     y0 += S[r][2] * lo2(R.wr[1]);
;     y1 += S[r][3] * hi2(R.wr[1]);
;     a0 += a1; y0 += y1;
;     sa[r] = a0.x + a0.y; sy[r] = y0.x + y0.y;
;   }
;   sa[0] = red8(sa[0]); sa[1] = red8(sa[1]); sy[0] = red8(sy[0]); sy[1] = red8(sy[1]);
;   f32x2 yv;
; #pragma unroll
;   for (int r = 0; r < 2; ++r) {
;     const float vr = r ? R.v.y : R.v.x;
;     const f32x2 sa2 = splat2(sa[r]), vv2 = splat2(vr);
;     S[r][0] = S[r][0] * lo2(R.w[0]) + (sa2 * lo2(R.b[0]) + vv2 * lo2(R.k[0]));
;     S[r][1] = S[r][1] * hi2(R.w[0]) + (sa2 * hi2(R.b[0]) + vv2 * hi2(R.k[0]));
;     S[r][2] = S[r][2] * lo2(R.w[1]) + (sa2 * lo2(R.b[1]) + vv2 * lo2(R.k[1]));
;     S[r][3] = S[r][3] * hi2(R.w[1]) + (sa2 * hi2(R.b[1]) + vv2 * hi2(R.k[1]));
;     const float y = sy[r] + sa[r] * R.sc.x + vr * R.sc.y;
;     if (r) yv.y = y; else yv.x = y;
;   }
;   return yv;
; }
; __device__ __forceinline__ void scan_rwkv(const Params& p, int l, int seq, int h, char* smem, const unsigned* wflags, unsigned wexpect) {
;     ...
;     rw_load(RA, vb, sb, 0, k0, vrow0);
;     for (int t = 0; t < nsteps; t += 2) {
;       rw_load(RB, vb, sb, min(t + 1, 15), k0, vrow0);
;       const f32x2 y0v = rw_step(S, RA);
;       *(f32x2*)((part == 0) ? (yb + t * 64 + vrow0) : ydummy) = y0v;
;       SCAN_INTERLEAVE(13, 4);
;       if (t + 1 < nsteps) {
;         rw_load(RA, vb, sb, min(t + 2, 15), k0, vrow0);
;         const f32x2 y1v = rw_step(S, RB);
;         *(f32x2*)((part == 0) ? (yb + (t + 1) * 64 + vrow0) : ydummy) = y1v;
;         SCAN_INTERLEAVE(13, 4);
;       }
	v_add_f32_e32 v144, v144, v145
	v_pk_mul_f32 v[128:129], v[92:93], v[84:85] op_sel_hi:[0,1]
	v_pk_mul_f32 v[136:137], v[92:93], v[84:85] op_sel:[1,0]
	v_add_f32_e64 v148, v148, v149
	v_add_f32_e64 v145, v146, v147
	v_add_f32_e64 v149, v174, v175
	v_pk_mul_f32 v[130:131], v[92:93], v[86:87] op_sel_hi:[0,1]
	v_pk_mul_f32 v[138:139], v[92:93], v[86:87] op_sel:[1,0]
	v_add_f32_dpp v144, v144, v144 quad_perm:[1,0,3,2] row_mask:0xf bank_mask:0xf bound_ctrl:1
	v_add_f32_dpp v148, v148, v148 quad_perm:[1,0,3,2] row_mask:0xf bank_mask:0xf bound_ctrl:1
	v_add_f32_dpp v145, v145, v145 quad_perm:[1,0,3,2] row_mask:0xf bank_mask:0xf bound_ctrl:1
	v_add_f32_dpp v149, v149, v149 quad_perm:[1,0,3,2] row_mask:0xf bank_mask:0xf bound_ctrl:1
	v_pk_mul_f32 v[132:133], v[92:93], v[88:89] op_sel_hi:[0,1]
	v_pk_mul_f32 v[140:141], v[92:93], v[88:89] op_sel:[1,0]
	v_add_f32_dpp v144, v144, v144 quad_perm:[2,3,0,1] row_mask:0xf bank_mask:0xf bound_ctrl:1
	v_add_f32_dpp v148, v148, v148 quad_perm:[2,3,0,1] row_mask:0xf bank_mask:0xf bound_ctrl:1
	v_add_f32_dpp v145, v145, v145 quad_perm:[2,3,0,1] row_mask:0xf bank_mask:0xf bound_ctrl:1
	v_add_f32_dpp v149, v149, v149 quad_perm:[2,3,0,1] row_mask:0xf bank_mask:0xf bound_ctrl:1
	v_pk_mul_f32 v[134:135], v[92:93], v[90:91] op_sel_hi:[0,1]
	v_pk_mul_f32 v[142:143], v[92:93], v[90:91] op_sel:[1,0]
	v_add_f32_dpp v144, v144, v144 row_half_mirror row_mask:0xf bank_mask:0xf bound_ctrl:1
	v_add_f32_dpp v148, v148, v148 row_half_mirror row_mask:0xf bank_mask:0xf bound_ctrl:1
	v_add_f32_dpp v145, v145, v145 row_half_mirror row_mask:0xf bank_mask:0xf bound_ctrl:1
	v_add_f32_dpp v149, v149, v149 row_half_mirror row_mask:0xf bank_mask:0xf bound_ctrl:1
	v_pk_fma_f32 v[176:177], v[144:145], v[94:95], v[148:149] op_sel_hi:[1,0,1]
	v_pk_fma_f32 v[128:129], v[96:97], v[144:145], v[128:129] op_sel_hi:[1,0,1]
	v_pk_fma_f32 v[176:177], v[92:93], v[94:95], v[176:177] op_sel:[0,1,0]
	v_pk_fma_f32 v[136:137], v[96:97], v[144:145], v[136:137] op_sel:[0,1,0]
	ds_read_b64 v[94:95], v207 offset:49296
	ds_read_b128 v[84:87], v205 offset:14848
	ds_read_b128 v[88:91], v205 offset:14864
	ds_read_b64 v[92:93], v206 offset:15104
	ds_write_b64 v208, v[176:177] offset:2048
	v_pk_fma_f32 v[8:9], v[8:9], v[112:113], v[128:129]
	v_pk_fma_f32 v[16:17], v[16:17], v[112:113], v[136:137]
	v_pk_fma_f32 v[130:131], v[98:99], v[144:145], v[130:131] op_sel_hi:[1,0,1]
	v_pk_fma_f32 v[138:139], v[98:99], v[144:145], v[138:139] op_sel:[0,1,0]
	v_pk_fma_f32 v[10:11], v[10:11], v[114:115], v[130:131]
	v_pk_fma_f32 v[18:19], v[18:19], v[114:115], v[138:139]
	v_pk_fma_f32 v[132:133], v[100:101], v[144:145], v[132:133] op_sel_hi:[1,0,1]
	v_pk_fma_f32 v[140:141], v[100:101], v[144:145], v[140:141] op_sel:[0,1,0]
	v_pk_fma_f32 v[4:5], v[4:5], v[116:117], v[132:133]
	v_pk_fma_f32 v[12:13], v[12:13], v[116:117], v[140:141]
	v_pk_fma_f32 v[134:135], v[102:103], v[144:145], v[134:135] op_sel_hi:[1,0,1]
	v_pk_fma_f32 v[142:143], v[102:103], v[144:145], v[142:143] op_sel:[0,1,0]
	v_pk_fma_f32 v[6:7], v[6:7], v[118:119], v[134:135]
	v_pk_fma_f32 v[14:15], v[14:15], v[118:119], v[142:143]
	s_waitcnt lgkmcnt(5)
	s_nop 0
	v_pk_mul_f32 v[144:145], v[8:9], v[68:69]
	v_pk_mul_f32 v[148:149], v[8:9], v[76:77]
	v_pk_mul_f32 v[146:147], v[16:17], v[68:69]
	v_pk_mul_f32 v[174:175], v[16:17], v[76:77]
	v_pk_fma_f32 v[144:145], v[10:11], v[70:71], v[144:145]
	v_pk_fma_f32 v[148:149], v[10:11], v[78:79], v[148:149]
	v_pk_fma_f32 v[146:147], v[18:19], v[70:71], v[146:147]
	v_pk_fma_f32 v[174:175], v[18:19], v[78:79], v[174:175]
	v_pk_fma_f32 v[144:145], v[4:5], v[72:73], v[144:145]
	v_pk_fma_f32 v[148:149], v[4:5], v[80:81], v[148:149]
	v_pk_fma_f32 v[146:147], v[12:13], v[72:73], v[146:147]
	v_pk_fma_f32 v[174:175], v[12:13], v[80:81], v[174:175]
	v_pk_fma_f32 v[144:145], v[6:7], v[74:75], v[144:145]
	v_pk_fma_f32 v[148:149], v[6:7], v[82:83], v[148:149]
	v_pk_fma_f32 v[146:147], v[14:15], v[74:75], v[146:147]
	v_pk_fma_f32 v[174:175], v[14:15], v[82:83], v[174:175]
	ds_read_b128 v[68:71], v205 offset:15360
	ds_read_b128 v[72:75], v205 offset:15376
	ds_read_b128 v[76:79], v205 offset:15872
	ds_read_b128 v[80:83], v205 offset:15888
	ds_read_b128 v[96:99], v205 offset:16128
	ds_read_b128 v[100:103], v205 offset:16144
	ds_read_b128 v[112:115], v205 offset:15616
	ds_read_b128 v[116:119], v205 offset:15632
	s_waitcnt lgkmcnt(9)
; __device__ __forceinline__ float red8(float v) { v = red4(v); v += dppf<0x141>(v); return v; }
; __device__ __forceinline__ f32x2 lo2(const f32x4& v) { return __builtin_shufflevector(v, v, 0, 1); }
; __device__ __forceinline__ f32x2 hi2(const f32x4& v) { return __builtin_shufflevector(v, v, 2, 3); }
; __device__ __forceinline__ f32x2 splat2(float x) { return (f32x2){x, x}; }
; __device__ __forceinline__ f32x2 rw_step(f32x2 (&S)[2][4], const RwRegs& R) {
;   float sa[2], sy[2];
; #pragma unroll
;   for (int r = 0; r < 2; ++r) {
;     f32x2 a0 = S[r][0] * lo2(R.a[0]);
;     f32x2 a1 = S[r][1] * hi2(R.a[0]);
;     f32x2 y0 = S[r][0] * lo2(R.wr[0]);
;     f32x2 y1 = S[r][1] * hi2(R.wr[0]);
;     a0 += S[r][2] * lo2(R.a[1]);
;     a1 += S[r][3] * hi2(R.a[1]);
;     y0 += S[r][2] * lo2(R.wr[1]);
;     y1 += S[r][3] * hi2(R.wr[1]);
;     a0 += a1; y0 += y1;
;     sa[r] = a0.x + a0.y; sy[r] = y0.x + y0.y;
;   }
;   sa[0] = red8(sa[0]); sa[1] = red8(sa[1]); sy[0] = red8(sy[0]); sy[1] = red8(sy[1]);
;   f32x2 yv;
; #pragma unroll
;   for (int r = 0; r < 2; ++r) {
;     const float vr = r ? R.v.y : R.v.x;
;     const f32x2 sa2 = splat2(sa[r]), vv2 = splat2(vr);
;     S[r][0] = S[r][0] * lo2(R.w[0]) + (sa2 * lo2(R.b[0]) + vv2 * lo2(R.k[0]));
;     S[r][1] = S[r][1] * hi2(R.w[0]) + (sa2 * hi2(R.b[0]) + vv2 * hi2(R.k[0]));
;     S[r][2] = S[r][2] * lo2(R.w[1]) + (sa2 * lo2(R.b[1]) + vv2 * lo2(R.k[1]));
;     S[r][3] = S[r][3] * hi2(R.w[1]) + (sa2 * hi2(R.b[1]) + vv2 * hi2(R.k[1]));
;     const float y = sy[r] + sa[r] * R.sc.x + vr * R.sc.y;
;     if (r) yv.y = y; else yv.x = y;
;   }
;   return yv;
; }
; __device__ __forceinline__ void scan_rwkv(const Params& p, int l, int seq, int h, char* smem, const unsigned* wflags, unsigned wexpect) {
;     ...
;     rw_load(RA, vb, sb, 0, k0, vrow0);
;     for (int t = 0; t < nsteps; t += 2) {
;       rw_load(RB, vb, sb, min(t + 1, 15), k0, vrow0);
;       const f32x2 y0v = rw_step(S, RA);
;       *(f32x2*)((part == 0) ? (yb + t * 64 + vrow0) : ydummy) = y0v;
;       SCAN_INTERLEAVE(13, 4);
;       if (t + 1 < nsteps) {
;         rw_load(RA, vb, sb, min(t + 2, 15), k0, vrow0);
;         const f32x2 y1v = rw_step(S, RB);
;         *(f32x2*)((part == 0) ? (yb + (t + 1) * 64 + vrow0) : ydummy) = y1v;
;         SCAN_INTERLEAVE(13, 4);
;       }
	v_add_f32_e32 v144, v144, v145
	v_pk_mul_f32 v[128:129], v[92:93], v[84:85] op_sel_hi:[0,1]
	v_pk_mul_f32 v[136:137], v[92:93], v[84:85] op_sel:[1,0]
	v_add_f32_e64 v148, v148, v149
	v_add_f32_e64 v145, v146, v147
	v_add_f32_e64 v149, v174, v175
	v_pk_mul_f32 v[130:131], v[92:93], v[86:87] op_sel_hi:[0,1]
	v_pk_mul_f32 v[138:139], v[92:93], v[86:87] op_sel:[1,0]
	v_add_f32_dpp v144, v144, v144 quad_perm:[1,0,3,2] row_mask:0xf bank_mask:0xf bound_ctrl:1
	v_add_f32_dpp v148, v148, v148 quad_perm:[1,0,3,2] row_mask:0xf bank_mask:0xf bound_ctrl:1
	v_add_f32_dpp v145, v145, v145 quad_perm:[1,0,3,2] row_mask:0xf bank_mask:0xf bound_ctrl:1
	v_add_f32_dpp v149, v149, v149 quad_perm:[1,0,3,2] row_mask:0xf bank_mask:0xf bound_ctrl:1
	v_pk_mul_f32 v[132:133], v[92:93], v[88:89] op_sel_hi:[0,1]
	v_pk_mul_f32 v[140:141], v[92:93], v[88:89] op_sel:[1,0]
	v_add_f32_dpp v144, v144, v144 quad_perm:[2,3,0,1] row_mask:0xf bank_mask:0xf bound_ctrl:1
	v_add_f32_dpp v148, v148, v148 quad_perm:[2,3,0,1] row_mask:0xf bank_mask:0xf bound_ctrl:1
	v_add_f32_dpp v145, v145, v145 quad_perm:[2,3,0,1] row_mask:0xf bank_mask:0xf bound_ctrl:1
	v_add_f32_dpp v149, v149, v149 quad_perm:[2,3,0,1] row_mask:0xf bank_mask:0xf bound_ctrl:1
	v_pk_mul_f32 v[134:135], v[92:93], v[90:91] op_sel_hi:[0,1]
	v_pk_mul_f32 v[142:143], v[92:93], v[90:91] op_sel:[1,0]
	v_add_f32_dpp v144, v144, v144 row_half_mirror row_mask:0xf bank_mask:0xf bound_ctrl:1
	v_add_f32_dpp v148, v148, v148 row_half_mirror row_mask:0xf bank_mask:0xf bound_ctrl:1
	v_add_f32_dpp v145, v145, v145 row_half_mirror row_mask:0xf bank_mask:0xf bound_ctrl:1
	v_add_f32_dpp v149, v149, v149 row_half_mirror row_mask:0xf bank_mask:0xf bound_ctrl:1
	v_pk_fma_f32 v[176:177], v[144:145], v[94:95], v[148:149] op_sel_hi:[1,0,1]
	v_pk_fma_f32 v[128:129], v[104:105], v[144:145], v[128:129] op_sel_hi:[1,0,1]
	v_pk_fma_f32 v[176:177], v[92:93], v[94:95], v[176:177] op_sel:[0,1,0]
	v_pk_fma_f32 v[136:137], v[104:105], v[144:145], v[136:137] op_sel:[0,1,0]
	ds_read_b64 v[94:95], v207 offset:49312
	ds_read_b128 v[84:87], v205 offset:16384
	ds_read_b128 v[88:91], v205 offset:16400
	ds_read_b64 v[92:93], v206 offset:16640
	ds_write_b64 v208, v[176:177] offset:2304
	v_pk_fma_f32 v[8:9], v[8:9], v[120:121], v[128:129]
	v_pk_fma_f32 v[16:17], v[16:17], v[120:121], v[136:137]
	v_pk_fma_f32 v[130:131], v[106:107], v[144:145], v[130:131] op_sel_hi:[1,0,1]
	v_pk_fma_f32 v[138:139], v[106:107], v[144:145], v[138:139] op_sel:[0,1,0]
	v_pk_fma_f32 v[10:11], v[10:11], v[122:123], v[130:131]
	v_pk_fma_f32 v[18:19], v[18:19], v[122:123], v[138:139]
	v_pk_fma_f32 v[132:133], v[108:109], v[144:145], v[132:133] op_sel_hi:[1,0,1]
	v_pk_fma_f32 v[140:141], v[108:109], v[144:145], v[140:141] op_sel:[0,1,0]
	v_pk_fma_f32 v[4:5], v[4:5], v[124:125], v[132:133]
	v_pk_fma_f32 v[12:13], v[12:13], v[124:125], v[140:141]
	v_pk_fma_f32 v[134:135], v[110:111], v[144:145], v[134:135] op_sel_hi:[1,0,1]
	v_pk_fma_f32 v[142:143], v[110:111], v[144:145], v[142:143] op_sel:[0,1,0]
	v_pk_fma_f32 v[6:7], v[6:7], v[126:127], v[134:135]
	v_pk_fma_f32 v[14:15], v[14:15], v[126:127], v[142:143]
	s_waitcnt lgkmcnt(5)
	s_nop 0
	v_pk_mul_f32 v[144:145], v[8:9], v[68:69]
	v_pk_mul_f32 v[148:149], v[8:9], v[76:77]
	v_pk_mul_f32 v[146:147], v[16:17], v[68:69]
	v_pk_mul_f32 v[174:175], v[16:17], v[76:77]
	v_pk_fma_f32 v[144:145], v[10:11], v[70:71], v[144:145]
	v_pk_fma_f32 v[148:149], v[10:11], v[78:79], v[148:149]
	v_pk_fma_f32 v[146:147], v[18:19], v[70:71], v[146:147]
	v_pk_fma_f32 v[174:175], v[18:19], v[78:79], v[174:175]
	v_pk_fma_f32 v[144:145], v[4:5], v[72:73], v[144:145]
	v_pk_fma_f32 v[148:149], v[4:5], v[80:81], v[148:149]
	v_pk_fma_f32 v[146:147], v[12:13], v[72:73], v[146:147]
	v_pk_fma_f32 v[174:175], v[12:13], v[80:81], v[174:175]
	v_pk_fma_f32 v[144:145], v[6:7], v[74:75], v[144:145]
	v_pk_fma_f32 v[148:149], v[6:7], v[82:83], v[148:149]
	v_pk_fma_f32 v[146:147], v[14:15], v[74:75], v[146:147]
	v_pk_fma_f32 v[174:175], v[14:15], v[82:83], v[174:175]
	ds_read_b128 v[68:71], v205 offset:16896
	ds_read_b128 v[72:75], v205 offset:16912
	ds_read_b128 v[76:79], v205 offset:17408
	ds_read_b128 v[80:83], v205 offset:17424
	ds_read_b128 v[104:107], v205 offset:17664
	ds_read_b128 v[108:111], v205 offset:17680
	ds_read_b128 v[120:123], v205 offset:17152
	ds_read_b128 v[124:127], v205 offset:17168
	s_waitcnt lgkmcnt(9)
; __device__ __forceinline__ float red8(float v) { v = red4(v); v += dppf<0x141>(v); return v; }
; __device__ __forceinline__ f32x2 lo2(const f32x4& v) { return __builtin_shufflevector(v, v, 0, 1); }
; __device__ __forceinline__ f32x2 hi2(const f32x4& v) { return __builtin_shufflevector(v, v, 2, 3); }
; __device__ __forceinline__ f32x2 splat2(float x) { return (f32x2){x, x}; }
; __device__ __forceinline__ f32x2 rw_step(f32x2 (&S)[2][4], const RwRegs& R) {
;   float sa[2], sy[2];
; #pragma unroll
;   for (int r = 0; r < 2; ++r) {
;     f32x2 a0 = S[r][0] * lo2(R.a[0]);
;     f32x2 a1 = S[r][1] * hi2(R.a[0]);
;     f32x2 y0 = S[r][0] * lo2(R.wr[0]);
;     f32x2 y1 = S[r][1] * hi2(R.wr[0]);
;     a0 += S[r][2] * lo2(R.a[1]);
;     a1 += S[r][3] * hi2(R.a[1]);
;     y0 += S[r][2] * lo2(R.wr[1]);
;     y1 += S[r][3] * hi2(R.wr[1]);
;     a0 += a1; y0 += y1;
;     sa[r] = a0.x + a0.y; sy[r] = y0.x + y0.y;
;   }
;   sa[0] = red8(sa[0]); sa[1] = red8(sa[1]); sy[0] = red8(sy[0]); sy[1] = red8(sy[1]);
;   f32x2 yv;
; #pragma unroll
;   for (int r = 0; r < 2; ++r) {
;     const float vr = r ? R.v.y : R.v.x;
;     const f32x2 sa2 = splat2(sa[r]), vv2 = splat2(vr);
;     S[r][0] = S[r][0] * lo2(R.w[0]) + (sa2 * lo2(R.b[0]) + vv2 * lo2(R.k[0]));
;     S[r][1] = S[r][1] * hi2(R.w[0]) + (sa2 * hi2(R.b[0]) + vv2 * hi2(R.k[0]));
;     S[r][2] = S[r][2] * lo2(R.w[1]) + (sa2 * lo2(R.b[1]) + vv2 * lo2(R.k[1]));
;     S[r][3] = S[r][3] * hi2(R.w[1]) + (sa2 * hi2(R.b[1]) + vv2 * hi2(R.k[1]));
;     const float y = sy[r] + sa[r] * R.sc.x + vr * R.sc.y;
;     if (r) yv.y = y; else yv.x = y;
;   }
;   return yv;
; }
; __device__ __forceinline__ void scan_rwkv(const Params& p, int l, int seq, int h, char* smem, const unsigned* wflags, unsigned wexpect) {
;     ...
;     rw_load(RA, vb, sb, 0, k0, vrow0);
;     for (int t = 0; t < nsteps; t += 2) {
;       rw_load(RB, vb, sb, min(t + 1, 15), k0, vrow0);
;       const f32x2 y0v = rw_step(S, RA);
;       *(f32x2*)((part == 0) ? (yb + t * 64 + vrow0) : ydummy) = y0v;
;       SCAN_INTERLEAVE(13, 4);
;       if (t + 1 < nsteps) {
;         rw_load(RA, vb, sb, min(t + 2, 15), k0, vrow0);
;         const f32x2 y1v = rw_step(S, RB);
;         *(f32x2*)((part == 0) ? (yb + (t + 1) * 64 + vrow0) : ydummy) = y1v;
;         SCAN_INTERLEAVE(13, 4);
;       }
	v_add_f32_e32 v144, v144, v145
	v_pk_mul_f32 v[128:129], v[92:93], v[84:85] op_sel_hi:[0,1]
	v_pk_mul_f32 v[136:137], v[92:93], v[84:85] op_sel:[1,0]
	v_add_f32_e64 v148, v148, v149
	v_add_f32_e64 v145, v146, v147
	v_add_f32_e64 v149, v174, v175
	v_pk_mul_f32 v[130:131], v[92:93], v[86:87] op_sel_hi:[0,1]
	v_pk_mul_f32 v[138:139], v[92:93], v[86:87] op_sel:[1,0]
	v_add_f32_dpp v144, v144, v144 quad_perm:[1,0,3,2] row_mask:0xf bank_mask:0xf bound_ctrl:1
	v_add_f32_dpp v148, v148, v148 quad_perm:[1,0,3,2] row_mask:0xf bank_mask:0xf bound_ctrl:1
	v_add_f32_dpp v145, v145, v145 quad_perm:[1,0,3,2] row_mask:0xf bank_mask:0xf bound_ctrl:1
	v_add_f32_dpp v149, v149, v149 quad_perm:[1,0,3,2] row_mask:0xf bank_mask:0xf bound_ctrl:1
	v_pk_mul_f32 v[132:133], v[92:93], v[88:89] op_sel_hi:[0,1]
	v_pk_mul_f32 v[140:141], v[92:93], v[88:89] op_sel:[1,0]
	v_add_f32_dpp v144, v144, v144 quad_perm:[2,3,0,1] row_mask:0xf bank_mask:0xf bound_ctrl:1
	v_add_f32_dpp v148, v148, v148 quad_perm:[2,3,0,1] row_mask:0xf bank_mask:0xf bound_ctrl:1
	v_add_f32_dpp v145, v145, v145 quad_perm:[2,3,0,1] row_mask:0xf bank_mask:0xf bound_ctrl:1
	v_add_f32_dpp v149, v149, v149 quad_perm:[2,3,0,1] row_mask:0xf bank_mask:0xf bound_ctrl:1
	v_pk_mul_f32 v[134:135], v[92:93], v[90:91] op_sel_hi:[0,1]
	v_pk_mul_f32 v[142:143], v[92:93], v[90:91] op_sel:[1,0]
	v_add_f32_dpp v144, v144, v144 row_half_mirror row_mask:0xf bank_mask:0xf bound_ctrl:1
	v_add_f32_dpp v148, v148, v148 row_half_mirror row_mask:0xf bank_mask:0xf bound_ctrl:1
	v_add_f32_dpp v145, v145, v145 row_half_mirror row_mask:0xf bank_mask:0xf bound_ctrl:1
	v_add_f32_dpp v149, v149, v149 row_half_mirror row_mask:0xf bank_mask:0xf bound_ctrl:1
	v_pk_fma_f32 v[176:177], v[144:145], v[94:95], v[148:149] op_sel_hi:[1,0,1]
	v_pk_fma_f32 v[128:129], v[96:97], v[144:145], v[128:129] op_sel_hi:[1,0,1]
	v_pk_fma_f32 v[176:177], v[92:93], v[94:95], v[176:177] op_sel:[0,1,0]
	v_pk_fma_f32 v[136:137], v[96:97], v[144:145], v[136:137] op_sel:[0,1,0]
	ds_read_b64 v[94:95], v207 offset:49328
	ds_read_b128 v[84:87], v205 offset:17920
	ds_read_b128 v[88:91], v205 offset:17936
	ds_read_b64 v[92:93], v206 offset:18176
	ds_write_b64 v208, v[176:177] offset:2560
	v_pk_fma_f32 v[8:9], v[8:9], v[112:113], v[128:129]
	v_pk_fma_f32 v[16:17], v[16:17], v[112:113], v[136:137]
	v_pk_fma_f32 v[130:131], v[98:99], v[144:145], v[130:131] op_sel_hi:[1,0,1]
	v_pk_fma_f32 v[138:139], v[98:99], v[144:145], v[138:139] op_sel:[0,1,0]
	v_pk_fma_f32 v[10:11], v[10:11], v[114:115], v[130:131]
	v_pk_fma_f32 v[18:19], v[18:19], v[114:115], v[138:139]
	v_pk_fma_f32 v[132:133], v[100:101], v[144:145], v[132:133] op_sel_hi:[1,0,1]
	v_pk_fma_f32 v[140:141], v[100:101], v[144:145], v[140:141] op_sel:[0,1,0]
	v_pk_fma_f32 v[4:5], v[4:5], v[116:117], v[132:133]
	v_pk_fma_f32 v[12:13], v[12:13], v[116:117], v[140:141]
	v_pk_fma_f32 v[134:135], v[102:103], v[144:145], v[134:135] op_sel_hi:[1,0,1]
	v_pk_fma_f32 v[142:143], v[102:103], v[144:145], v[142:143] op_sel:[0,1,0]
	v_pk_fma_f32 v[6:7], v[6:7], v[118:119], v[134:135]
	v_pk_fma_f32 v[14:15], v[14:15], v[118:119], v[142:143]
	s_waitcnt lgkmcnt(5)
	s_nop 0
	v_pk_mul_f32 v[144:145], v[8:9], v[68:69]
	v_pk_mul_f32 v[148:149], v[8:9], v[76:77]
	v_pk_mul_f32 v[146:147], v[16:17], v[68:69]
	v_pk_mul_f32 v[174:175], v[16:17], v[76:77]
	v_pk_fma_f32 v[144:145], v[10:11], v[70:71], v[144:145]
	v_pk_fma_f32 v[148:149], v[10:11], v[78:79], v[148:149]
	v_pk_fma_f32 v[146:147], v[18:19], v[70:71], v[146:147]
	v_pk_fma_f32 v[174:175], v[18:19], v[78:79], v[174:175]
	v_pk_fma_f32 v[144:145], v[4:5], v[72:73], v[144:145]
	v_pk_fma_f32 v[148:149], v[4:5], v[80:81], v[148:149]
	v_pk_fma_f32 v[146:147], v[12:13], v[72:73], v[146:147]
	v_pk_fma_f32 v[174:175], v[12:13], v[80:81], v[174:175]
	v_pk_fma_f32 v[144:145], v[6:7], v[74:75], v[144:145]
	v_pk_fma_f32 v[148:149], v[6:7], v[82:83], v[148:149]
	v_pk_fma_f32 v[146:147], v[14:15], v[74:75], v[146:147]
	v_pk_fma_f32 v[174:175], v[14:15], v[82:83], v[174:175]
	ds_read_b128 v[68:71], v205 offset:18432
	ds_read_b128 v[72:75], v205 offset:18448
	ds_read_b128 v[76:79], v205 offset:18944
	ds_read_b128 v[80:83], v205 offset:18960
	ds_read_b128 v[96:99], v205 offset:19200
	ds_read_b128 v[100:103], v205 offset:19216
	ds_read_b128 v[112:115], v205 offset:18688
	ds_read_b128 v[116:119], v205 offset:18704
	s_waitcnt lgkmcnt(9)
; __device__ __forceinline__ float red8(float v) { v = red4(v); v += dppf<0x141>(v); return v; }
; __device__ __forceinline__ f32x2 lo2(const f32x4& v) { return __builtin_shufflevector(v, v, 0, 1); }
; __device__ __forceinline__ f32x2 hi2(const f32x4& v) { return __builtin_shufflevector(v, v, 2, 3); }
; __device__ __forceinline__ f32x2 splat2(float x) { return (f32x2){x, x}; }
; __device__ __forceinline__ f32x2 rw_step(f32x2 (&S)[2][4], const RwRegs& R) {
;   float sa[2], sy[2];
; #pragma unroll
;   for (int r = 0; r < 2; ++r) {
;     f32x2 a0 = S[r][0] * lo2(R.a[0]);
;     f32x2 a1 = S[r][1] * hi2(R.a[0]);
;     f32x2 y0 = S[r][0] * lo2(R.wr[0]);
;     f32x2 y1 = S[r][1] * hi2(R.wr[0]);
;     a0 += S[r][2] * lo2(R.a[1]);
;     a1 += S[r][3] * hi2(R.a[1]);
;     y0 += S[r][2] * lo2(R.wr[1]);
;     y1 += S[r][3] * hi2(R.wr[1]);
;     a0 += a1; y0 += y1;
;     sa[r] = a0.x + a0.y; sy[r] = y0.x + y0.y;
;   }
;   sa[0] = red8(sa[0]); sa[1] = red8(sa[1]); sy[0] = red8(sy[0]); sy[1] = red8(sy[1]);
;   f32x2 yv;
; #pragma unroll
;   for (int r = 0; r < 2; ++r) {
;     const float vr = r ? R.v.y : R.v.x;
;     const f32x2 sa2 = splat2(sa[r]), vv2 = splat2(vr);
;     S[r][0] = S[r][0] * lo2(R.w[0]) + (sa2 * lo2(R.b[0]) + vv2 * lo2(R.k[0]));
;     S[r][1] = S[r][1] * hi2(R.w[0]) + (sa2 * hi2(R.b[0]) + vv2 * hi2(R.k[0]));
;     S[r][2] = S[r][2] * lo2(R.w[1]) + (sa2 * lo2(R.b[1]) + vv2 * lo2(R.k[1]));
;     S[r][3] = S[r][3] * hi2(R.w[1]) + (sa2 * hi2(R.b[1]) + vv2 * hi2(R.k[1]));
;     const float y = sy[r] + sa[r] * R.sc.x + vr * R.sc.y;
;     if (r) yv.y = y; else yv.x = y;
;   }
;   return yv;
; }
; __device__ __forceinline__ void scan_rwkv(const Params& p, int l, int seq, int h, char* smem, const unsigned* wflags, unsigned wexpect) {
;     ...
;     rw_load(RA, vb, sb, 0, k0, vrow0);
;     for (int t = 0; t < nsteps; t += 2) {
;       rw_load(RB, vb, sb, min(t + 1, 15), k0, vrow0);
;       const f32x2 y0v = rw_step(S, RA);
;       *(f32x2*)((part == 0) ? (yb + t * 64 + vrow0) : ydummy) = y0v;
;       SCAN_INTERLEAVE(13, 4);
;       if (t + 1 < nsteps) {
;         rw_load(RA, vb, sb, min(t + 2, 15), k0, vrow0);
;         const f32x2 y1v = rw_step(S, RB);
;         *(f32x2*)((part == 0) ? (yb + (t + 1) * 64 + vrow0) : ydummy) = y1v;
;         SCAN_INTERLEAVE(13, 4);
;       }
	v_add_f32_e32 v144, v144, v145
	v_pk_mul_f32 v[128:129], v[92:93], v[84:85] op_sel_hi:[0,1]
	v_pk_mul_f32 v[136:137], v[92:93], v[84:85] op_sel:[1,0]
	v_add_f32_e64 v148, v148, v149
	v_add_f32_e64 v145, v146, v147
	v_add_f32_e64 v149, v174, v175
	v_pk_mul_f32 v[130:131], v[92:93], v[86:87] op_sel_hi:[0,1]
	v_pk_mul_f32 v[138:139], v[92:93], v[86:87] op_sel:[1,0]
	v_add_f32_dpp v144, v144, v144 quad_perm:[1,0,3,2] row_mask:0xf bank_mask:0xf bound_ctrl:1
	v_add_f32_dpp v148, v148, v148 quad_perm:[1,0,3,2] row_mask:0xf bank_mask:0xf bound_ctrl:1
	v_add_f32_dpp v145, v145, v145 quad_perm:[1,0,3,2] row_mask:0xf bank_mask:0xf bound_ctrl:1
	v_add_f32_dpp v149, v149, v149 quad_perm:[1,0,3,2] row_mask:0xf bank_mask:0xf bound_ctrl:1
	v_pk_mul_f32 v[132:133], v[92:93], v[88:89] op_sel_hi:[0,1]
	v_pk_mul_f32 v[140:141], v[92:93], v[88:89] op_sel:[1,0]
	v_add_f32_dpp v144, v144, v144 quad_perm:[2,3,0,1] row_mask:0xf bank_mask:0xf bound_ctrl:1
	v_add_f32_dpp v148, v148, v148 quad_perm:[2,3,0,1] row_mask:0xf bank_mask:0xf bound_ctrl:1
	v_add_f32_dpp v145, v145, v145 quad_perm:[2,3,0,1] row_mask:0xf bank_mask:0xf bound_ctrl:1
	v_add_f32_dpp v149, v149, v149 quad_perm:[2,3,0,1] row_mask:0xf bank_mask:0xf bound_ctrl:1
	v_pk_mul_f32 v[134:135], v[92:93], v[90:91] op_sel_hi:[0,1]
	v_pk_mul_f32 v[142:143], v[92:93], v[90:91] op_sel:[1,0]
	v_add_f32_dpp v144, v144, v144 row_half_mirror row_mask:0xf bank_mask:0xf bound_ctrl:1
	v_add_f32_dpp v148, v148, v148 row_half_mirror row_mask:0xf bank_mask:0xf bound_ctrl:1
	v_add_f32_dpp v145, v145, v145 row_half_mirror row_mask:0xf bank_mask:0xf bound_ctrl:1
	v_add_f32_dpp v149, v149, v149 row_half_mirror row_mask:0xf bank_mask:0xf bound_ctrl:1
	v_pk_fma_f32 v[176:177], v[144:145], v[94:95], v[148:149] op_sel_hi:[1,0,1]
	v_pk_fma_f32 v[128:129], v[104:105], v[144:145], v[128:129] op_sel_hi:[1,0,1]
	v_pk_fma_f32 v[176:177], v[92:93], v[94:95], v[176:177] op_sel:[0,1,0]
	v_pk_fma_f32 v[136:137], v[104:105], v[144:145], v[136:137] op_sel:[0,1,0]
	ds_read_b64 v[94:95], v207 offset:49344
	ds_read_b128 v[84:87], v205 offset:19456
	ds_read_b128 v[88:91], v205 offset:19472
	ds_read_b64 v[92:93], v206 offset:19712
	ds_write_b64 v208, v[176:177] offset:2816
	v_pk_fma_f32 v[8:9], v[8:9], v[120:121], v[128:129]
	v_pk_fma_f32 v[16:17], v[16:17], v[120:121], v[136:137]
	v_pk_fma_f32 v[130:131], v[106:107], v[144:145], v[130:131] op_sel_hi:[1,0,1]
	v_pk_fma_f32 v[138:139], v[106:107], v[144:145], v[138:139] op_sel:[0,1,0]
	v_pk_fma_f32 v[10:11], v[10:11], v[122:123], v[130:131]
	v_pk_fma_f32 v[18:19], v[18:19], v[122:123], v[138:139]
	v_pk_fma_f32 v[132:133], v[108:109], v[144:145], v[132:133] op_sel_hi:[1,0,1]
	v_pk_fma_f32 v[140:141], v[108:109], v[144:145], v[140:141] op_sel:[0,1,0]
	v_pk_fma_f32 v[4:5], v[4:5], v[124:125], v[132:133]
	v_pk_fma_f32 v[12:13], v[12:13], v[124:125], v[140:141]
	v_pk_fma_f32 v[134:135], v[110:111], v[144:145], v[134:135] op_sel_hi:[1,0,1]
	v_pk_fma_f32 v[142:143], v[110:111], v[144:145], v[142:143] op_sel:[0,1,0]
	v_pk_fma_f32 v[6:7], v[6:7], v[126:127], v[134:135]
	v_pk_fma_f32 v[14:15], v[14:15], v[126:127], v[142:143]
	s_waitcnt lgkmcnt(5)
	s_nop 0
	v_pk_mul_f32 v[144:145], v[8:9], v[68:69]
	v_pk_mul_f32 v[148:149], v[8:9], v[76:77]
	v_pk_mul_f32 v[146:147], v[16:17], v[68:69]
	v_pk_mul_f32 v[174:175], v[16:17], v[76:77]
	v_pk_fma_f32 v[144:145], v[10:11], v[70:71], v[144:145]
	v_pk_fma_f32 v[148:149], v[10:11], v[78:79], v[148:149]
	v_pk_fma_f32 v[146:147], v[18:19], v[70:71], v[146:147]
	v_pk_fma_f32 v[174:175], v[18:19], v[78:79], v[174:175]
	v_pk_fma_f32 v[144:145], v[4:5], v[72:73], v[144:145]
	v_pk_fma_f32 v[148:149], v[4:5], v[80:81], v[148:149]
	v_pk_fma_f32 v[146:147], v[12:13], v[72:73], v[146:147]
	v_pk_fma_f32 v[174:175], v[12:13], v[80:81], v[174:175]
	v_pk_fma_f32 v[144:145], v[6:7], v[74:75], v[144:145]
	v_pk_fma_f32 v[148:149], v[6:7], v[82:83], v[148:149]
	v_pk_fma_f32 v[146:147], v[14:15], v[74:75], v[146:147]
	v_pk_fma_f32 v[174:175], v[14:15], v[82:83], v[174:175]
	ds_read_b128 v[68:71], v205 offset:19968
	ds_read_b128 v[72:75], v205 offset:19984
	ds_read_b128 v[76:79], v205 offset:20480
	ds_read_b128 v[80:83], v205 offset:20496
	ds_read_b128 v[104:107], v205 offset:20736
	ds_read_b128 v[108:111], v205 offset:20752
	ds_read_b128 v[120:123], v205 offset:20224
	ds_read_b128 v[124:127], v205 offset:20240
	s_waitcnt lgkmcnt(9)
; __device__ __forceinline__ float red8(float v) { v = red4(v); v += dppf<0x141>(v); return v; }
; __device__ __forceinline__ f32x2 lo2(const f32x4& v) { return __builtin_shufflevector(v, v, 0, 1); }
; __device__ __forceinline__ f32x2 hi2(const f32x4& v) { return __builtin_shufflevector(v, v, 2, 3); }
; __device__ __forceinline__ f32x2 splat2(float x) { return (f32x2){x, x}; }
; __device__ __forceinline__ f32x2 rw_step(f32x2 (&S)[2][4], const RwRegs& R) {
;   float sa[2], sy[2];
; #pragma unroll
;   for (int r = 0; r < 2; ++r) {
;     f32x2 a0 = S[r][0] * lo2(R.a[0]);
;     f32x2 a1 = S[r][1] * hi2(R.a[0]);
;     f32x2 y0 = S[r][0] * lo2(R.wr[0]);
;     f32x2 y1 = S[r][1] * hi2(R.wr[0]);
;     a0 += S[r][2] * lo2(R.a[1]);
;     a1 += S[r][3] * hi2(R.a[1]);
;     y0 += S[r][2] * lo2(R.wr[1]);
;     y1 += S[r][3] * hi2(R.wr[1]);
;     a0 += a1; y0 += y1;
;     sa[r] = a0.x + a0.y; sy[r] = y0.x + y0.y;
;   }
;   sa[0] = red8(sa[0]); sa[1] = red8(sa[1]); sy[0] = red8(sy[0]); sy[1] = red8(sy[1]);
;   f32x2 yv;
; #pragma unroll
;   for (int r = 0; r < 2; ++r) {
;     const float vr = r ? R.v.y : R.v.x;
;     const f32x2 sa2 = splat2(sa[r]), vv2 = splat2(vr);
;     S[r][0] = S[r][0] * lo2(R.w[0]) + (sa2 * lo2(R.b[0]) + vv2 * lo2(R.k[0]));
;     S[r][1] = S[r][1] * hi2(R.w[0]) + (sa2 * hi2(R.b[0]) + vv2 * hi2(R.k[0]));
;     S[r][2] = S[r][2] * lo2(R.w[1]) + (sa2 * lo2(R.b[1]) + vv2 * lo2(R.k[1]));
;     S[r][3] = S[r][3] * hi2(R.w[1]) + (sa2 * hi2(R.b[1]) + vv2 * hi2(R.k[1]));
;     const float y = sy[r] + sa[r] * R.sc.x + vr * R.sc.y;
;     if (r) yv.y = y; else yv.x = y;
;   }
;   return yv;
; }
; __device__ __forceinline__ void scan_rwkv(const Params& p, int l, int seq, int h, char* smem, const unsigned* wflags, unsigned wexpect) {
;     ...
;     rw_load(RA, vb, sb, 0, k0, vrow0);
;     for (int t = 0; t < nsteps; t += 2) {
;       rw_load(RB, vb, sb, min(t + 1, 15), k0, vrow0);
;       const f32x2 y0v = rw_step(S, RA);
;       *(f32x2*)((part == 0) ? (yb + t * 64 + vrow0) : ydummy) = y0v;
;       SCAN_INTERLEAVE(13, 4);
;       if (t + 1 < nsteps) {
;         rw_load(RA, vb, sb, min(t + 2, 15), k0, vrow0);
;         const f32x2 y1v = rw_step(S, RB);
;         *(f32x2*)((part == 0) ? (yb + (t + 1) * 64 + vrow0) : ydummy) = y1v;
;         SCAN_INTERLEAVE(13, 4);
;       }
	v_add_f32_e32 v144, v144, v145
	v_pk_mul_f32 v[128:129], v[92:93], v[84:85] op_sel_hi:[0,1]
	v_pk_mul_f32 v[136:137], v[92:93], v[84:85] op_sel:[1,0]
	v_add_f32_e64 v148, v148, v149
	v_add_f32_e64 v145, v146, v147
	v_add_f32_e64 v149, v174, v175
	v_pk_mul_f32 v[130:131], v[92:93], v[86:87] op_sel_hi:[0,1]
	v_pk_mul_f32 v[138:139], v[92:93], v[86:87] op_sel:[1,0]
	v_add_f32_dpp v144, v144, v144 quad_perm:[1,0,3,2] row_mask:0xf bank_mask:0xf bound_ctrl:1
	v_add_f32_dpp v148, v148, v148 quad_perm:[1,0,3,2] row_mask:0xf bank_mask:0xf bound_ctrl:1
	v_add_f32_dpp v145, v145, v145 quad_perm:[1,0,3,2] row_mask:0xf bank_mask:0xf bound_ctrl:1
	v_add_f32_dpp v149, v149, v149 quad_perm:[1,0,3,2] row_mask:0xf bank_mask:0xf bound_ctrl:1
	v_pk_mul_f32 v[132:133], v[92:93], v[88:89] op_sel_hi:[0,1]
	v_pk_mul_f32 v[140:141], v[92:93], v[88:89] op_sel:[1,0]
	v_add_f32_dpp v144, v144, v144 quad_perm:[2,3,0,1] row_mask:0xf bank_mask:0xf bound_ctrl:1
	v_add_f32_dpp v148, v148, v148 quad_perm:[2,3,0,1] row_mask:0xf bank_mask:0xf bound_ctrl:1
	v_add_f32_dpp v145, v145, v145 quad_perm:[2,3,0,1] row_mask:0xf bank_mask:0xf bound_ctrl:1
	v_add_f32_dpp v149, v149, v149 quad_perm:[2,3,0,1] row_mask:0xf bank_mask:0xf bound_ctrl:1
	v_pk_mul_f32 v[134:135], v[92:93], v[90:91] op_sel_hi:[0,1]
	v_pk_mul_f32 v[142:143], v[92:93], v[90:91] op_sel:[1,0]
	v_add_f32_dpp v144, v144, v144 row_half_mirror row_mask:0xf bank_mask:0xf bound_ctrl:1
	v_add_f32_dpp v148, v148, v148 row_half_mirror row_mask:0xf bank_mask:0xf bound_ctrl:1
	v_add_f32_dpp v145, v145, v145 row_half_mirror row_mask:0xf bank_mask:0xf bound_ctrl:1
	v_add_f32_dpp v149, v149, v149 row_half_mirror row_mask:0xf bank_mask:0xf bound_ctrl:1
	v_pk_fma_f32 v[176:177], v[144:145], v[94:95], v[148:149] op_sel_hi:[1,0,1]
	v_pk_fma_f32 v[128:129], v[96:97], v[144:145], v[128:129] op_sel_hi:[1,0,1]
	v_pk_fma_f32 v[176:177], v[92:93], v[94:95], v[176:177] op_sel:[0,1,0]
	v_pk_fma_f32 v[136:137], v[96:97], v[144:145], v[136:137] op_sel:[0,1,0]
	ds_read_b64 v[94:95], v207 offset:49360
	ds_read_b128 v[84:87], v205 offset:20992
	ds_read_b128 v[88:91], v205 offset:21008
	ds_read_b64 v[92:93], v206 offset:21248
	ds_write_b64 v208, v[176:177] offset:3072
	v_pk_fma_f32 v[8:9], v[8:9], v[112:113], v[128:129]
	v_pk_fma_f32 v[16:17], v[16:17], v[112:113], v[136:137]
	v_pk_fma_f32 v[130:131], v[98:99], v[144:145], v[130:131] op_sel_hi:[1,0,1]
	v_pk_fma_f32 v[138:139], v[98:99], v[144:145], v[138:139] op_sel:[0,1,0]
	v_pk_fma_f32 v[10:11], v[10:11], v[114:115], v[130:131]
	v_pk_fma_f32 v[18:19], v[18:19], v[114:115], v[138:139]
	v_pk_fma_f32 v[132:133], v[100:101], v[144:145], v[132:133] op_sel_hi:[1,0,1]
	v_pk_fma_f32 v[140:141], v[100:101], v[144:145], v[140:141] op_sel:[0,1,0]
	v_pk_fma_f32 v[4:5], v[4:5], v[116:117], v[132:133]
	v_pk_fma_f32 v[12:13], v[12:13], v[116:117], v[140:141]
	v_pk_fma_f32 v[134:135], v[102:103], v[144:145], v[134:135] op_sel_hi:[1,0,1]
	v_pk_fma_f32 v[142:143], v[102:103], v[144:145], v[142:143] op_sel:[0,1,0]
	v_pk_fma_f32 v[6:7], v[6:7], v[118:119], v[134:135]
	v_pk_fma_f32 v[14:15], v[14:15], v[118:119], v[142:143]
	s_waitcnt lgkmcnt(5)
	s_nop 0
	v_pk_mul_f32 v[144:145], v[8:9], v[68:69]
	v_pk_mul_f32 v[148:149], v[8:9], v[76:77]
	v_pk_mul_f32 v[146:147], v[16:17], v[68:69]
	v_pk_mul_f32 v[174:175], v[16:17], v[76:77]
	v_pk_fma_f32 v[144:145], v[10:11], v[70:71], v[144:145]
	v_pk_fma_f32 v[148:149], v[10:11], v[78:79], v[148:149]
	v_pk_fma_f32 v[146:147], v[18:19], v[70:71], v[146:147]
	v_pk_fma_f32 v[174:175], v[18:19], v[78:79], v[174:175]
	v_pk_fma_f32 v[144:145], v[4:5], v[72:73], v[144:145]
	v_pk_fma_f32 v[148:149], v[4:5], v[80:81], v[148:149]
	v_pk_fma_f32 v[146:147], v[12:13], v[72:73], v[146:147]
	v_pk_fma_f32 v[174:175], v[12:13], v[80:81], v[174:175]
	v_pk_fma_f32 v[144:145], v[6:7], v[74:75], v[144:145]
	v_pk_fma_f32 v[148:149], v[6:7], v[82:83], v[148:149]
	v_pk_fma_f32 v[146:147], v[14:15], v[74:75], v[146:147]
	v_pk_fma_f32 v[174:175], v[14:15], v[82:83], v[174:175]
	ds_read_b128 v[68:71], v205 offset:21504
	ds_read_b128 v[72:75], v205 offset:21520
	ds_read_b128 v[76:79], v205 offset:22016
	ds_read_b128 v[80:83], v205 offset:22032
	ds_read_b128 v[96:99], v205 offset:22272
	ds_read_b128 v[100:103], v205 offset:22288
	ds_read_b128 v[112:115], v205 offset:21760
	ds_read_b128 v[116:119], v205 offset:21776
	s_waitcnt lgkmcnt(9)
; __device__ __forceinline__ float red8(float v) { v = red4(v); v += dppf<0x141>(v); return v; }
; __device__ __forceinline__ f32x2 lo2(const f32x4& v) { return __builtin_shufflevector(v, v, 0, 1); }
; __device__ __forceinline__ f32x2 hi2(const f32x4& v) { return __builtin_shufflevector(v, v, 2, 3); }
; __device__ __forceinline__ f32x2 splat2(float x) { return (f32x2){x, x}; }
; __device__ __forceinline__ f32x2 rw_step(f32x2 (&S)[2][4], const RwRegs& R) {
;   float sa[2], sy[2];
; #pragma unroll
;   for (int r = 0; r < 2; ++r) {
;     f32x2 a0 = S[r][0] * lo2(R.a[0]);
;     f32x2 a1 = S[r][1] * hi2(R.a[0]);
;     f32x2 y0 = S[r][0] * lo2(R.wr[0]);
;     f32x2 y1 = S[r][1] * hi2(R.wr[0]);
;     a0 += S[r][2] * lo2(R.a[1]);
;     a1 += S[r][3] * hi2(R.a[1]);
;     y0 += S[r][2] * lo2(R.wr[1]);
;     y1 += S[r][3] * hi2(R.wr[1]);
;     a0 += a1; y0 += y1;
;     sa[r] = a0.x + a0.y; sy[r] = y0.x + y0.y;
;   }
;   sa[0] = red8(sa[0]); sa[1] = red8(sa[1]); sy[0] = red8(sy[0]); sy[1] = red8(sy[1]);
;   f32x2 yv;
; #pragma unroll
;   for (int r = 0; r < 2; ++r) {
;     const float vr = r ? R.v.y : R.v.x;
;     const f32x2 sa2 = splat2(sa[r]), vv2 = splat2(vr);
;     S[r][0] = S[r][0] * lo2(R.w[0]) + (sa2 * lo2(R.b[0]) + vv2 * lo2(R.k[0]));
;     S[r][1] = S[r][1] * hi2(R.w[0]) + (sa2 * hi2(R.b[0]) + vv2 * hi2(R.k[0]));
;     S[r][2] = S[r][2] * lo2(R.w[1]) + (sa2 * lo2(R.b[1]) + vv2 * lo2(R.k[1]));
;     S[r][3] = S[r][3] * hi2(R.w[1]) + (sa2 * hi2(R.b[1]) + vv2 * hi2(R.k[1]));
;     const float y = sy[r] + sa[r] * R.sc.x + vr * R.sc.y;
;     if (r) yv.y = y; else yv.x = y;
;   }
;   return yv;
; }
; __device__ __forceinline__ void scan_rwkv(const Params& p, int l, int seq, int h, char* smem, const unsigned* wflags, unsigned wexpect) {
;     ...
;     rw_load(RA, vb, sb, 0, k0, vrow0);
;     for (int t = 0; t < nsteps; t += 2) {
;       rw_load(RB, vb, sb, min(t + 1, 15), k0, vrow0);
;       const f32x2 y0v = rw_step(S, RA);
;       *(f32x2*)((part == 0) ? (yb + t * 64 + vrow0) : ydummy) = y0v;
;       SCAN_INTERLEAVE(13, 4);
;       if (t + 1 < nsteps) {
;         rw_load(RA, vb, sb, min(t + 2, 15), k0, vrow0);
;         const f32x2 y1v = rw_step(S, RB);
;         *(f32x2*)((part == 0) ? (yb + (t + 1) * 64 + vrow0) : ydummy) = y1v;
;         SCAN_INTERLEAVE(13, 4);
;       }
	v_add_f32_e32 v144, v144, v145
	v_pk_mul_f32 v[128:129], v[92:93], v[84:85] op_sel_hi:[0,1]
	v_pk_mul_f32 v[136:137], v[92:93], v[84:85] op_sel:[1,0]
	v_add_f32_e64 v148, v148, v149
	v_add_f32_e64 v145, v146, v147
	v_add_f32_e64 v149, v174, v175
	v_pk_mul_f32 v[130:131], v[92:93], v[86:87] op_sel_hi:[0,1]
	v_pk_mul_f32 v[138:139], v[92:93], v[86:87] op_sel:[1,0]
	v_add_f32_dpp v144, v144, v144 quad_perm:[1,0,3,2] row_mask:0xf bank_mask:0xf bound_ctrl:1
	v_add_f32_dpp v148, v148, v148 quad_perm:[1,0,3,2] row_mask:0xf bank_mask:0xf bound_ctrl:1
	v_add_f32_dpp v145, v145, v145 quad_perm:[1,0,3,2] row_mask:0xf bank_mask:0xf bound_ctrl:1
	v_add_f32_dpp v149, v149, v149 quad_perm:[1,0,3,2] row_mask:0xf bank_mask:0xf bound_ctrl:1
	v_pk_mul_f32 v[132:133], v[92:93], v[88:89] op_sel_hi:[0,1]
	v_pk_mul_f32 v[140:141], v[92:93], v[88:89] op_sel:[1,0]
	v_add_f32_dpp v144, v144, v144 quad_perm:[2,3,0,1] row_mask:0xf bank_mask:0xf bound_ctrl:1
	v_add_f32_dpp v148, v148, v148 quad_perm:[2,3,0,1] row_mask:0xf bank_mask:0xf bound_ctrl:1
	v_add_f32_dpp v145, v145, v145 quad_perm:[2,3,0,1] row_mask:0xf bank_mask:0xf bound_ctrl:1
	v_add_f32_dpp v149, v149, v149 quad_perm:[2,3,0,1] row_mask:0xf bank_mask:0xf bound_ctrl:1
	v_pk_mul_f32 v[134:135], v[92:93], v[90:91] op_sel_hi:[0,1]
	v_pk_mul_f32 v[142:143], v[92:93], v[90:91] op_sel:[1,0]
	v_add_f32_dpp v144, v144, v144 row_half_mirror row_mask:0xf bank_mask:0xf bound_ctrl:1
	v_add_f32_dpp v148, v148, v148 row_half_mirror row_mask:0xf bank_mask:0xf bound_ctrl:1
	v_add_f32_dpp v145, v145, v145 row_half_mirror row_mask:0xf bank_mask:0xf bound_ctrl:1
	v_add_f32_dpp v149, v149, v149 row_half_mirror row_mask:0xf bank_mask:0xf bound_ctrl:1
	v_pk_fma_f32 v[176:177], v[144:145], v[94:95], v[148:149] op_sel_hi:[1,0,1]
	v_pk_fma_f32 v[128:129], v[104:105], v[144:145], v[128:129] op_sel_hi:[1,0,1]
	v_pk_fma_f32 v[176:177], v[92:93], v[94:95], v[176:177] op_sel:[0,1,0]
	v_pk_fma_f32 v[136:137], v[104:105], v[144:145], v[136:137] op_sel:[0,1,0]
	ds_read_b64 v[94:95], v207 offset:49376
	ds_read_b128 v[84:87], v205 offset:22528
	ds_read_b128 v[88:91], v205 offset:22544
	ds_read_b64 v[92:93], v206 offset:22784
	ds_write_b64 v208, v[176:177] offset:3328
	v_pk_fma_f32 v[8:9], v[8:9], v[120:121], v[128:129]
	v_pk_fma_f32 v[16:17], v[16:17], v[120:121], v[136:137]
	v_pk_fma_f32 v[130:131], v[106:107], v[144:145], v[130:131] op_sel_hi:[1,0,1]
	v_pk_fma_f32 v[138:139], v[106:107], v[144:145], v[138:139] op_sel:[0,1,0]
	v_pk_fma_f32 v[10:11], v[10:11], v[122:123], v[130:131]
	v_pk_fma_f32 v[18:19], v[18:19], v[122:123], v[138:139]
	v_pk_fma_f32 v[132:133], v[108:109], v[144:145], v[132:133] op_sel_hi:[1,0,1]
	v_pk_fma_f32 v[140:141], v[108:109], v[144:145], v[140:141] op_sel:[0,1,0]
	v_pk_fma_f32 v[4:5], v[4:5], v[124:125], v[132:133]
	v_pk_fma_f32 v[12:13], v[12:13], v[124:125], v[140:141]
	v_pk_fma_f32 v[134:135], v[110:111], v[144:145], v[134:135] op_sel_hi:[1,0,1]
	v_pk_fma_f32 v[142:143], v[110:111], v[144:145], v[142:143] op_sel:[0,1,0]
	v_pk_fma_f32 v[6:7], v[6:7], v[126:127], v[134:135]
	v_pk_fma_f32 v[14:15], v[14:15], v[126:127], v[142:143]
	s_waitcnt lgkmcnt(5)
	s_nop 0
	v_pk_mul_f32 v[144:145], v[8:9], v[68:69]
	v_pk_mul_f32 v[148:149], v[8:9], v[76:77]
	v_pk_mul_f32 v[146:147], v[16:17], v[68:69]
	v_pk_mul_f32 v[174:175], v[16:17], v[76:77]
	v_pk_fma_f32 v[144:145], v[10:11], v[70:71], v[144:145]
	v_pk_fma_f32 v[148:149], v[10:11], v[78:79], v[148:149]
	v_pk_fma_f32 v[146:147], v[18:19], v[70:71], v[146:147]
	v_pk_fma_f32 v[174:175], v[18:19], v[78:79], v[174:175]
	v_pk_fma_f32 v[144:145], v[4:5], v[72:73], v[144:145]
	v_pk_fma_f32 v[148:149], v[4:5], v[80:81], v[148:149]
	v_pk_fma_f32 v[146:147], v[12:13], v[72:73], v[146:147]
	v_pk_fma_f32 v[174:175], v[12:13], v[80:81], v[174:175]
	v_pk_fma_f32 v[144:145], v[6:7], v[74:75], v[144:145]
	v_pk_fma_f32 v[148:149], v[6:7], v[82:83], v[148:149]
	v_pk_fma_f32 v[146:147], v[14:15], v[74:75], v[146:147]
	v_pk_fma_f32 v[174:175], v[14:15], v[82:83], v[174:175]
	ds_read_b128 v[68:71], v205 offset:23040
	ds_read_b128 v[72:75], v205 offset:23056
	ds_read_b128 v[76:79], v205 offset:23552
	ds_read_b128 v[80:83], v205 offset:23568
	ds_read_b128 v[104:107], v205 offset:23808
	ds_read_b128 v[108:111], v205 offset:23824
	ds_read_b128 v[120:123], v205 offset:23296
	ds_read_b128 v[124:127], v205 offset:23312
	s_waitcnt lgkmcnt(9)
; __device__ __forceinline__ float red8(float v) { v = red4(v); v += dppf<0x141>(v); return v; }
; __device__ __forceinline__ f32x2 lo2(const f32x4& v) { return __builtin_shufflevector(v, v, 0, 1); }
; __device__ __forceinline__ f32x2 hi2(const f32x4& v) { return __builtin_shufflevector(v, v, 2, 3); }
; __device__ __forceinline__ f32x2 splat2(float x) { return (f32x2){x, x}; }
; __device__ __forceinline__ f32x2 rw_step(f32x2 (&S)[2][4], const RwRegs& R) {
;   float sa[2], sy[2];
; #pragma unroll
;   for (int r = 0; r < 2; ++r) {
;     f32x2 a0 = S[r][0] * lo2(R.a[0]);
;     f32x2 a1 = S[r][1] * hi2(R.a[0]);
;     f32x2 y0 = S[r][0] * lo2(R.wr[0]);
;     f32x2 y1 = S[r][1] * hi2(R.wr[0]);
;     a0 += S[r][2] * lo2(R.a[1]);
;     a1 += S[r][3] * hi2(R.a[1]);
;     y0 += S[r][2] * lo2(R.wr[1]);
;     y1 += S[r][3] * hi2(R.wr[1]);
;     a0 += a1; y0 += y1;
;     sa[r] = a0.x + a0.y; sy[r] = y0.x + y0.y;
;   }
;   sa[0] = red8(sa[0]); sa[1] = red8(sa[1]); sy[0] = red8(sy[0]); sy[1] = red8(sy[1]);
;   f32x2 yv;
; #pragma unroll
;   for (int r = 0; r < 2; ++r) {
;     const float vr = r ? R.v.y : R.v.x;
;     const f32x2 sa2 = splat2(sa[r]), vv2 = splat2(vr);
;     S[r][0] = S[r][0] * lo2(R.w[0]) + (sa2 * lo2(R.b[0]) + vv2 * lo2(R.k[0]));
;     S[r][1] = S[r][1] * hi2(R.w[0]) + (sa2 * hi2(R.b[0]) + vv2 * hi2(R.k[0]));
;     S[r][2] = S[r][2] * lo2(R.w[1]) + (sa2 * lo2(R.b[1]) + vv2 * lo2(R.k[1]));
;     S[r][3] = S[r][3] * hi2(R.w[1]) + (sa2 * hi2(R.b[1]) + vv2 * hi2(R.k[1]));
;     const float y = sy[r] + sa[r] * R.sc.x + vr * R.sc.y;
;     if (r) yv.y = y; else yv.x = y;
;   }
;   return yv;
; }
; __device__ __forceinline__ void scan_rwkv(const Params& p, int l, int seq, int h, char* smem, const unsigned* wflags, unsigned wexpect) {
;     ...
;     rw_load(RA, vb, sb, 0, k0, vrow0);
;     for (int t = 0; t < nsteps; t += 2) {
;       rw_load(RB, vb, sb, min(t + 1, 15), k0, vrow0);
;       const f32x2 y0v = rw_step(S, RA);
;       *(f32x2*)((part == 0) ? (yb + t * 64 + vrow0) : ydummy) = y0v;
;       SCAN_INTERLEAVE(13, 4);
;       if (t + 1 < nsteps) {
;         rw_load(RA, vb, sb, min(t + 2, 15), k0, vrow0);
;         const f32x2 y1v = rw_step(S, RB);
;         *(f32x2*)((part == 0) ? (yb + (t + 1) * 64 + vrow0) : ydummy) = y1v;
;         SCAN_INTERLEAVE(13, 4);
;       }
	v_add_f32_e32 v144, v144, v145
	v_pk_mul_f32 v[128:129], v[92:93], v[84:85] op_sel_hi:[0,1]
	v_pk_mul_f32 v[136:137], v[92:93], v[84:85] op_sel:[1,0]
	v_add_f32_e64 v148, v148, v149
	v_add_f32_e64 v145, v146, v147
	v_add_f32_e64 v149, v174, v175
	v_pk_mul_f32 v[130:131], v[92:93], v[86:87] op_sel_hi:[0,1]
	v_pk_mul_f32 v[138:139], v[92:93], v[86:87] op_sel:[1,0]
	v_add_f32_dpp v144, v144, v144 quad_perm:[1,0,3,2] row_mask:0xf bank_mask:0xf bound_ctrl:1
	v_add_f32_dpp v148, v148, v148 quad_perm:[1,0,3,2] row_mask:0xf bank_mask:0xf bound_ctrl:1
	v_add_f32_dpp v145, v145, v145 quad_perm:[1,0,3,2] row_mask:0xf bank_mask:0xf bound_ctrl:1
	v_add_f32_dpp v149, v149, v149 quad_perm:[1,0,3,2] row_mask:0xf bank_mask:0xf bound_ctrl:1
	v_pk_mul_f32 v[132:133], v[92:93], v[88:89] op_sel_hi:[0,1]
	v_pk_mul_f32 v[140:141], v[92:93], v[88:89] op_sel:[1,0]
	v_add_f32_dpp v144, v144, v144 quad_perm:[2,3,0,1] row_mask:0xf bank_mask:0xf bound_ctrl:1
	v_add_f32_dpp v148, v148, v148 quad_perm:[2,3,0,1] row_mask:0xf bank_mask:0xf bound_ctrl:1
	v_add_f32_dpp v145, v145, v145 quad_perm:[2,3,0,1] row_mask:0xf bank_mask:0xf bound_ctrl:1
	v_add_f32_dpp v149, v149, v149 quad_perm:[2,3,0,1] row_mask:0xf bank_mask:0xf bound_ctrl:1
	v_pk_mul_f32 v[134:135], v[92:93], v[90:91] op_sel_hi:[0,1]
	v_pk_mul_f32 v[142:143], v[92:93], v[90:91] op_sel:[1,0]
	v_add_f32_dpp v144, v144, v144 row_half_mirror row_mask:0xf bank_mask:0xf bound_ctrl:1
	v_add_f32_dpp v148, v148, v148 row_half_mirror row_mask:0xf bank_mask:0xf bound_ctrl:1
	v_add_f32_dpp v145, v145, v145 row_half_mirror row_mask:0xf bank_mask:0xf bound_ctrl:1
	v_add_f32_dpp v149, v149, v149 row_half_mirror row_mask:0xf bank_mask:0xf bound_ctrl:1
	v_pk_fma_f32 v[176:177], v[144:145], v[94:95], v[148:149] op_sel_hi:[1,0,1]
	v_pk_fma_f32 v[128:129], v[96:97], v[144:145], v[128:129] op_sel_hi:[1,0,1]
	v_pk_fma_f32 v[176:177], v[92:93], v[94:95], v[176:177] op_sel:[0,1,0]
	v_pk_fma_f32 v[136:137], v[96:97], v[144:145], v[136:137] op_sel:[0,1,0]
	ds_read_b64 v[94:95], v207 offset:49392
	ds_read_b128 v[84:87], v205 offset:24064
	ds_read_b128 v[88:91], v205 offset:24080
	ds_read_b64 v[92:93], v206 offset:24320
	ds_write_b64 v208, v[176:177] offset:3584
	v_pk_fma_f32 v[8:9], v[8:9], v[112:113], v[128:129]
	v_pk_fma_f32 v[16:17], v[16:17], v[112:113], v[136:137]
	v_pk_fma_f32 v[130:131], v[98:99], v[144:145], v[130:131] op_sel_hi:[1,0,1]
	v_pk_fma_f32 v[138:139], v[98:99], v[144:145], v[138:139] op_sel:[0,1,0]
	v_pk_fma_f32 v[10:11], v[10:11], v[114:115], v[130:131]
	v_pk_fma_f32 v[18:19], v[18:19], v[114:115], v[138:139]
	v_pk_fma_f32 v[132:133], v[100:101], v[144:145], v[132:133] op_sel_hi:[1,0,1]
	v_pk_fma_f32 v[140:141], v[100:101], v[144:145], v[140:141] op_sel:[0,1,0]
	v_pk_fma_f32 v[4:5], v[4:5], v[116:117], v[132:133]
	v_pk_fma_f32 v[12:13], v[12:13], v[116:117], v[140:141]
	v_pk_fma_f32 v[134:135], v[102:103], v[144:145], v[134:135] op_sel_hi:[1,0,1]
	v_pk_fma_f32 v[142:143], v[102:103], v[144:145], v[142:143] op_sel:[0,1,0]
	v_pk_fma_f32 v[6:7], v[6:7], v[118:119], v[134:135]
	v_pk_fma_f32 v[14:15], v[14:15], v[118:119], v[142:143]
	s_waitcnt lgkmcnt(5)
	s_nop 0
	v_pk_mul_f32 v[144:145], v[8:9], v[68:69]
	v_pk_mul_f32 v[148:149], v[8:9], v[76:77]
	v_pk_mul_f32 v[146:147], v[16:17], v[68:69]
	v_pk_mul_f32 v[174:175], v[16:17], v[76:77]
	v_pk_fma_f32 v[144:145], v[10:11], v[70:71], v[144:145]
	v_pk_fma_f32 v[148:149], v[10:11], v[78:79], v[148:149]
	v_pk_fma_f32 v[146:147], v[18:19], v[70:71], v[146:147]
	v_pk_fma_f32 v[174:175], v[18:19], v[78:79], v[174:175]
	v_pk_fma_f32 v[144:145], v[4:5], v[72:73], v[144:145]
	v_pk_fma_f32 v[148:149], v[4:5], v[80:81], v[148:149]
	v_pk_fma_f32 v[146:147], v[12:13], v[72:73], v[146:147]
	v_pk_fma_f32 v[174:175], v[12:13], v[80:81], v[174:175]
	v_pk_fma_f32 v[144:145], v[6:7], v[74:75], v[144:145]
	v_pk_fma_f32 v[148:149], v[6:7], v[82:83], v[148:149]
	v_pk_fma_f32 v[146:147], v[14:15], v[74:75], v[146:147]
	v_pk_fma_f32 v[174:175], v[14:15], v[82:83], v[174:175]
	ds_read_b128 v[68:71], v205 offset:24576
	ds_read_b128 v[72:75], v205 offset:24592
	ds_read_b128 v[76:79], v205 offset:25088
	ds_read_b128 v[80:83], v205 offset:25104
	ds_read_b128 v[96:99], v205 offset:25344
	ds_read_b128 v[100:103], v205 offset:25360
	ds_read_b128 v[112:115], v205 offset:24832
	ds_read_b128 v[116:119], v205 offset:24848
	s_waitcnt lgkmcnt(9)
; __device__ __forceinline__ f32x2 rw_step(f32x2 (&S)[2][4], const RwRegs& R) {
;   float sa[2], sy[2];
; #pragma unroll
;   for (int r = 0; r < 2; ++r) {
;     f32x2 a0 = S[r][0] * lo2(R.a[0]);
;     f32x2 a1 = S[r][1] * hi2(R.a[0]);
;     f32x2 y0 = S[r][0] * lo2(R.wr[0]);
;     f32x2 y1 = S[r][1] * hi2(R.wr[0]);
;     a0 += S[r][2] * lo2(R.a[1]);
;     a1 += S[r][3] * hi2(R.a[1]);
;     y0 += S[r][2] * lo2(R.wr[1]);
;     y1 += S[r][3] * hi2(R.wr[1]);
;     a0 += a1; y0 += y1;
;     sa[r] = a0.x + a0.y; sy[r] = y0.x + y0.y;
;   }
;   sa[0] = red8(sa[0]); sa[1] = red8(sa[1]); sy[0] = red8(sy[0]); sy[1] = red8(sy[1]);
;   f32x2 yv;
; #pragma unroll
;   for (int r = 0; r < 2; ++r) {
;     const float vr = r ? R.v.y : R.v.x;
;     const f32x2 sa2 = splat2(sa[r]), vv2 = splat2(vr);
;     S[r][0] = S[r][0] * lo2(R.w[0]) + (sa2 * lo2(R.b[0]) + vv2 * lo2(R.k[0]));
;     S[r][1] = S[r][1] * hi2(R.w[0]) + (sa2 * hi2(R.b[0]) + vv2 * hi2(R.k[0]));
;     S[r][2] = S[r][2] * lo2(R.w[1]) + (sa2 * lo2(R.b[1]) + vv2 * lo2(R.k[1]));
;     S[r][3] = S[r][3] * hi2(R.w[1]) + (sa2 * hi2(R.b[1]) + vv2 * hi2(R.k[1]));
;     const float y = sy[r] + sa[r] * R.sc.x + vr * R.sc.y;
;     if (r) yv.y = y; else yv.x = y;
;   }
;   return yv;
; }
; __device__ __forceinline__ f32x2 ss_step(f32x2 (&S)[2][8], const SsRegs& R) {
;   const f32x2 dA2 = splat2(R.sc.y);
;   f32x2 out;
; #pragma unroll
;   for (int r = 0; r < 2; ++r) {
;     const f32x2 xdt2 = splat2((r ? R.x.y : R.x.x) * R.sc.x);
;     f32x2 y0 = splat2(0.f), y1 = splat2(0.f);
; #pragma unroll
;     for (int q = 0; q < 4; ++q) {
;       S[r][2 * q] = S[r][2 * q] * dA2 + xdt2 * lo2(R.B[q]);
;       S[r][2 * q + 1] = S[r][2 * q + 1] * dA2 + xdt2 * hi2(R.B[q]);
;       y0 += S[r][2 * q] * lo2(R.C[q]);
;       y1 += S[r][2 * q + 1] * hi2(R.C[q]);
;     }
;     y0 += y1;
;     const float y = red8(y0.x + y0.y);
;     if (r) out.y = y; else out.x = y;
;   }
;   return out;
; }
; __device__ __forceinline__ void scan_ssm(const Params& p, int l, int seq, int h, char* smem, const unsigned* wflags, unsigned wexpect) {
;     ...
;     ss_load(RA, vb, sb, 0, n0, prow0);
;     for (int t = 0; t < nsteps; t += 2) {
;       ss_load(RB, vb, sb, min(t + 1, 15), n0, prow0);
;       const f32x2 y0v = ss_step(S, RA);
;       *(f32x2*)((part == 0) ? (yb + t * 64 + prow0) : ydummy) = y0v;
;       SCAN_INTERLEAVE(10, 5);
;       if (t + 1 < nsteps) {
	v_add_f32_e32 v144, v144, v145
	v_pk_mul_f32 v[128:129], v[92:93], v[84:85] op_sel_hi:[0,1]
	v_pk_mul_f32 v[136:137], v[92:93], v[84:85] op_sel:[1,0]
	v_add_f32_e64 v148, v148, v149
	v_add_f32_e64 v145, v146, v147
	v_add_f32_e64 v149, v174, v175
	v_pk_mul_f32 v[130:131], v[92:93], v[86:87] op_sel_hi:[0,1]
	v_pk_mul_f32 v[138:139], v[92:93], v[86:87] op_sel:[1,0]
	v_add_f32_dpp v144, v144, v144 quad_perm:[1,0,3,2] row_mask:0xf bank_mask:0xf bound_ctrl:1
	v_add_f32_dpp v148, v148, v148 quad_perm:[1,0,3,2] row_mask:0xf bank_mask:0xf bound_ctrl:1
	v_add_f32_dpp v145, v145, v145 quad_perm:[1,0,3,2] row_mask:0xf bank_mask:0xf bound_ctrl:1
	v_add_f32_dpp v149, v149, v149 quad_perm:[1,0,3,2] row_mask:0xf bank_mask:0xf bound_ctrl:1
	v_pk_mul_f32 v[132:133], v[92:93], v[88:89] op_sel_hi:[0,1]
	v_pk_mul_f32 v[140:141], v[92:93], v[88:89] op_sel:[1,0]
	v_add_f32_dpp v144, v144, v144 quad_perm:[2,3,0,1] row_mask:0xf bank_mask:0xf bound_ctrl:1
	v_add_f32_dpp v148, v148, v148 quad_perm:[2,3,0,1] row_mask:0xf bank_mask:0xf bound_ctrl:1
	v_add_f32_dpp v145, v145, v145 quad_perm:[2,3,0,1] row_mask:0xf bank_mask:0xf bound_ctrl:1
	v_add_f32_dpp v149, v149, v149 quad_perm:[2,3,0,1] row_mask:0xf bank_mask:0xf bound_ctrl:1
	v_pk_mul_f32 v[134:135], v[92:93], v[90:91] op_sel_hi:[0,1]
	v_pk_mul_f32 v[142:143], v[92:93], v[90:91] op_sel:[1,0]
	v_add_f32_dpp v144, v144, v144 row_half_mirror row_mask:0xf bank_mask:0xf bound_ctrl:1
	v_add_f32_dpp v148, v148, v148 row_half_mirror row_mask:0xf bank_mask:0xf bound_ctrl:1
	v_add_f32_dpp v145, v145, v145 row_half_mirror row_mask:0xf bank_mask:0xf bound_ctrl:1
	v_add_f32_dpp v149, v149, v149 row_half_mirror row_mask:0xf bank_mask:0xf bound_ctrl:1
	v_pk_fma_f32 v[176:177], v[144:145], v[94:95], v[148:149] op_sel_hi:[1,0,1]
	v_pk_fma_f32 v[128:129], v[104:105], v[144:145], v[128:129] op_sel_hi:[1,0,1]
	v_pk_fma_f32 v[176:177], v[92:93], v[94:95], v[176:177] op_sel:[0,1,0]
	v_pk_fma_f32 v[136:137], v[104:105], v[144:145], v[136:137] op_sel:[0,1,0]
	ds_read_b64 v[94:95], v207 offset:49408
	ds_read_b128 v[84:87], v205 offset:25600
	ds_read_b128 v[88:91], v205 offset:25616
	ds_read_b64 v[92:93], v206 offset:25856
	ds_write_b64 v208, v[176:177] offset:3840
	v_pk_fma_f32 v[8:9], v[8:9], v[120:121], v[128:129]
	v_pk_fma_f32 v[16:17], v[16:17], v[120:121], v[136:137]
	v_pk_fma_f32 v[130:131], v[106:107], v[144:145], v[130:131] op_sel_hi:[1,0,1]
	v_pk_fma_f32 v[138:139], v[106:107], v[144:145], v[138:139] op_sel:[0,1,0]
	v_pk_fma_f32 v[10:11], v[10:11], v[122:123], v[130:131]
	v_pk_fma_f32 v[18:19], v[18:19], v[122:123], v[138:139]
	v_pk_fma_f32 v[132:133], v[108:109], v[144:145], v[132:133] op_sel_hi:[1,0,1]
	v_pk_fma_f32 v[140:141], v[108:109], v[144:145], v[140:141] op_sel:[0,1,0]
	v_pk_fma_f32 v[4:5], v[4:5], v[124:125], v[132:133]
	v_pk_fma_f32 v[12:13], v[12:13], v[124:125], v[140:141]
	v_pk_fma_f32 v[134:135], v[110:111], v[144:145], v[134:135] op_sel_hi:[1,0,1]
	v_pk_fma_f32 v[142:143], v[110:111], v[144:145], v[142:143] op_sel:[0,1,0]
	v_pk_fma_f32 v[6:7], v[6:7], v[126:127], v[134:135]
	v_pk_fma_f32 v[14:15], v[14:15], v[126:127], v[142:143]
	s_cmp_eq_u32 s39, 0
	s_cbranch_scc1 .LBB0_283
	s_branch .LBB0_301
	.p2align 3
.Lssf_body:
	ds_read_b64 v[108:109], v152 offset:1024
	ds_read_b64 v[110:111], v153 offset:40960
	ds_read_b128 v[60:63], v150 offset:0
	ds_read_b128 v[84:87], v150 offset:512
	ds_read_b128 v[64:67], v151 offset:16
	ds_read_b128 v[88:91], v151 offset:528
	ds_read_b128 v[68:71], v150 offset:32
	ds_read_b128 v[92:95], v150 offset:544
	ds_read_b128 v[76:79], v151 offset:48
	ds_read_b128 v[100:103], v151 offset:560
	s_waitcnt lgkmcnt(0)
	s_nop 0
	ds_read_b64 v[112:113], v152 offset:2304
	ds_read_b64 v[114:115], v153 offset:40968
	ds_read_b128 v[72:75], v150 offset:1312
	ds_read_b128 v[96:99], v150 offset:1824
	ds_read_b128 v[80:83], v151 offset:1328
	ds_read_b128 v[104:107], v151 offset:1840
	v_pk_mul_f32 v[156:157], v[108:109], v[110:111] op_sel_hi:[1,0]
	v_pk_mul_f32 v[116:117], v[156:157], v[60:61] op_sel_hi:[0,1]
	v_pk_mul_f32 v[118:119], v[156:157], v[60:61] op_sel:[1,0]
	v_pk_fma_f32 v[28:29], v[28:29], v[110:111], v[116:117] op_sel:[0,1,0]
	v_pk_fma_f32 v[24:25], v[24:25], v[110:111], v[118:119] op_sel:[0,1,0]
	v_pk_mul_f32 v[188:189], v[28:29], v[84:85]
	v_pk_mul_f32 v[190:191], v[24:25], v[84:85]
	v_pk_mul_f32 v[120:121], v[156:157], v[62:63] op_sel_hi:[0,1]
	v_pk_mul_f32 v[122:123], v[156:157], v[62:63] op_sel:[1,0]
	v_pk_fma_f32 v[30:31], v[30:31], v[110:111], v[120:121] op_sel:[0,1,0]
	v_pk_fma_f32 v[26:27], v[26:27], v[110:111], v[122:123] op_sel:[0,1,0]
	v_pk_fma_f32 v[188:189], v[30:31], v[86:87], v[188:189]
	v_pk_fma_f32 v[190:191], v[26:27], v[86:87], v[190:191]
	v_pk_mul_f32 v[116:117], v[156:157], v[64:65] op_sel_hi:[0,1]
	v_pk_mul_f32 v[118:119], v[156:157], v[64:65] op_sel:[1,0]
	v_pk_fma_f32 v[12:13], v[12:13], v[110:111], v[116:117] op_sel:[0,1,0]
	v_pk_fma_f32 v[32:33], v[32:33], v[110:111], v[118:119] op_sel:[0,1,0]
	v_pk_fma_f32 v[188:189], v[12:13], v[88:89], v[188:189]
	v_pk_fma_f32 v[190:191], v[32:33], v[88:89], v[190:191]
	v_pk_mul_f32 v[120:121], v[156:157], v[66:67] op_sel_hi:[0,1]
	v_pk_mul_f32 v[122:123], v[156:157], v[66:67] op_sel:[1,0]
	v_pk_fma_f32 v[14:15], v[14:15], v[110:111], v[120:121] op_sel:[0,1,0]
	v_pk_fma_f32 v[34:35], v[34:35], v[110:111], v[122:123] op_sel:[0,1,0]
	v_pk_fma_f32 v[188:189], v[14:15], v[90:91], v[188:189]
	v_pk_fma_f32 v[190:191], v[34:35], v[90:91], v[190:191]
	ds_read_b128 v[60:63], v150 offset:1280
	ds_read_b128 v[84:87], v150 offset:1792
	ds_read_b128 v[64:67], v151 offset:1296
	ds_read_b128 v[88:91], v151 offset:1808
; __device__ __forceinline__ float red8(float v) { v = red4(v); v += dppf<0x141>(v); return v; }
; __device__ __forceinline__ f32x2 lo2(const f32x4& v) { return __builtin_shufflevector(v, v, 0, 1); }
; __device__ __forceinline__ f32x2 hi2(const f32x4& v) { return __builtin_shufflevector(v, v, 2, 3); }
; __device__ __forceinline__ f32x2 splat2(float x) { return (f32x2){x, x}; }
; #define SCAN_INTERLEAVE(nds, nvalu)                                   \
;   _Pragma("unroll") for (int i_ = 0; i_ < (nds); ++i_) {               \
;     __builtin_amdgcn_sched_group_barrier(0x100, 1, 0);                 \
;     __builtin_amdgcn_sched_group_barrier(0x002, (nvalu), 0);           \
;   }
; __device__ __forceinline__ f32x2 ss_step(f32x2 (&S)[2][8], const SsRegs& R) {
;   const f32x2 dA2 = splat2(R.sc.y);
;   f32x2 out;
; #pragma unroll
;   for (int r = 0; r < 2; ++r) {
;     const f32x2 xdt2 = splat2((r ? R.x.y : R.x.x) * R.sc.x);
;     f32x2 y0 = splat2(0.f), y1 = splat2(0.f);
; #pragma unroll
;     for (int q = 0; q < 4; ++q) {
;       S[r][2 * q] = S[r][2 * q] * dA2 + xdt2 * lo2(R.B[q]);
;       S[r][2 * q + 1] = S[r][2 * q + 1] * dA2 + xdt2 * hi2(R.B[q]);
;       y0 += S[r][2 * q] * lo2(R.C[q]);
;       y1 += S[r][2 * q + 1] * hi2(R.C[q]);
;     }
;     y0 += y1;
;     const float y = red8(y0.x + y0.y);
;     if (r) out.y = y; else out.x = y;
;   }
;   return out;
; }
; __device__ __forceinline__ void scan_ssm(const Params& p, int l, int seq, int h, char* smem, const unsigned* wflags, unsigned wexpect) {
;     ...
;     ss_load(RA, vb, sb, 0, n0, prow0);
;     for (int t = 0; t < nsteps; t += 2) {
;       ss_load(RB, vb, sb, min(t + 1, 15), n0, prow0);
;       const f32x2 y0v = ss_step(S, RA);
;       *(f32x2*)((part == 0) ? (yb + t * 64 + prow0) : ydummy) = y0v;
;       SCAN_INTERLEAVE(10, 5);
;       if (t + 1 < nsteps) {
;         ss_load(RA, vb, sb, min(t + 2, 15), n0, prow0);
;         const f32x2 y1v = ss_step(S, RB);
;         *(f32x2*)((part == 0) ? (yb + (t + 1) * 64 + prow0) : ydummy) = y1v;
;         SCAN_INTERLEAVE(10, 5);
;       }
;     }
	v_pk_mul_f32 v[116:117], v[156:157], v[68:69] op_sel_hi:[0,1]
	v_pk_mul_f32 v[118:119], v[156:157], v[68:69] op_sel:[1,0]
	v_pk_fma_f32 v[8:9], v[8:9], v[110:111], v[116:117] op_sel:[0,1,0]
	v_pk_fma_f32 v[20:21], v[20:21], v[110:111], v[118:119] op_sel:[0,1,0]
	v_pk_fma_f32 v[188:189], v[8:9], v[92:93], v[188:189]
	v_pk_fma_f32 v[190:191], v[20:21], v[92:93], v[190:191]
	v_pk_mul_f32 v[120:121], v[156:157], v[70:71] op_sel_hi:[0,1]
	v_pk_mul_f32 v[122:123], v[156:157], v[70:71] op_sel:[1,0]
	v_pk_fma_f32 v[10:11], v[10:11], v[110:111], v[120:121] op_sel:[0,1,0]
	v_pk_fma_f32 v[22:23], v[22:23], v[110:111], v[122:123] op_sel:[0,1,0]
	v_pk_fma_f32 v[188:189], v[10:11], v[94:95], v[188:189]
	v_pk_fma_f32 v[190:191], v[22:23], v[94:95], v[190:191]
	v_pk_mul_f32 v[116:117], v[156:157], v[76:77] op_sel_hi:[0,1]
	v_pk_mul_f32 v[118:119], v[156:157], v[76:77] op_sel:[1,0]
	v_pk_fma_f32 v[4:5], v[4:5], v[110:111], v[116:117] op_sel:[0,1,0]
	v_pk_fma_f32 v[16:17], v[16:17], v[110:111], v[118:119] op_sel:[0,1,0]
	v_pk_fma_f32 v[188:189], v[4:5], v[100:101], v[188:189]
	v_pk_fma_f32 v[190:191], v[16:17], v[100:101], v[190:191]
	v_pk_mul_f32 v[120:121], v[156:157], v[78:79] op_sel_hi:[0,1]
	v_pk_mul_f32 v[122:123], v[156:157], v[78:79] op_sel:[1,0]
	v_pk_fma_f32 v[6:7], v[6:7], v[110:111], v[120:121] op_sel:[0,1,0]
	v_pk_fma_f32 v[18:19], v[18:19], v[110:111], v[122:123] op_sel:[0,1,0]
	v_pk_fma_f32 v[188:189], v[6:7], v[102:103], v[188:189]
	v_pk_fma_f32 v[190:191], v[18:19], v[102:103], v[190:191]
	v_add_f32_e64 v192, v188, v189
	v_add_f32_e64 v193, v190, v191
	s_waitcnt lgkmcnt(0)
	s_nop 0
	ds_read_b64 v[108:109], v152 offset:3584
	ds_read_b64 v[110:111], v153 offset:40976
	ds_read_b128 v[68:71], v150 offset:2592
	ds_read_b128 v[92:95], v150 offset:3104
	ds_read_b128 v[76:79], v151 offset:2608
	ds_read_b128 v[100:103], v151 offset:3120
	v_pk_mul_f32 v[156:157], v[112:113], v[114:115] op_sel_hi:[1,0]
	v_pk_mul_f32 v[116:117], v[156:157], v[60:61] op_sel_hi:[0,1]
	v_pk_mul_f32 v[118:119], v[156:157], v[60:61] op_sel:[1,0]
	v_pk_fma_f32 v[28:29], v[28:29], v[114:115], v[116:117] op_sel:[0,1,0]
	v_pk_fma_f32 v[24:25], v[24:25], v[114:115], v[118:119] op_sel:[0,1,0]
	v_pk_mul_f32 v[188:189], v[28:29], v[84:85]
	v_pk_mul_f32 v[190:191], v[24:25], v[84:85]
	v_add_f32_dpp v192, v192, v192 quad_perm:[1,0,3,2] row_mask:0xf bank_mask:0xf bound_ctrl:1
	v_add_f32_dpp v193, v193, v193 quad_perm:[1,0,3,2] row_mask:0xf bank_mask:0xf bound_ctrl:1
	v_pk_mul_f32 v[120:121], v[156:157], v[62:63] op_sel_hi:[0,1]
	v_pk_mul_f32 v[122:123], v[156:157], v[62:63] op_sel:[1,0]
	v_pk_fma_f32 v[30:31], v[30:31], v[114:115], v[120:121] op_sel:[0,1,0]
	v_pk_fma_f32 v[26:27], v[26:27], v[114:115], v[122:123] op_sel:[0,1,0]
	v_pk_fma_f32 v[188:189], v[30:31], v[86:87], v[188:189]
	v_pk_fma_f32 v[190:191], v[26:27], v[86:87], v[190:191]
	v_add_f32_dpp v192, v192, v192 quad_perm:[2,3,0,1] row_mask:0xf bank_mask:0xf bound_ctrl:1
	v_add_f32_dpp v193, v193, v193 quad_perm:[2,3,0,1] row_mask:0xf bank_mask:0xf bound_ctrl:1
	v_pk_mul_f32 v[116:117], v[156:157], v[64:65] op_sel_hi:[0,1]
	v_pk_mul_f32 v[118:119], v[156:157], v[64:65] op_sel:[1,0]
	v_pk_fma_f32 v[12:13], v[12:13], v[114:115], v[116:117] op_sel:[0,1,0]
	v_pk_fma_f32 v[32:33], v[32:33], v[114:115], v[118:119] op_sel:[0,1,0]
	v_pk_fma_f32 v[188:189], v[12:13], v[88:89], v[188:189]
	v_pk_fma_f32 v[190:191], v[32:33], v[88:89], v[190:191]
	v_add_f32_dpp v192, v192, v192 row_half_mirror row_mask:0xf bank_mask:0xf bound_ctrl:1
	v_add_f32_dpp v193, v193, v193 row_half_mirror row_mask:0xf bank_mask:0xf bound_ctrl:1
	v_pk_mul_f32 v[120:121], v[156:157], v[66:67] op_sel_hi:[0,1]
	v_pk_mul_f32 v[122:123], v[156:157], v[66:67] op_sel:[1,0]
	v_pk_fma_f32 v[14:15], v[14:15], v[114:115], v[120:121] op_sel:[0,1,0]
	v_pk_fma_f32 v[34:35], v[34:35], v[114:115], v[122:123] op_sel:[0,1,0]
	v_pk_fma_f32 v[188:189], v[14:15], v[90:91], v[188:189]
	v_pk_fma_f32 v[190:191], v[34:35], v[90:91], v[190:191]
	ds_read_b128 v[60:63], v150 offset:2560
	ds_read_b128 v[84:87], v150 offset:3072
	ds_read_b128 v[64:67], v151 offset:2576
	ds_read_b128 v[88:91], v151 offset:3088
	ds_write_b64 v154, v[192:193] offset:0
	v_pk_mul_f32 v[116:117], v[156:157], v[72:73] op_sel_hi:[0,1]
	v_pk_mul_f32 v[118:119], v[156:157], v[72:73] op_sel:[1,0]
	v_pk_fma_f32 v[8:9], v[8:9], v[114:115], v[116:117] op_sel:[0,1,0]
	v_pk_fma_f32 v[20:21], v[20:21], v[114:115], v[118:119] op_sel:[0,1,0]
	v_pk_fma_f32 v[188:189], v[8:9], v[96:97], v[188:189]
	v_pk_fma_f32 v[190:191], v[20:21], v[96:97], v[190:191]
	v_pk_mul_f32 v[120:121], v[156:157], v[74:75] op_sel_hi:[0,1]
	v_pk_mul_f32 v[122:123], v[156:157], v[74:75] op_sel:[1,0]
	v_pk_fma_f32 v[10:11], v[10:11], v[114:115], v[120:121] op_sel:[0,1,0]
	v_pk_fma_f32 v[22:23], v[22:23], v[114:115], v[122:123] op_sel:[0,1,0]
	v_pk_fma_f32 v[188:189], v[10:11], v[98:99], v[188:189]
	v_pk_fma_f32 v[190:191], v[22:23], v[98:99], v[190:191]
	v_pk_mul_f32 v[116:117], v[156:157], v[80:81] op_sel_hi:[0,1]
	v_pk_mul_f32 v[118:119], v[156:157], v[80:81] op_sel:[1,0]
	v_pk_fma_f32 v[4:5], v[4:5], v[114:115], v[116:117] op_sel:[0,1,0]
	v_pk_fma_f32 v[16:17], v[16:17], v[114:115], v[118:119] op_sel:[0,1,0]
	v_pk_fma_f32 v[188:189], v[4:5], v[104:105], v[188:189]
	v_pk_fma_f32 v[190:191], v[16:17], v[104:105], v[190:191]
	v_pk_mul_f32 v[120:121], v[156:157], v[82:83] op_sel_hi:[0,1]
	v_pk_mul_f32 v[122:123], v[156:157], v[82:83] op_sel:[1,0]
	v_pk_fma_f32 v[6:7], v[6:7], v[114:115], v[120:121] op_sel:[0,1,0]
	v_pk_fma_f32 v[18:19], v[18:19], v[114:115], v[122:123] op_sel:[0,1,0]
	v_pk_fma_f32 v[188:189], v[6:7], v[106:107], v[188:189]
	v_pk_fma_f32 v[190:191], v[18:19], v[106:107], v[190:191]
	v_add_f32_e64 v192, v188, v189
	v_add_f32_e64 v193, v190, v191
	s_waitcnt lgkmcnt(0)
; __device__ __forceinline__ float red8(float v) { v = red4(v); v += dppf<0x141>(v); return v; }
; __device__ __forceinline__ f32x2 lo2(const f32x4& v) { return __builtin_shufflevector(v, v, 0, 1); }
; __device__ __forceinline__ f32x2 hi2(const f32x4& v) { return __builtin_shufflevector(v, v, 2, 3); }
; __device__ __forceinline__ f32x2 splat2(float x) { return (f32x2){x, x}; }
; #define SCAN_INTERLEAVE(nds, nvalu)                                   \
;   _Pragma("unroll") for (int i_ = 0; i_ < (nds); ++i_) {               \
;     __builtin_amdgcn_sched_group_barrier(0x100, 1, 0);                 \
;     __builtin_amdgcn_sched_group_barrier(0x002, (nvalu), 0);           \
;   }
; __device__ __forceinline__ f32x2 ss_step(f32x2 (&S)[2][8], const SsRegs& R) {
;   const f32x2 dA2 = splat2(R.sc.y);
;   f32x2 out;
; #pragma unroll
;   for (int r = 0; r < 2; ++r) {
;     const f32x2 xdt2 = splat2((r ? R.x.y : R.x.x) * R.sc.x);
;     f32x2 y0 = splat2(0.f), y1 = splat2(0.f);
; #pragma unroll
;     for (int q = 0; q < 4; ++q) {
;       S[r][2 * q] = S[r][2 * q] * dA2 + xdt2 * lo2(R.B[q]);
;       S[r][2 * q + 1] = S[r][2 * q + 1] * dA2 + xdt2 * hi2(R.B[q]);
;       y0 += S[r][2 * q] * lo2(R.C[q]);
;       y1 += S[r][2 * q + 1] * hi2(R.C[q]);
;     }
;     y0 += y1;
;     const float y = red8(y0.x + y0.y);
;     if (r) out.y = y; else out.x = y;
;   }
;   return out;
; }
; __device__ __forceinline__ void scan_ssm(const Params& p, int l, int seq, int h, char* smem, const unsigned* wflags, unsigned wexpect) {
;     ...
;     ss_load(RA, vb, sb, 0, n0, prow0);
;     for (int t = 0; t < nsteps; t += 2) {
;       ss_load(RB, vb, sb, min(t + 1, 15), n0, prow0);
;       const f32x2 y0v = ss_step(S, RA);
;       *(f32x2*)((part == 0) ? (yb + t * 64 + prow0) : ydummy) = y0v;
;       SCAN_INTERLEAVE(10, 5);
;       if (t + 1 < nsteps) {
;         ss_load(RA, vb, sb, min(t + 2, 15), n0, prow0);
;         const f32x2 y1v = ss_step(S, RB);
;         *(f32x2*)((part == 0) ? (yb + (t + 1) * 64 + prow0) : ydummy) = y1v;
;         SCAN_INTERLEAVE(10, 5);
;       }
;     }
	s_nop 0
	ds_read_b64 v[112:113], v152 offset:4864
	ds_read_b64 v[114:115], v153 offset:40984
	ds_read_b128 v[72:75], v150 offset:3872
	ds_read_b128 v[96:99], v150 offset:4384
	ds_read_b128 v[80:83], v151 offset:3888
	ds_read_b128 v[104:107], v151 offset:4400
	v_pk_mul_f32 v[156:157], v[108:109], v[110:111] op_sel_hi:[1,0]
	v_pk_mul_f32 v[116:117], v[156:157], v[60:61] op_sel_hi:[0,1]
	v_pk_mul_f32 v[118:119], v[156:157], v[60:61] op_sel:[1,0]
	v_pk_fma_f32 v[28:29], v[28:29], v[110:111], v[116:117] op_sel:[0,1,0]
	v_pk_fma_f32 v[24:25], v[24:25], v[110:111], v[118:119] op_sel:[0,1,0]
	v_pk_mul_f32 v[188:189], v[28:29], v[84:85]
	v_pk_mul_f32 v[190:191], v[24:25], v[84:85]
	v_add_f32_dpp v192, v192, v192 quad_perm:[1,0,3,2] row_mask:0xf bank_mask:0xf bound_ctrl:1
	v_add_f32_dpp v193, v193, v193 quad_perm:[1,0,3,2] row_mask:0xf bank_mask:0xf bound_ctrl:1
	v_pk_mul_f32 v[120:121], v[156:157], v[62:63] op_sel_hi:[0,1]
	v_pk_mul_f32 v[122:123], v[156:157], v[62:63] op_sel:[1,0]
	v_pk_fma_f32 v[30:31], v[30:31], v[110:111], v[120:121] op_sel:[0,1,0]
	v_pk_fma_f32 v[26:27], v[26:27], v[110:111], v[122:123] op_sel:[0,1,0]
	v_pk_fma_f32 v[188:189], v[30:31], v[86:87], v[188:189]
	v_pk_fma_f32 v[190:191], v[26:27], v[86:87], v[190:191]
	v_add_f32_dpp v192, v192, v192 quad_perm:[2,3,0,1] row_mask:0xf bank_mask:0xf bound_ctrl:1
	v_add_f32_dpp v193, v193, v193 quad_perm:[2,3,0,1] row_mask:0xf bank_mask:0xf bound_ctrl:1
	v_pk_mul_f32 v[116:117], v[156:157], v[64:65] op_sel_hi:[0,1]
	v_pk_mul_f32 v[118:119], v[156:157], v[64:65] op_sel:[1,0]
	v_pk_fma_f32 v[12:13], v[12:13], v[110:111], v[116:117] op_sel:[0,1,0]
	v_pk_fma_f32 v[32:33], v[32:33], v[110:111], v[118:119] op_sel:[0,1,0]
	v_pk_fma_f32 v[188:189], v[12:13], v[88:89], v[188:189]
	v_pk_fma_f32 v[190:191], v[32:33], v[88:89], v[190:191]
	v_add_f32_dpp v192, v192, v192 row_half_mirror row_mask:0xf bank_mask:0xf bound_ctrl:1
	v_add_f32_dpp v193, v193, v193 row_half_mirror row_mask:0xf bank_mask:0xf bound_ctrl:1
	v_pk_mul_f32 v[120:121], v[156:157], v[66:67] op_sel_hi:[0,1]
	v_pk_mul_f32 v[122:123], v[156:157], v[66:67] op_sel:[1,0]
	v_pk_fma_f32 v[14:15], v[14:15], v[110:111], v[120:121] op_sel:[0,1,0]
	v_pk_fma_f32 v[34:35], v[34:35], v[110:111], v[122:123] op_sel:[0,1,0]
	v_pk_fma_f32 v[188:189], v[14:15], v[90:91], v[188:189]
	v_pk_fma_f32 v[190:191], v[34:35], v[90:91], v[190:191]
	ds_read_b128 v[60:63], v150 offset:3840
	ds_read_b128 v[84:87], v150 offset:4352
	ds_read_b128 v[64:67], v151 offset:3856
	ds_read_b128 v[88:91], v151 offset:4368
	ds_write_b64 v154, v[192:193] offset:256
	v_pk_mul_f32 v[116:117], v[156:157], v[68:69] op_sel_hi:[0,1]
	v_pk_mul_f32 v[118:119], v[156:157], v[68:69] op_sel:[1,0]
	v_pk_fma_f32 v[8:9], v[8:9], v[110:111], v[116:117] op_sel:[0,1,0]
	v_pk_fma_f32 v[20:21], v[20:21], v[110:111], v[118:119] op_sel:[0,1,0]
	v_pk_fma_f32 v[188:189], v[8:9], v[92:93], v[188:189]
	v_pk_fma_f32 v[190:191], v[20:21], v[92:93], v[190:191]
	v_pk_mul_f32 v[120:121], v[156:157], v[70:71] op_sel_hi:[0,1]
	v_pk_mul_f32 v[122:123], v[156:157], v[70:71] op_sel:[1,0]
	v_pk_fma_f32 v[10:11], v[10:11], v[110:111], v[120:121] op_sel:[0,1,0]
	v_pk_fma_f32 v[22:23], v[22:23], v[110:111], v[122:123] op_sel:[0,1,0]
	v_pk_fma_f32 v[188:189], v[10:11], v[94:95], v[188:189]
	v_pk_fma_f32 v[190:191], v[22:23], v[94:95], v[190:191]
	v_pk_mul_f32 v[116:117], v[156:157], v[76:77] op_sel_hi:[0,1]
	v_pk_mul_f32 v[118:119], v[156:157], v[76:77] op_sel:[1,0]
	v_pk_fma_f32 v[4:5], v[4:5], v[110:111], v[116:117] op_sel:[0,1,0]
	v_pk_fma_f32 v[16:17], v[16:17], v[110:111], v[118:119] op_sel:[0,1,0]
	v_pk_fma_f32 v[188:189], v[4:5], v[100:101], v[188:189]
	v_pk_fma_f32 v[190:191], v[16:17], v[100:101], v[190:191]
	v_pk_mul_f32 v[120:121], v[156:157], v[78:79] op_sel_hi:[0,1]
	v_pk_mul_f32 v[122:123], v[156:157], v[78:79] op_sel:[1,0]
	v_pk_fma_f32 v[6:7], v[6:7], v[110:111], v[120:121] op_sel:[0,1,0]
	v_pk_fma_f32 v[18:19], v[18:19], v[110:111], v[122:123] op_sel:[0,1,0]
	v_pk_fma_f32 v[188:189], v[6:7], v[102:103], v[188:189]
	v_pk_fma_f32 v[190:191], v[18:19], v[102:103], v[190:191]
	v_add_f32_e64 v192, v188, v189
	v_add_f32_e64 v193, v190, v191
	s_waitcnt lgkmcnt(0)
	s_nop 0
	ds_read_b64 v[108:109], v152 offset:6144
	ds_read_b64 v[110:111], v153 offset:40992
	ds_read_b128 v[68:71], v150 offset:5152
	ds_read_b128 v[92:95], v150 offset:5664
	ds_read_b128 v[76:79], v151 offset:5168
	ds_read_b128 v[100:103], v151 offset:5680
	v_pk_mul_f32 v[156:157], v[112:113], v[114:115] op_sel_hi:[1,0]
	v_pk_mul_f32 v[116:117], v[156:157], v[60:61] op_sel_hi:[0,1]
	v_pk_mul_f32 v[118:119], v[156:157], v[60:61] op_sel:[1,0]
	v_pk_fma_f32 v[28:29], v[28:29], v[114:115], v[116:117] op_sel:[0,1,0]
	v_pk_fma_f32 v[24:25], v[24:25], v[114:115], v[118:119] op_sel:[0,1,0]
	v_pk_mul_f32 v[188:189], v[28:29], v[84:85]
	v_pk_mul_f32 v[190:191], v[24:25], v[84:85]
	v_add_f32_dpp v192, v192, v192 quad_perm:[1,0,3,2] row_mask:0xf bank_mask:0xf bound_ctrl:1
	v_add_f32_dpp v193, v193, v193 quad_perm:[1,0,3,2] row_mask:0xf bank_mask:0xf bound_ctrl:1
	v_pk_mul_f32 v[120:121], v[156:157], v[62:63] op_sel_hi:[0,1]
	v_pk_mul_f32 v[122:123], v[156:157], v[62:63] op_sel:[1,0]
	v_pk_fma_f32 v[30:31], v[30:31], v[114:115], v[120:121] op_sel:[0,1,0]
	v_pk_fma_f32 v[26:27], v[26:27], v[114:115], v[122:123] op_sel:[0,1,0]
	v_pk_fma_f32 v[188:189], v[30:31], v[86:87], v[188:189]
	v_pk_fma_f32 v[190:191], v[26:27], v[86:87], v[190:191]
	v_add_f32_dpp v192, v192, v192 quad_perm:[2,3,0,1] row_mask:0xf bank_mask:0xf bound_ctrl:1
	v_add_f32_dpp v193, v193, v193 quad_perm:[2,3,0,1] row_mask:0xf bank_mask:0xf bound_ctrl:1
	v_pk_mul_f32 v[116:117], v[156:157], v[64:65] op_sel_hi:[0,1]
; __device__ __forceinline__ float red8(float v) { v = red4(v); v += dppf<0x141>(v); return v; }
; __device__ __forceinline__ f32x2 lo2(const f32x4& v) { return __builtin_shufflevector(v, v, 0, 1); }
; __device__ __forceinline__ f32x2 hi2(const f32x4& v) { return __builtin_shufflevector(v, v, 2, 3); }
; __device__ __forceinline__ f32x2 splat2(float x) { return (f32x2){x, x}; }
; #define SCAN_INTERLEAVE(nds, nvalu)                                   \
;   _Pragma("unroll") for (int i_ = 0; i_ < (nds); ++i_) {               \
;     __builtin_amdgcn_sched_group_barrier(0x100, 1, 0);                 \
;     __builtin_amdgcn_sched_group_barrier(0x002, (nvalu), 0);           \
;   }
; __device__ __forceinline__ f32x2 ss_step(f32x2 (&S)[2][8], const SsRegs& R) {
;   const f32x2 dA2 = splat2(R.sc.y);
;   f32x2 out;
; #pragma unroll
;   for (int r = 0; r < 2; ++r) {
;     const f32x2 xdt2 = splat2((r ? R.x.y : R.x.x) * R.sc.x);
;     f32x2 y0 = splat2(0.f), y1 = splat2(0.f);
; #pragma unroll
;     for (int q = 0; q < 4; ++q) {
;       S[r][2 * q] = S[r][2 * q] * dA2 + xdt2 * lo2(R.B[q]);
;       S[r][2 * q + 1] = S[r][2 * q + 1] * dA2 + xdt2 * hi2(R.B[q]);
;       y0 += S[r][2 * q] * lo2(R.C[q]);
;       y1 += S[r][2 * q + 1] * hi2(R.C[q]);
;     }
;     y0 += y1;
;     const float y = red8(y0.x + y0.y);
;     if (r) out.y = y; else out.x = y;
;   }
;   return out;
; }
; __device__ __forceinline__ void scan_ssm(const Params& p, int l, int seq, int h, char* smem, const unsigned* wflags, unsigned wexpect) {
;     ...
;     ss_load(RA, vb, sb, 0, n0, prow0);
;     for (int t = 0; t < nsteps; t += 2) {
;       ss_load(RB, vb, sb, min(t + 1, 15), n0, prow0);
;       const f32x2 y0v = ss_step(S, RA);
;       *(f32x2*)((part == 0) ? (yb + t * 64 + prow0) : ydummy) = y0v;
;       SCAN_INTERLEAVE(10, 5);
;       if (t + 1 < nsteps) {
;         ss_load(RA, vb, sb, min(t + 2, 15), n0, prow0);
;         const f32x2 y1v = ss_step(S, RB);
;         *(f32x2*)((part == 0) ? (yb + (t + 1) * 64 + prow0) : ydummy) = y1v;
;         SCAN_INTERLEAVE(10, 5);
;       }
;     }
	v_pk_mul_f32 v[118:119], v[156:157], v[64:65] op_sel:[1,0]
	v_pk_fma_f32 v[12:13], v[12:13], v[114:115], v[116:117] op_sel:[0,1,0]
	v_pk_fma_f32 v[32:33], v[32:33], v[114:115], v[118:119] op_sel:[0,1,0]
	v_pk_fma_f32 v[188:189], v[12:13], v[88:89], v[188:189]
	v_pk_fma_f32 v[190:191], v[32:33], v[88:89], v[190:191]
	v_add_f32_dpp v192, v192, v192 row_half_mirror row_mask:0xf bank_mask:0xf bound_ctrl:1
	v_add_f32_dpp v193, v193, v193 row_half_mirror row_mask:0xf bank_mask:0xf bound_ctrl:1
	v_pk_mul_f32 v[120:121], v[156:157], v[66:67] op_sel_hi:[0,1]
	v_pk_mul_f32 v[122:123], v[156:157], v[66:67] op_sel:[1,0]
	v_pk_fma_f32 v[14:15], v[14:15], v[114:115], v[120:121] op_sel:[0,1,0]
	v_pk_fma_f32 v[34:35], v[34:35], v[114:115], v[122:123] op_sel:[0,1,0]
	v_pk_fma_f32 v[188:189], v[14:15], v[90:91], v[188:189]
	v_pk_fma_f32 v[190:191], v[34:35], v[90:91], v[190:191]
	ds_read_b128 v[60:63], v150 offset:5120
	ds_read_b128 v[84:87], v150 offset:5632
	ds_read_b128 v[64:67], v151 offset:5136
	ds_read_b128 v[88:91], v151 offset:5648
	ds_write_b64 v154, v[192:193] offset:512
	v_pk_mul_f32 v[116:117], v[156:157], v[72:73] op_sel_hi:[0,1]
	v_pk_mul_f32 v[118:119], v[156:157], v[72:73] op_sel:[1,0]
	v_pk_fma_f32 v[8:9], v[8:9], v[114:115], v[116:117] op_sel:[0,1,0]
	v_pk_fma_f32 v[20:21], v[20:21], v[114:115], v[118:119] op_sel:[0,1,0]
	v_pk_fma_f32 v[188:189], v[8:9], v[96:97], v[188:189]
	v_pk_fma_f32 v[190:191], v[20:21], v[96:97], v[190:191]
	v_pk_mul_f32 v[120:121], v[156:157], v[74:75] op_sel_hi:[0,1]
	v_pk_mul_f32 v[122:123], v[156:157], v[74:75] op_sel:[1,0]
	v_pk_fma_f32 v[10:11], v[10:11], v[114:115], v[120:121] op_sel:[0,1,0]
	v_pk_fma_f32 v[22:23], v[22:23], v[114:115], v[122:123] op_sel:[0,1,0]
	v_pk_fma_f32 v[188:189], v[10:11], v[98:99], v[188:189]
	v_pk_fma_f32 v[190:191], v[22:23], v[98:99], v[190:191]
	v_pk_mul_f32 v[116:117], v[156:157], v[80:81] op_sel_hi:[0,1]
	v_pk_mul_f32 v[118:119], v[156:157], v[80:81] op_sel:[1,0]
	v_pk_fma_f32 v[4:5], v[4:5], v[114:115], v[116:117] op_sel:[0,1,0]
	v_pk_fma_f32 v[16:17], v[16:17], v[114:115], v[118:119] op_sel:[0,1,0]
	v_pk_fma_f32 v[188:189], v[4:5], v[104:105], v[188:189]
	v_pk_fma_f32 v[190:191], v[16:17], v[104:105], v[190:191]
	v_pk_mul_f32 v[120:121], v[156:157], v[82:83] op_sel_hi:[0,1]
	v_pk_mul_f32 v[122:123], v[156:157], v[82:83] op_sel:[1,0]
	v_pk_fma_f32 v[6:7], v[6:7], v[114:115], v[120:121] op_sel:[0,1,0]
	v_pk_fma_f32 v[18:19], v[18:19], v[114:115], v[122:123] op_sel:[0,1,0]
	v_pk_fma_f32 v[188:189], v[6:7], v[106:107], v[188:189]
	v_pk_fma_f32 v[190:191], v[18:19], v[106:107], v[190:191]
	v_add_f32_e64 v192, v188, v189
	v_add_f32_e64 v193, v190, v191
	s_waitcnt lgkmcnt(0)
	s_nop 0
	ds_read_b64 v[112:113], v152 offset:7424
	ds_read_b64 v[114:115], v153 offset:41000
	ds_read_b128 v[72:75], v150 offset:6432
	ds_read_b128 v[96:99], v150 offset:6944
	ds_read_b128 v[80:83], v151 offset:6448
	ds_read_b128 v[104:107], v151 offset:6960
	v_pk_mul_f32 v[156:157], v[108:109], v[110:111] op_sel_hi:[1,0]
	v_pk_mul_f32 v[116:117], v[156:157], v[60:61] op_sel_hi:[0,1]
	v_pk_mul_f32 v[118:119], v[156:157], v[60:61] op_sel:[1,0]
	v_pk_fma_f32 v[28:29], v[28:29], v[110:111], v[116:117] op_sel:[0,1,0]
	v_pk_fma_f32 v[24:25], v[24:25], v[110:111], v[118:119] op_sel:[0,1,0]
	v_pk_mul_f32 v[188:189], v[28:29], v[84:85]
	v_pk_mul_f32 v[190:191], v[24:25], v[84:85]
	v_add_f32_dpp v192, v192, v192 quad_perm:[1,0,3,2] row_mask:0xf bank_mask:0xf bound_ctrl:1
	v_add_f32_dpp v193, v193, v193 quad_perm:[1,0,3,2] row_mask:0xf bank_mask:0xf bound_ctrl:1
	v_pk_mul_f32 v[120:121], v[156:157], v[62:63] op_sel_hi:[0,1]
	v_pk_mul_f32 v[122:123], v[156:157], v[62:63] op_sel:[1,0]
	v_pk_fma_f32 v[30:31], v[30:31], v[110:111], v[120:121] op_sel:[0,1,0]
	v_pk_fma_f32 v[26:27], v[26:27], v[110:111], v[122:123] op_sel:[0,1,0]
	v_pk_fma_f32 v[188:189], v[30:31], v[86:87], v[188:189]
	v_pk_fma_f32 v[190:191], v[26:27], v[86:87], v[190:191]
	v_add_f32_dpp v192, v192, v192 quad_perm:[2,3,0,1] row_mask:0xf bank_mask:0xf bound_ctrl:1
	v_add_f32_dpp v193, v193, v193 quad_perm:[2,3,0,1] row_mask:0xf bank_mask:0xf bound_ctrl:1
	v_pk_mul_f32 v[116:117], v[156:157], v[64:65] op_sel_hi:[0,1]
	v_pk_mul_f32 v[118:119], v[156:157], v[64:65] op_sel:[1,0]
	v_pk_fma_f32 v[12:13], v[12:13], v[110:111], v[116:117] op_sel:[0,1,0]
	v_pk_fma_f32 v[32:33], v[32:33], v[110:111], v[118:119] op_sel:[0,1,0]
	v_pk_fma_f32 v[188:189], v[12:13], v[88:89], v[188:189]
	v_pk_fma_f32 v[190:191], v[32:33], v[88:89], v[190:191]
	v_add_f32_dpp v192, v192, v192 row_half_mirror row_mask:0xf bank_mask:0xf bound_ctrl:1
	v_add_f32_dpp v193, v193, v193 row_half_mirror row_mask:0xf bank_mask:0xf bound_ctrl:1
	v_pk_mul_f32 v[120:121], v[156:157], v[66:67] op_sel_hi:[0,1]
	v_pk_mul_f32 v[122:123], v[156:157], v[66:67] op_sel:[1,0]
	v_pk_fma_f32 v[14:15], v[14:15], v[110:111], v[120:121] op_sel:[0,1,0]
	v_pk_fma_f32 v[34:35], v[34:35], v[110:111], v[122:123] op_sel:[0,1,0]
	v_pk_fma_f32 v[188:189], v[14:15], v[90:91], v[188:189]
	v_pk_fma_f32 v[190:191], v[34:35], v[90:91], v[190:191]
	ds_read_b128 v[60:63], v150 offset:6400
	ds_read_b128 v[84:87], v150 offset:6912
	ds_read_b128 v[64:67], v151 offset:6416
	ds_read_b128 v[88:91], v151 offset:6928
	ds_write_b64 v154, v[192:193] offset:768
	v_pk_mul_f32 v[116:117], v[156:157], v[68:69] op_sel_hi:[0,1]
	v_pk_mul_f32 v[118:119], v[156:157], v[68:69] op_sel:[1,0]
	v_pk_fma_f32 v[8:9], v[8:9], v[110:111], v[116:117] op_sel:[0,1,0]
	v_pk_fma_f32 v[20:21], v[20:21], v[110:111], v[118:119] op_sel:[0,1,0]
	v_pk_fma_f32 v[188:189], v[8:9], v[92:93], v[188:189]
	v_pk_fma_f32 v[190:191], v[20:21], v[92:93], v[190:191]
	v_pk_mul_f32 v[120:121], v[156:157], v[70:71] op_sel_hi:[0,1]
	v_pk_mul_f32 v[122:123], v[156:157], v[70:71] op_sel:[1,0]
	v_pk_fma_f32 v[10:11], v[10:11], v[110:111], v[120:121] op_sel:[0,1,0]
	v_pk_fma_f32 v[22:23], v[22:23], v[110:111], v[122:123] op_sel:[0,1,0]
	v_pk_fma_f32 v[188:189], v[10:11], v[94:95], v[188:189]
	v_pk_fma_f32 v[190:191], v[22:23], v[94:95], v[190:191]
	v_pk_mul_f32 v[116:117], v[156:157], v[76:77] op_sel_hi:[0,1]
	v_pk_mul_f32 v[118:119], v[156:157], v[76:77] op_sel:[1,0]
	v_pk_fma_f32 v[4:5], v[4:5], v[110:111], v[116:117] op_sel:[0,1,0]
	v_pk_fma_f32 v[16:17], v[16:17], v[110:111], v[118:119] op_sel:[0,1,0]
	v_pk_fma_f32 v[188:189], v[4:5], v[100:101], v[188:189]
	v_pk_fma_f32 v[190:191], v[16:17], v[100:101], v[190:191]
	v_pk_mul_f32 v[120:121], v[156:157], v[78:79] op_sel_hi:[0,1]
	v_pk_mul_f32 v[122:123], v[156:157], v[78:79] op_sel:[1,0]
	v_pk_fma_f32 v[6:7], v[6:7], v[110:111], v[120:121] op_sel:[0,1,0]
	v_pk_fma_f32 v[18:19], v[18:19], v[110:111], v[122:123] op_sel:[0,1,0]
	v_pk_fma_f32 v[188:189], v[6:7], v[102:103], v[188:189]
	v_pk_fma_f32 v[190:191], v[18:19], v[102:103], v[190:191]
	v_add_f32_e64 v192, v188, v189
	v_add_f32_e64 v193, v190, v191
	s_waitcnt lgkmcnt(0)
; __device__ __forceinline__ float red8(float v) { v = red4(v); v += dppf<0x141>(v); return v; }
; __device__ __forceinline__ f32x2 lo2(const f32x4& v) { return __builtin_shufflevector(v, v, 0, 1); }
; __device__ __forceinline__ f32x2 hi2(const f32x4& v) { return __builtin_shufflevector(v, v, 2, 3); }
; __device__ __forceinline__ f32x2 splat2(float x) { return (f32x2){x, x}; }
; #define SCAN_INTERLEAVE(nds, nvalu)                                   \
;   _Pragma("unroll") for (int i_ = 0; i_ < (nds); ++i_) {               \
;     __builtin_amdgcn_sched_group_barrier(0x100, 1, 0);                 \
;     __builtin_amdgcn_sched_group_barrier(0x002, (nvalu), 0);           \
;   }
; __device__ __forceinline__ f32x2 ss_step(f32x2 (&S)[2][8], const SsRegs& R) {
;   const f32x2 dA2 = splat2(R.sc.y);
;   f32x2 out;
; #pragma unroll
;   for (int r = 0; r < 2; ++r) {
;     const f32x2 xdt2 = splat2((r ? R.x.y : R.x.x) * R.sc.x);
;     f32x2 y0 = splat2(0.f), y1 = splat2(0.f);
; #pragma unroll
;     for (int q = 0; q < 4; ++q) {
;       S[r][2 * q] = S[r][2 * q] * dA2 + xdt2 * lo2(R.B[q]);
;       S[r][2 * q + 1] = S[r][2 * q + 1] * dA2 + xdt2 * hi2(R.B[q]);
;       y0 += S[r][2 * q] * lo2(R.C[q]);
;       y1 += S[r][2 * q + 1] * hi2(R.C[q]);
;     }
;     y0 += y1;
;     const float y = red8(y0.x + y0.y);
;     if (r) out.y = y; else out.x = y;
;   }
;   return out;
; }
; __device__ __forceinline__ void scan_ssm(const Params& p, int l, int seq, int h, char* smem, const unsigned* wflags, unsigned wexpect) {
;     ...
;     ss_load(RA, vb, sb, 0, n0, prow0);
;     for (int t = 0; t < nsteps; t += 2) {
;       ss_load(RB, vb, sb, min(t + 1, 15), n0, prow0);
;       const f32x2 y0v = ss_step(S, RA);
;       *(f32x2*)((part == 0) ? (yb + t * 64 + prow0) : ydummy) = y0v;
;       SCAN_INTERLEAVE(10, 5);
;       if (t + 1 < nsteps) {
;         ss_load(RA, vb, sb, min(t + 2, 15), n0, prow0);
;         const f32x2 y1v = ss_step(S, RB);
;         *(f32x2*)((part == 0) ? (yb + (t + 1) * 64 + prow0) : ydummy) = y1v;
;         SCAN_INTERLEAVE(10, 5);
;       }
;     }
	s_nop 0
	ds_read_b64 v[108:109], v152 offset:8704
	ds_read_b64 v[110:111], v153 offset:41008
	ds_read_b128 v[68:71], v150 offset:7712
	ds_read_b128 v[92:95], v150 offset:8224
	ds_read_b128 v[76:79], v151 offset:7728
	ds_read_b128 v[100:103], v151 offset:8240
	v_pk_mul_f32 v[156:157], v[112:113], v[114:115] op_sel_hi:[1,0]
	v_pk_mul_f32 v[116:117], v[156:157], v[60:61] op_sel_hi:[0,1]
	v_pk_mul_f32 v[118:119], v[156:157], v[60:61] op_sel:[1,0]
	v_pk_fma_f32 v[28:29], v[28:29], v[114:115], v[116:117] op_sel:[0,1,0]
	v_pk_fma_f32 v[24:25], v[24:25], v[114:115], v[118:119] op_sel:[0,1,0]
	v_pk_mul_f32 v[188:189], v[28:29], v[84:85]
	v_pk_mul_f32 v[190:191], v[24:25], v[84:85]
	v_add_f32_dpp v192, v192, v192 quad_perm:[1,0,3,2] row_mask:0xf bank_mask:0xf bound_ctrl:1
	v_add_f32_dpp v193, v193, v193 quad_perm:[1,0,3,2] row_mask:0xf bank_mask:0xf bound_ctrl:1
	v_pk_mul_f32 v[120:121], v[156:157], v[62:63] op_sel_hi:[0,1]
	v_pk_mul_f32 v[122:123], v[156:157], v[62:63] op_sel:[1,0]
	v_pk_fma_f32 v[30:31], v[30:31], v[114:115], v[120:121] op_sel:[0,1,0]
	v_pk_fma_f32 v[26:27], v[26:27], v[114:115], v[122:123] op_sel:[0,1,0]
	v_pk_fma_f32 v[188:189], v[30:31], v[86:87], v[188:189]
	v_pk_fma_f32 v[190:191], v[26:27], v[86:87], v[190:191]
	v_add_f32_dpp v192, v192, v192 quad_perm:[2,3,0,1] row_mask:0xf bank_mask:0xf bound_ctrl:1
	v_add_f32_dpp v193, v193, v193 quad_perm:[2,3,0,1] row_mask:0xf bank_mask:0xf bound_ctrl:1
	v_pk_mul_f32 v[116:117], v[156:157], v[64:65] op_sel_hi:[0,1]
	v_pk_mul_f32 v[118:119], v[156:157], v[64:65] op_sel:[1,0]
	v_pk_fma_f32 v[12:13], v[12:13], v[114:115], v[116:117] op_sel:[0,1,0]
	v_pk_fma_f32 v[32:33], v[32:33], v[114:115], v[118:119] op_sel:[0,1,0]
	v_pk_fma_f32 v[188:189], v[12:13], v[88:89], v[188:189]
	v_pk_fma_f32 v[190:191], v[32:33], v[88:89], v[190:191]
	v_add_f32_dpp v192, v192, v192 row_half_mirror row_mask:0xf bank_mask:0xf bound_ctrl:1
	v_add_f32_dpp v193, v193, v193 row_half_mirror row_mask:0xf bank_mask:0xf bound_ctrl:1
	v_pk_mul_f32 v[120:121], v[156:157], v[66:67] op_sel_hi:[0,1]
	v_pk_mul_f32 v[122:123], v[156:157], v[66:67] op_sel:[1,0]
	v_pk_fma_f32 v[14:15], v[14:15], v[114:115], v[120:121] op_sel:[0,1,0]
	v_pk_fma_f32 v[34:35], v[34:35], v[114:115], v[122:123] op_sel:[0,1,0]
	v_pk_fma_f32 v[188:189], v[14:15], v[90:91], v[188:189]
	v_pk_fma_f32 v[190:191], v[34:35], v[90:91], v[190:191]
	ds_read_b128 v[60:63], v150 offset:7680
	ds_read_b128 v[84:87], v150 offset:8192
	ds_read_b128 v[64:67], v151 offset:7696
	ds_read_b128 v[88:91], v151 offset:8208
	ds_write_b64 v154, v[192:193] offset:1024
	v_pk_mul_f32 v[116:117], v[156:157], v[72:73] op_sel_hi:[0,1]
	v_pk_mul_f32 v[118:119], v[156:157], v[72:73] op_sel:[1,0]
	v_pk_fma_f32 v[8:9], v[8:9], v[114:115], v[116:117] op_sel:[0,1,0]
	v_pk_fma_f32 v[20:21], v[20:21], v[114:115], v[118:119] op_sel:[0,1,0]
	v_pk_fma_f32 v[188:189], v[8:9], v[96:97], v[188:189]
	v_pk_fma_f32 v[190:191], v[20:21], v[96:97], v[190:191]
	v_pk_mul_f32 v[120:121], v[156:157], v[74:75] op_sel_hi:[0,1]
	v_pk_mul_f32 v[122:123], v[156:157], v[74:75] op_sel:[1,0]
	v_pk_fma_f32 v[10:11], v[10:11], v[114:115], v[120:121] op_sel:[0,1,0]
	v_pk_fma_f32 v[22:23], v[22:23], v[114:115], v[122:123] op_sel:[0,1,0]
	v_pk_fma_f32 v[188:189], v[10:11], v[98:99], v[188:189]
	v_pk_fma_f32 v[190:191], v[22:23], v[98:99], v[190:191]
	v_pk_mul_f32 v[116:117], v[156:157], v[80:81] op_sel_hi:[0,1]
	v_pk_mul_f32 v[118:119], v[156:157], v[80:81] op_sel:[1,0]
	v_pk_fma_f32 v[4:5], v[4:5], v[114:115], v[116:117] op_sel:[0,1,0]
	v_pk_fma_f32 v[16:17], v[16:17], v[114:115], v[118:119] op_sel:[0,1,0]
	v_pk_fma_f32 v[188:189], v[4:5], v[104:105], v[188:189]
	v_pk_fma_f32 v[190:191], v[16:17], v[104:105], v[190:191]
	v_pk_mul_f32 v[120:121], v[156:157], v[82:83] op_sel_hi:[0,1]
	v_pk_mul_f32 v[122:123], v[156:157], v[82:83] op_sel:[1,0]
	v_pk_fma_f32 v[6:7], v[6:7], v[114:115], v[120:121] op_sel:[0,1,0]
	v_pk_fma_f32 v[18:19], v[18:19], v[114:115], v[122:123] op_sel:[0,1,0]
	v_pk_fma_f32 v[188:189], v[6:7], v[106:107], v[188:189]
	v_pk_fma_f32 v[190:191], v[18:19], v[106:107], v[190:191]
	v_add_f32_e64 v192, v188, v189
	v_add_f32_e64 v193, v190, v191
	s_waitcnt lgkmcnt(0)
	s_nop 0
	ds_read_b64 v[112:113], v152 offset:9984
	ds_read_b64 v[114:115], v153 offset:41016
	ds_read_b128 v[72:75], v150 offset:8992
	ds_read_b128 v[96:99], v150 offset:9504
	ds_read_b128 v[80:83], v151 offset:9008
	ds_read_b128 v[104:107], v151 offset:9520
	v_pk_mul_f32 v[156:157], v[108:109], v[110:111] op_sel_hi:[1,0]
	v_pk_mul_f32 v[116:117], v[156:157], v[60:61] op_sel_hi:[0,1]
	v_pk_mul_f32 v[118:119], v[156:157], v[60:61] op_sel:[1,0]
	v_pk_fma_f32 v[28:29], v[28:29], v[110:111], v[116:117] op_sel:[0,1,0]
	v_pk_fma_f32 v[24:25], v[24:25], v[110:111], v[118:119] op_sel:[0,1,0]
	v_pk_mul_f32 v[188:189], v[28:29], v[84:85]
	v_pk_mul_f32 v[190:191], v[24:25], v[84:85]
	v_add_f32_dpp v192, v192, v192 quad_perm:[1,0,3,2] row_mask:0xf bank_mask:0xf bound_ctrl:1
	v_add_f32_dpp v193, v193, v193 quad_perm:[1,0,3,2] row_mask:0xf bank_mask:0xf bound_ctrl:1
	v_pk_mul_f32 v[120:121], v[156:157], v[62:63] op_sel_hi:[0,1]
	v_pk_mul_f32 v[122:123], v[156:157], v[62:63] op_sel:[1,0]
	v_pk_fma_f32 v[30:31], v[30:31], v[110:111], v[120:121] op_sel:[0,1,0]
	v_pk_fma_f32 v[26:27], v[26:27], v[110:111], v[122:123] op_sel:[0,1,0]
	v_pk_fma_f32 v[188:189], v[30:31], v[86:87], v[188:189]
	v_pk_fma_f32 v[190:191], v[26:27], v[86:87], v[190:191]
	v_add_f32_dpp v192, v192, v192 quad_perm:[2,3,0,1] row_mask:0xf bank_mask:0xf bound_ctrl:1
	v_add_f32_dpp v193, v193, v193 quad_perm:[2,3,0,1] row_mask:0xf bank_mask:0xf bound_ctrl:1
	v_pk_mul_f32 v[116:117], v[156:157], v[64:65] op_sel_hi:[0,1]
; __device__ __forceinline__ float red8(float v) { v = red4(v); v += dppf<0x141>(v); return v; }
; __device__ __forceinline__ f32x2 lo2(const f32x4& v) { return __builtin_shufflevector(v, v, 0, 1); }
; __device__ __forceinline__ f32x2 hi2(const f32x4& v) { return __builtin_shufflevector(v, v, 2, 3); }
; __device__ __forceinline__ f32x2 splat2(float x) { return (f32x2){x, x}; }
; #define SCAN_INTERLEAVE(nds, nvalu)                                   \
;   _Pragma("unroll") for (int i_ = 0; i_ < (nds); ++i_) {               \
;     __builtin_amdgcn_sched_group_barrier(0x100, 1, 0);                 \
;     __builtin_amdgcn_sched_group_barrier(0x002, (nvalu), 0);           \
;   }
; __device__ __forceinline__ f32x2 ss_step(f32x2 (&S)[2][8], const SsRegs& R) {
;   const f32x2 dA2 = splat2(R.sc.y);
;   f32x2 out;
; #pragma unroll
;   for (int r = 0; r < 2; ++r) {
;     const f32x2 xdt2 = splat2((r ? R.x.y : R.x.x) * R.sc.x);
;     f32x2 y0 = splat2(0.f), y1 = splat2(0.f);
; #pragma unroll
;     for (int q = 0; q < 4; ++q) {
;       S[r][2 * q] = S[r][2 * q] * dA2 + xdt2 * lo2(R.B[q]);
;       S[r][2 * q + 1] = S[r][2 * q + 1] * dA2 + xdt2 * hi2(R.B[q]);
;       y0 += S[r][2 * q] * lo2(R.C[q]);
;       y1 += S[r][2 * q + 1] * hi2(R.C[q]);
;     }
;     y0 += y1;
;     const float y = red8(y0.x + y0.y);
;     if (r) out.y = y; else out.x = y;
;   }
;   return out;
; }
; __device__ __forceinline__ void scan_ssm(const Params& p, int l, int seq, int h, char* smem, const unsigned* wflags, unsigned wexpect) {
;     ...
;     ss_load(RA, vb, sb, 0, n0, prow0);
;     for (int t = 0; t < nsteps; t += 2) {
;       ss_load(RB, vb, sb, min(t + 1, 15), n0, prow0);
;       const f32x2 y0v = ss_step(S, RA);
;       *(f32x2*)((part == 0) ? (yb + t * 64 + prow0) : ydummy) = y0v;
;       SCAN_INTERLEAVE(10, 5);
;       if (t + 1 < nsteps) {
;         ss_load(RA, vb, sb, min(t + 2, 15), n0, prow0);
;         const f32x2 y1v = ss_step(S, RB);
;         *(f32x2*)((part == 0) ? (yb + (t + 1) * 64 + prow0) : ydummy) = y1v;
;         SCAN_INTERLEAVE(10, 5);
;       }
;     }
	v_pk_mul_f32 v[118:119], v[156:157], v[64:65] op_sel:[1,0]
	v_pk_fma_f32 v[12:13], v[12:13], v[110:111], v[116:117] op_sel:[0,1,0]
	v_pk_fma_f32 v[32:33], v[32:33], v[110:111], v[118:119] op_sel:[0,1,0]
	v_pk_fma_f32 v[188:189], v[12:13], v[88:89], v[188:189]
	v_pk_fma_f32 v[190:191], v[32:33], v[88:89], v[190:191]
	v_add_f32_dpp v192, v192, v192 row_half_mirror row_mask:0xf bank_mask:0xf bound_ctrl:1
	v_add_f32_dpp v193, v193, v193 row_half_mirror row_mask:0xf bank_mask:0xf bound_ctrl:1
	v_pk_mul_f32 v[120:121], v[156:157], v[66:67] op_sel_hi:[0,1]
	v_pk_mul_f32 v[122:123], v[156:157], v[66:67] op_sel:[1,0]
	v_pk_fma_f32 v[14:15], v[14:15], v[110:111], v[120:121] op_sel:[0,1,0]
	v_pk_fma_f32 v[34:35], v[34:35], v[110:111], v[122:123] op_sel:[0,1,0]
	v_pk_fma_f32 v[188:189], v[14:15], v[90:91], v[188:189]
	v_pk_fma_f32 v[190:191], v[34:35], v[90:91], v[190:191]
	ds_read_b128 v[60:63], v150 offset:8960
	ds_read_b128 v[84:87], v150 offset:9472
	ds_read_b128 v[64:67], v151 offset:8976
	ds_read_b128 v[88:91], v151 offset:9488
	ds_write_b64 v154, v[192:193] offset:1280
	v_pk_mul_f32 v[116:117], v[156:157], v[68:69] op_sel_hi:[0,1]
	v_pk_mul_f32 v[118:119], v[156:157], v[68:69] op_sel:[1,0]
	v_pk_fma_f32 v[8:9], v[8:9], v[110:111], v[116:117] op_sel:[0,1,0]
	v_pk_fma_f32 v[20:21], v[20:21], v[110:111], v[118:119] op_sel:[0,1,0]
	v_pk_fma_f32 v[188:189], v[8:9], v[92:93], v[188:189]
	v_pk_fma_f32 v[190:191], v[20:21], v[92:93], v[190:191]
	v_pk_mul_f32 v[120:121], v[156:157], v[70:71] op_sel_hi:[0,1]
	v_pk_mul_f32 v[122:123], v[156:157], v[70:71] op_sel:[1,0]
	v_pk_fma_f32 v[10:11], v[10:11], v[110:111], v[120:121] op_sel:[0,1,0]
	v_pk_fma_f32 v[22:23], v[22:23], v[110:111], v[122:123] op_sel:[0,1,0]
	v_pk_fma_f32 v[188:189], v[10:11], v[94:95], v[188:189]
	v_pk_fma_f32 v[190:191], v[22:23], v[94:95], v[190:191]
	v_pk_mul_f32 v[116:117], v[156:157], v[76:77] op_sel_hi:[0,1]
	v_pk_mul_f32 v[118:119], v[156:157], v[76:77] op_sel:[1,0]
	v_pk_fma_f32 v[4:5], v[4:5], v[110:111], v[116:117] op_sel:[0,1,0]
	v_pk_fma_f32 v[16:17], v[16:17], v[110:111], v[118:119] op_sel:[0,1,0]
	v_pk_fma_f32 v[188:189], v[4:5], v[100:101], v[188:189]
	v_pk_fma_f32 v[190:191], v[16:17], v[100:101], v[190:191]
	v_pk_mul_f32 v[120:121], v[156:157], v[78:79] op_sel_hi:[0,1]
	v_pk_mul_f32 v[122:123], v[156:157], v[78:79] op_sel:[1,0]
	v_pk_fma_f32 v[6:7], v[6:7], v[110:111], v[120:121] op_sel:[0,1,0]
	v_pk_fma_f32 v[18:19], v[18:19], v[110:111], v[122:123] op_sel:[0,1,0]
	v_pk_fma_f32 v[188:189], v[6:7], v[102:103], v[188:189]
	v_pk_fma_f32 v[190:191], v[18:19], v[102:103], v[190:191]
	v_add_f32_e64 v192, v188, v189
	v_add_f32_e64 v193, v190, v191
	s_waitcnt lgkmcnt(0)
	s_nop 0
	ds_read_b64 v[108:109], v152 offset:11264
	ds_read_b64 v[110:111], v153 offset:41024
	ds_read_b128 v[68:71], v150 offset:10272
	ds_read_b128 v[92:95], v150 offset:10784
	ds_read_b128 v[76:79], v151 offset:10288
	ds_read_b128 v[100:103], v151 offset:10800
	v_pk_mul_f32 v[156:157], v[112:113], v[114:115] op_sel_hi:[1,0]
	v_pk_mul_f32 v[116:117], v[156:157], v[60:61] op_sel_hi:[0,1]
	v_pk_mul_f32 v[118:119], v[156:157], v[60:61] op_sel:[1,0]
	v_pk_fma_f32 v[28:29], v[28:29], v[114:115], v[116:117] op_sel:[0,1,0]
	v_pk_fma_f32 v[24:25], v[24:25], v[114:115], v[118:119] op_sel:[0,1,0]
	v_pk_mul_f32 v[188:189], v[28:29], v[84:85]
	v_pk_mul_f32 v[190:191], v[24:25], v[84:85]
	v_add_f32_dpp v192, v192, v192 quad_perm:[1,0,3,2] row_mask:0xf bank_mask:0xf bound_ctrl:1
	v_add_f32_dpp v193, v193, v193 quad_perm:[1,0,3,2] row_mask:0xf bank_mask:0xf bound_ctrl:1
	v_pk_mul_f32 v[120:121], v[156:157], v[62:63] op_sel_hi:[0,1]
	v_pk_mul_f32 v[122:123], v[156:157], v[62:63] op_sel:[1,0]
	v_pk_fma_f32 v[30:31], v[30:31], v[114:115], v[120:121] op_sel:[0,1,0]
	v_pk_fma_f32 v[26:27], v[26:27], v[114:115], v[122:123] op_sel:[0,1,0]
	v_pk_fma_f32 v[188:189], v[30:31], v[86:87], v[188:189]
	v_pk_fma_f32 v[190:191], v[26:27], v[86:87], v[190:191]
	v_add_f32_dpp v192, v192, v192 quad_perm:[2,3,0,1] row_mask:0xf bank_mask:0xf bound_ctrl:1
	v_add_f32_dpp v193, v193, v193 quad_perm:[2,3,0,1] row_mask:0xf bank_mask:0xf bound_ctrl:1
	v_pk_mul_f32 v[116:117], v[156:157], v[64:65] op_sel_hi:[0,1]
	v_pk_mul_f32 v[118:119], v[156:157], v[64:65] op_sel:[1,0]
	v_pk_fma_f32 v[12:13], v[12:13], v[114:115], v[116:117] op_sel:[0,1,0]
	v_pk_fma_f32 v[32:33], v[32:33], v[114:115], v[118:119] op_sel:[0,1,0]
	v_pk_fma_f32 v[188:189], v[12:13], v[88:89], v[188:189]
	v_pk_fma_f32 v[190:191], v[32:33], v[88:89], v[190:191]
	v_add_f32_dpp v192, v192, v192 row_half_mirror row_mask:0xf bank_mask:0xf bound_ctrl:1
	v_add_f32_dpp v193, v193, v193 row_half_mirror row_mask:0xf bank_mask:0xf bound_ctrl:1
	v_pk_mul_f32 v[120:121], v[156:157], v[66:67] op_sel_hi:[0,1]
	v_pk_mul_f32 v[122:123], v[156:157], v[66:67] op_sel:[1,0]
	v_pk_fma_f32 v[14:15], v[14:15], v[114:115], v[120:121] op_sel:[0,1,0]
	v_pk_fma_f32 v[34:35], v[34:35], v[114:115], v[122:123] op_sel:[0,1,0]
	v_pk_fma_f32 v[188:189], v[14:15], v[90:91], v[188:189]
	v_pk_fma_f32 v[190:191], v[34:35], v[90:91], v[190:191]
	ds_read_b128 v[60:63], v150 offset:10240
	ds_read_b128 v[84:87], v150 offset:10752
	ds_read_b128 v[64:67], v151 offset:10256
	ds_read_b128 v[88:91], v151 offset:10768
	ds_write_b64 v154, v[192:193] offset:1536
	v_pk_mul_f32 v[116:117], v[156:157], v[72:73] op_sel_hi:[0,1]
	v_pk_mul_f32 v[118:119], v[156:157], v[72:73] op_sel:[1,0]
	v_pk_fma_f32 v[8:9], v[8:9], v[114:115], v[116:117] op_sel:[0,1,0]
	v_pk_fma_f32 v[20:21], v[20:21], v[114:115], v[118:119] op_sel:[0,1,0]
	v_pk_fma_f32 v[188:189], v[8:9], v[96:97], v[188:189]
	v_pk_fma_f32 v[190:191], v[20:21], v[96:97], v[190:191]
	v_pk_mul_f32 v[120:121], v[156:157], v[74:75] op_sel_hi:[0,1]
	v_pk_mul_f32 v[122:123], v[156:157], v[74:75] op_sel:[1,0]
	v_pk_fma_f32 v[10:11], v[10:11], v[114:115], v[120:121] op_sel:[0,1,0]
	v_pk_fma_f32 v[22:23], v[22:23], v[114:115], v[122:123] op_sel:[0,1,0]
	v_pk_fma_f32 v[188:189], v[10:11], v[98:99], v[188:189]
	v_pk_fma_f32 v[190:191], v[22:23], v[98:99], v[190:191]
	v_pk_mul_f32 v[116:117], v[156:157], v[80:81] op_sel_hi:[0,1]
	v_pk_mul_f32 v[118:119], v[156:157], v[80:81] op_sel:[1,0]
	v_pk_fma_f32 v[4:5], v[4:5], v[114:115], v[116:117] op_sel:[0,1,0]
	v_pk_fma_f32 v[16:17], v[16:17], v[114:115], v[118:119] op_sel:[0,1,0]
	v_pk_fma_f32 v[188:189], v[4:5], v[104:105], v[188:189]
	v_pk_fma_f32 v[190:191], v[16:17], v[104:105], v[190:191]
	v_pk_mul_f32 v[120:121], v[156:157], v[82:83] op_sel_hi:[0,1]
	v_pk_mul_f32 v[122:123], v[156:157], v[82:83] op_sel:[1,0]
	v_pk_fma_f32 v[6:7], v[6:7], v[114:115], v[120:121] op_sel:[0,1,0]
	v_pk_fma_f32 v[18:19], v[18:19], v[114:115], v[122:123] op_sel:[0,1,0]
	v_pk_fma_f32 v[188:189], v[6:7], v[106:107], v[188:189]
	v_pk_fma_f32 v[190:191], v[18:19], v[106:107], v[190:191]
	v_add_f32_e64 v192, v188, v189
	v_add_f32_e64 v193, v190, v191
	s_waitcnt lgkmcnt(0)
; __device__ __forceinline__ float red8(float v) { v = red4(v); v += dppf<0x141>(v); return v; }
; __device__ __forceinline__ f32x2 lo2(const f32x4& v) { return __builtin_shufflevector(v, v, 0, 1); }
; __device__ __forceinline__ f32x2 hi2(const f32x4& v) { return __builtin_shufflevector(v, v, 2, 3); }
; __device__ __forceinline__ f32x2 splat2(float x) { return (f32x2){x, x}; }
; #define SCAN_INTERLEAVE(nds, nvalu)                                   \
;   _Pragma("unroll") for (int i_ = 0; i_ < (nds); ++i_) {               \
;     __builtin_amdgcn_sched_group_barrier(0x100, 1, 0);                 \
;     __builtin_amdgcn_sched_group_barrier(0x002, (nvalu), 0);           \
;   }
; __device__ __forceinline__ f32x2 ss_step(f32x2 (&S)[2][8], const SsRegs& R) {
;   const f32x2 dA2 = splat2(R.sc.y);
;   f32x2 out;
; #pragma unroll
;   for (int r = 0; r < 2; ++r) {
;     const f32x2 xdt2 = splat2((r ? R.x.y : R.x.x) * R.sc.x);
;     f32x2 y0 = splat2(0.f), y1 = splat2(0.f);
; #pragma unroll
;     for (int q = 0; q < 4; ++q) {
;       S[r][2 * q] = S[r][2 * q] * dA2 + xdt2 * lo2(R.B[q]);
;       S[r][2 * q + 1] = S[r][2 * q + 1] * dA2 + xdt2 * hi2(R.B[q]);
;       y0 += S[r][2 * q] * lo2(R.C[q]);
;       y1 += S[r][2 * q + 1] * hi2(R.C[q]);
;     }
;     y0 += y1;
;     const float y = red8(y0.x + y0.y);
;     if (r) out.y = y; else out.x = y;
;   }
;   return out;
; }
; __device__ __forceinline__ void scan_ssm(const Params& p, int l, int seq, int h, char* smem, const unsigned* wflags, unsigned wexpect) {
;     ...
;     ss_load(RA, vb, sb, 0, n0, prow0);
;     for (int t = 0; t < nsteps; t += 2) {
;       ss_load(RB, vb, sb, min(t + 1, 15), n0, prow0);
;       const f32x2 y0v = ss_step(S, RA);
;       *(f32x2*)((part == 0) ? (yb + t * 64 + prow0) : ydummy) = y0v;
;       SCAN_INTERLEAVE(10, 5);
;       if (t + 1 < nsteps) {
;         ss_load(RA, vb, sb, min(t + 2, 15), n0, prow0);
;         const f32x2 y1v = ss_step(S, RB);
;         *(f32x2*)((part == 0) ? (yb + (t + 1) * 64 + prow0) : ydummy) = y1v;
;         SCAN_INTERLEAVE(10, 5);
;       }
;     }
	s_nop 0
	ds_read_b64 v[112:113], v152 offset:12544
	ds_read_b64 v[114:115], v153 offset:41032
	ds_read_b128 v[72:75], v150 offset:11552
	ds_read_b128 v[96:99], v150 offset:12064
	ds_read_b128 v[80:83], v151 offset:11568
	ds_read_b128 v[104:107], v151 offset:12080
	v_pk_mul_f32 v[156:157], v[108:109], v[110:111] op_sel_hi:[1,0]
	v_pk_mul_f32 v[116:117], v[156:157], v[60:61] op_sel_hi:[0,1]
	v_pk_mul_f32 v[118:119], v[156:157], v[60:61] op_sel:[1,0]
	v_pk_fma_f32 v[28:29], v[28:29], v[110:111], v[116:117] op_sel:[0,1,0]
	v_pk_fma_f32 v[24:25], v[24:25], v[110:111], v[118:119] op_sel:[0,1,0]
	v_pk_mul_f32 v[188:189], v[28:29], v[84:85]
	v_pk_mul_f32 v[190:191], v[24:25], v[84:85]
	v_add_f32_dpp v192, v192, v192 quad_perm:[1,0,3,2] row_mask:0xf bank_mask:0xf bound_ctrl:1
	v_add_f32_dpp v193, v193, v193 quad_perm:[1,0,3,2] row_mask:0xf bank_mask:0xf bound_ctrl:1
	v_pk_mul_f32 v[120:121], v[156:157], v[62:63] op_sel_hi:[0,1]
	v_pk_mul_f32 v[122:123], v[156:157], v[62:63] op_sel:[1,0]
	v_pk_fma_f32 v[30:31], v[30:31], v[110:111], v[120:121] op_sel:[0,1,0]
	v_pk_fma_f32 v[26:27], v[26:27], v[110:111], v[122:123] op_sel:[0,1,0]
	v_pk_fma_f32 v[188:189], v[30:31], v[86:87], v[188:189]
	v_pk_fma_f32 v[190:191], v[26:27], v[86:87], v[190:191]
	v_add_f32_dpp v192, v192, v192 quad_perm:[2,3,0,1] row_mask:0xf bank_mask:0xf bound_ctrl:1
	v_add_f32_dpp v193, v193, v193 quad_perm:[2,3,0,1] row_mask:0xf bank_mask:0xf bound_ctrl:1
	v_pk_mul_f32 v[116:117], v[156:157], v[64:65] op_sel_hi:[0,1]
	v_pk_mul_f32 v[118:119], v[156:157], v[64:65] op_sel:[1,0]
	v_pk_fma_f32 v[12:13], v[12:13], v[110:111], v[116:117] op_sel:[0,1,0]
	v_pk_fma_f32 v[32:33], v[32:33], v[110:111], v[118:119] op_sel:[0,1,0]
	v_pk_fma_f32 v[188:189], v[12:13], v[88:89], v[188:189]
	v_pk_fma_f32 v[190:191], v[32:33], v[88:89], v[190:191]
	v_add_f32_dpp v192, v192, v192 row_half_mirror row_mask:0xf bank_mask:0xf bound_ctrl:1
	v_add_f32_dpp v193, v193, v193 row_half_mirror row_mask:0xf bank_mask:0xf bound_ctrl:1
	v_pk_mul_f32 v[120:121], v[156:157], v[66:67] op_sel_hi:[0,1]
	v_pk_mul_f32 v[122:123], v[156:157], v[66:67] op_sel:[1,0]
	v_pk_fma_f32 v[14:15], v[14:15], v[110:111], v[120:121] op_sel:[0,1,0]
	v_pk_fma_f32 v[34:35], v[34:35], v[110:111], v[122:123] op_sel:[0,1,0]
	v_pk_fma_f32 v[188:189], v[14:15], v[90:91], v[188:189]
	v_pk_fma_f32 v[190:191], v[34:35], v[90:91], v[190:191]
	ds_read_b128 v[60:63], v150 offset:11520
	ds_read_b128 v[84:87], v150 offset:12032
	ds_read_b128 v[64:67], v151 offset:11536
	ds_read_b128 v[88:91], v151 offset:12048
	ds_write_b64 v154, v[192:193] offset:1792
	v_pk_mul_f32 v[116:117], v[156:157], v[68:69] op_sel_hi:[0,1]
	v_pk_mul_f32 v[118:119], v[156:157], v[68:69] op_sel:[1,0]
	v_pk_fma_f32 v[8:9], v[8:9], v[110:111], v[116:117] op_sel:[0,1,0]
	v_pk_fma_f32 v[20:21], v[20:21], v[110:111], v[118:119] op_sel:[0,1,0]
	v_pk_fma_f32 v[188:189], v[8:9], v[92:93], v[188:189]
	v_pk_fma_f32 v[190:191], v[20:21], v[92:93], v[190:191]
	v_pk_mul_f32 v[120:121], v[156:157], v[70:71] op_sel_hi:[0,1]
	v_pk_mul_f32 v[122:123], v[156:157], v[70:71] op_sel:[1,0]
	v_pk_fma_f32 v[10:11], v[10:11], v[110:111], v[120:121] op_sel:[0,1,0]
	v_pk_fma_f32 v[22:23], v[22:23], v[110:111], v[122:123] op_sel:[0,1,0]
	v_pk_fma_f32 v[188:189], v[10:11], v[94:95], v[188:189]
	v_pk_fma_f32 v[190:191], v[22:23], v[94:95], v[190:191]
	v_pk_mul_f32 v[116:117], v[156:157], v[76:77] op_sel_hi:[0,1]
	v_pk_mul_f32 v[118:119], v[156:157], v[76:77] op_sel:[1,0]
	v_pk_fma_f32 v[4:5], v[4:5], v[110:111], v[116:117] op_sel:[0,1,0]
	v_pk_fma_f32 v[16:17], v[16:17], v[110:111], v[118:119] op_sel:[0,1,0]
	v_pk_fma_f32 v[188:189], v[4:5], v[100:101], v[188:189]
	v_pk_fma_f32 v[190:191], v[16:17], v[100:101], v[190:191]
	v_pk_mul_f32 v[120:121], v[156:157], v[78:79] op_sel_hi:[0,1]
	v_pk_mul_f32 v[122:123], v[156:157], v[78:79] op_sel:[1,0]
	v_pk_fma_f32 v[6:7], v[6:7], v[110:111], v[120:121] op_sel:[0,1,0]
	v_pk_fma_f32 v[18:19], v[18:19], v[110:111], v[122:123] op_sel:[0,1,0]
	v_pk_fma_f32 v[188:189], v[6:7], v[102:103], v[188:189]
	v_pk_fma_f32 v[190:191], v[18:19], v[102:103], v[190:191]
	v_add_f32_e64 v192, v188, v189
	v_add_f32_e64 v193, v190, v191
	s_waitcnt lgkmcnt(0)
	s_nop 0
	ds_read_b64 v[108:109], v152 offset:13824
	ds_read_b64 v[110:111], v153 offset:41040
	ds_read_b128 v[68:71], v150 offset:12832
	ds_read_b128 v[92:95], v150 offset:13344
	ds_read_b128 v[76:79], v151 offset:12848
	ds_read_b128 v[100:103], v151 offset:13360
	v_pk_mul_f32 v[156:157], v[112:113], v[114:115] op_sel_hi:[1,0]
	v_pk_mul_f32 v[116:117], v[156:157], v[60:61] op_sel_hi:[0,1]
	v_pk_mul_f32 v[118:119], v[156:157], v[60:61] op_sel:[1,0]
	v_pk_fma_f32 v[28:29], v[28:29], v[114:115], v[116:117] op_sel:[0,1,0]
	v_pk_fma_f32 v[24:25], v[24:25], v[114:115], v[118:119] op_sel:[0,1,0]
	v_pk_mul_f32 v[188:189], v[28:29], v[84:85]
	v_pk_mul_f32 v[190:191], v[24:25], v[84:85]
	v_add_f32_dpp v192, v192, v192 quad_perm:[1,0,3,2] row_mask:0xf bank_mask:0xf bound_ctrl:1
	v_add_f32_dpp v193, v193, v193 quad_perm:[1,0,3,2] row_mask:0xf bank_mask:0xf bound_ctrl:1
	v_pk_mul_f32 v[120:121], v[156:157], v[62:63] op_sel_hi:[0,1]
	v_pk_mul_f32 v[122:123], v[156:157], v[62:63] op_sel:[1,0]
	v_pk_fma_f32 v[30:31], v[30:31], v[114:115], v[120:121] op_sel:[0,1,0]
	v_pk_fma_f32 v[26:27], v[26:27], v[114:115], v[122:123] op_sel:[0,1,0]
	v_pk_fma_f32 v[188:189], v[30:31], v[86:87], v[188:189]
	v_pk_fma_f32 v[190:191], v[26:27], v[86:87], v[190:191]
	v_add_f32_dpp v192, v192, v192 quad_perm:[2,3,0,1] row_mask:0xf bank_mask:0xf bound_ctrl:1
	v_add_f32_dpp v193, v193, v193 quad_perm:[2,3,0,1] row_mask:0xf bank_mask:0xf bound_ctrl:1
; __device__ __forceinline__ float red8(float v) { v = red4(v); v += dppf<0x141>(v); return v; }
; __device__ __forceinline__ f32x2 lo2(const f32x4& v) { return __builtin_shufflevector(v, v, 0, 1); }
; __device__ __forceinline__ f32x2 hi2(const f32x4& v) { return __builtin_shufflevector(v, v, 2, 3); }
; __device__ __forceinline__ f32x2 splat2(float x) { return (f32x2){x, x}; }
; #define SCAN_INTERLEAVE(nds, nvalu)                                   \
;   _Pragma("unroll") for (int i_ = 0; i_ < (nds); ++i_) {               \
;     __builtin_amdgcn_sched_group_barrier(0x100, 1, 0);                 \
;     __builtin_amdgcn_sched_group_barrier(0x002, (nvalu), 0);           \
;   }
; __device__ __forceinline__ f32x2 ss_step(f32x2 (&S)[2][8], const SsRegs& R) {
;   const f32x2 dA2 = splat2(R.sc.y);
;   f32x2 out;
; #pragma unroll
;   for (int r = 0; r < 2; ++r) {
;     const f32x2 xdt2 = splat2((r ? R.x.y : R.x.x) * R.sc.x);
;     f32x2 y0 = splat2(0.f), y1 = splat2(0.f);
; #pragma unroll
;     for (int q = 0; q < 4; ++q) {
;       S[r][2 * q] = S[r][2 * q] * dA2 + xdt2 * lo2(R.B[q]);
;       S[r][2 * q + 1] = S[r][2 * q + 1] * dA2 + xdt2 * hi2(R.B[q]);
;       y0 += S[r][2 * q] * lo2(R.C[q]);
;       y1 += S[r][2 * q + 1] * hi2(R.C[q]);
;     }
;     y0 += y1;
;     const float y = red8(y0.x + y0.y);
;     if (r) out.y = y; else out.x = y;
;   }
;   return out;
; }
; __device__ __forceinline__ void scan_ssm(const Params& p, int l, int seq, int h, char* smem, const unsigned* wflags, unsigned wexpect) {
;     ...
;     ss_load(RA, vb, sb, 0, n0, prow0);
;     for (int t = 0; t < nsteps; t += 2) {
;       ss_load(RB, vb, sb, min(t + 1, 15), n0, prow0);
;       const f32x2 y0v = ss_step(S, RA);
;       *(f32x2*)((part == 0) ? (yb + t * 64 + prow0) : ydummy) = y0v;
;       SCAN_INTERLEAVE(10, 5);
;       if (t + 1 < nsteps) {
;         ss_load(RA, vb, sb, min(t + 2, 15), n0, prow0);
;         const f32x2 y1v = ss_step(S, RB);
;         *(f32x2*)((part == 0) ? (yb + (t + 1) * 64 + prow0) : ydummy) = y1v;
;         SCAN_INTERLEAVE(10, 5);
;       }
;     }
	v_pk_mul_f32 v[116:117], v[156:157], v[64:65] op_sel_hi:[0,1]
	v_pk_mul_f32 v[118:119], v[156:157], v[64:65] op_sel:[1,0]
	v_pk_fma_f32 v[12:13], v[12:13], v[114:115], v[116:117] op_sel:[0,1,0]
	v_pk_fma_f32 v[32:33], v[32:33], v[114:115], v[118:119] op_sel:[0,1,0]
	v_pk_fma_f32 v[188:189], v[12:13], v[88:89], v[188:189]
	v_pk_fma_f32 v[190:191], v[32:33], v[88:89], v[190:191]
	v_add_f32_dpp v192, v192, v192 row_half_mirror row_mask:0xf bank_mask:0xf bound_ctrl:1
	v_add_f32_dpp v193, v193, v193 row_half_mirror row_mask:0xf bank_mask:0xf bound_ctrl:1
	v_pk_mul_f32 v[120:121], v[156:157], v[66:67] op_sel_hi:[0,1]
	v_pk_mul_f32 v[122:123], v[156:157], v[66:67] op_sel:[1,0]
	v_pk_fma_f32 v[14:15], v[14:15], v[114:115], v[120:121] op_sel:[0,1,0]
	v_pk_fma_f32 v[34:35], v[34:35], v[114:115], v[122:123] op_sel:[0,1,0]
	v_pk_fma_f32 v[188:189], v[14:15], v[90:91], v[188:189]
	v_pk_fma_f32 v[190:191], v[34:35], v[90:91], v[190:191]
	ds_read_b128 v[60:63], v150 offset:12800
	ds_read_b128 v[84:87], v150 offset:13312
	ds_read_b128 v[64:67], v151 offset:12816
	ds_read_b128 v[88:91], v151 offset:13328
	ds_write_b64 v154, v[192:193] offset:2048
	v_pk_mul_f32 v[116:117], v[156:157], v[72:73] op_sel_hi:[0,1]
	v_pk_mul_f32 v[118:119], v[156:157], v[72:73] op_sel:[1,0]
	v_pk_fma_f32 v[8:9], v[8:9], v[114:115], v[116:117] op_sel:[0,1,0]
	v_pk_fma_f32 v[20:21], v[20:21], v[114:115], v[118:119] op_sel:[0,1,0]
	v_pk_fma_f32 v[188:189], v[8:9], v[96:97], v[188:189]
	v_pk_fma_f32 v[190:191], v[20:21], v[96:97], v[190:191]
	v_pk_mul_f32 v[120:121], v[156:157], v[74:75] op_sel_hi:[0,1]
	v_pk_mul_f32 v[122:123], v[156:157], v[74:75] op_sel:[1,0]
	v_pk_fma_f32 v[10:11], v[10:11], v[114:115], v[120:121] op_sel:[0,1,0]
	v_pk_fma_f32 v[22:23], v[22:23], v[114:115], v[122:123] op_sel:[0,1,0]
	v_pk_fma_f32 v[188:189], v[10:11], v[98:99], v[188:189]
	v_pk_fma_f32 v[190:191], v[22:23], v[98:99], v[190:191]
	v_pk_mul_f32 v[116:117], v[156:157], v[80:81] op_sel_hi:[0,1]
	v_pk_mul_f32 v[118:119], v[156:157], v[80:81] op_sel:[1,0]
	v_pk_fma_f32 v[4:5], v[4:5], v[114:115], v[116:117] op_sel:[0,1,0]
	v_pk_fma_f32 v[16:17], v[16:17], v[114:115], v[118:119] op_sel:[0,1,0]
	v_pk_fma_f32 v[188:189], v[4:5], v[104:105], v[188:189]
	v_pk_fma_f32 v[190:191], v[16:17], v[104:105], v[190:191]
	v_pk_mul_f32 v[120:121], v[156:157], v[82:83] op_sel_hi:[0,1]
	v_pk_mul_f32 v[122:123], v[156:157], v[82:83] op_sel:[1,0]
	v_pk_fma_f32 v[6:7], v[6:7], v[114:115], v[120:121] op_sel:[0,1,0]
	v_pk_fma_f32 v[18:19], v[18:19], v[114:115], v[122:123] op_sel:[0,1,0]
	v_pk_fma_f32 v[188:189], v[6:7], v[106:107], v[188:189]
	v_pk_fma_f32 v[190:191], v[18:19], v[106:107], v[190:191]
	v_add_f32_e64 v192, v188, v189
	v_add_f32_e64 v193, v190, v191
	s_waitcnt lgkmcnt(0)
	s_nop 0
	ds_read_b64 v[112:113], v152 offset:15104
	ds_read_b64 v[114:115], v153 offset:41048
	ds_read_b128 v[72:75], v150 offset:14112
	ds_read_b128 v[96:99], v150 offset:14624
	ds_read_b128 v[80:83], v151 offset:14128
	ds_read_b128 v[104:107], v151 offset:14640
	v_pk_mul_f32 v[156:157], v[108:109], v[110:111] op_sel_hi:[1,0]
	v_pk_mul_f32 v[116:117], v[156:157], v[60:61] op_sel_hi:[0,1]
	v_pk_mul_f32 v[118:119], v[156:157], v[60:61] op_sel:[1,0]
	v_pk_fma_f32 v[28:29], v[28:29], v[110:111], v[116:117] op_sel:[0,1,0]
	v_pk_fma_f32 v[24:25], v[24:25], v[110:111], v[118:119] op_sel:[0,1,0]
	v_pk_mul_f32 v[188:189], v[28:29], v[84:85]
	v_pk_mul_f32 v[190:191], v[24:25], v[84:85]
	v_add_f32_dpp v192, v192, v192 quad_perm:[1,0,3,2] row_mask:0xf bank_mask:0xf bound_ctrl:1
	v_add_f32_dpp v193, v193, v193 quad_perm:[1,0,3,2] row_mask:0xf bank_mask:0xf bound_ctrl:1
	v_pk_mul_f32 v[120:121], v[156:157], v[62:63] op_sel_hi:[0,1]
	v_pk_mul_f32 v[122:123], v[156:157], v[62:63] op_sel:[1,0]
	v_pk_fma_f32 v[30:31], v[30:31], v[110:111], v[120:121] op_sel:[0,1,0]
	v_pk_fma_f32 v[26:27], v[26:27], v[110:111], v[122:123] op_sel:[0,1,0]
	v_pk_fma_f32 v[188:189], v[30:31], v[86:87], v[188:189]
	v_pk_fma_f32 v[190:191], v[26:27], v[86:87], v[190:191]
	v_add_f32_dpp v192, v192, v192 quad_perm:[2,3,0,1] row_mask:0xf bank_mask:0xf bound_ctrl:1
	v_add_f32_dpp v193, v193, v193 quad_perm:[2,3,0,1] row_mask:0xf bank_mask:0xf bound_ctrl:1
	v_pk_mul_f32 v[116:117], v[156:157], v[64:65] op_sel_hi:[0,1]
	v_pk_mul_f32 v[118:119], v[156:157], v[64:65] op_sel:[1,0]
	v_pk_fma_f32 v[12:13], v[12:13], v[110:111], v[116:117] op_sel:[0,1,0]
	v_pk_fma_f32 v[32:33], v[32:33], v[110:111], v[118:119] op_sel:[0,1,0]
	v_pk_fma_f32 v[188:189], v[12:13], v[88:89], v[188:189]
	v_pk_fma_f32 v[190:191], v[32:33], v[88:89], v[190:191]
	v_add_f32_dpp v192, v192, v192 row_half_mirror row_mask:0xf bank_mask:0xf bound_ctrl:1
	v_add_f32_dpp v193, v193, v193 row_half_mirror row_mask:0xf bank_mask:0xf bound_ctrl:1
	v_pk_mul_f32 v[120:121], v[156:157], v[66:67] op_sel_hi:[0,1]
	v_pk_mul_f32 v[122:123], v[156:157], v[66:67] op_sel:[1,0]
	v_pk_fma_f32 v[14:15], v[14:15], v[110:111], v[120:121] op_sel:[0,1,0]
	v_pk_fma_f32 v[34:35], v[34:35], v[110:111], v[122:123] op_sel:[0,1,0]
	v_pk_fma_f32 v[188:189], v[14:15], v[90:91], v[188:189]
	v_pk_fma_f32 v[190:191], v[34:35], v[90:91], v[190:191]
	ds_read_b128 v[60:63], v150 offset:14080
	ds_read_b128 v[84:87], v150 offset:14592
	ds_read_b128 v[64:67], v151 offset:14096
	ds_read_b128 v[88:91], v151 offset:14608
	ds_write_b64 v154, v[192:193] offset:2304
	v_pk_mul_f32 v[116:117], v[156:157], v[68:69] op_sel_hi:[0,1]
	v_pk_mul_f32 v[118:119], v[156:157], v[68:69] op_sel:[1,0]
	v_pk_fma_f32 v[8:9], v[8:9], v[110:111], v[116:117] op_sel:[0,1,0]
	v_pk_fma_f32 v[20:21], v[20:21], v[110:111], v[118:119] op_sel:[0,1,0]
	v_pk_fma_f32 v[188:189], v[8:9], v[92:93], v[188:189]
	v_pk_fma_f32 v[190:191], v[20:21], v[92:93], v[190:191]
	v_pk_mul_f32 v[120:121], v[156:157], v[70:71] op_sel_hi:[0,1]
	v_pk_mul_f32 v[122:123], v[156:157], v[70:71] op_sel:[1,0]
	v_pk_fma_f32 v[10:11], v[10:11], v[110:111], v[120:121] op_sel:[0,1,0]
	v_pk_fma_f32 v[22:23], v[22:23], v[110:111], v[122:123] op_sel:[0,1,0]
	v_pk_fma_f32 v[188:189], v[10:11], v[94:95], v[188:189]
	v_pk_fma_f32 v[190:191], v[22:23], v[94:95], v[190:191]
	v_pk_mul_f32 v[116:117], v[156:157], v[76:77] op_sel_hi:[0,1]
	v_pk_mul_f32 v[118:119], v[156:157], v[76:77] op_sel:[1,0]
	v_pk_fma_f32 v[4:5], v[4:5], v[110:111], v[116:117] op_sel:[0,1,0]
	v_pk_fma_f32 v[16:17], v[16:17], v[110:111], v[118:119] op_sel:[0,1,0]
	v_pk_fma_f32 v[188:189], v[4:5], v[100:101], v[188:189]
	v_pk_fma_f32 v[190:191], v[16:17], v[100:101], v[190:191]
	v_pk_mul_f32 v[120:121], v[156:157], v[78:79] op_sel_hi:[0,1]
	v_pk_mul_f32 v[122:123], v[156:157], v[78:79] op_sel:[1,0]
	v_pk_fma_f32 v[6:7], v[6:7], v[110:111], v[120:121] op_sel:[0,1,0]
	v_pk_fma_f32 v[18:19], v[18:19], v[110:111], v[122:123] op_sel:[0,1,0]
	v_pk_fma_f32 v[188:189], v[6:7], v[102:103], v[188:189]
	v_pk_fma_f32 v[190:191], v[18:19], v[102:103], v[190:191]
	v_add_f32_e64 v192, v188, v189
	v_add_f32_e64 v193, v190, v191
	s_waitcnt lgkmcnt(0)
; __device__ __forceinline__ float red8(float v) { v = red4(v); v += dppf<0x141>(v); return v; }
; __device__ __forceinline__ f32x2 lo2(const f32x4& v) { return __builtin_shufflevector(v, v, 0, 1); }
; __device__ __forceinline__ f32x2 hi2(const f32x4& v) { return __builtin_shufflevector(v, v, 2, 3); }
; __device__ __forceinline__ f32x2 splat2(float x) { return (f32x2){x, x}; }
; #define SCAN_INTERLEAVE(nds, nvalu)                                   \
;   _Pragma("unroll") for (int i_ = 0; i_ < (nds); ++i_) {               \
;     __builtin_amdgcn_sched_group_barrier(0x100, 1, 0);                 \
;     __builtin_amdgcn_sched_group_barrier(0x002, (nvalu), 0);           \
;   }
; __device__ __forceinline__ f32x2 ss_step(f32x2 (&S)[2][8], const SsRegs& R) {
;   const f32x2 dA2 = splat2(R.sc.y);
;   f32x2 out;
; #pragma unroll
;   for (int r = 0; r < 2; ++r) {
;     const f32x2 xdt2 = splat2((r ? R.x.y : R.x.x) * R.sc.x);
;     f32x2 y0 = splat2(0.f), y1 = splat2(0.f);
; #pragma unroll
;     for (int q = 0; q < 4; ++q) {
;       S[r][2 * q] = S[r][2 * q] * dA2 + xdt2 * lo2(R.B[q]);
;       S[r][2 * q + 1] = S[r][2 * q + 1] * dA2 + xdt2 * hi2(R.B[q]);
;       y0 += S[r][2 * q] * lo2(R.C[q]);
;       y1 += S[r][2 * q + 1] * hi2(R.C[q]);
;     }
;     y0 += y1;
;     const float y = red8(y0.x + y0.y);
;     if (r) out.y = y; else out.x = y;
;   }
;   return out;
; }
; __device__ __forceinline__ void scan_ssm(const Params& p, int l, int seq, int h, char* smem, const unsigned* wflags, unsigned wexpect) {
;     ...
;     ss_load(RA, vb, sb, 0, n0, prow0);
;     for (int t = 0; t < nsteps; t += 2) {
;       ss_load(RB, vb, sb, min(t + 1, 15), n0, prow0);
;       const f32x2 y0v = ss_step(S, RA);
;       *(f32x2*)((part == 0) ? (yb + t * 64 + prow0) : ydummy) = y0v;
;       SCAN_INTERLEAVE(10, 5);
;       if (t + 1 < nsteps) {
;         ss_load(RA, vb, sb, min(t + 2, 15), n0, prow0);
;         const f32x2 y1v = ss_step(S, RB);
;         *(f32x2*)((part == 0) ? (yb + (t + 1) * 64 + prow0) : ydummy) = y1v;
;         SCAN_INTERLEAVE(10, 5);
;       }
;     }
	s_nop 0
	ds_read_b64 v[108:109], v152 offset:16384
	ds_read_b64 v[110:111], v153 offset:41056
	ds_read_b128 v[68:71], v150 offset:15392
	ds_read_b128 v[92:95], v150 offset:15904
	ds_read_b128 v[76:79], v151 offset:15408
	ds_read_b128 v[100:103], v151 offset:15920
	v_pk_mul_f32 v[156:157], v[112:113], v[114:115] op_sel_hi:[1,0]
	v_pk_mul_f32 v[116:117], v[156:157], v[60:61] op_sel_hi:[0,1]
	v_pk_mul_f32 v[118:119], v[156:157], v[60:61] op_sel:[1,0]
	v_pk_fma_f32 v[28:29], v[28:29], v[114:115], v[116:117] op_sel:[0,1,0]
	v_pk_fma_f32 v[24:25], v[24:25], v[114:115], v[118:119] op_sel:[0,1,0]
	v_pk_mul_f32 v[188:189], v[28:29], v[84:85]
	v_pk_mul_f32 v[190:191], v[24:25], v[84:85]
	v_add_f32_dpp v192, v192, v192 quad_perm:[1,0,3,2] row_mask:0xf bank_mask:0xf bound_ctrl:1
	v_add_f32_dpp v193, v193, v193 quad_perm:[1,0,3,2] row_mask:0xf bank_mask:0xf bound_ctrl:1
	v_pk_mul_f32 v[120:121], v[156:157], v[62:63] op_sel_hi:[0,1]
	v_pk_mul_f32 v[122:123], v[156:157], v[62:63] op_sel:[1,0]
	v_pk_fma_f32 v[30:31], v[30:31], v[114:115], v[120:121] op_sel:[0,1,0]
	v_pk_fma_f32 v[26:27], v[26:27], v[114:115], v[122:123] op_sel:[0,1,0]
	v_pk_fma_f32 v[188:189], v[30:31], v[86:87], v[188:189]
	v_pk_fma_f32 v[190:191], v[26:27], v[86:87], v[190:191]
	v_add_f32_dpp v192, v192, v192 quad_perm:[2,3,0,1] row_mask:0xf bank_mask:0xf bound_ctrl:1
	v_add_f32_dpp v193, v193, v193 quad_perm:[2,3,0,1] row_mask:0xf bank_mask:0xf bound_ctrl:1
	v_pk_mul_f32 v[116:117], v[156:157], v[64:65] op_sel_hi:[0,1]
	v_pk_mul_f32 v[118:119], v[156:157], v[64:65] op_sel:[1,0]
	v_pk_fma_f32 v[12:13], v[12:13], v[114:115], v[116:117] op_sel:[0,1,0]
	v_pk_fma_f32 v[32:33], v[32:33], v[114:115], v[118:119] op_sel:[0,1,0]
	v_pk_fma_f32 v[188:189], v[12:13], v[88:89], v[188:189]
	v_pk_fma_f32 v[190:191], v[32:33], v[88:89], v[190:191]
	v_add_f32_dpp v192, v192, v192 row_half_mirror row_mask:0xf bank_mask:0xf bound_ctrl:1
	v_add_f32_dpp v193, v193, v193 row_half_mirror row_mask:0xf bank_mask:0xf bound_ctrl:1
	v_pk_mul_f32 v[120:121], v[156:157], v[66:67] op_sel_hi:[0,1]
	v_pk_mul_f32 v[122:123], v[156:157], v[66:67] op_sel:[1,0]
	v_pk_fma_f32 v[14:15], v[14:15], v[114:115], v[120:121] op_sel:[0,1,0]
	v_pk_fma_f32 v[34:35], v[34:35], v[114:115], v[122:123] op_sel:[0,1,0]
	v_pk_fma_f32 v[188:189], v[14:15], v[90:91], v[188:189]
	v_pk_fma_f32 v[190:191], v[34:35], v[90:91], v[190:191]
	ds_read_b128 v[60:63], v150 offset:15360
	ds_read_b128 v[84:87], v150 offset:15872
	ds_read_b128 v[64:67], v151 offset:15376
	ds_read_b128 v[88:91], v151 offset:15888
	ds_write_b64 v154, v[192:193] offset:2560
	v_pk_mul_f32 v[116:117], v[156:157], v[72:73] op_sel_hi:[0,1]
	v_pk_mul_f32 v[118:119], v[156:157], v[72:73] op_sel:[1,0]
	v_pk_fma_f32 v[8:9], v[8:9], v[114:115], v[116:117] op_sel:[0,1,0]
	v_pk_fma_f32 v[20:21], v[20:21], v[114:115], v[118:119] op_sel:[0,1,0]
	v_pk_fma_f32 v[188:189], v[8:9], v[96:97], v[188:189]
	v_pk_fma_f32 v[190:191], v[20:21], v[96:97], v[190:191]
	v_pk_mul_f32 v[120:121], v[156:157], v[74:75] op_sel_hi:[0,1]
	v_pk_mul_f32 v[122:123], v[156:157], v[74:75] op_sel:[1,0]
	v_pk_fma_f32 v[10:11], v[10:11], v[114:115], v[120:121] op_sel:[0,1,0]
	v_pk_fma_f32 v[22:23], v[22:23], v[114:115], v[122:123] op_sel:[0,1,0]
	v_pk_fma_f32 v[188:189], v[10:11], v[98:99], v[188:189]
	v_pk_fma_f32 v[190:191], v[22:23], v[98:99], v[190:191]
	v_pk_mul_f32 v[116:117], v[156:157], v[80:81] op_sel_hi:[0,1]
	v_pk_mul_f32 v[118:119], v[156:157], v[80:81] op_sel:[1,0]
	v_pk_fma_f32 v[4:5], v[4:5], v[114:115], v[116:117] op_sel:[0,1,0]
	v_pk_fma_f32 v[16:17], v[16:17], v[114:115], v[118:119] op_sel:[0,1,0]
	v_pk_fma_f32 v[188:189], v[4:5], v[104:105], v[188:189]
	v_pk_fma_f32 v[190:191], v[16:17], v[104:105], v[190:191]
	v_pk_mul_f32 v[120:121], v[156:157], v[82:83] op_sel_hi:[0,1]
	v_pk_mul_f32 v[122:123], v[156:157], v[82:83] op_sel:[1,0]
	v_pk_fma_f32 v[6:7], v[6:7], v[114:115], v[120:121] op_sel:[0,1,0]
	v_pk_fma_f32 v[18:19], v[18:19], v[114:115], v[122:123] op_sel:[0,1,0]
	v_pk_fma_f32 v[188:189], v[6:7], v[106:107], v[188:189]
	v_pk_fma_f32 v[190:191], v[18:19], v[106:107], v[190:191]
	v_add_f32_e64 v192, v188, v189
	v_add_f32_e64 v193, v190, v191
	s_waitcnt lgkmcnt(0)
	s_nop 0
	ds_read_b64 v[112:113], v152 offset:17664
	ds_read_b64 v[114:115], v153 offset:41064
	ds_read_b128 v[72:75], v150 offset:16672
	ds_read_b128 v[96:99], v150 offset:17184
	ds_read_b128 v[80:83], v151 offset:16688
	ds_read_b128 v[104:107], v151 offset:17200
	v_pk_mul_f32 v[156:157], v[108:109], v[110:111] op_sel_hi:[1,0]
	v_pk_mul_f32 v[116:117], v[156:157], v[60:61] op_sel_hi:[0,1]
	v_pk_mul_f32 v[118:119], v[156:157], v[60:61] op_sel:[1,0]
	v_pk_fma_f32 v[28:29], v[28:29], v[110:111], v[116:117] op_sel:[0,1,0]
	v_pk_fma_f32 v[24:25], v[24:25], v[110:111], v[118:119] op_sel:[0,1,0]
	v_pk_mul_f32 v[188:189], v[28:29], v[84:85]
	v_pk_mul_f32 v[190:191], v[24:25], v[84:85]
	v_add_f32_dpp v192, v192, v192 quad_perm:[1,0,3,2] row_mask:0xf bank_mask:0xf bound_ctrl:1
	v_add_f32_dpp v193, v193, v193 quad_perm:[1,0,3,2] row_mask:0xf bank_mask:0xf bound_ctrl:1
	v_pk_mul_f32 v[120:121], v[156:157], v[62:63] op_sel_hi:[0,1]
	v_pk_mul_f32 v[122:123], v[156:157], v[62:63] op_sel:[1,0]
	v_pk_fma_f32 v[30:31], v[30:31], v[110:111], v[120:121] op_sel:[0,1,0]
	v_pk_fma_f32 v[26:27], v[26:27], v[110:111], v[122:123] op_sel:[0,1,0]
	v_pk_fma_f32 v[188:189], v[30:31], v[86:87], v[188:189]
	v_pk_fma_f32 v[190:191], v[26:27], v[86:87], v[190:191]
	v_add_f32_dpp v192, v192, v192 quad_perm:[2,3,0,1] row_mask:0xf bank_mask:0xf bound_ctrl:1
	v_add_f32_dpp v193, v193, v193 quad_perm:[2,3,0,1] row_mask:0xf bank_mask:0xf bound_ctrl:1
; __device__ __forceinline__ float red8(float v) { v = red4(v); v += dppf<0x141>(v); return v; }
; __device__ __forceinline__ f32x2 lo2(const f32x4& v) { return __builtin_shufflevector(v, v, 0, 1); }
; __device__ __forceinline__ f32x2 hi2(const f32x4& v) { return __builtin_shufflevector(v, v, 2, 3); }
; __device__ __forceinline__ f32x2 splat2(float x) { return (f32x2){x, x}; }
; #define SCAN_INTERLEAVE(nds, nvalu)                                   \
;   _Pragma("unroll") for (int i_ = 0; i_ < (nds); ++i_) {               \
;     __builtin_amdgcn_sched_group_barrier(0x100, 1, 0);                 \
;     __builtin_amdgcn_sched_group_barrier(0x002, (nvalu), 0);           \
;   }
; __device__ __forceinline__ f32x2 ss_step(f32x2 (&S)[2][8], const SsRegs& R) {
;   const f32x2 dA2 = splat2(R.sc.y);
;   f32x2 out;
; #pragma unroll
;   for (int r = 0; r < 2; ++r) {
;     const f32x2 xdt2 = splat2((r ? R.x.y : R.x.x) * R.sc.x);
;     f32x2 y0 = splat2(0.f), y1 = splat2(0.f);
; #pragma unroll
;     for (int q = 0; q < 4; ++q) {
;       S[r][2 * q] = S[r][2 * q] * dA2 + xdt2 * lo2(R.B[q]);
;       S[r][2 * q + 1] = S[r][2 * q + 1] * dA2 + xdt2 * hi2(R.B[q]);
;       y0 += S[r][2 * q] * lo2(R.C[q]);
;       y1 += S[r][2 * q + 1] * hi2(R.C[q]);
;     }
;     y0 += y1;
;     const float y = red8(y0.x + y0.y);
;     if (r) out.y = y; else out.x = y;
;   }
;   return out;
; }
; __device__ __forceinline__ void scan_ssm(const Params& p, int l, int seq, int h, char* smem, const unsigned* wflags, unsigned wexpect) {
;     ...
;     ss_load(RA, vb, sb, 0, n0, prow0);
;     for (int t = 0; t < nsteps; t += 2) {
;       ss_load(RB, vb, sb, min(t + 1, 15), n0, prow0);
;       const f32x2 y0v = ss_step(S, RA);
;       *(f32x2*)((part == 0) ? (yb + t * 64 + prow0) : ydummy) = y0v;
;       SCAN_INTERLEAVE(10, 5);
;       if (t + 1 < nsteps) {
;         ss_load(RA, vb, sb, min(t + 2, 15), n0, prow0);
;         const f32x2 y1v = ss_step(S, RB);
;         *(f32x2*)((part == 0) ? (yb + (t + 1) * 64 + prow0) : ydummy) = y1v;
;         SCAN_INTERLEAVE(10, 5);
;       }
;     }
	v_pk_mul_f32 v[116:117], v[156:157], v[64:65] op_sel_hi:[0,1]
	v_pk_mul_f32 v[118:119], v[156:157], v[64:65] op_sel:[1,0]
	v_pk_fma_f32 v[12:13], v[12:13], v[110:111], v[116:117] op_sel:[0,1,0]
	v_pk_fma_f32 v[32:33], v[32:33], v[110:111], v[118:119] op_sel:[0,1,0]
	v_pk_fma_f32 v[188:189], v[12:13], v[88:89], v[188:189]
	v_pk_fma_f32 v[190:191], v[32:33], v[88:89], v[190:191]
	v_add_f32_dpp v192, v192, v192 row_half_mirror row_mask:0xf bank_mask:0xf bound_ctrl:1
	v_add_f32_dpp v193, v193, v193 row_half_mirror row_mask:0xf bank_mask:0xf bound_ctrl:1
	v_pk_mul_f32 v[120:121], v[156:157], v[66:67] op_sel_hi:[0,1]
	v_pk_mul_f32 v[122:123], v[156:157], v[66:67] op_sel:[1,0]
	v_pk_fma_f32 v[14:15], v[14:15], v[110:111], v[120:121] op_sel:[0,1,0]
	v_pk_fma_f32 v[34:35], v[34:35], v[110:111], v[122:123] op_sel:[0,1,0]
	v_pk_fma_f32 v[188:189], v[14:15], v[90:91], v[188:189]
	v_pk_fma_f32 v[190:191], v[34:35], v[90:91], v[190:191]
	ds_read_b128 v[60:63], v150 offset:16640
	ds_read_b128 v[84:87], v150 offset:17152
	ds_read_b128 v[64:67], v151 offset:16656
	ds_read_b128 v[88:91], v151 offset:17168
	ds_write_b64 v154, v[192:193] offset:2816
	v_pk_mul_f32 v[116:117], v[156:157], v[68:69] op_sel_hi:[0,1]
	v_pk_mul_f32 v[118:119], v[156:157], v[68:69] op_sel:[1,0]
	v_pk_fma_f32 v[8:9], v[8:9], v[110:111], v[116:117] op_sel:[0,1,0]
	v_pk_fma_f32 v[20:21], v[20:21], v[110:111], v[118:119] op_sel:[0,1,0]
	v_pk_fma_f32 v[188:189], v[8:9], v[92:93], v[188:189]
	v_pk_fma_f32 v[190:191], v[20:21], v[92:93], v[190:191]
	v_pk_mul_f32 v[120:121], v[156:157], v[70:71] op_sel_hi:[0,1]
	v_pk_mul_f32 v[122:123], v[156:157], v[70:71] op_sel:[1,0]
	v_pk_fma_f32 v[10:11], v[10:11], v[110:111], v[120:121] op_sel:[0,1,0]
	v_pk_fma_f32 v[22:23], v[22:23], v[110:111], v[122:123] op_sel:[0,1,0]
	v_pk_fma_f32 v[188:189], v[10:11], v[94:95], v[188:189]
	v_pk_fma_f32 v[190:191], v[22:23], v[94:95], v[190:191]
	v_pk_mul_f32 v[116:117], v[156:157], v[76:77] op_sel_hi:[0,1]
	v_pk_mul_f32 v[118:119], v[156:157], v[76:77] op_sel:[1,0]
	v_pk_fma_f32 v[4:5], v[4:5], v[110:111], v[116:117] op_sel:[0,1,0]
	v_pk_fma_f32 v[16:17], v[16:17], v[110:111], v[118:119] op_sel:[0,1,0]
	v_pk_fma_f32 v[188:189], v[4:5], v[100:101], v[188:189]
	v_pk_fma_f32 v[190:191], v[16:17], v[100:101], v[190:191]
	v_pk_mul_f32 v[120:121], v[156:157], v[78:79] op_sel_hi:[0,1]
	v_pk_mul_f32 v[122:123], v[156:157], v[78:79] op_sel:[1,0]
	v_pk_fma_f32 v[6:7], v[6:7], v[110:111], v[120:121] op_sel:[0,1,0]
	v_pk_fma_f32 v[18:19], v[18:19], v[110:111], v[122:123] op_sel:[0,1,0]
	v_pk_fma_f32 v[188:189], v[6:7], v[102:103], v[188:189]
	v_pk_fma_f32 v[190:191], v[18:19], v[102:103], v[190:191]
	v_add_f32_e64 v192, v188, v189
	v_add_f32_e64 v193, v190, v191
	s_waitcnt lgkmcnt(0)
	s_nop 0
	ds_read_b64 v[108:109], v152 offset:18944
	ds_read_b64 v[110:111], v153 offset:41072
	ds_read_b128 v[68:71], v150 offset:17952
	ds_read_b128 v[92:95], v150 offset:18464
	ds_read_b128 v[76:79], v151 offset:17968
	ds_read_b128 v[100:103], v151 offset:18480
	v_pk_mul_f32 v[156:157], v[112:113], v[114:115] op_sel_hi:[1,0]
	v_pk_mul_f32 v[116:117], v[156:157], v[60:61] op_sel_hi:[0,1]
	v_pk_mul_f32 v[118:119], v[156:157], v[60:61] op_sel:[1,0]
	v_pk_fma_f32 v[28:29], v[28:29], v[114:115], v[116:117] op_sel:[0,1,0]
	v_pk_fma_f32 v[24:25], v[24:25], v[114:115], v[118:119] op_sel:[0,1,0]
	v_pk_mul_f32 v[188:189], v[28:29], v[84:85]
	v_pk_mul_f32 v[190:191], v[24:25], v[84:85]
	v_add_f32_dpp v192, v192, v192 quad_perm:[1,0,3,2] row_mask:0xf bank_mask:0xf bound_ctrl:1
	v_add_f32_dpp v193, v193, v193 quad_perm:[1,0,3,2] row_mask:0xf bank_mask:0xf bound_ctrl:1
	v_pk_mul_f32 v[120:121], v[156:157], v[62:63] op_sel_hi:[0,1]
	v_pk_mul_f32 v[122:123], v[156:157], v[62:63] op_sel:[1,0]
	v_pk_fma_f32 v[30:31], v[30:31], v[114:115], v[120:121] op_sel:[0,1,0]
	v_pk_fma_f32 v[26:27], v[26:27], v[114:115], v[122:123] op_sel:[0,1,0]
	v_pk_fma_f32 v[188:189], v[30:31], v[86:87], v[188:189]
	v_pk_fma_f32 v[190:191], v[26:27], v[86:87], v[190:191]
	v_add_f32_dpp v192, v192, v192 quad_perm:[2,3,0,1] row_mask:0xf bank_mask:0xf bound_ctrl:1
	v_add_f32_dpp v193, v193, v193 quad_perm:[2,3,0,1] row_mask:0xf bank_mask:0xf bound_ctrl:1
	v_pk_mul_f32 v[116:117], v[156:157], v[64:65] op_sel_hi:[0,1]
	v_pk_mul_f32 v[118:119], v[156:157], v[64:65] op_sel:[1,0]
	v_pk_fma_f32 v[12:13], v[12:13], v[114:115], v[116:117] op_sel:[0,1,0]
	v_pk_fma_f32 v[32:33], v[32:33], v[114:115], v[118:119] op_sel:[0,1,0]
	v_pk_fma_f32 v[188:189], v[12:13], v[88:89], v[188:189]
	v_pk_fma_f32 v[190:191], v[32:33], v[88:89], v[190:191]
	v_add_f32_dpp v192, v192, v192 row_half_mirror row_mask:0xf bank_mask:0xf bound_ctrl:1
	v_add_f32_dpp v193, v193, v193 row_half_mirror row_mask:0xf bank_mask:0xf bound_ctrl:1
	v_pk_mul_f32 v[120:121], v[156:157], v[66:67] op_sel_hi:[0,1]
	v_pk_mul_f32 v[122:123], v[156:157], v[66:67] op_sel:[1,0]
	v_pk_fma_f32 v[14:15], v[14:15], v[114:115], v[120:121] op_sel:[0,1,0]
	v_pk_fma_f32 v[34:35], v[34:35], v[114:115], v[122:123] op_sel:[0,1,0]
	v_pk_fma_f32 v[188:189], v[14:15], v[90:91], v[188:189]
	v_pk_fma_f32 v[190:191], v[34:35], v[90:91], v[190:191]
	ds_read_b128 v[60:63], v150 offset:17920
	ds_read_b128 v[84:87], v150 offset:18432
	ds_read_b128 v[64:67], v151 offset:17936
	ds_read_b128 v[88:91], v151 offset:18448
	ds_write_b64 v154, v[192:193] offset:3072
	v_pk_mul_f32 v[116:117], v[156:157], v[72:73] op_sel_hi:[0,1]
	v_pk_mul_f32 v[118:119], v[156:157], v[72:73] op_sel:[1,0]
	v_pk_fma_f32 v[8:9], v[8:9], v[114:115], v[116:117] op_sel:[0,1,0]
	v_pk_fma_f32 v[20:21], v[20:21], v[114:115], v[118:119] op_sel:[0,1,0]
	v_pk_fma_f32 v[188:189], v[8:9], v[96:97], v[188:189]
	v_pk_fma_f32 v[190:191], v[20:21], v[96:97], v[190:191]
	v_pk_mul_f32 v[120:121], v[156:157], v[74:75] op_sel_hi:[0,1]
	v_pk_mul_f32 v[122:123], v[156:157], v[74:75] op_sel:[1,0]
	v_pk_fma_f32 v[10:11], v[10:11], v[114:115], v[120:121] op_sel:[0,1,0]
	v_pk_fma_f32 v[22:23], v[22:23], v[114:115], v[122:123] op_sel:[0,1,0]
	v_pk_fma_f32 v[188:189], v[10:11], v[98:99], v[188:189]
	v_pk_fma_f32 v[190:191], v[22:23], v[98:99], v[190:191]
	v_pk_mul_f32 v[116:117], v[156:157], v[80:81] op_sel_hi:[0,1]
	v_pk_mul_f32 v[118:119], v[156:157], v[80:81] op_sel:[1,0]
	v_pk_fma_f32 v[4:5], v[4:5], v[114:115], v[116:117] op_sel:[0,1,0]
	v_pk_fma_f32 v[16:17], v[16:17], v[114:115], v[118:119] op_sel:[0,1,0]
	v_pk_fma_f32 v[188:189], v[4:5], v[104:105], v[188:189]
	v_pk_fma_f32 v[190:191], v[16:17], v[104:105], v[190:191]
	v_pk_mul_f32 v[120:121], v[156:157], v[82:83] op_sel_hi:[0,1]
	v_pk_mul_f32 v[122:123], v[156:157], v[82:83] op_sel:[1,0]
	v_pk_fma_f32 v[6:7], v[6:7], v[114:115], v[120:121] op_sel:[0,1,0]
	v_pk_fma_f32 v[18:19], v[18:19], v[114:115], v[122:123] op_sel:[0,1,0]
	v_pk_fma_f32 v[188:189], v[6:7], v[106:107], v[188:189]
	v_pk_fma_f32 v[190:191], v[18:19], v[106:107], v[190:191]
	v_add_f32_e64 v192, v188, v189
	v_add_f32_e64 v193, v190, v191
	s_waitcnt lgkmcnt(0)
; __device__ __forceinline__ float red8(float v) { v = red4(v); v += dppf<0x141>(v); return v; }
; __device__ __forceinline__ f32x2 lo2(const f32x4& v) { return __builtin_shufflevector(v, v, 0, 1); }
; __device__ __forceinline__ f32x2 hi2(const f32x4& v) { return __builtin_shufflevector(v, v, 2, 3); }
; __device__ __forceinline__ f32x2 splat2(float x) { return (f32x2){x, x}; }
; #define SCAN_INTERLEAVE(nds, nvalu)                                   \
;   _Pragma("unroll") for (int i_ = 0; i_ < (nds); ++i_) {               \
;     __builtin_amdgcn_sched_group_barrier(0x100, 1, 0);                 \
;     __builtin_amdgcn_sched_group_barrier(0x002, (nvalu), 0);           \
;   }
; __device__ __forceinline__ f32x2 ss_step(f32x2 (&S)[2][8], const SsRegs& R) {
;   const f32x2 dA2 = splat2(R.sc.y);
;   f32x2 out;
; #pragma unroll
;   for (int r = 0; r < 2; ++r) {
;     const f32x2 xdt2 = splat2((r ? R.x.y : R.x.x) * R.sc.x);
;     f32x2 y0 = splat2(0.f), y1 = splat2(0.f);
; #pragma unroll
;     for (int q = 0; q < 4; ++q) {
;       S[r][2 * q] = S[r][2 * q] * dA2 + xdt2 * lo2(R.B[q]);
;       S[r][2 * q + 1] = S[r][2 * q + 1] * dA2 + xdt2 * hi2(R.B[q]);
;       y0 += S[r][2 * q] * lo2(R.C[q]);
;       y1 += S[r][2 * q + 1] * hi2(R.C[q]);
;     }
;     y0 += y1;
;     const float y = red8(y0.x + y0.y);
;     if (r) out.y = y; else out.x = y;
;   }
;   return out;
; }
; __device__ __forceinline__ void scan_ssm(const Params& p, int l, int seq, int h, char* smem, const unsigned* wflags, unsigned wexpect) {
;     ...
;     ss_load(RA, vb, sb, 0, n0, prow0);
;     for (int t = 0; t < nsteps; t += 2) {
;       ss_load(RB, vb, sb, min(t + 1, 15), n0, prow0);
;       const f32x2 y0v = ss_step(S, RA);
;       *(f32x2*)((part == 0) ? (yb + t * 64 + prow0) : ydummy) = y0v;
;       SCAN_INTERLEAVE(10, 5);
;       if (t + 1 < nsteps) {
;         ss_load(RA, vb, sb, min(t + 2, 15), n0, prow0);
;         const f32x2 y1v = ss_step(S, RB);
;         *(f32x2*)((part == 0) ? (yb + (t + 1) * 64 + prow0) : ydummy) = y1v;
;         SCAN_INTERLEAVE(10, 5);
;       }
;     }
	s_nop 0
	ds_read_b64 v[112:113], v152 offset:20224
	ds_read_b64 v[114:115], v153 offset:41080
	ds_read_b128 v[72:75], v150 offset:19232
	ds_read_b128 v[96:99], v150 offset:19744
	ds_read_b128 v[80:83], v151 offset:19248
	ds_read_b128 v[104:107], v151 offset:19760
	v_pk_mul_f32 v[156:157], v[108:109], v[110:111] op_sel_hi:[1,0]
	v_pk_mul_f32 v[116:117], v[156:157], v[60:61] op_sel_hi:[0,1]
	v_pk_mul_f32 v[118:119], v[156:157], v[60:61] op_sel:[1,0]
	v_pk_fma_f32 v[28:29], v[28:29], v[110:111], v[116:117] op_sel:[0,1,0]
	v_pk_fma_f32 v[24:25], v[24:25], v[110:111], v[118:119] op_sel:[0,1,0]
	v_pk_mul_f32 v[188:189], v[28:29], v[84:85]
	v_pk_mul_f32 v[190:191], v[24:25], v[84:85]
	v_add_f32_dpp v192, v192, v192 quad_perm:[1,0,3,2] row_mask:0xf bank_mask:0xf bound_ctrl:1
	v_add_f32_dpp v193, v193, v193 quad_perm:[1,0,3,2] row_mask:0xf bank_mask:0xf bound_ctrl:1
	v_pk_mul_f32 v[120:121], v[156:157], v[62:63] op_sel_hi:[0,1]
	v_pk_mul_f32 v[122:123], v[156:157], v[62:63] op_sel:[1,0]
	v_pk_fma_f32 v[30:31], v[30:31], v[110:111], v[120:121] op_sel:[0,1,0]
	v_pk_fma_f32 v[26:27], v[26:27], v[110:111], v[122:123] op_sel:[0,1,0]
	v_pk_fma_f32 v[188:189], v[30:31], v[86:87], v[188:189]
	v_pk_fma_f32 v[190:191], v[26:27], v[86:87], v[190:191]
	v_add_f32_dpp v192, v192, v192 quad_perm:[2,3,0,1] row_mask:0xf bank_mask:0xf bound_ctrl:1
	v_add_f32_dpp v193, v193, v193 quad_perm:[2,3,0,1] row_mask:0xf bank_mask:0xf bound_ctrl:1
	v_pk_mul_f32 v[116:117], v[156:157], v[64:65] op_sel_hi:[0,1]
	v_pk_mul_f32 v[118:119], v[156:157], v[64:65] op_sel:[1,0]
	v_pk_fma_f32 v[12:13], v[12:13], v[110:111], v[116:117] op_sel:[0,1,0]
	v_pk_fma_f32 v[32:33], v[32:33], v[110:111], v[118:119] op_sel:[0,1,0]
	v_pk_fma_f32 v[188:189], v[12:13], v[88:89], v[188:189]
	v_pk_fma_f32 v[190:191], v[32:33], v[88:89], v[190:191]
	v_add_f32_dpp v192, v192, v192 row_half_mirror row_mask:0xf bank_mask:0xf bound_ctrl:1
	v_add_f32_dpp v193, v193, v193 row_half_mirror row_mask:0xf bank_mask:0xf bound_ctrl:1
	v_pk_mul_f32 v[120:121], v[156:157], v[66:67] op_sel_hi:[0,1]
	v_pk_mul_f32 v[122:123], v[156:157], v[66:67] op_sel:[1,0]
	v_pk_fma_f32 v[14:15], v[14:15], v[110:111], v[120:121] op_sel:[0,1,0]
	v_pk_fma_f32 v[34:35], v[34:35], v[110:111], v[122:123] op_sel:[0,1,0]
	v_pk_fma_f32 v[188:189], v[14:15], v[90:91], v[188:189]
	v_pk_fma_f32 v[190:191], v[34:35], v[90:91], v[190:191]
	ds_read_b128 v[60:63], v150 offset:19200
	ds_read_b128 v[84:87], v150 offset:19712
	ds_read_b128 v[64:67], v151 offset:19216
	ds_read_b128 v[88:91], v151 offset:19728
	ds_write_b64 v154, v[192:193] offset:3328
	v_pk_mul_f32 v[116:117], v[156:157], v[68:69] op_sel_hi:[0,1]
	v_pk_mul_f32 v[118:119], v[156:157], v[68:69] op_sel:[1,0]
	v_pk_fma_f32 v[8:9], v[8:9], v[110:111], v[116:117] op_sel:[0,1,0]
	v_pk_fma_f32 v[20:21], v[20:21], v[110:111], v[118:119] op_sel:[0,1,0]
	v_pk_fma_f32 v[188:189], v[8:9], v[92:93], v[188:189]
	v_pk_fma_f32 v[190:191], v[20:21], v[92:93], v[190:191]
	v_pk_mul_f32 v[120:121], v[156:157], v[70:71] op_sel_hi:[0,1]
	v_pk_mul_f32 v[122:123], v[156:157], v[70:71] op_sel:[1,0]
	v_pk_fma_f32 v[10:11], v[10:11], v[110:111], v[120:121] op_sel:[0,1,0]
	v_pk_fma_f32 v[22:23], v[22:23], v[110:111], v[122:123] op_sel:[0,1,0]
	v_pk_fma_f32 v[188:189], v[10:11], v[94:95], v[188:189]
	v_pk_fma_f32 v[190:191], v[22:23], v[94:95], v[190:191]
	v_pk_mul_f32 v[116:117], v[156:157], v[76:77] op_sel_hi:[0,1]
	v_pk_mul_f32 v[118:119], v[156:157], v[76:77] op_sel:[1,0]
	v_pk_fma_f32 v[4:5], v[4:5], v[110:111], v[116:117] op_sel:[0,1,0]
	v_pk_fma_f32 v[16:17], v[16:17], v[110:111], v[118:119] op_sel:[0,1,0]
	v_pk_fma_f32 v[188:189], v[4:5], v[100:101], v[188:189]
	v_pk_fma_f32 v[190:191], v[16:17], v[100:101], v[190:191]
	v_pk_mul_f32 v[120:121], v[156:157], v[78:79] op_sel_hi:[0,1]
	v_pk_mul_f32 v[122:123], v[156:157], v[78:79] op_sel:[1,0]
	v_pk_fma_f32 v[6:7], v[6:7], v[110:111], v[120:121] op_sel:[0,1,0]
	v_pk_fma_f32 v[18:19], v[18:19], v[110:111], v[122:123] op_sel:[0,1,0]
	v_pk_fma_f32 v[188:189], v[6:7], v[102:103], v[188:189]
	v_pk_fma_f32 v[190:191], v[18:19], v[102:103], v[190:191]
	v_add_f32_e64 v192, v188, v189
	v_add_f32_e64 v193, v190, v191
	s_waitcnt lgkmcnt(0)
; __device__ __forceinline__ float red8(float v) { v = red4(v); v += dppf<0x141>(v); return v; }
; __device__ __forceinline__ f32x2 lo2(const f32x4& v) { return __builtin_shufflevector(v, v, 0, 1); }
; __device__ __forceinline__ f32x2 hi2(const f32x4& v) { return __builtin_shufflevector(v, v, 2, 3); }
; __device__ __forceinline__ f32x2 splat2(float x) { return (f32x2){x, x}; }
; #define SCAN_INTERLEAVE(nds, nvalu)                                   \
;   _Pragma("unroll") for (int i_ = 0; i_ < (nds); ++i_) {               \
;     __builtin_amdgcn_sched_group_barrier(0x100, 1, 0);                 \
;     __builtin_amdgcn_sched_group_barrier(0x002, (nvalu), 0);           \
;   }
; __device__ __forceinline__ f32x2 ss_step(f32x2 (&S)[2][8], const SsRegs& R) {
;   const f32x2 dA2 = splat2(R.sc.y);
;   f32x2 out;
; #pragma unroll
;   for (int r = 0; r < 2; ++r) {
;     const f32x2 xdt2 = splat2((r ? R.x.y : R.x.x) * R.sc.x);
;     f32x2 y0 = splat2(0.f), y1 = splat2(0.f);
; #pragma unroll
;     for (int q = 0; q < 4; ++q) {
;       S[r][2 * q] = S[r][2 * q] * dA2 + xdt2 * lo2(R.B[q]);
;       S[r][2 * q + 1] = S[r][2 * q + 1] * dA2 + xdt2 * hi2(R.B[q]);
;       y0 += S[r][2 * q] * lo2(R.C[q]);
;       y1 += S[r][2 * q + 1] * hi2(R.C[q]);
;     }
;     y0 += y1;
;     const float y = red8(y0.x + y0.y);
;     if (r) out.y = y; else out.x = y;
;   }
;   return out;
; }
; __device__ __forceinline__ void scan_ssm(const Params& p, int l, int seq, int h, char* smem, const unsigned* wflags, unsigned wexpect) {
;     ...
;     ss_load(RA, vb, sb, 0, n0, prow0);
;     for (int t = 0; t < nsteps; t += 2) {
;       ss_load(RB, vb, sb, min(t + 1, 15), n0, prow0);
;       const f32x2 y0v = ss_step(S, RA);
;       *(f32x2*)((part == 0) ? (yb + t * 64 + prow0) : ydummy) = y0v;
;       SCAN_INTERLEAVE(10, 5);
;       if (t + 1 < nsteps) {
;         ss_load(RA, vb, sb, min(t + 2, 15), n0, prow0);
;         const f32x2 y1v = ss_step(S, RB);
;         *(f32x2*)((part == 0) ? (yb + (t + 1) * 64 + prow0) : ydummy) = y1v;
;         SCAN_INTERLEAVE(10, 5);
;       }
;     }
	s_nop 0
	ds_read_b64 v[108:109], v152 offset:21504
	ds_read_b64 v[110:111], v153 offset:41088
	ds_read_b128 v[68:71], v150 offset:20512
	ds_read_b128 v[92:95], v150 offset:21024
	ds_read_b128 v[76:79], v151 offset:20528
	ds_read_b128 v[100:103], v151 offset:21040
	v_pk_mul_f32 v[156:157], v[112:113], v[114:115] op_sel_hi:[1,0]
	v_pk_mul_f32 v[116:117], v[156:157], v[60:61] op_sel_hi:[0,1]
	v_pk_mul_f32 v[118:119], v[156:157], v[60:61] op_sel:[1,0]
	v_pk_fma_f32 v[28:29], v[28:29], v[114:115], v[116:117] op_sel:[0,1,0]
	v_pk_fma_f32 v[24:25], v[24:25], v[114:115], v[118:119] op_sel:[0,1,0]
	v_pk_mul_f32 v[188:189], v[28:29], v[84:85]
	v_pk_mul_f32 v[190:191], v[24:25], v[84:85]
	v_add_f32_dpp v192, v192, v192 quad_perm:[1,0,3,2] row_mask:0xf bank_mask:0xf bound_ctrl:1
	v_add_f32_dpp v193, v193, v193 quad_perm:[1,0,3,2] row_mask:0xf bank_mask:0xf bound_ctrl:1
	v_pk_mul_f32 v[120:121], v[156:157], v[62:63] op_sel_hi:[0,1]
	v_pk_mul_f32 v[122:123], v[156:157], v[62:63] op_sel:[1,0]
	v_pk_fma_f32 v[30:31], v[30:31], v[114:115], v[120:121] op_sel:[0,1,0]
	v_pk_fma_f32 v[26:27], v[26:27], v[114:115], v[122:123] op_sel:[0,1,0]
	v_pk_fma_f32 v[188:189], v[30:31], v[86:87], v[188:189]
	v_pk_fma_f32 v[190:191], v[26:27], v[86:87], v[190:191]
	v_add_f32_dpp v192, v192, v192 quad_perm:[2,3,0,1] row_mask:0xf bank_mask:0xf bound_ctrl:1
	v_add_f32_dpp v193, v193, v193 quad_perm:[2,3,0,1] row_mask:0xf bank_mask:0xf bound_ctrl:1
	v_pk_mul_f32 v[116:117], v[156:157], v[64:65] op_sel_hi:[0,1]
	v_pk_mul_f32 v[118:119], v[156:157], v[64:65] op_sel:[1,0]
	v_pk_fma_f32 v[12:13], v[12:13], v[114:115], v[116:117] op_sel:[0,1,0]
	v_pk_fma_f32 v[32:33], v[32:33], v[114:115], v[118:119] op_sel:[0,1,0]
	v_pk_fma_f32 v[188:189], v[12:13], v[88:89], v[188:189]
	v_pk_fma_f32 v[190:191], v[32:33], v[88:89], v[190:191]
	v_add_f32_dpp v192, v192, v192 row_half_mirror row_mask:0xf bank_mask:0xf bound_ctrl:1
	v_add_f32_dpp v193, v193, v193 row_half_mirror row_mask:0xf bank_mask:0xf bound_ctrl:1
	v_pk_mul_f32 v[120:121], v[156:157], v[66:67] op_sel_hi:[0,1]
	v_pk_mul_f32 v[122:123], v[156:157], v[66:67] op_sel:[1,0]
	v_pk_fma_f32 v[14:15], v[14:15], v[114:115], v[120:121] op_sel:[0,1,0]
	v_pk_fma_f32 v[34:35], v[34:35], v[114:115], v[122:123] op_sel:[0,1,0]
	v_pk_fma_f32 v[188:189], v[14:15], v[90:91], v[188:189]
	v_pk_fma_f32 v[190:191], v[34:35], v[90:91], v[190:191]
	ds_read_b128 v[60:63], v150 offset:20480
	ds_read_b128 v[84:87], v150 offset:20992
	ds_read_b128 v[64:67], v151 offset:20496
	ds_read_b128 v[88:91], v151 offset:21008
	ds_write_b64 v154, v[192:193] offset:3584
	v_pk_mul_f32 v[116:117], v[156:157], v[72:73] op_sel_hi:[0,1]
	v_pk_mul_f32 v[118:119], v[156:157], v[72:73] op_sel:[1,0]
	v_pk_fma_f32 v[8:9], v[8:9], v[114:115], v[116:117] op_sel:[0,1,0]
	v_pk_fma_f32 v[20:21], v[20:21], v[114:115], v[118:119] op_sel:[0,1,0]
	v_pk_fma_f32 v[188:189], v[8:9], v[96:97], v[188:189]
	v_pk_fma_f32 v[190:191], v[20:21], v[96:97], v[190:191]
	v_pk_mul_f32 v[120:121], v[156:157], v[74:75] op_sel_hi:[0,1]
	v_pk_mul_f32 v[122:123], v[156:157], v[74:75] op_sel:[1,0]
	v_pk_fma_f32 v[10:11], v[10:11], v[114:115], v[120:121] op_sel:[0,1,0]
	v_pk_fma_f32 v[22:23], v[22:23], v[114:115], v[122:123] op_sel:[0,1,0]
	v_pk_fma_f32 v[188:189], v[10:11], v[98:99], v[188:189]
	v_pk_fma_f32 v[190:191], v[22:23], v[98:99], v[190:191]
	v_pk_mul_f32 v[116:117], v[156:157], v[80:81] op_sel_hi:[0,1]
	v_pk_mul_f32 v[118:119], v[156:157], v[80:81] op_sel:[1,0]
	v_pk_fma_f32 v[4:5], v[4:5], v[114:115], v[116:117] op_sel:[0,1,0]
	v_pk_fma_f32 v[16:17], v[16:17], v[114:115], v[118:119] op_sel:[0,1,0]
	v_pk_fma_f32 v[188:189], v[4:5], v[104:105], v[188:189]
	v_pk_fma_f32 v[190:191], v[16:17], v[104:105], v[190:191]
	v_pk_mul_f32 v[120:121], v[156:157], v[82:83] op_sel_hi:[0,1]
	v_pk_mul_f32 v[122:123], v[156:157], v[82:83] op_sel:[1,0]
	v_pk_fma_f32 v[6:7], v[6:7], v[114:115], v[120:121] op_sel:[0,1,0]
	v_pk_fma_f32 v[18:19], v[18:19], v[114:115], v[122:123] op_sel:[0,1,0]
	v_pk_fma_f32 v[188:189], v[6:7], v[106:107], v[188:189]
	v_pk_fma_f32 v[190:191], v[18:19], v[106:107], v[190:191]
	v_add_f32_e64 v192, v188, v189
	v_add_f32_e64 v193, v190, v191
	s_nop 0
	s_nop 0
	v_add_f32_dpp v192, v192, v192 quad_perm:[1,0,3,2] row_mask:0xf bank_mask:0xf bound_ctrl:1
	v_add_f32_dpp v193, v193, v193 quad_perm:[1,0,3,2] row_mask:0xf bank_mask:0xf bound_ctrl:1
	s_nop 0
	s_nop 0
	v_add_f32_dpp v192, v192, v192 quad_perm:[2,3,0,1] row_mask:0xf bank_mask:0xf bound_ctrl:1
	v_add_f32_dpp v193, v193, v193 quad_perm:[2,3,0,1] row_mask:0xf bank_mask:0xf bound_ctrl:1
	s_nop 0
	s_nop 0
	v_add_f32_dpp v192, v192, v192 row_half_mirror row_mask:0xf bank_mask:0xf bound_ctrl:1
	v_add_f32_dpp v193, v193, v193 row_half_mirror row_mask:0xf bank_mask:0xf bound_ctrl:1
	ds_write_b64 v154, v[192:193] offset:3840
	s_cmp_eq_u32 s50, 0
	s_cbranch_scc1 .LBB0_648
	s_branch .LBB0_684
